# baseline (speedup 1.0000x reference)
;     DI size_t aoff(const Unit& u, size_t tstep) const { return (size_t)u.pm * tstep; }
;     DI size_t boff(const Unit& u, size_t tstep) const { return (size_t)u.pn * tstep; }
;     DI bool next(int i, Unit& u) const { const long L = (long)i * G + c; if (L >= np) return false; u.pm = pmv; u.pn = (int)(L % nN); u.ks = (int)(L / nN); return true; }
;     DI size_t aoff(const Unit& u, size_t) const { return (size_t)u.ks * kbytes; }
;     DI size_t boff(const Unit& u, size_t tstep) const { return (size_t)u.pn * tstep + (size_t)u.ks * kbytes; }
;     DI bool next(int i, Unit& u) const { Unit t; if (!S.next(i / 3, t)) return false; u.pm = t.pm; u.pn = t.pn; u.ks = i % 3; return true; }
;     DI size_t aoff(const Unit& u, size_t tstep) const { return (u.ks < 2 ? offU : offOA) + (size_t)u.pm * tstep; }
; #define PG8_LDA(dst, b, h) do { _Pragma("unroll") for (int m = 0; m < 4; ++m) _Pragma("unroll") for (int k = 0; k < 2; ++k) dst[m][k] = *(const LAS bf16x8*)(lds + PG8_SA(b, h) + aoff + m * 2048 + k * 1024); } while (0)
; template <class Epi, class Sched>
; DI void gemm_phase(LAS unsigned char* lds, const Gemm g, const Sched& S, const Epi& E) {
;     ...
;         const bool has_next = S.next(ui + 1, nxt);
;         const char* nA = has_next ? (const char*)g.A + S.aoff(nxt, tstep) : cA; const char* nB = has_next ? (const char*)g.Bt + S.boff(nxt, tstep) : cB;
;         for (int t = 0; t < nt; t += 2) {
;             if constexpr (Epi::HAS_MID) { if (t == E.mid_t(nt)) { int fr3 = fr, fq3 = fq; asm volatile("" : "+v"(fr3), "+v"(fq3)); E.mid(acc, cur, wr, wc, fr3, fq3); } }
;             const bool last = (t == nt - 2);
;             const char* a1 = cA + (size_t)(t + 1) * kstep;
;             const char* a2 = last ? nA : cA + (size_t)(t + 2) * kstep; const char* b2 = last ? nB : cB + (size_t)(t + 2) * kstep;
;             const char* a3 = a2 + kstep; const char* b3 = b2 + kstep;
;             PG8_LDB(B0, 0, 0); PG8_SCHED; PG8_LDA(At, 0, 0); PG8_STAGE(PG8_SA(1, 1), a1 + hstep, voffA);
;             PG8_WAIT_L(8); PG8_BAR; PG8_WAIT_L(0); PG8_MMA(0, 0, At, B0); PG8_BAR; PG8_SCHED;
;             PG8_LDB(B1, 0, 1); PG8_STAGE(PG8_SB(0, 0), b2, voffB);
;             PG8_BAR; PG8_WAIT_L(0); PG8_MMA(0, 1, At, B1); PG8_BAR;
;             PG8_LDA(At, 0, 1); PG8_STAGE(PG8_SA(0, 0), a2, voffA);
;             PG8_BAR; PG8_WAIT_L(0); PG8_MMA(1, 0, At, B0); PG8_BAR; PG8_SCHED;
.LBB0_218:
	s_ashr_i32 s17, s16, 31
	s_lshl_b64 s[0:1], s[16:17], 20
	v_cmp_lt_i64_e32 vcc, s[18:19], v[140:141]
	s_add_u32 s18, s47, s0
	s_addc_u32 s19, s48, s1
	s_and_b64 s[0:1], vcc, exec
	s_cselect_b32 s17, s19, s41
	s_cselect_b32 s65, s18, s40
	s_ashr_i32 s15, s14, 31
	s_lshl_b64 s[0:1], s[14:15], 20
	s_add_u32 s36, s49, s0
	s_addc_u32 s37, s50, s1
	s_and_b64 s[0:1], vcc, exec
	s_cselect_b32 s15, s37, s43
	s_cselect_b32 s66, s36, s42
	s_add_u32 s40, s40, 0x80080
	s_addc_u32 s41, s41, 0
	s_add_u32 s67, s42, 0x100
	v_mov_b32_e32 v0, 0
	s_addc_u32 s68, s43, 0
	s_mov_b32 s69, -2
	ds_read_b128 v[150:153], v147
	ds_read_b128 v[154:157], v147 offset:1024
	ds_read_b128 v[162:165], v147 offset:2048
	ds_read_b128 v[166:169], v147 offset:3072
	s_add_u32 s0, s40, 0xfff80080
	s_addc_u32 s1, s41, -1
	s_cmp_eq_u32 s69, 28
	s_cselect_b32 s45, s17, s1
	s_cselect_b32 s44, s65, s0
	s_cselect_b32 s43, s15, s68
	s_cselect_b32 s42, s66, s67
	s_add_i32 m0, s39, 0xc000
	ds_read_b128 v[170:173], v148
	ds_read_b128 v[174:177], v148 offset:1024
	ds_read_b128 v[178:181], v148 offset:2048
	ds_read_b128 v[188:191], v148 offset:3072
	ds_read_b128 v[194:197], v148 offset:4096
	ds_read_b128 v[198:201], v148 offset:5120
	ds_read_b128 v[202:205], v148 offset:6144
	global_load_lds_dwordx4 v136, s[40:41]
	s_add_i32 m0, s39, 0xe000
	ds_read_b128 v[206:209], v148 offset:7168
	global_load_lds_dwordx4 v138, s[40:41]
	s_waitcnt lgkmcnt(8)
	s_barrier
	s_waitcnt lgkmcnt(0)
	s_setprio 1
	v_mfma_f32_16x16x32_bf16 v[124:127], v[150:153], v[170:173], 0
	v_mfma_f32_16x16x32_bf16 v[120:123], v[162:165], v[170:173], 0
	v_mfma_f32_16x16x32_bf16 v[108:111], v[150:153], v[178:181], 0
	v_mfma_f32_16x16x32_bf16 v[104:107], v[162:165], v[178:181], 0
	v_mfma_f32_16x16x32_bf16 v[92:95], v[150:153], v[194:197], 0
	v_mfma_f32_16x16x32_bf16 v[88:91], v[162:165], v[194:197], 0
	v_mfma_f32_16x16x32_bf16 v[76:79], v[150:153], v[202:205], 0
	v_mfma_f32_16x16x32_bf16 v[72:75], v[162:165], v[202:205], 0
	v_mfma_f32_16x16x32_bf16 v[124:127], v[154:157], v[174:177], v[124:127]
	v_mfma_f32_16x16x32_bf16 v[120:123], v[166:169], v[174:177], v[120:123]
	v_mfma_f32_16x16x32_bf16 v[108:111], v[154:157], v[188:191], v[108:111]
	v_mfma_f32_16x16x32_bf16 v[104:107], v[166:169], v[188:191], v[104:107]
	v_mfma_f32_16x16x32_bf16 v[92:95], v[154:157], v[198:201], v[92:95]
	v_mfma_f32_16x16x32_bf16 v[88:91], v[166:169], v[198:201], v[88:91]
	v_mfma_f32_16x16x32_bf16 v[76:79], v[154:157], v[206:209], v[76:79]
	v_mfma_f32_16x16x32_bf16 v[72:75], v[166:169], v[206:209], v[72:75]
	s_setprio 0
	s_barrier
	s_add_i32 s0, s34, s52
	s_mov_b32 m0, s0
	ds_read_b128 v[210:213], v149
	ds_read_b128 v[214:217], v149 offset:1024
	ds_read_b128 v[218:221], v149 offset:2048
	global_load_lds_dwordx4 v130, s[42:43]
	s_add_i32 m0, s0, 0x2000
	ds_read_b128 v[222:225], v149 offset:3072
	global_load_lds_dwordx4 v134, s[42:43]
	s_barrier
	s_waitcnt lgkmcnt(0)
	s_setprio 1
	v_mfma_f32_16x16x32_bf16 v[116:119], v[210:213], v[170:173], 0
	v_mfma_f32_16x16x32_bf16 v[112:115], v[218:221], v[170:173], 0
	v_mfma_f32_16x16x32_bf16 v[100:103], v[210:213], v[178:181], 0
	v_mfma_f32_16x16x32_bf16 v[96:99], v[218:221], v[178:181], 0
	v_mfma_f32_16x16x32_bf16 v[84:87], v[210:213], v[194:197], 0
	v_mfma_f32_16x16x32_bf16 v[80:83], v[218:221], v[194:197], 0
	v_mfma_f32_16x16x32_bf16 v[68:71], v[210:213], v[202:205], 0
	v_mfma_f32_16x16x32_bf16 v[64:67], v[218:221], v[202:205], 0
	v_mfma_f32_16x16x32_bf16 v[116:119], v[214:217], v[174:177], v[116:119]
	v_mfma_f32_16x16x32_bf16 v[112:115], v[222:225], v[174:177], v[112:115]
	v_mfma_f32_16x16x32_bf16 v[100:103], v[214:217], v[188:191], v[100:103]
	v_mfma_f32_16x16x32_bf16 v[96:99], v[222:225], v[188:191], v[96:99]
	v_mfma_f32_16x16x32_bf16 v[84:87], v[214:217], v[198:201], v[84:87]
	v_mfma_f32_16x16x32_bf16 v[80:83], v[222:225], v[198:201], v[80:83]
	v_mfma_f32_16x16x32_bf16 v[68:71], v[214:217], v[206:209], v[68:71]
	v_mfma_f32_16x16x32_bf16 v[64:67], v[222:225], v[206:209], v[64:67]
	s_setprio 0
	s_mov_b32 m0, s39
	s_barrier
	ds_read_b128 v[170:173], v148 offset:16384
	ds_read_b128 v[174:177], v148 offset:17408
	ds_read_b128 v[178:181], v148 offset:18432
	ds_read_b128 v[188:191], v148 offset:19456
	ds_read_b128 v[194:197], v148 offset:20480
	ds_read_b128 v[198:201], v148 offset:21504
	ds_read_b128 v[202:205], v148 offset:22528
	global_load_lds_dwordx4 v128, s[44:45]
	s_mov_b32 m0, s53
	ds_read_b128 v[206:209], v148 offset:23552
	global_load_lds_dwordx4 v132, s[44:45]
	s_barrier
	s_waitcnt lgkmcnt(0)
	s_setprio 1
	v_mfma_f32_16x16x32_bf16 v[60:63], v[150:153], v[170:173], 0
	v_mfma_f32_16x16x32_bf16 v[56:59], v[162:165], v[170:173], 0
	v_mfma_f32_16x16x32_bf16 v[44:47], v[150:153], v[178:181], 0
	v_mfma_f32_16x16x32_bf16 v[40:43], v[162:165], v[178:181], 0
	v_mfma_f32_16x16x32_bf16 v[28:31], v[150:153], v[194:197], 0
	v_mfma_f32_16x16x32_bf16 v[24:27], v[162:165], v[194:197], 0
	v_mfma_f32_16x16x32_bf16 v[12:15], v[150:153], v[202:205], 0
	v_mfma_f32_16x16x32_bf16 v[8:11], v[162:165], v[202:205], 0
	v_mfma_f32_16x16x32_bf16 v[60:63], v[154:157], v[174:177], v[60:63]
	v_mfma_f32_16x16x32_bf16 v[56:59], v[166:169], v[174:177], v[56:59]
	v_mfma_f32_16x16x32_bf16 v[44:47], v[154:157], v[188:191], v[44:47]
	v_mfma_f32_16x16x32_bf16 v[40:43], v[166:169], v[188:191], v[40:43]
	v_mfma_f32_16x16x32_bf16 v[28:31], v[154:157], v[198:201], v[28:31]
	v_mfma_f32_16x16x32_bf16 v[24:27], v[166:169], v[198:201], v[24:27]
	v_mfma_f32_16x16x32_bf16 v[12:15], v[154:157], v[206:209], v[12:15]
	v_mfma_f32_16x16x32_bf16 v[8:11], v[166:169], v[206:209], v[8:11]
	s_setprio 0
	s_barrier
; #define PG8_STAGE(bufoff, gbase, voff) do { _Pragma("unroll") for (int _i = 0; _i < 2; ++_i) \
;         __builtin_amdgcn_global_load_lds((const unsigned*)((const char*)(gbase) + (voff)[_i]), (LAS unsigned*)(lds + (bufoff) + ldsw + _i * 8192), 16, 0, 0); } while (0)
; #define PG8_LDA(dst, b, h) do { _Pragma("unroll") for (int m = 0; m < 4; ++m) _Pragma("unroll") for (int k = 0; k < 2; ++k) dst[m][k] = *(const LAS bf16x8*)(lds + PG8_SA(b, h) + aoff + m * 2048 + k * 1024); } while (0)
; #define PG8_LDB(dst, b, h) do { _Pragma("unroll") for (int n = 0; n < 2; ++n) _Pragma("unroll") for (int k = 0; k < 2; ++k) dst[n][k] = *(const LAS bf16x8*)(lds + PG8_SB(b, h) + boff + n * 2048 + k * 1024); } while (0)
; #define PG8_MMA(ai, bj, At, Bt) do { __builtin_amdgcn_s_setprio(1); _Pragma("unroll") for (int m = 0; m < 4; ++m) _Pragma("unroll") for (int n = 0; n < 2; ++n) _Pragma("unroll") for (int k = 0; k < 2; ++k) \
;         acc[ai][bj][m][n] = __builtin_amdgcn_mfma_f32_16x16x32_bf16(Bt[n][k], At[m][k], acc[ai][bj][m][n], 0, 0, 0); __builtin_amdgcn_s_setprio(0); } while (0)
; #define PG8_WAIT_V(n) asm volatile("s_waitcnt vmcnt(" #n ")" ::: "memory")
; #define PG8_WAIT_L(n) asm volatile("s_waitcnt lgkmcnt(" #n ")" ::: "memory")
; #define PG8_BAR __builtin_amdgcn_s_barrier()
; #define PG8_SCHED __builtin_amdgcn_sched_barrier(0)
; template <class Epi, class Sched>
; DI void gemm_phase(LAS unsigned char* lds, const Gemm g, const Sched& S, const Epi& E) {
;     ...
;             PG8_STAGE(PG8_SB(0, 1), b2 + hstep, voffB);
;             PG8_WAIT_V(6); PG8_BAR; PG8_MMA(1, 1, At, B1); PG8_BAR;
;             PG8_LDB(B0, 1, 0); PG8_SCHED; PG8_LDA(At, 1, 0); PG8_STAGE(PG8_SA(0, 1), a2 + hstep, voffA);
;             PG8_WAIT_L(8); PG8_BAR; PG8_WAIT_L(0); PG8_MMA(0, 0, At, B0); PG8_BAR; PG8_SCHED;
;             PG8_LDB(B1, 1, 1); PG8_STAGE(PG8_SB(1, 0), b3, voffB);
;             PG8_BAR; PG8_WAIT_L(0); PG8_MMA(0, 1, At, B1); PG8_BAR;
;             PG8_LDA(At, 1, 1); PG8_STAGE(PG8_SA(1, 0), a3, voffA);
;             PG8_BAR; PG8_WAIT_L(0); PG8_MMA(1, 0, At, B0); PG8_BAR; PG8_SCHED;
	s_add_i32 s4, s35, s52
	s_mov_b32 m0, s4
	s_add_u32 s0, s42, 0x80000
	s_addc_u32 s1, s43, 0
	global_load_lds_dwordx4 v130, s[0:1]
	s_add_i32 m0, s4, 0x2000
	s_nop 0
	global_load_lds_dwordx4 v134, s[0:1]
	s_waitcnt vmcnt(6)
	s_barrier
	s_setprio 1
	v_mfma_f32_16x16x32_bf16 v[52:55], v[210:213], v[170:173], 0
	v_mfma_f32_16x16x32_bf16 v[48:51], v[218:221], v[170:173], 0
	v_mfma_f32_16x16x32_bf16 v[36:39], v[210:213], v[178:181], 0
	v_mfma_f32_16x16x32_bf16 v[32:35], v[218:221], v[178:181], 0
	v_mfma_f32_16x16x32_bf16 v[20:23], v[210:213], v[194:197], 0
	v_mfma_f32_16x16x32_bf16 v[16:19], v[218:221], v[194:197], 0
	v_mfma_f32_16x16x32_bf16 v[4:7], v[210:213], v[202:205], 0
	v_mfma_f32_16x16x32_bf16 v[0:3], v[218:221], v[202:205], 0
	v_mfma_f32_16x16x32_bf16 v[52:55], v[214:217], v[174:177], v[52:55]
	v_mfma_f32_16x16x32_bf16 v[48:51], v[222:225], v[174:177], v[48:51]
	v_mfma_f32_16x16x32_bf16 v[36:39], v[214:217], v[188:191], v[36:39]
	v_mfma_f32_16x16x32_bf16 v[32:35], v[222:225], v[188:191], v[32:35]
	v_mfma_f32_16x16x32_bf16 v[20:23], v[214:217], v[198:201], v[20:23]
	v_mfma_f32_16x16x32_bf16 v[16:19], v[222:225], v[198:201], v[16:19]
	v_mfma_f32_16x16x32_bf16 v[4:7], v[214:217], v[206:209], v[4:7]
	v_mfma_f32_16x16x32_bf16 v[0:3], v[222:225], v[206:209], v[0:3]
	s_setprio 0
	s_add_i32 s4, 0, 0x18000
	v_add_u32_e32 v158, s4, v146
	s_barrier
	ds_read_b128 v[150:153], v158
	ds_read_b128 v[154:157], v158 offset:1024
	ds_read_b128 v[162:165], v158 offset:2048
	ds_read_b128 v[166:169], v158 offset:3072
	s_add_u32 s0, s44, 0x80000
	s_addc_u32 s1, s45, 0
	s_mov_b32 m0, s54
	ds_read_b128 v[170:173], v148 offset:32768
	ds_read_b128 v[174:177], v148 offset:33792
	ds_read_b128 v[178:181], v148 offset:34816
	ds_read_b128 v[188:191], v148 offset:35840
	ds_read_b128 v[194:197], v148 offset:36864
	ds_read_b128 v[198:201], v148 offset:37888
	ds_read_b128 v[202:205], v148 offset:38912
	global_load_lds_dwordx4 v128, s[0:1]
	s_mov_b32 m0, s55
	ds_read_b128 v[206:209], v148 offset:39936
	global_load_lds_dwordx4 v132, s[0:1]
	s_waitcnt lgkmcnt(8)
	s_barrier
	s_waitcnt lgkmcnt(0)
	s_setprio 1
	v_mfma_f32_16x16x32_bf16 v[124:127], v[150:153], v[170:173], v[124:127]
	v_mfma_f32_16x16x32_bf16 v[120:123], v[162:165], v[170:173], v[120:123]
	v_mfma_f32_16x16x32_bf16 v[108:111], v[150:153], v[178:181], v[108:111]
	v_mfma_f32_16x16x32_bf16 v[104:107], v[162:165], v[178:181], v[104:107]
	v_mfma_f32_16x16x32_bf16 v[92:95], v[150:153], v[194:197], v[92:95]
	v_mfma_f32_16x16x32_bf16 v[88:91], v[162:165], v[194:197], v[88:91]
	v_mfma_f32_16x16x32_bf16 v[76:79], v[150:153], v[202:205], v[76:79]
	v_mfma_f32_16x16x32_bf16 v[72:75], v[162:165], v[202:205], v[72:75]
	v_mfma_f32_16x16x32_bf16 v[124:127], v[154:157], v[174:177], v[124:127]
	v_mfma_f32_16x16x32_bf16 v[120:123], v[166:169], v[174:177], v[120:123]
	v_mfma_f32_16x16x32_bf16 v[108:111], v[154:157], v[188:191], v[108:111]
	v_mfma_f32_16x16x32_bf16 v[104:107], v[166:169], v[188:191], v[104:107]
	v_mfma_f32_16x16x32_bf16 v[92:95], v[154:157], v[198:201], v[92:95]
	v_mfma_f32_16x16x32_bf16 v[88:91], v[166:169], v[198:201], v[88:91]
	v_mfma_f32_16x16x32_bf16 v[76:79], v[154:157], v[206:209], v[76:79]
	v_mfma_f32_16x16x32_bf16 v[72:75], v[166:169], v[206:209], v[72:75]
	s_setprio 0
	s_barrier
	s_add_i32 s5, 0, 0x1c000
	s_add_i32 s0, s4, s52
	v_add_u32_e32 v159, s5, v146
	s_add_i32 m0, s0, 0xffffff80
	ds_read_b128 v[210:213], v159
	ds_read_b128 v[214:217], v159 offset:1024
	ds_read_b128 v[218:221], v159 offset:2048
	global_load_lds_dwordx4 v130, s[42:43] offset:128
	s_add_i32 m0, s0, 0x1f80
	ds_read_b128 v[222:225], v159 offset:3072
	global_load_lds_dwordx4 v134, s[42:43] offset:128
	s_barrier
	s_waitcnt lgkmcnt(0)
	s_setprio 1
	v_mfma_f32_16x16x32_bf16 v[116:119], v[210:213], v[170:173], v[116:119]
	v_mfma_f32_16x16x32_bf16 v[112:115], v[218:221], v[170:173], v[112:115]
	v_mfma_f32_16x16x32_bf16 v[100:103], v[210:213], v[178:181], v[100:103]
	v_mfma_f32_16x16x32_bf16 v[96:99], v[218:221], v[178:181], v[96:99]
	v_mfma_f32_16x16x32_bf16 v[84:87], v[210:213], v[194:197], v[84:87]
	v_mfma_f32_16x16x32_bf16 v[80:83], v[218:221], v[194:197], v[80:83]
	v_mfma_f32_16x16x32_bf16 v[68:71], v[210:213], v[202:205], v[68:71]
	v_mfma_f32_16x16x32_bf16 v[64:67], v[218:221], v[202:205], v[64:67]
	v_mfma_f32_16x16x32_bf16 v[116:119], v[214:217], v[174:177], v[116:119]
	v_mfma_f32_16x16x32_bf16 v[112:115], v[222:225], v[174:177], v[112:115]
	v_mfma_f32_16x16x32_bf16 v[100:103], v[214:217], v[188:191], v[100:103]
	v_mfma_f32_16x16x32_bf16 v[96:99], v[222:225], v[188:191], v[96:99]
	v_mfma_f32_16x16x32_bf16 v[84:87], v[214:217], v[198:201], v[84:87]
	v_mfma_f32_16x16x32_bf16 v[80:83], v[222:225], v[198:201], v[80:83]
	v_mfma_f32_16x16x32_bf16 v[68:71], v[214:217], v[206:209], v[68:71]
	v_mfma_f32_16x16x32_bf16 v[64:67], v[222:225], v[206:209], v[64:67]
	s_setprio 0
	s_add_i32 m0, s59, 0xffffff80
	s_barrier
	ds_read_b128 v[170:173], v148 offset:49152
	ds_read_b128 v[174:177], v148 offset:50176
	ds_read_b128 v[178:181], v148 offset:51200
	ds_read_b128 v[188:191], v148 offset:52224
	ds_read_b128 v[194:197], v148 offset:53248
	ds_read_b128 v[198:201], v148 offset:54272
	ds_read_b128 v[202:205], v148 offset:55296
	global_load_lds_dwordx4 v128, s[44:45] offset:128
	s_add_i32 m0, s60, 0xffffff80
	ds_read_b128 v[206:209], v148 offset:56320
	global_load_lds_dwordx4 v132, s[44:45] offset:128
	s_barrier
; #define PG8_STAGE(bufoff, gbase, voff) do { _Pragma("unroll") for (int _i = 0; _i < 2; ++_i) \
;         __builtin_amdgcn_global_load_lds((const unsigned*)((const char*)(gbase) + (voff)[_i]), (LAS unsigned*)(lds + (bufoff) + ldsw + _i * 8192), 16, 0, 0); } while (0)
; #define PG8_LDA(dst, b, h) do { _Pragma("unroll") for (int m = 0; m < 4; ++m) _Pragma("unroll") for (int k = 0; k < 2; ++k) dst[m][k] = *(const LAS bf16x8*)(lds + PG8_SA(b, h) + aoff + m * 2048 + k * 1024); } while (0)
; #define PG8_LDB(dst, b, h) do { _Pragma("unroll") for (int n = 0; n < 2; ++n) _Pragma("unroll") for (int k = 0; k < 2; ++k) dst[n][k] = *(const LAS bf16x8*)(lds + PG8_SB(b, h) + boff + n * 2048 + k * 1024); } while (0)
; #define PG8_MMA(ai, bj, At, Bt) do { __builtin_amdgcn_s_setprio(1); _Pragma("unroll") for (int m = 0; m < 4; ++m) _Pragma("unroll") for (int n = 0; n < 2; ++n) _Pragma("unroll") for (int k = 0; k < 2; ++k) \
;         acc[ai][bj][m][n] = __builtin_amdgcn_mfma_f32_16x16x32_bf16(Bt[n][k], At[m][k], acc[ai][bj][m][n], 0, 0, 0); __builtin_amdgcn_s_setprio(0); } while (0)
; #define PG8_WAIT_V(n) asm volatile("s_waitcnt vmcnt(" #n ")" ::: "memory")
; #define PG8_WAIT_L(n) asm volatile("s_waitcnt lgkmcnt(" #n ")" ::: "memory")
; #define PG8_BAR __builtin_amdgcn_s_barrier()
; #define PG8_SCHED __builtin_amdgcn_sched_barrier(0)
; template <class Epi, class Sched>
; DI void gemm_phase(LAS unsigned char* lds, const Gemm g, const Sched& S, const Epi& E) {
;     ...
;             PG8_LDB(B0, 0, 0); PG8_SCHED; PG8_LDA(At, 0, 0); PG8_STAGE(PG8_SA(1, 1), a1 + hstep, voffA);
;             PG8_WAIT_L(8); PG8_BAR; PG8_WAIT_L(0); PG8_MMA(0, 0, At, B0); PG8_BAR; PG8_SCHED;
;             PG8_LDB(B1, 0, 1); PG8_STAGE(PG8_SB(0, 0), b2, voffB);
;             PG8_BAR; PG8_WAIT_L(0); PG8_MMA(0, 1, At, B1); PG8_BAR;
;     ...
;             PG8_BAR; PG8_WAIT_L(0); PG8_MMA(1, 0, At, B0); PG8_BAR; PG8_SCHED;
;             PG8_STAGE(PG8_SB(1, 1), b3 + hstep, voffB);
;             PG8_WAIT_V(6); PG8_BAR; PG8_MMA(1, 1, At, B1); PG8_BAR;
	s_waitcnt lgkmcnt(0)
	s_setprio 1
	v_mfma_f32_16x16x32_bf16 v[60:63], v[150:153], v[170:173], v[60:63]
	v_mfma_f32_16x16x32_bf16 v[56:59], v[162:165], v[170:173], v[56:59]
	v_mfma_f32_16x16x32_bf16 v[44:47], v[150:153], v[178:181], v[44:47]
	v_mfma_f32_16x16x32_bf16 v[40:43], v[162:165], v[178:181], v[40:43]
	v_mfma_f32_16x16x32_bf16 v[28:31], v[150:153], v[194:197], v[28:31]
	v_mfma_f32_16x16x32_bf16 v[24:27], v[162:165], v[194:197], v[24:27]
	v_mfma_f32_16x16x32_bf16 v[12:15], v[150:153], v[202:205], v[12:15]
	v_mfma_f32_16x16x32_bf16 v[8:11], v[162:165], v[202:205], v[8:11]
	v_mfma_f32_16x16x32_bf16 v[60:63], v[154:157], v[174:177], v[60:63]
	v_mfma_f32_16x16x32_bf16 v[56:59], v[166:169], v[174:177], v[56:59]
	v_mfma_f32_16x16x32_bf16 v[44:47], v[154:157], v[188:191], v[44:47]
	v_mfma_f32_16x16x32_bf16 v[40:43], v[166:169], v[188:191], v[40:43]
	v_mfma_f32_16x16x32_bf16 v[28:31], v[154:157], v[198:201], v[28:31]
	v_mfma_f32_16x16x32_bf16 v[24:27], v[166:169], v[198:201], v[24:27]
	v_mfma_f32_16x16x32_bf16 v[12:15], v[154:157], v[206:209], v[12:15]
	v_mfma_f32_16x16x32_bf16 v[8:11], v[166:169], v[206:209], v[8:11]
	s_setprio 0
	s_barrier
	s_add_i32 s4, s5, s52
	s_mov_b32 m0, s4
	s_add_u32 s0, s42, 0x80080
	s_addc_u32 s1, s43, 0
	global_load_lds_dwordx4 v130, s[0:1]
	s_add_i32 m0, s4, 0x2000
	s_nop 0
	global_load_lds_dwordx4 v134, s[0:1]
	s_waitcnt vmcnt(6)
	s_barrier
	s_setprio 1
	v_mfma_f32_16x16x32_bf16 v[52:55], v[210:213], v[170:173], v[52:55]
	v_mfma_f32_16x16x32_bf16 v[48:51], v[218:221], v[170:173], v[48:51]
	v_mfma_f32_16x16x32_bf16 v[36:39], v[210:213], v[178:181], v[36:39]
	v_mfma_f32_16x16x32_bf16 v[32:35], v[218:221], v[178:181], v[32:35]
	v_mfma_f32_16x16x32_bf16 v[20:23], v[210:213], v[194:197], v[20:23]
	v_mfma_f32_16x16x32_bf16 v[16:19], v[218:221], v[194:197], v[16:19]
	v_mfma_f32_16x16x32_bf16 v[4:7], v[210:213], v[202:205], v[4:7]
	v_mfma_f32_16x16x32_bf16 v[0:3], v[218:221], v[202:205], v[0:3]
	v_mfma_f32_16x16x32_bf16 v[52:55], v[214:217], v[174:177], v[52:55]
	v_mfma_f32_16x16x32_bf16 v[48:51], v[222:225], v[174:177], v[48:51]
	v_mfma_f32_16x16x32_bf16 v[36:39], v[214:217], v[188:191], v[36:39]
	v_mfma_f32_16x16x32_bf16 v[32:35], v[222:225], v[188:191], v[32:35]
	v_mfma_f32_16x16x32_bf16 v[20:23], v[214:217], v[198:201], v[20:23]
	v_mfma_f32_16x16x32_bf16 v[16:19], v[222:225], v[198:201], v[16:19]
	v_mfma_f32_16x16x32_bf16 v[4:7], v[214:217], v[206:209], v[4:7]
	v_mfma_f32_16x16x32_bf16 v[0:3], v[222:225], v[206:209], v[0:3]
	s_setprio 0
	s_add_i32 s69, s69, 2
	s_add_u32 s40, s40, 0x100
	s_addc_u32 s41, s41, 0
	s_add_u32 s67, s67, 0x100
	s_addc_u32 s68, s68, 0
	s_cmp_gt_u32 s69, 29
	s_barrier
	s_cbranch_scc0 .LBB0_219
	s_branch .Lpeel_done_219
.LBB0_219:
	ds_read_b128 v[150:153], v147
	ds_read_b128 v[154:157], v147 offset:1024
	ds_read_b128 v[162:165], v147 offset:2048
	ds_read_b128 v[166:169], v147 offset:3072
	s_add_u32 s0, s40, 0xfff80080
	s_addc_u32 s1, s41, -1
	s_cmp_eq_u32 s69, 28
	s_cselect_b32 s45, s17, s1
	s_cselect_b32 s44, s65, s0
	s_cselect_b32 s43, s15, s68
	s_cselect_b32 s42, s66, s67
	s_add_i32 m0, s39, 0xc000
	ds_read_b128 v[170:173], v148
	ds_read_b128 v[174:177], v148 offset:1024
	ds_read_b128 v[178:181], v148 offset:2048
	ds_read_b128 v[188:191], v148 offset:3072
	ds_read_b128 v[194:197], v148 offset:4096
	ds_read_b128 v[198:201], v148 offset:5120
	ds_read_b128 v[202:205], v148 offset:6144
	global_load_lds_dwordx4 v136, s[40:41]
	s_add_i32 m0, s39, 0xe000
	ds_read_b128 v[206:209], v148 offset:7168
	global_load_lds_dwordx4 v138, s[40:41]
	s_waitcnt lgkmcnt(8)
	s_barrier
	s_waitcnt lgkmcnt(0)
	s_setprio 1
	v_mfma_f32_16x16x32_bf16 v[124:127], v[150:153], v[170:173], v[124:127]
	v_mfma_f32_16x16x32_bf16 v[120:123], v[162:165], v[170:173], v[120:123]
	v_mfma_f32_16x16x32_bf16 v[108:111], v[150:153], v[178:181], v[108:111]
	v_mfma_f32_16x16x32_bf16 v[104:107], v[162:165], v[178:181], v[104:107]
	v_mfma_f32_16x16x32_bf16 v[92:95], v[150:153], v[194:197], v[92:95]
	v_mfma_f32_16x16x32_bf16 v[88:91], v[162:165], v[194:197], v[88:91]
	v_mfma_f32_16x16x32_bf16 v[76:79], v[150:153], v[202:205], v[76:79]
	v_mfma_f32_16x16x32_bf16 v[72:75], v[162:165], v[202:205], v[72:75]
	v_mfma_f32_16x16x32_bf16 v[124:127], v[154:157], v[174:177], v[124:127]
	v_mfma_f32_16x16x32_bf16 v[120:123], v[166:169], v[174:177], v[120:123]
	v_mfma_f32_16x16x32_bf16 v[108:111], v[154:157], v[188:191], v[108:111]
	v_mfma_f32_16x16x32_bf16 v[104:107], v[166:169], v[188:191], v[104:107]
	v_mfma_f32_16x16x32_bf16 v[92:95], v[154:157], v[198:201], v[92:95]
	v_mfma_f32_16x16x32_bf16 v[88:91], v[166:169], v[198:201], v[88:91]
	v_mfma_f32_16x16x32_bf16 v[76:79], v[154:157], v[206:209], v[76:79]
	v_mfma_f32_16x16x32_bf16 v[72:75], v[166:169], v[206:209], v[72:75]
	s_setprio 0
	s_barrier
	s_add_i32 s0, s34, s52
	s_mov_b32 m0, s0
	ds_read_b128 v[210:213], v149
	ds_read_b128 v[214:217], v149 offset:1024
	ds_read_b128 v[218:221], v149 offset:2048
	global_load_lds_dwordx4 v130, s[42:43]
	s_add_i32 m0, s0, 0x2000
	ds_read_b128 v[222:225], v149 offset:3072
	global_load_lds_dwordx4 v134, s[42:43]
	s_barrier
; #define PG8_STAGE(bufoff, gbase, voff) do { _Pragma("unroll") for (int _i = 0; _i < 2; ++_i) \
;         __builtin_amdgcn_global_load_lds((const unsigned*)((const char*)(gbase) + (voff)[_i]), (LAS unsigned*)(lds + (bufoff) + ldsw + _i * 8192), 16, 0, 0); } while (0)
; #define PG8_LDA(dst, b, h) do { _Pragma("unroll") for (int m = 0; m < 4; ++m) _Pragma("unroll") for (int k = 0; k < 2; ++k) dst[m][k] = *(const LAS bf16x8*)(lds + PG8_SA(b, h) + aoff + m * 2048 + k * 1024); } while (0)
; #define PG8_LDB(dst, b, h) do { _Pragma("unroll") for (int n = 0; n < 2; ++n) _Pragma("unroll") for (int k = 0; k < 2; ++k) dst[n][k] = *(const LAS bf16x8*)(lds + PG8_SB(b, h) + boff + n * 2048 + k * 1024); } while (0)
; #define PG8_MMA(ai, bj, At, Bt) do { __builtin_amdgcn_s_setprio(1); _Pragma("unroll") for (int m = 0; m < 4; ++m) _Pragma("unroll") for (int n = 0; n < 2; ++n) _Pragma("unroll") for (int k = 0; k < 2; ++k) \
;         acc[ai][bj][m][n] = __builtin_amdgcn_mfma_f32_16x16x32_bf16(Bt[n][k], At[m][k], acc[ai][bj][m][n], 0, 0, 0); __builtin_amdgcn_s_setprio(0); } while (0)
; #define PG8_WAIT_V(n) asm volatile("s_waitcnt vmcnt(" #n ")" ::: "memory")
; #define PG8_WAIT_L(n) asm volatile("s_waitcnt lgkmcnt(" #n ")" ::: "memory")
; #define PG8_BAR __builtin_amdgcn_s_barrier()
; #define PG8_SCHED __builtin_amdgcn_sched_barrier(0)
; template <class Epi, class Sched>
; DI void gemm_phase(LAS unsigned char* lds, const Gemm g, const Sched& S, const Epi& E) {
;     ...
;             PG8_BAR; PG8_WAIT_L(0); PG8_MMA(0, 1, At, B1); PG8_BAR;
;             PG8_LDA(At, 0, 1); PG8_STAGE(PG8_SA(0, 0), a2, voffA);
;             PG8_BAR; PG8_WAIT_L(0); PG8_MMA(1, 0, At, B0); PG8_BAR; PG8_SCHED;
;             PG8_STAGE(PG8_SB(0, 1), b2 + hstep, voffB);
;             PG8_WAIT_V(6); PG8_BAR; PG8_MMA(1, 1, At, B1); PG8_BAR;
;             PG8_LDB(B0, 1, 0); PG8_SCHED; PG8_LDA(At, 1, 0); PG8_STAGE(PG8_SA(0, 1), a2 + hstep, voffA);
;             PG8_WAIT_L(8); PG8_BAR; PG8_WAIT_L(0); PG8_MMA(0, 0, At, B0); PG8_BAR; PG8_SCHED;
;             PG8_LDB(B1, 1, 1); PG8_STAGE(PG8_SB(1, 0), b3, voffB);
	s_waitcnt lgkmcnt(0)
	s_setprio 1
	v_mfma_f32_16x16x32_bf16 v[116:119], v[210:213], v[170:173], v[116:119]
	v_mfma_f32_16x16x32_bf16 v[112:115], v[218:221], v[170:173], v[112:115]
	v_mfma_f32_16x16x32_bf16 v[100:103], v[210:213], v[178:181], v[100:103]
	v_mfma_f32_16x16x32_bf16 v[96:99], v[218:221], v[178:181], v[96:99]
	v_mfma_f32_16x16x32_bf16 v[84:87], v[210:213], v[194:197], v[84:87]
	v_mfma_f32_16x16x32_bf16 v[80:83], v[218:221], v[194:197], v[80:83]
	v_mfma_f32_16x16x32_bf16 v[68:71], v[210:213], v[202:205], v[68:71]
	v_mfma_f32_16x16x32_bf16 v[64:67], v[218:221], v[202:205], v[64:67]
	v_mfma_f32_16x16x32_bf16 v[116:119], v[214:217], v[174:177], v[116:119]
	v_mfma_f32_16x16x32_bf16 v[112:115], v[222:225], v[174:177], v[112:115]
	v_mfma_f32_16x16x32_bf16 v[100:103], v[214:217], v[188:191], v[100:103]
	v_mfma_f32_16x16x32_bf16 v[96:99], v[222:225], v[188:191], v[96:99]
	v_mfma_f32_16x16x32_bf16 v[84:87], v[214:217], v[198:201], v[84:87]
	v_mfma_f32_16x16x32_bf16 v[80:83], v[222:225], v[198:201], v[80:83]
	v_mfma_f32_16x16x32_bf16 v[68:71], v[214:217], v[206:209], v[68:71]
	v_mfma_f32_16x16x32_bf16 v[64:67], v[222:225], v[206:209], v[64:67]
	s_setprio 0
	s_mov_b32 m0, s39
	s_barrier
	ds_read_b128 v[170:173], v148 offset:16384
	ds_read_b128 v[174:177], v148 offset:17408
	ds_read_b128 v[178:181], v148 offset:18432
	ds_read_b128 v[188:191], v148 offset:19456
	ds_read_b128 v[194:197], v148 offset:20480
	ds_read_b128 v[198:201], v148 offset:21504
	ds_read_b128 v[202:205], v148 offset:22528
	global_load_lds_dwordx4 v128, s[44:45]
	s_mov_b32 m0, s53
	ds_read_b128 v[206:209], v148 offset:23552
	global_load_lds_dwordx4 v132, s[44:45]
	s_barrier
	s_waitcnt lgkmcnt(0)
	s_setprio 1
	v_mfma_f32_16x16x32_bf16 v[60:63], v[150:153], v[170:173], v[60:63]
	v_mfma_f32_16x16x32_bf16 v[56:59], v[162:165], v[170:173], v[56:59]
	v_mfma_f32_16x16x32_bf16 v[44:47], v[150:153], v[178:181], v[44:47]
	v_mfma_f32_16x16x32_bf16 v[40:43], v[162:165], v[178:181], v[40:43]
	v_mfma_f32_16x16x32_bf16 v[28:31], v[150:153], v[194:197], v[28:31]
	v_mfma_f32_16x16x32_bf16 v[24:27], v[162:165], v[194:197], v[24:27]
	v_mfma_f32_16x16x32_bf16 v[12:15], v[150:153], v[202:205], v[12:15]
	v_mfma_f32_16x16x32_bf16 v[8:11], v[162:165], v[202:205], v[8:11]
	v_mfma_f32_16x16x32_bf16 v[60:63], v[154:157], v[174:177], v[60:63]
	v_mfma_f32_16x16x32_bf16 v[56:59], v[166:169], v[174:177], v[56:59]
	v_mfma_f32_16x16x32_bf16 v[44:47], v[154:157], v[188:191], v[44:47]
	v_mfma_f32_16x16x32_bf16 v[40:43], v[166:169], v[188:191], v[40:43]
	v_mfma_f32_16x16x32_bf16 v[28:31], v[154:157], v[198:201], v[28:31]
	v_mfma_f32_16x16x32_bf16 v[24:27], v[166:169], v[198:201], v[24:27]
	v_mfma_f32_16x16x32_bf16 v[12:15], v[154:157], v[206:209], v[12:15]
	v_mfma_f32_16x16x32_bf16 v[8:11], v[166:169], v[206:209], v[8:11]
	s_setprio 0
	s_barrier
	s_add_i32 s4, s35, s52
	s_mov_b32 m0, s4
	s_add_u32 s0, s42, 0x80000
	s_addc_u32 s1, s43, 0
	global_load_lds_dwordx4 v130, s[0:1]
	s_add_i32 m0, s4, 0x2000
	s_nop 0
	global_load_lds_dwordx4 v134, s[0:1]
	s_waitcnt vmcnt(6)
	s_barrier
	s_setprio 1
	v_mfma_f32_16x16x32_bf16 v[52:55], v[210:213], v[170:173], v[52:55]
	v_mfma_f32_16x16x32_bf16 v[48:51], v[218:221], v[170:173], v[48:51]
	v_mfma_f32_16x16x32_bf16 v[36:39], v[210:213], v[178:181], v[36:39]
	v_mfma_f32_16x16x32_bf16 v[32:35], v[218:221], v[178:181], v[32:35]
	v_mfma_f32_16x16x32_bf16 v[20:23], v[210:213], v[194:197], v[20:23]
	v_mfma_f32_16x16x32_bf16 v[16:19], v[218:221], v[194:197], v[16:19]
	v_mfma_f32_16x16x32_bf16 v[4:7], v[210:213], v[202:205], v[4:7]
	v_mfma_f32_16x16x32_bf16 v[0:3], v[218:221], v[202:205], v[0:3]
	v_mfma_f32_16x16x32_bf16 v[52:55], v[214:217], v[174:177], v[52:55]
	v_mfma_f32_16x16x32_bf16 v[48:51], v[222:225], v[174:177], v[48:51]
	v_mfma_f32_16x16x32_bf16 v[36:39], v[214:217], v[188:191], v[36:39]
	v_mfma_f32_16x16x32_bf16 v[32:35], v[222:225], v[188:191], v[32:35]
	v_mfma_f32_16x16x32_bf16 v[20:23], v[214:217], v[198:201], v[20:23]
	v_mfma_f32_16x16x32_bf16 v[16:19], v[222:225], v[198:201], v[16:19]
	v_mfma_f32_16x16x32_bf16 v[4:7], v[214:217], v[206:209], v[4:7]
	v_mfma_f32_16x16x32_bf16 v[0:3], v[222:225], v[206:209], v[0:3]
	s_setprio 0
	s_add_i32 s4, 0, 0x18000
	s_barrier
	ds_read_b128 v[150:153], v158
	ds_read_b128 v[154:157], v158 offset:1024
	ds_read_b128 v[162:165], v158 offset:2048
	ds_read_b128 v[166:169], v158 offset:3072
	s_add_u32 s0, s44, 0x80000
	s_addc_u32 s1, s45, 0
	s_mov_b32 m0, s54
	ds_read_b128 v[170:173], v148 offset:32768
	ds_read_b128 v[174:177], v148 offset:33792
	ds_read_b128 v[178:181], v148 offset:34816
	ds_read_b128 v[188:191], v148 offset:35840
	ds_read_b128 v[194:197], v148 offset:36864
	ds_read_b128 v[198:201], v148 offset:37888
	ds_read_b128 v[202:205], v148 offset:38912
	global_load_lds_dwordx4 v128, s[0:1]
	s_mov_b32 m0, s55
	ds_read_b128 v[206:209], v148 offset:39936
	global_load_lds_dwordx4 v132, s[0:1]
	s_waitcnt lgkmcnt(8)
	s_barrier
; #define PG8_STAGE(bufoff, gbase, voff) do { _Pragma("unroll") for (int _i = 0; _i < 2; ++_i) \
;         __builtin_amdgcn_global_load_lds((const unsigned*)((const char*)(gbase) + (voff)[_i]), (LAS unsigned*)(lds + (bufoff) + ldsw + _i * 8192), 16, 0, 0); } while (0)
; #define PG8_LDA(dst, b, h) do { _Pragma("unroll") for (int m = 0; m < 4; ++m) _Pragma("unroll") for (int k = 0; k < 2; ++k) dst[m][k] = *(const LAS bf16x8*)(lds + PG8_SA(b, h) + aoff + m * 2048 + k * 1024); } while (0)
; #define PG8_LDB(dst, b, h) do { _Pragma("unroll") for (int n = 0; n < 2; ++n) _Pragma("unroll") for (int k = 0; k < 2; ++k) dst[n][k] = *(const LAS bf16x8*)(lds + PG8_SB(b, h) + boff + n * 2048 + k * 1024); } while (0)
; #define PG8_MMA(ai, bj, At, Bt) do { __builtin_amdgcn_s_setprio(1); _Pragma("unroll") for (int m = 0; m < 4; ++m) _Pragma("unroll") for (int n = 0; n < 2; ++n) _Pragma("unroll") for (int k = 0; k < 2; ++k) \
;         acc[ai][bj][m][n] = __builtin_amdgcn_mfma_f32_16x16x32_bf16(Bt[n][k], At[m][k], acc[ai][bj][m][n], 0, 0, 0); __builtin_amdgcn_s_setprio(0); } while (0)
; #define PG8_WAIT_V(n) asm volatile("s_waitcnt vmcnt(" #n ")" ::: "memory")
; #define PG8_WAIT_L(n) asm volatile("s_waitcnt lgkmcnt(" #n ")" ::: "memory")
; #define PG8_BAR __builtin_amdgcn_s_barrier()
; #define PG8_SCHED __builtin_amdgcn_sched_barrier(0)
; template <class Epi, class Sched>
; DI void gemm_phase(LAS unsigned char* lds, const Gemm g, const Sched& S, const Epi& E) {
;     ...
;             PG8_LDB(B1, 1, 1); PG8_STAGE(PG8_SB(1, 0), b3, voffB);
;             PG8_BAR; PG8_WAIT_L(0); PG8_MMA(0, 1, At, B1); PG8_BAR;
;             PG8_LDA(At, 1, 1); PG8_STAGE(PG8_SA(1, 0), a3, voffA);
;             PG8_BAR; PG8_WAIT_L(0); PG8_MMA(1, 0, At, B0); PG8_BAR; PG8_SCHED;
;             PG8_STAGE(PG8_SB(1, 1), b3 + hstep, voffB);
;             PG8_WAIT_V(6); PG8_BAR; PG8_MMA(1, 1, At, B1); PG8_BAR;
	s_waitcnt lgkmcnt(0)
	s_setprio 1
	v_mfma_f32_16x16x32_bf16 v[124:127], v[150:153], v[170:173], v[124:127]
	v_mfma_f32_16x16x32_bf16 v[120:123], v[162:165], v[170:173], v[120:123]
	v_mfma_f32_16x16x32_bf16 v[108:111], v[150:153], v[178:181], v[108:111]
	v_mfma_f32_16x16x32_bf16 v[104:107], v[162:165], v[178:181], v[104:107]
	v_mfma_f32_16x16x32_bf16 v[92:95], v[150:153], v[194:197], v[92:95]
	v_mfma_f32_16x16x32_bf16 v[88:91], v[162:165], v[194:197], v[88:91]
	v_mfma_f32_16x16x32_bf16 v[76:79], v[150:153], v[202:205], v[76:79]
	v_mfma_f32_16x16x32_bf16 v[72:75], v[162:165], v[202:205], v[72:75]
	v_mfma_f32_16x16x32_bf16 v[124:127], v[154:157], v[174:177], v[124:127]
	v_mfma_f32_16x16x32_bf16 v[120:123], v[166:169], v[174:177], v[120:123]
	v_mfma_f32_16x16x32_bf16 v[108:111], v[154:157], v[188:191], v[108:111]
	v_mfma_f32_16x16x32_bf16 v[104:107], v[166:169], v[188:191], v[104:107]
	v_mfma_f32_16x16x32_bf16 v[92:95], v[154:157], v[198:201], v[92:95]
	v_mfma_f32_16x16x32_bf16 v[88:91], v[166:169], v[198:201], v[88:91]
	v_mfma_f32_16x16x32_bf16 v[76:79], v[154:157], v[206:209], v[76:79]
	v_mfma_f32_16x16x32_bf16 v[72:75], v[166:169], v[206:209], v[72:75]
	s_setprio 0
	s_barrier
	s_add_i32 s5, 0, 0x1c000
	s_add_i32 s0, s4, s52
	s_add_i32 m0, s0, 0xffffff80
	ds_read_b128 v[210:213], v159
	ds_read_b128 v[214:217], v159 offset:1024
	ds_read_b128 v[218:221], v159 offset:2048
	global_load_lds_dwordx4 v130, s[42:43] offset:128
	s_add_i32 m0, s0, 0x1f80
	ds_read_b128 v[222:225], v159 offset:3072
	global_load_lds_dwordx4 v134, s[42:43] offset:128
	s_barrier
	s_waitcnt lgkmcnt(0)
	s_setprio 1
	v_mfma_f32_16x16x32_bf16 v[116:119], v[210:213], v[170:173], v[116:119]
	v_mfma_f32_16x16x32_bf16 v[112:115], v[218:221], v[170:173], v[112:115]
	v_mfma_f32_16x16x32_bf16 v[100:103], v[210:213], v[178:181], v[100:103]
	v_mfma_f32_16x16x32_bf16 v[96:99], v[218:221], v[178:181], v[96:99]
	v_mfma_f32_16x16x32_bf16 v[84:87], v[210:213], v[194:197], v[84:87]
	v_mfma_f32_16x16x32_bf16 v[80:83], v[218:221], v[194:197], v[80:83]
	v_mfma_f32_16x16x32_bf16 v[68:71], v[210:213], v[202:205], v[68:71]
	v_mfma_f32_16x16x32_bf16 v[64:67], v[218:221], v[202:205], v[64:67]
	v_mfma_f32_16x16x32_bf16 v[116:119], v[214:217], v[174:177], v[116:119]
	v_mfma_f32_16x16x32_bf16 v[112:115], v[222:225], v[174:177], v[112:115]
	v_mfma_f32_16x16x32_bf16 v[100:103], v[214:217], v[188:191], v[100:103]
	v_mfma_f32_16x16x32_bf16 v[96:99], v[222:225], v[188:191], v[96:99]
	v_mfma_f32_16x16x32_bf16 v[84:87], v[214:217], v[198:201], v[84:87]
	v_mfma_f32_16x16x32_bf16 v[80:83], v[222:225], v[198:201], v[80:83]
	v_mfma_f32_16x16x32_bf16 v[68:71], v[214:217], v[206:209], v[68:71]
	v_mfma_f32_16x16x32_bf16 v[64:67], v[222:225], v[206:209], v[64:67]
	s_setprio 0
	s_add_i32 m0, s59, 0xffffff80
	s_barrier
	ds_read_b128 v[170:173], v148 offset:49152
	ds_read_b128 v[174:177], v148 offset:50176
	ds_read_b128 v[178:181], v148 offset:51200
	ds_read_b128 v[188:191], v148 offset:52224
	ds_read_b128 v[194:197], v148 offset:53248
	ds_read_b128 v[198:201], v148 offset:54272
	ds_read_b128 v[202:205], v148 offset:55296
	global_load_lds_dwordx4 v128, s[44:45] offset:128
	s_add_i32 m0, s60, 0xffffff80
	ds_read_b128 v[206:209], v148 offset:56320
	global_load_lds_dwordx4 v132, s[44:45] offset:128
	s_barrier
	s_waitcnt lgkmcnt(0)
	s_setprio 1
	v_mfma_f32_16x16x32_bf16 v[60:63], v[150:153], v[170:173], v[60:63]
	v_mfma_f32_16x16x32_bf16 v[56:59], v[162:165], v[170:173], v[56:59]
	v_mfma_f32_16x16x32_bf16 v[44:47], v[150:153], v[178:181], v[44:47]
	v_mfma_f32_16x16x32_bf16 v[40:43], v[162:165], v[178:181], v[40:43]
	v_mfma_f32_16x16x32_bf16 v[28:31], v[150:153], v[194:197], v[28:31]
	v_mfma_f32_16x16x32_bf16 v[24:27], v[162:165], v[194:197], v[24:27]
	v_mfma_f32_16x16x32_bf16 v[12:15], v[150:153], v[202:205], v[12:15]
	v_mfma_f32_16x16x32_bf16 v[8:11], v[162:165], v[202:205], v[8:11]
	v_mfma_f32_16x16x32_bf16 v[60:63], v[154:157], v[174:177], v[60:63]
	v_mfma_f32_16x16x32_bf16 v[56:59], v[166:169], v[174:177], v[56:59]
	v_mfma_f32_16x16x32_bf16 v[44:47], v[154:157], v[188:191], v[44:47]
	v_mfma_f32_16x16x32_bf16 v[40:43], v[166:169], v[188:191], v[40:43]
	v_mfma_f32_16x16x32_bf16 v[28:31], v[154:157], v[198:201], v[28:31]
	v_mfma_f32_16x16x32_bf16 v[24:27], v[166:169], v[198:201], v[24:27]
	v_mfma_f32_16x16x32_bf16 v[12:15], v[154:157], v[206:209], v[12:15]
	v_mfma_f32_16x16x32_bf16 v[8:11], v[166:169], v[206:209], v[8:11]
	s_setprio 0
	s_barrier
	s_add_i32 s4, s5, s52
	s_mov_b32 m0, s4
	s_add_u32 s0, s42, 0x80080
	s_addc_u32 s1, s43, 0
	global_load_lds_dwordx4 v130, s[0:1]
	s_add_i32 m0, s4, 0x2000
	s_nop 0
	global_load_lds_dwordx4 v134, s[0:1]
	s_waitcnt vmcnt(6)
	s_barrier
	s_setprio 1
	v_mfma_f32_16x16x32_bf16 v[52:55], v[210:213], v[170:173], v[52:55]
	v_mfma_f32_16x16x32_bf16 v[48:51], v[218:221], v[170:173], v[48:51]
	v_mfma_f32_16x16x32_bf16 v[36:39], v[210:213], v[178:181], v[36:39]
	v_mfma_f32_16x16x32_bf16 v[32:35], v[218:221], v[178:181], v[32:35]
	v_mfma_f32_16x16x32_bf16 v[20:23], v[210:213], v[194:197], v[20:23]
	v_mfma_f32_16x16x32_bf16 v[16:19], v[218:221], v[194:197], v[16:19]
	v_mfma_f32_16x16x32_bf16 v[4:7], v[210:213], v[202:205], v[4:7]
	v_mfma_f32_16x16x32_bf16 v[0:3], v[218:221], v[202:205], v[0:3]
	v_mfma_f32_16x16x32_bf16 v[52:55], v[214:217], v[174:177], v[52:55]
	v_mfma_f32_16x16x32_bf16 v[48:51], v[222:225], v[174:177], v[48:51]
	v_mfma_f32_16x16x32_bf16 v[36:39], v[214:217], v[188:191], v[36:39]
	v_mfma_f32_16x16x32_bf16 v[32:35], v[222:225], v[188:191], v[32:35]
	v_mfma_f32_16x16x32_bf16 v[20:23], v[214:217], v[198:201], v[20:23]
	v_mfma_f32_16x16x32_bf16 v[16:19], v[222:225], v[198:201], v[16:19]
	v_mfma_f32_16x16x32_bf16 v[4:7], v[214:217], v[206:209], v[4:7]
	v_mfma_f32_16x16x32_bf16 v[0:3], v[222:225], v[206:209], v[0:3]
	s_setprio 0
	s_add_i32 s69, s69, 2
	s_add_u32 s40, s40, 0x100
	s_addc_u32 s41, s41, 0
	s_add_u32 s67, s67, 0x100
	s_addc_u32 s68, s68, 0
	s_cmp_gt_u32 s69, 29
	s_barrier
	s_cbranch_scc0 .LBB0_219

;     DI size_t aoff(const Unit& u, size_t tstep) const { return (size_t)u.pm * tstep; }
;     DI size_t boff(const Unit& u, size_t tstep) const { return (size_t)u.pn * tstep; }
;     DI bool next(int i, Unit& u) const { const long L = (long)i * G + c; if (L >= np) return false; u.pm = pmv; u.pn = (int)(L % nN); u.ks = (int)(L / nN); return true; }
;     DI size_t aoff(const Unit& u, size_t) const { return (size_t)u.ks * kbytes; }
;     DI size_t boff(const Unit& u, size_t tstep) const { return (size_t)u.pn * tstep + (size_t)u.ks * kbytes; }
;     DI bool next(int i, Unit& u) const { Unit t; if (!S.next(i / 3, t)) return false; u.pm = t.pm; u.pn = t.pn; u.ks = i % 3; return true; }
;     DI size_t aoff(const Unit& u, size_t tstep) const { return (u.ks < 2 ? offU : offOA) + (size_t)u.pm * tstep; }
; #define PG8_WAIT_V(n) asm volatile("s_waitcnt vmcnt(" #n ")" ::: "memory")
; template <class Epi, class Sched>
; DI void gemm_phase(LAS unsigned char* lds, const Gemm g, const Sched& S, const Epi& E) {
;     ...
;         const bool has_next = S.next(ui + 1, nxt);
;         const char* nA = has_next ? (const char*)g.A + S.aoff(nxt, tstep) : cA; const char* nB = has_next ? (const char*)g.Bt + S.boff(nxt, tstep) : cB;
;         for (int t = 0; t < nt; t += 2) {
;             if constexpr (Epi::HAS_MID) { if (t == E.mid_t(nt)) { int fr3 = fr, fq3 = fq; asm volatile("" : "+v"(fr3), "+v"(fq3)); E.mid(acc, cur, wr, wc, fr3, fq3); } }
;             const bool last = (t == nt - 2);
;             const char* a1 = cA + (size_t)(t + 1) * kstep;
;             const char* a2 = last ? nA : cA + (size_t)(t + 2) * kstep; const char* b2 = last ? nB : cB + (size_t)(t + 2) * kstep;
;             const char* a3 = a2 + kstep; const char* b3 = b2 + kstep;
;             PG8_LDB(B0, 0, 0); PG8_SCHED; PG8_LDA(At, 0, 0); PG8_STAGE(PG8_SA(1, 1), a1 + hstep, voffA);
;             PG8_WAIT_L(8); PG8_BAR; PG8_WAIT_L(0); PG8_MMA(0, 0, At, B0); PG8_BAR; PG8_SCHED;
;             PG8_LDB(B1, 0, 1); PG8_STAGE(PG8_SB(0, 0), b2, voffB);
;             PG8_BAR; PG8_WAIT_L(0); PG8_MMA(0, 1, At, B1); PG8_BAR;
;             PG8_LDA(At, 0, 1); PG8_STAGE(PG8_SA(0, 0), a2, voffA);
;             PG8_BAR; PG8_WAIT_L(0); PG8_MMA(1, 0, At, B0); PG8_BAR; PG8_SCHED;
;             PG8_STAGE(PG8_SB(0, 1), b2 + hstep, voffB);
;             PG8_WAIT_V(6); PG8_BAR; PG8_MMA(1, 1, At, B1); PG8_BAR;
.LBB0_296:
	s_add_u32 s40, s40, 0x160080
	s_addc_u32 s41, s41, 0
	s_add_u32 s35, s42, 0x100
	v_mov_b32_e32 v0, 0
	s_addc_u32 s68, s43, 0
	s_mov_b32 s69, -2
	s_waitcnt lgkmcnt(0)
	ds_read_b128 v[144:147], v158
	ds_read_b128 v[164:167], v158 offset:1024
	ds_read_b128 v[168:171], v158 offset:2048
	ds_read_b128 v[172:175], v158 offset:3072
	s_add_u32 s0, s40, 0xffea0080
	s_addc_u32 s1, s41, -1
	s_cmpk_eq_i32 s69, 0x54
	s_cselect_b32 s45, s9, s1
	s_cselect_b32 s44, s8, s0
	s_cselect_b32 s43, s11, s68
	s_cselect_b32 s42, s10, s35
	s_add_i32 m0, s54, 0xc000
	ds_read_b128 v[176:179], v159
	ds_read_b128 v[180:183], v159 offset:1024
	ds_read_b128 v[188:191], v159 offset:2048
	ds_read_b128 v[194:197], v159 offset:3072
	ds_read_b128 v[198:201], v159 offset:4096
	ds_read_b128 v[202:205], v159 offset:5120
	ds_read_b128 v[206:209], v159 offset:6144
	global_load_lds_dwordx4 v136, s[40:41]
	s_add_i32 m0, s54, 0xe000
	ds_read_b128 v[210:213], v159 offset:7168
	global_load_lds_dwordx4 v138, s[40:41]
	s_waitcnt lgkmcnt(8)
	s_barrier
	s_waitcnt lgkmcnt(0)
	s_setprio 1
	v_mfma_f32_16x16x32_bf16 v[124:127], v[144:147], v[176:179], 0
	v_mfma_f32_16x16x32_bf16 v[120:123], v[168:171], v[176:179], 0
	v_mfma_f32_16x16x32_bf16 v[108:111], v[144:147], v[188:191], 0
	v_mfma_f32_16x16x32_bf16 v[104:107], v[168:171], v[188:191], 0
	v_mfma_f32_16x16x32_bf16 v[92:95], v[144:147], v[198:201], 0
	v_mfma_f32_16x16x32_bf16 v[88:91], v[168:171], v[198:201], 0
	v_mfma_f32_16x16x32_bf16 v[76:79], v[144:147], v[206:209], 0
	v_mfma_f32_16x16x32_bf16 v[72:75], v[168:171], v[206:209], 0
	v_mfma_f32_16x16x32_bf16 v[124:127], v[164:167], v[180:183], v[124:127]
	v_mfma_f32_16x16x32_bf16 v[120:123], v[172:175], v[180:183], v[120:123]
	v_mfma_f32_16x16x32_bf16 v[108:111], v[164:167], v[194:197], v[108:111]
	v_mfma_f32_16x16x32_bf16 v[104:107], v[172:175], v[194:197], v[104:107]
	v_mfma_f32_16x16x32_bf16 v[92:95], v[164:167], v[202:205], v[92:95]
	v_mfma_f32_16x16x32_bf16 v[88:91], v[172:175], v[202:205], v[88:91]
	v_mfma_f32_16x16x32_bf16 v[76:79], v[164:167], v[210:213], v[76:79]
	v_mfma_f32_16x16x32_bf16 v[72:75], v[172:175], v[210:213], v[72:75]
	s_setprio 0
	s_barrier
	s_add_i32 s0, s63, s53
	s_mov_b32 m0, s0
	ds_read_b128 v[214:217], v161
	ds_read_b128 v[218:221], v161 offset:1024
	ds_read_b128 v[222:225], v161 offset:2048
	global_load_lds_dwordx4 v130, s[42:43]
	s_add_i32 m0, s0, 0x2000
	ds_read_b128 v[226:229], v161 offset:3072
	global_load_lds_dwordx4 v134, s[42:43]
	s_barrier
	s_waitcnt lgkmcnt(0)
	s_setprio 1
	v_mfma_f32_16x16x32_bf16 v[116:119], v[214:217], v[176:179], 0
	v_mfma_f32_16x16x32_bf16 v[112:115], v[222:225], v[176:179], 0
	v_mfma_f32_16x16x32_bf16 v[100:103], v[214:217], v[188:191], 0
	v_mfma_f32_16x16x32_bf16 v[96:99], v[222:225], v[188:191], 0
	v_mfma_f32_16x16x32_bf16 v[84:87], v[214:217], v[198:201], 0
	v_mfma_f32_16x16x32_bf16 v[80:83], v[222:225], v[198:201], 0
	v_mfma_f32_16x16x32_bf16 v[68:71], v[214:217], v[206:209], 0
	v_mfma_f32_16x16x32_bf16 v[64:67], v[222:225], v[206:209], 0
	v_mfma_f32_16x16x32_bf16 v[116:119], v[218:221], v[180:183], v[116:119]
	v_mfma_f32_16x16x32_bf16 v[112:115], v[226:229], v[180:183], v[112:115]
	v_mfma_f32_16x16x32_bf16 v[100:103], v[218:221], v[194:197], v[100:103]
	v_mfma_f32_16x16x32_bf16 v[96:99], v[226:229], v[194:197], v[96:99]
	v_mfma_f32_16x16x32_bf16 v[84:87], v[218:221], v[202:205], v[84:87]
	v_mfma_f32_16x16x32_bf16 v[80:83], v[226:229], v[202:205], v[80:83]
	v_mfma_f32_16x16x32_bf16 v[68:71], v[218:221], v[210:213], v[68:71]
	v_mfma_f32_16x16x32_bf16 v[64:67], v[226:229], v[210:213], v[64:67]
	s_setprio 0
	s_mov_b32 m0, s54
	s_barrier
	ds_read_b128 v[176:179], v159 offset:16384
	ds_read_b128 v[180:183], v159 offset:17408
	ds_read_b128 v[188:191], v159 offset:18432
	ds_read_b128 v[194:197], v159 offset:19456
	ds_read_b128 v[198:201], v159 offset:20480
	ds_read_b128 v[202:205], v159 offset:21504
	ds_read_b128 v[206:209], v159 offset:22528
	global_load_lds_dwordx4 v128, s[44:45]
	s_mov_b32 m0, s55
	ds_read_b128 v[210:213], v159 offset:23552
	global_load_lds_dwordx4 v132, s[44:45]
	s_barrier
	s_waitcnt lgkmcnt(0)
	s_setprio 1
	v_mfma_f32_16x16x32_bf16 v[60:63], v[144:147], v[176:179], 0
	v_mfma_f32_16x16x32_bf16 v[56:59], v[168:171], v[176:179], 0
	v_mfma_f32_16x16x32_bf16 v[44:47], v[144:147], v[188:191], 0
	v_mfma_f32_16x16x32_bf16 v[40:43], v[168:171], v[188:191], 0
	v_mfma_f32_16x16x32_bf16 v[28:31], v[144:147], v[198:201], 0
	v_mfma_f32_16x16x32_bf16 v[24:27], v[168:171], v[198:201], 0
	v_mfma_f32_16x16x32_bf16 v[12:15], v[144:147], v[206:209], 0
	v_mfma_f32_16x16x32_bf16 v[8:11], v[168:171], v[206:209], 0
	v_mfma_f32_16x16x32_bf16 v[60:63], v[164:167], v[180:183], v[60:63]
	v_mfma_f32_16x16x32_bf16 v[56:59], v[172:175], v[180:183], v[56:59]
	v_mfma_f32_16x16x32_bf16 v[44:47], v[164:167], v[194:197], v[44:47]
	v_mfma_f32_16x16x32_bf16 v[40:43], v[172:175], v[194:197], v[40:43]
	v_mfma_f32_16x16x32_bf16 v[28:31], v[164:167], v[202:205], v[28:31]
	v_mfma_f32_16x16x32_bf16 v[24:27], v[172:175], v[202:205], v[24:27]
	v_mfma_f32_16x16x32_bf16 v[12:15], v[164:167], v[210:213], v[12:15]
	v_mfma_f32_16x16x32_bf16 v[8:11], v[172:175], v[210:213], v[8:11]
	s_setprio 0
	s_barrier
	s_add_i32 s4, s64, s53
	s_mov_b32 m0, s4
	s_add_u32 s0, s42, 0x160000
	s_addc_u32 s1, s43, 0
	global_load_lds_dwordx4 v130, s[0:1]
	s_add_i32 m0, s4, 0x2000
	s_nop 0
	global_load_lds_dwordx4 v134, s[0:1]
	s_waitcnt vmcnt(6)
	s_barrier
; #define PG8_STAGE(bufoff, gbase, voff) do { _Pragma("unroll") for (int _i = 0; _i < 2; ++_i) \
;         __builtin_amdgcn_global_load_lds((const unsigned*)((const char*)(gbase) + (voff)[_i]), (LAS unsigned*)(lds + (bufoff) + ldsw + _i * 8192), 16, 0, 0); } while (0)
; #define PG8_LDA(dst, b, h) do { _Pragma("unroll") for (int m = 0; m < 4; ++m) _Pragma("unroll") for (int k = 0; k < 2; ++k) dst[m][k] = *(const LAS bf16x8*)(lds + PG8_SA(b, h) + aoff + m * 2048 + k * 1024); } while (0)
; #define PG8_LDB(dst, b, h) do { _Pragma("unroll") for (int n = 0; n < 2; ++n) _Pragma("unroll") for (int k = 0; k < 2; ++k) dst[n][k] = *(const LAS bf16x8*)(lds + PG8_SB(b, h) + boff + n * 2048 + k * 1024); } while (0)
; #define PG8_MMA(ai, bj, At, Bt) do { __builtin_amdgcn_s_setprio(1); _Pragma("unroll") for (int m = 0; m < 4; ++m) _Pragma("unroll") for (int n = 0; n < 2; ++n) _Pragma("unroll") for (int k = 0; k < 2; ++k) \
;         acc[ai][bj][m][n] = __builtin_amdgcn_mfma_f32_16x16x32_bf16(Bt[n][k], At[m][k], acc[ai][bj][m][n], 0, 0, 0); __builtin_amdgcn_s_setprio(0); } while (0)
; #define PG8_WAIT_V(n) asm volatile("s_waitcnt vmcnt(" #n ")" ::: "memory")
; #define PG8_WAIT_L(n) asm volatile("s_waitcnt lgkmcnt(" #n ")" ::: "memory")
; #define PG8_BAR __builtin_amdgcn_s_barrier()
; #define PG8_SCHED __builtin_amdgcn_sched_barrier(0)
; template <class Epi, class Sched>
; DI void gemm_phase(LAS unsigned char* lds, const Gemm g, const Sched& S, const Epi& E) {
;     ...
;             PG8_WAIT_V(6); PG8_BAR; PG8_MMA(1, 1, At, B1); PG8_BAR;
;             PG8_LDB(B0, 1, 0); PG8_SCHED; PG8_LDA(At, 1, 0); PG8_STAGE(PG8_SA(0, 1), a2 + hstep, voffA);
;             PG8_WAIT_L(8); PG8_BAR; PG8_WAIT_L(0); PG8_MMA(0, 0, At, B0); PG8_BAR; PG8_SCHED;
;             PG8_LDB(B1, 1, 1); PG8_STAGE(PG8_SB(1, 0), b3, voffB);
;             PG8_BAR; PG8_WAIT_L(0); PG8_MMA(0, 1, At, B1); PG8_BAR;
;             PG8_LDA(At, 1, 1); PG8_STAGE(PG8_SA(1, 0), a3, voffA);
;             PG8_BAR; PG8_WAIT_L(0); PG8_MMA(1, 0, At, B0); PG8_BAR; PG8_SCHED;
	s_setprio 1
	v_mfma_f32_16x16x32_bf16 v[52:55], v[214:217], v[176:179], 0
	v_mfma_f32_16x16x32_bf16 v[48:51], v[222:225], v[176:179], 0
	v_mfma_f32_16x16x32_bf16 v[36:39], v[214:217], v[188:191], 0
	v_mfma_f32_16x16x32_bf16 v[32:35], v[222:225], v[188:191], 0
	v_mfma_f32_16x16x32_bf16 v[20:23], v[214:217], v[198:201], 0
	v_mfma_f32_16x16x32_bf16 v[16:19], v[222:225], v[198:201], 0
	v_mfma_f32_16x16x32_bf16 v[4:7], v[214:217], v[206:209], 0
	v_mfma_f32_16x16x32_bf16 v[0:3], v[222:225], v[206:209], 0
	v_mfma_f32_16x16x32_bf16 v[52:55], v[218:221], v[180:183], v[52:55]
	v_mfma_f32_16x16x32_bf16 v[48:51], v[226:229], v[180:183], v[48:51]
	v_mfma_f32_16x16x32_bf16 v[36:39], v[218:221], v[194:197], v[36:39]
	v_mfma_f32_16x16x32_bf16 v[32:35], v[226:229], v[194:197], v[32:35]
	v_mfma_f32_16x16x32_bf16 v[20:23], v[218:221], v[202:205], v[20:23]
	v_mfma_f32_16x16x32_bf16 v[16:19], v[226:229], v[202:205], v[16:19]
	v_mfma_f32_16x16x32_bf16 v[4:7], v[218:221], v[210:213], v[4:7]
	v_mfma_f32_16x16x32_bf16 v[0:3], v[226:229], v[210:213], v[0:3]
	s_setprio 0
	s_add_i32 s4, 0, 0x18000
	v_add_u32_e32 v230, s4, v157
	s_barrier
	ds_read_b128 v[144:147], v230
	ds_read_b128 v[164:167], v230 offset:1024
	ds_read_b128 v[168:171], v230 offset:2048
	ds_read_b128 v[172:175], v230 offset:3072
	s_add_u32 s0, s44, 0x160000
	s_addc_u32 s1, s45, 0
	s_mov_b32 m0, s56
	ds_read_b128 v[176:179], v159 offset:32768
	ds_read_b128 v[180:183], v159 offset:33792
	ds_read_b128 v[188:191], v159 offset:34816
	ds_read_b128 v[194:197], v159 offset:35840
	ds_read_b128 v[198:201], v159 offset:36864
	ds_read_b128 v[202:205], v159 offset:37888
	ds_read_b128 v[206:209], v159 offset:38912
	global_load_lds_dwordx4 v128, s[0:1]
	s_mov_b32 m0, s57
	ds_read_b128 v[210:213], v159 offset:39936
	global_load_lds_dwordx4 v132, s[0:1]
	s_waitcnt lgkmcnt(8)
	s_barrier
	s_waitcnt lgkmcnt(0)
	s_setprio 1
	v_mfma_f32_16x16x32_bf16 v[124:127], v[144:147], v[176:179], v[124:127]
	v_mfma_f32_16x16x32_bf16 v[120:123], v[168:171], v[176:179], v[120:123]
	v_mfma_f32_16x16x32_bf16 v[108:111], v[144:147], v[188:191], v[108:111]
	v_mfma_f32_16x16x32_bf16 v[104:107], v[168:171], v[188:191], v[104:107]
	v_mfma_f32_16x16x32_bf16 v[92:95], v[144:147], v[198:201], v[92:95]
	v_mfma_f32_16x16x32_bf16 v[88:91], v[168:171], v[198:201], v[88:91]
	v_mfma_f32_16x16x32_bf16 v[76:79], v[144:147], v[206:209], v[76:79]
	v_mfma_f32_16x16x32_bf16 v[72:75], v[168:171], v[206:209], v[72:75]
	v_mfma_f32_16x16x32_bf16 v[124:127], v[164:167], v[180:183], v[124:127]
	v_mfma_f32_16x16x32_bf16 v[120:123], v[172:175], v[180:183], v[120:123]
	v_mfma_f32_16x16x32_bf16 v[108:111], v[164:167], v[194:197], v[108:111]
	v_mfma_f32_16x16x32_bf16 v[104:107], v[172:175], v[194:197], v[104:107]
	v_mfma_f32_16x16x32_bf16 v[92:95], v[164:167], v[202:205], v[92:95]
	v_mfma_f32_16x16x32_bf16 v[88:91], v[172:175], v[202:205], v[88:91]
	v_mfma_f32_16x16x32_bf16 v[76:79], v[164:167], v[210:213], v[76:79]
	v_mfma_f32_16x16x32_bf16 v[72:75], v[172:175], v[210:213], v[72:75]
	s_setprio 0
	s_barrier
	s_add_i32 s5, 0, 0x1c000
	s_add_i32 s0, s4, s53
	v_add_u32_e32 v231, s5, v157
	s_add_i32 m0, s0, 0xffffff80
	ds_read_b128 v[214:217], v231
	ds_read_b128 v[218:221], v231 offset:1024
	ds_read_b128 v[222:225], v231 offset:2048
	global_load_lds_dwordx4 v130, s[42:43] offset:128
	s_add_i32 m0, s0, 0x1f80
	ds_read_b128 v[226:229], v231 offset:3072
	global_load_lds_dwordx4 v134, s[42:43] offset:128
	s_barrier
	s_waitcnt lgkmcnt(0)
	s_setprio 1
	v_mfma_f32_16x16x32_bf16 v[116:119], v[214:217], v[176:179], v[116:119]
	v_mfma_f32_16x16x32_bf16 v[112:115], v[222:225], v[176:179], v[112:115]
	v_mfma_f32_16x16x32_bf16 v[100:103], v[214:217], v[188:191], v[100:103]
	v_mfma_f32_16x16x32_bf16 v[96:99], v[222:225], v[188:191], v[96:99]
	v_mfma_f32_16x16x32_bf16 v[84:87], v[214:217], v[198:201], v[84:87]
	v_mfma_f32_16x16x32_bf16 v[80:83], v[222:225], v[198:201], v[80:83]
	v_mfma_f32_16x16x32_bf16 v[68:71], v[214:217], v[206:209], v[68:71]
	v_mfma_f32_16x16x32_bf16 v[64:67], v[222:225], v[206:209], v[64:67]
	v_mfma_f32_16x16x32_bf16 v[116:119], v[218:221], v[180:183], v[116:119]
	v_mfma_f32_16x16x32_bf16 v[112:115], v[226:229], v[180:183], v[112:115]
	v_mfma_f32_16x16x32_bf16 v[100:103], v[218:221], v[194:197], v[100:103]
	v_mfma_f32_16x16x32_bf16 v[96:99], v[226:229], v[194:197], v[96:99]
	v_mfma_f32_16x16x32_bf16 v[84:87], v[218:221], v[202:205], v[84:87]
	v_mfma_f32_16x16x32_bf16 v[80:83], v[226:229], v[202:205], v[80:83]
	v_mfma_f32_16x16x32_bf16 v[68:71], v[218:221], v[210:213], v[68:71]
	v_mfma_f32_16x16x32_bf16 v[64:67], v[226:229], v[210:213], v[64:67]
	s_setprio 0
	s_add_i32 m0, s61, 0xffffff80
	s_barrier
	ds_read_b128 v[176:179], v159 offset:49152
	ds_read_b128 v[180:183], v159 offset:50176
	ds_read_b128 v[188:191], v159 offset:51200
	ds_read_b128 v[194:197], v159 offset:52224
	ds_read_b128 v[198:201], v159 offset:53248
	ds_read_b128 v[202:205], v159 offset:54272
	ds_read_b128 v[206:209], v159 offset:55296
	global_load_lds_dwordx4 v128, s[44:45] offset:128
	s_add_i32 m0, s62, 0xffffff80
	ds_read_b128 v[210:213], v159 offset:56320
	global_load_lds_dwordx4 v132, s[44:45] offset:128
	s_barrier
; #define PG8_STAGE(bufoff, gbase, voff) do { _Pragma("unroll") for (int _i = 0; _i < 2; ++_i) \
;         __builtin_amdgcn_global_load_lds((const unsigned*)((const char*)(gbase) + (voff)[_i]), (LAS unsigned*)(lds + (bufoff) + ldsw + _i * 8192), 16, 0, 0); } while (0)
; #define PG8_LDA(dst, b, h) do { _Pragma("unroll") for (int m = 0; m < 4; ++m) _Pragma("unroll") for (int k = 0; k < 2; ++k) dst[m][k] = *(const LAS bf16x8*)(lds + PG8_SA(b, h) + aoff + m * 2048 + k * 1024); } while (0)
; #define PG8_LDB(dst, b, h) do { _Pragma("unroll") for (int n = 0; n < 2; ++n) _Pragma("unroll") for (int k = 0; k < 2; ++k) dst[n][k] = *(const LAS bf16x8*)(lds + PG8_SB(b, h) + boff + n * 2048 + k * 1024); } while (0)
; #define PG8_MMA(ai, bj, At, Bt) do { __builtin_amdgcn_s_setprio(1); _Pragma("unroll") for (int m = 0; m < 4; ++m) _Pragma("unroll") for (int n = 0; n < 2; ++n) _Pragma("unroll") for (int k = 0; k < 2; ++k) \
;         acc[ai][bj][m][n] = __builtin_amdgcn_mfma_f32_16x16x32_bf16(Bt[n][k], At[m][k], acc[ai][bj][m][n], 0, 0, 0); __builtin_amdgcn_s_setprio(0); } while (0)
; #define PG8_WAIT_V(n) asm volatile("s_waitcnt vmcnt(" #n ")" ::: "memory")
; #define PG8_WAIT_L(n) asm volatile("s_waitcnt lgkmcnt(" #n ")" ::: "memory")
; #define PG8_BAR __builtin_amdgcn_s_barrier()
; #define PG8_SCHED __builtin_amdgcn_sched_barrier(0)
; template <class Epi, class Sched>
; DI void gemm_phase(LAS unsigned char* lds, const Gemm g, const Sched& S, const Epi& E) {
;     ...
;             PG8_LDB(B0, 0, 0); PG8_SCHED; PG8_LDA(At, 0, 0); PG8_STAGE(PG8_SA(1, 1), a1 + hstep, voffA);
;             PG8_WAIT_L(8); PG8_BAR; PG8_WAIT_L(0); PG8_MMA(0, 0, At, B0); PG8_BAR; PG8_SCHED;
;             PG8_LDB(B1, 0, 1); PG8_STAGE(PG8_SB(0, 0), b2, voffB);
;             PG8_BAR; PG8_WAIT_L(0); PG8_MMA(0, 1, At, B1); PG8_BAR;
;     ...
;             PG8_BAR; PG8_WAIT_L(0); PG8_MMA(1, 0, At, B0); PG8_BAR; PG8_SCHED;
;             PG8_STAGE(PG8_SB(1, 1), b3 + hstep, voffB);
;             PG8_WAIT_V(6); PG8_BAR; PG8_MMA(1, 1, At, B1); PG8_BAR;
	s_waitcnt lgkmcnt(0)
	s_setprio 1
	v_mfma_f32_16x16x32_bf16 v[60:63], v[144:147], v[176:179], v[60:63]
	v_mfma_f32_16x16x32_bf16 v[56:59], v[168:171], v[176:179], v[56:59]
	v_mfma_f32_16x16x32_bf16 v[44:47], v[144:147], v[188:191], v[44:47]
	v_mfma_f32_16x16x32_bf16 v[40:43], v[168:171], v[188:191], v[40:43]
	v_mfma_f32_16x16x32_bf16 v[28:31], v[144:147], v[198:201], v[28:31]
	v_mfma_f32_16x16x32_bf16 v[24:27], v[168:171], v[198:201], v[24:27]
	v_mfma_f32_16x16x32_bf16 v[12:15], v[144:147], v[206:209], v[12:15]
	v_mfma_f32_16x16x32_bf16 v[8:11], v[168:171], v[206:209], v[8:11]
	v_mfma_f32_16x16x32_bf16 v[60:63], v[164:167], v[180:183], v[60:63]
	v_mfma_f32_16x16x32_bf16 v[56:59], v[172:175], v[180:183], v[56:59]
	v_mfma_f32_16x16x32_bf16 v[44:47], v[164:167], v[194:197], v[44:47]
	v_mfma_f32_16x16x32_bf16 v[40:43], v[172:175], v[194:197], v[40:43]
	v_mfma_f32_16x16x32_bf16 v[28:31], v[164:167], v[202:205], v[28:31]
	v_mfma_f32_16x16x32_bf16 v[24:27], v[172:175], v[202:205], v[24:27]
	v_mfma_f32_16x16x32_bf16 v[12:15], v[164:167], v[210:213], v[12:15]
	v_mfma_f32_16x16x32_bf16 v[8:11], v[172:175], v[210:213], v[8:11]
	s_setprio 0
	s_barrier
	s_add_i32 s4, s5, s53
	s_mov_b32 m0, s4
	s_add_u32 s0, s42, 0x160080
	s_addc_u32 s1, s43, 0
	global_load_lds_dwordx4 v130, s[0:1]
	s_add_i32 m0, s4, 0x2000
	s_nop 0
	global_load_lds_dwordx4 v134, s[0:1]
	s_waitcnt vmcnt(6)
	s_barrier
	s_setprio 1
	v_mfma_f32_16x16x32_bf16 v[52:55], v[214:217], v[176:179], v[52:55]
	v_mfma_f32_16x16x32_bf16 v[48:51], v[222:225], v[176:179], v[48:51]
	v_mfma_f32_16x16x32_bf16 v[36:39], v[214:217], v[188:191], v[36:39]
	v_mfma_f32_16x16x32_bf16 v[32:35], v[222:225], v[188:191], v[32:35]
	v_mfma_f32_16x16x32_bf16 v[20:23], v[214:217], v[198:201], v[20:23]
	v_mfma_f32_16x16x32_bf16 v[16:19], v[222:225], v[198:201], v[16:19]
	v_mfma_f32_16x16x32_bf16 v[4:7], v[214:217], v[206:209], v[4:7]
	v_mfma_f32_16x16x32_bf16 v[0:3], v[222:225], v[206:209], v[0:3]
	v_mfma_f32_16x16x32_bf16 v[52:55], v[218:221], v[180:183], v[52:55]
	v_mfma_f32_16x16x32_bf16 v[48:51], v[226:229], v[180:183], v[48:51]
	v_mfma_f32_16x16x32_bf16 v[36:39], v[218:221], v[194:197], v[36:39]
	v_mfma_f32_16x16x32_bf16 v[32:35], v[226:229], v[194:197], v[32:35]
	v_mfma_f32_16x16x32_bf16 v[20:23], v[218:221], v[202:205], v[20:23]
	v_mfma_f32_16x16x32_bf16 v[16:19], v[226:229], v[202:205], v[16:19]
	v_mfma_f32_16x16x32_bf16 v[4:7], v[218:221], v[210:213], v[4:7]
	v_mfma_f32_16x16x32_bf16 v[0:3], v[226:229], v[210:213], v[0:3]
	s_setprio 0
	s_add_i32 s69, s69, 2
	s_add_u32 s40, s40, 0x100
	s_addc_u32 s41, s41, 0
	s_add_u32 s35, s35, 0x100
	s_addc_u32 s68, s68, 0
	s_cmpk_gt_u32 s69, 0x55
	s_barrier
	s_cbranch_scc0 .LBB0_297
	s_branch .Lpeel_done_297
.LBB0_297:
	ds_read_b128 v[144:147], v158
	ds_read_b128 v[164:167], v158 offset:1024
	ds_read_b128 v[168:171], v158 offset:2048
	ds_read_b128 v[172:175], v158 offset:3072
	s_add_u32 s0, s40, 0xffea0080
	s_addc_u32 s1, s41, -1
	s_cmpk_eq_i32 s69, 0x54
	s_cselect_b32 s45, s9, s1
	s_cselect_b32 s44, s8, s0
	s_cselect_b32 s43, s11, s68
	s_cselect_b32 s42, s10, s35
	s_add_i32 m0, s54, 0xc000
	ds_read_b128 v[176:179], v159
	ds_read_b128 v[180:183], v159 offset:1024
	ds_read_b128 v[188:191], v159 offset:2048
	ds_read_b128 v[194:197], v159 offset:3072
	ds_read_b128 v[198:201], v159 offset:4096
	ds_read_b128 v[202:205], v159 offset:5120
	ds_read_b128 v[206:209], v159 offset:6144
	global_load_lds_dwordx4 v136, s[40:41]
	s_add_i32 m0, s54, 0xe000
	ds_read_b128 v[210:213], v159 offset:7168
	global_load_lds_dwordx4 v138, s[40:41]
	s_waitcnt lgkmcnt(8)
	s_barrier
	s_waitcnt lgkmcnt(0)
	s_setprio 1
	v_mfma_f32_16x16x32_bf16 v[124:127], v[144:147], v[176:179], v[124:127]
	v_mfma_f32_16x16x32_bf16 v[120:123], v[168:171], v[176:179], v[120:123]
	v_mfma_f32_16x16x32_bf16 v[108:111], v[144:147], v[188:191], v[108:111]
	v_mfma_f32_16x16x32_bf16 v[104:107], v[168:171], v[188:191], v[104:107]
	v_mfma_f32_16x16x32_bf16 v[92:95], v[144:147], v[198:201], v[92:95]
	v_mfma_f32_16x16x32_bf16 v[88:91], v[168:171], v[198:201], v[88:91]
	v_mfma_f32_16x16x32_bf16 v[76:79], v[144:147], v[206:209], v[76:79]
	v_mfma_f32_16x16x32_bf16 v[72:75], v[168:171], v[206:209], v[72:75]
	v_mfma_f32_16x16x32_bf16 v[124:127], v[164:167], v[180:183], v[124:127]
	v_mfma_f32_16x16x32_bf16 v[120:123], v[172:175], v[180:183], v[120:123]
	v_mfma_f32_16x16x32_bf16 v[108:111], v[164:167], v[194:197], v[108:111]
	v_mfma_f32_16x16x32_bf16 v[104:107], v[172:175], v[194:197], v[104:107]
	v_mfma_f32_16x16x32_bf16 v[92:95], v[164:167], v[202:205], v[92:95]
	v_mfma_f32_16x16x32_bf16 v[88:91], v[172:175], v[202:205], v[88:91]
	v_mfma_f32_16x16x32_bf16 v[76:79], v[164:167], v[210:213], v[76:79]
	v_mfma_f32_16x16x32_bf16 v[72:75], v[172:175], v[210:213], v[72:75]
	s_setprio 0
	s_barrier
	s_add_i32 s0, s63, s53
	s_mov_b32 m0, s0
	ds_read_b128 v[214:217], v161
	ds_read_b128 v[218:221], v161 offset:1024
	ds_read_b128 v[222:225], v161 offset:2048
	global_load_lds_dwordx4 v130, s[42:43]
	s_add_i32 m0, s0, 0x2000
	ds_read_b128 v[226:229], v161 offset:3072
	global_load_lds_dwordx4 v134, s[42:43]
	s_barrier
; #define PG8_STAGE(bufoff, gbase, voff) do { _Pragma("unroll") for (int _i = 0; _i < 2; ++_i) \
;         __builtin_amdgcn_global_load_lds((const unsigned*)((const char*)(gbase) + (voff)[_i]), (LAS unsigned*)(lds + (bufoff) + ldsw + _i * 8192), 16, 0, 0); } while (0)
; #define PG8_LDA(dst, b, h) do { _Pragma("unroll") for (int m = 0; m < 4; ++m) _Pragma("unroll") for (int k = 0; k < 2; ++k) dst[m][k] = *(const LAS bf16x8*)(lds + PG8_SA(b, h) + aoff + m * 2048 + k * 1024); } while (0)
; #define PG8_LDB(dst, b, h) do { _Pragma("unroll") for (int n = 0; n < 2; ++n) _Pragma("unroll") for (int k = 0; k < 2; ++k) dst[n][k] = *(const LAS bf16x8*)(lds + PG8_SB(b, h) + boff + n * 2048 + k * 1024); } while (0)
; #define PG8_MMA(ai, bj, At, Bt) do { __builtin_amdgcn_s_setprio(1); _Pragma("unroll") for (int m = 0; m < 4; ++m) _Pragma("unroll") for (int n = 0; n < 2; ++n) _Pragma("unroll") for (int k = 0; k < 2; ++k) \
;         acc[ai][bj][m][n] = __builtin_amdgcn_mfma_f32_16x16x32_bf16(Bt[n][k], At[m][k], acc[ai][bj][m][n], 0, 0, 0); __builtin_amdgcn_s_setprio(0); } while (0)
; #define PG8_WAIT_V(n) asm volatile("s_waitcnt vmcnt(" #n ")" ::: "memory")
; #define PG8_WAIT_L(n) asm volatile("s_waitcnt lgkmcnt(" #n ")" ::: "memory")
; #define PG8_BAR __builtin_amdgcn_s_barrier()
; #define PG8_SCHED __builtin_amdgcn_sched_barrier(0)
; template <class Epi, class Sched>
; DI void gemm_phase(LAS unsigned char* lds, const Gemm g, const Sched& S, const Epi& E) {
;     ...
;             PG8_BAR; PG8_WAIT_L(0); PG8_MMA(0, 1, At, B1); PG8_BAR;
;             PG8_LDA(At, 0, 1); PG8_STAGE(PG8_SA(0, 0), a2, voffA);
;             PG8_BAR; PG8_WAIT_L(0); PG8_MMA(1, 0, At, B0); PG8_BAR; PG8_SCHED;
;             PG8_STAGE(PG8_SB(0, 1), b2 + hstep, voffB);
;             PG8_WAIT_V(6); PG8_BAR; PG8_MMA(1, 1, At, B1); PG8_BAR;
;             PG8_LDB(B0, 1, 0); PG8_SCHED; PG8_LDA(At, 1, 0); PG8_STAGE(PG8_SA(0, 1), a2 + hstep, voffA);
;             PG8_WAIT_L(8); PG8_BAR; PG8_WAIT_L(0); PG8_MMA(0, 0, At, B0); PG8_BAR; PG8_SCHED;
;             PG8_LDB(B1, 1, 1); PG8_STAGE(PG8_SB(1, 0), b3, voffB);
	s_waitcnt lgkmcnt(0)
	s_setprio 1
	v_mfma_f32_16x16x32_bf16 v[116:119], v[214:217], v[176:179], v[116:119]
	v_mfma_f32_16x16x32_bf16 v[112:115], v[222:225], v[176:179], v[112:115]
	v_mfma_f32_16x16x32_bf16 v[100:103], v[214:217], v[188:191], v[100:103]
	v_mfma_f32_16x16x32_bf16 v[96:99], v[222:225], v[188:191], v[96:99]
	v_mfma_f32_16x16x32_bf16 v[84:87], v[214:217], v[198:201], v[84:87]
	v_mfma_f32_16x16x32_bf16 v[80:83], v[222:225], v[198:201], v[80:83]
	v_mfma_f32_16x16x32_bf16 v[68:71], v[214:217], v[206:209], v[68:71]
	v_mfma_f32_16x16x32_bf16 v[64:67], v[222:225], v[206:209], v[64:67]
	v_mfma_f32_16x16x32_bf16 v[116:119], v[218:221], v[180:183], v[116:119]
	v_mfma_f32_16x16x32_bf16 v[112:115], v[226:229], v[180:183], v[112:115]
	v_mfma_f32_16x16x32_bf16 v[100:103], v[218:221], v[194:197], v[100:103]
	v_mfma_f32_16x16x32_bf16 v[96:99], v[226:229], v[194:197], v[96:99]
	v_mfma_f32_16x16x32_bf16 v[84:87], v[218:221], v[202:205], v[84:87]
	v_mfma_f32_16x16x32_bf16 v[80:83], v[226:229], v[202:205], v[80:83]
	v_mfma_f32_16x16x32_bf16 v[68:71], v[218:221], v[210:213], v[68:71]
	v_mfma_f32_16x16x32_bf16 v[64:67], v[226:229], v[210:213], v[64:67]
	s_setprio 0
	s_mov_b32 m0, s54
	s_barrier
	ds_read_b128 v[176:179], v159 offset:16384
	ds_read_b128 v[180:183], v159 offset:17408
	ds_read_b128 v[188:191], v159 offset:18432
	ds_read_b128 v[194:197], v159 offset:19456
	ds_read_b128 v[198:201], v159 offset:20480
	ds_read_b128 v[202:205], v159 offset:21504
	ds_read_b128 v[206:209], v159 offset:22528
	global_load_lds_dwordx4 v128, s[44:45]
	s_mov_b32 m0, s55
	ds_read_b128 v[210:213], v159 offset:23552
	global_load_lds_dwordx4 v132, s[44:45]
	s_barrier
	s_waitcnt lgkmcnt(0)
	s_setprio 1
	v_mfma_f32_16x16x32_bf16 v[60:63], v[144:147], v[176:179], v[60:63]
	v_mfma_f32_16x16x32_bf16 v[56:59], v[168:171], v[176:179], v[56:59]
	v_mfma_f32_16x16x32_bf16 v[44:47], v[144:147], v[188:191], v[44:47]
	v_mfma_f32_16x16x32_bf16 v[40:43], v[168:171], v[188:191], v[40:43]
	v_mfma_f32_16x16x32_bf16 v[28:31], v[144:147], v[198:201], v[28:31]
	v_mfma_f32_16x16x32_bf16 v[24:27], v[168:171], v[198:201], v[24:27]
	v_mfma_f32_16x16x32_bf16 v[12:15], v[144:147], v[206:209], v[12:15]
	v_mfma_f32_16x16x32_bf16 v[8:11], v[168:171], v[206:209], v[8:11]
	v_mfma_f32_16x16x32_bf16 v[60:63], v[164:167], v[180:183], v[60:63]
	v_mfma_f32_16x16x32_bf16 v[56:59], v[172:175], v[180:183], v[56:59]
	v_mfma_f32_16x16x32_bf16 v[44:47], v[164:167], v[194:197], v[44:47]
	v_mfma_f32_16x16x32_bf16 v[40:43], v[172:175], v[194:197], v[40:43]
	v_mfma_f32_16x16x32_bf16 v[28:31], v[164:167], v[202:205], v[28:31]
	v_mfma_f32_16x16x32_bf16 v[24:27], v[172:175], v[202:205], v[24:27]
	v_mfma_f32_16x16x32_bf16 v[12:15], v[164:167], v[210:213], v[12:15]
	v_mfma_f32_16x16x32_bf16 v[8:11], v[172:175], v[210:213], v[8:11]
	s_setprio 0
	s_barrier
	s_add_i32 s4, s64, s53
	s_mov_b32 m0, s4
	s_add_u32 s0, s42, 0x160000
	s_addc_u32 s1, s43, 0
	global_load_lds_dwordx4 v130, s[0:1]
	s_add_i32 m0, s4, 0x2000
	s_nop 0
	global_load_lds_dwordx4 v134, s[0:1]
	s_waitcnt vmcnt(6)
	s_barrier
	s_setprio 1
	v_mfma_f32_16x16x32_bf16 v[52:55], v[214:217], v[176:179], v[52:55]
	v_mfma_f32_16x16x32_bf16 v[48:51], v[222:225], v[176:179], v[48:51]
	v_mfma_f32_16x16x32_bf16 v[36:39], v[214:217], v[188:191], v[36:39]
	v_mfma_f32_16x16x32_bf16 v[32:35], v[222:225], v[188:191], v[32:35]
	v_mfma_f32_16x16x32_bf16 v[20:23], v[214:217], v[198:201], v[20:23]
	v_mfma_f32_16x16x32_bf16 v[16:19], v[222:225], v[198:201], v[16:19]
	v_mfma_f32_16x16x32_bf16 v[4:7], v[214:217], v[206:209], v[4:7]
	v_mfma_f32_16x16x32_bf16 v[0:3], v[222:225], v[206:209], v[0:3]
	v_mfma_f32_16x16x32_bf16 v[52:55], v[218:221], v[180:183], v[52:55]
	v_mfma_f32_16x16x32_bf16 v[48:51], v[226:229], v[180:183], v[48:51]
	v_mfma_f32_16x16x32_bf16 v[36:39], v[218:221], v[194:197], v[36:39]
	v_mfma_f32_16x16x32_bf16 v[32:35], v[226:229], v[194:197], v[32:35]
	v_mfma_f32_16x16x32_bf16 v[20:23], v[218:221], v[202:205], v[20:23]
	v_mfma_f32_16x16x32_bf16 v[16:19], v[226:229], v[202:205], v[16:19]
	v_mfma_f32_16x16x32_bf16 v[4:7], v[218:221], v[210:213], v[4:7]
	v_mfma_f32_16x16x32_bf16 v[0:3], v[226:229], v[210:213], v[0:3]
	s_setprio 0
	s_add_i32 s4, 0, 0x18000
	s_barrier
	ds_read_b128 v[144:147], v230
	ds_read_b128 v[164:167], v230 offset:1024
	ds_read_b128 v[168:171], v230 offset:2048
	ds_read_b128 v[172:175], v230 offset:3072
	s_add_u32 s0, s44, 0x160000
	s_addc_u32 s1, s45, 0
	s_mov_b32 m0, s56
	ds_read_b128 v[176:179], v159 offset:32768
	ds_read_b128 v[180:183], v159 offset:33792
	ds_read_b128 v[188:191], v159 offset:34816
	ds_read_b128 v[194:197], v159 offset:35840
	ds_read_b128 v[198:201], v159 offset:36864
	ds_read_b128 v[202:205], v159 offset:37888
	ds_read_b128 v[206:209], v159 offset:38912
	global_load_lds_dwordx4 v128, s[0:1]
	s_mov_b32 m0, s57
	ds_read_b128 v[210:213], v159 offset:39936
	global_load_lds_dwordx4 v132, s[0:1]
	s_waitcnt lgkmcnt(8)
	s_barrier
; #define PG8_STAGE(bufoff, gbase, voff) do { _Pragma("unroll") for (int _i = 0; _i < 2; ++_i) \
;         __builtin_amdgcn_global_load_lds((const unsigned*)((const char*)(gbase) + (voff)[_i]), (LAS unsigned*)(lds + (bufoff) + ldsw + _i * 8192), 16, 0, 0); } while (0)
; #define PG8_LDA(dst, b, h) do { _Pragma("unroll") for (int m = 0; m < 4; ++m) _Pragma("unroll") for (int k = 0; k < 2; ++k) dst[m][k] = *(const LAS bf16x8*)(lds + PG8_SA(b, h) + aoff + m * 2048 + k * 1024); } while (0)
; #define PG8_LDB(dst, b, h) do { _Pragma("unroll") for (int n = 0; n < 2; ++n) _Pragma("unroll") for (int k = 0; k < 2; ++k) dst[n][k] = *(const LAS bf16x8*)(lds + PG8_SB(b, h) + boff + n * 2048 + k * 1024); } while (0)
; #define PG8_MMA(ai, bj, At, Bt) do { __builtin_amdgcn_s_setprio(1); _Pragma("unroll") for (int m = 0; m < 4; ++m) _Pragma("unroll") for (int n = 0; n < 2; ++n) _Pragma("unroll") for (int k = 0; k < 2; ++k) \
;         acc[ai][bj][m][n] = __builtin_amdgcn_mfma_f32_16x16x32_bf16(Bt[n][k], At[m][k], acc[ai][bj][m][n], 0, 0, 0); __builtin_amdgcn_s_setprio(0); } while (0)
; #define PG8_WAIT_V(n) asm volatile("s_waitcnt vmcnt(" #n ")" ::: "memory")
; #define PG8_WAIT_L(n) asm volatile("s_waitcnt lgkmcnt(" #n ")" ::: "memory")
; #define PG8_BAR __builtin_amdgcn_s_barrier()
; #define PG8_SCHED __builtin_amdgcn_sched_barrier(0)
; template <class Epi, class Sched>
; DI void gemm_phase(LAS unsigned char* lds, const Gemm g, const Sched& S, const Epi& E) {
;     ...
;             PG8_LDB(B1, 1, 1); PG8_STAGE(PG8_SB(1, 0), b3, voffB);
;             PG8_BAR; PG8_WAIT_L(0); PG8_MMA(0, 1, At, B1); PG8_BAR;
;             PG8_LDA(At, 1, 1); PG8_STAGE(PG8_SA(1, 0), a3, voffA);
;             PG8_BAR; PG8_WAIT_L(0); PG8_MMA(1, 0, At, B0); PG8_BAR; PG8_SCHED;
;             PG8_STAGE(PG8_SB(1, 1), b3 + hstep, voffB);
;             PG8_WAIT_V(6); PG8_BAR; PG8_MMA(1, 1, At, B1); PG8_BAR;
	s_waitcnt lgkmcnt(0)
	s_setprio 1
	v_mfma_f32_16x16x32_bf16 v[124:127], v[144:147], v[176:179], v[124:127]
	v_mfma_f32_16x16x32_bf16 v[120:123], v[168:171], v[176:179], v[120:123]
	v_mfma_f32_16x16x32_bf16 v[108:111], v[144:147], v[188:191], v[108:111]
	v_mfma_f32_16x16x32_bf16 v[104:107], v[168:171], v[188:191], v[104:107]
	v_mfma_f32_16x16x32_bf16 v[92:95], v[144:147], v[198:201], v[92:95]
	v_mfma_f32_16x16x32_bf16 v[88:91], v[168:171], v[198:201], v[88:91]
	v_mfma_f32_16x16x32_bf16 v[76:79], v[144:147], v[206:209], v[76:79]
	v_mfma_f32_16x16x32_bf16 v[72:75], v[168:171], v[206:209], v[72:75]
	v_mfma_f32_16x16x32_bf16 v[124:127], v[164:167], v[180:183], v[124:127]
	v_mfma_f32_16x16x32_bf16 v[120:123], v[172:175], v[180:183], v[120:123]
	v_mfma_f32_16x16x32_bf16 v[108:111], v[164:167], v[194:197], v[108:111]
	v_mfma_f32_16x16x32_bf16 v[104:107], v[172:175], v[194:197], v[104:107]
	v_mfma_f32_16x16x32_bf16 v[92:95], v[164:167], v[202:205], v[92:95]
	v_mfma_f32_16x16x32_bf16 v[88:91], v[172:175], v[202:205], v[88:91]
	v_mfma_f32_16x16x32_bf16 v[76:79], v[164:167], v[210:213], v[76:79]
	v_mfma_f32_16x16x32_bf16 v[72:75], v[172:175], v[210:213], v[72:75]
	s_setprio 0
	s_barrier
	s_add_i32 s5, 0, 0x1c000
	s_add_i32 s0, s4, s53
	s_add_i32 m0, s0, 0xffffff80
	ds_read_b128 v[214:217], v231
	ds_read_b128 v[218:221], v231 offset:1024
	ds_read_b128 v[222:225], v231 offset:2048
	global_load_lds_dwordx4 v130, s[42:43] offset:128
	s_add_i32 m0, s0, 0x1f80
	ds_read_b128 v[226:229], v231 offset:3072
	global_load_lds_dwordx4 v134, s[42:43] offset:128
	s_barrier
	s_waitcnt lgkmcnt(0)
	s_setprio 1
	v_mfma_f32_16x16x32_bf16 v[116:119], v[214:217], v[176:179], v[116:119]
	v_mfma_f32_16x16x32_bf16 v[112:115], v[222:225], v[176:179], v[112:115]
	v_mfma_f32_16x16x32_bf16 v[100:103], v[214:217], v[188:191], v[100:103]
	v_mfma_f32_16x16x32_bf16 v[96:99], v[222:225], v[188:191], v[96:99]
	v_mfma_f32_16x16x32_bf16 v[84:87], v[214:217], v[198:201], v[84:87]
	v_mfma_f32_16x16x32_bf16 v[80:83], v[222:225], v[198:201], v[80:83]
	v_mfma_f32_16x16x32_bf16 v[68:71], v[214:217], v[206:209], v[68:71]
	v_mfma_f32_16x16x32_bf16 v[64:67], v[222:225], v[206:209], v[64:67]
	v_mfma_f32_16x16x32_bf16 v[116:119], v[218:221], v[180:183], v[116:119]
	v_mfma_f32_16x16x32_bf16 v[112:115], v[226:229], v[180:183], v[112:115]
	v_mfma_f32_16x16x32_bf16 v[100:103], v[218:221], v[194:197], v[100:103]
	v_mfma_f32_16x16x32_bf16 v[96:99], v[226:229], v[194:197], v[96:99]
	v_mfma_f32_16x16x32_bf16 v[84:87], v[218:221], v[202:205], v[84:87]
	v_mfma_f32_16x16x32_bf16 v[80:83], v[226:229], v[202:205], v[80:83]
	v_mfma_f32_16x16x32_bf16 v[68:71], v[218:221], v[210:213], v[68:71]
	v_mfma_f32_16x16x32_bf16 v[64:67], v[226:229], v[210:213], v[64:67]
	s_setprio 0
	s_add_i32 m0, s61, 0xffffff80
	s_barrier
	ds_read_b128 v[176:179], v159 offset:49152
	ds_read_b128 v[180:183], v159 offset:50176
	ds_read_b128 v[188:191], v159 offset:51200
	ds_read_b128 v[194:197], v159 offset:52224
	ds_read_b128 v[198:201], v159 offset:53248
	ds_read_b128 v[202:205], v159 offset:54272
	ds_read_b128 v[206:209], v159 offset:55296
	global_load_lds_dwordx4 v128, s[44:45] offset:128
	s_add_i32 m0, s62, 0xffffff80
	ds_read_b128 v[210:213], v159 offset:56320
	global_load_lds_dwordx4 v132, s[44:45] offset:128
	s_barrier
	s_waitcnt lgkmcnt(0)
	s_setprio 1
	v_mfma_f32_16x16x32_bf16 v[60:63], v[144:147], v[176:179], v[60:63]
	v_mfma_f32_16x16x32_bf16 v[56:59], v[168:171], v[176:179], v[56:59]
	v_mfma_f32_16x16x32_bf16 v[44:47], v[144:147], v[188:191], v[44:47]
	v_mfma_f32_16x16x32_bf16 v[40:43], v[168:171], v[188:191], v[40:43]
	v_mfma_f32_16x16x32_bf16 v[28:31], v[144:147], v[198:201], v[28:31]
	v_mfma_f32_16x16x32_bf16 v[24:27], v[168:171], v[198:201], v[24:27]
	v_mfma_f32_16x16x32_bf16 v[12:15], v[144:147], v[206:209], v[12:15]
	v_mfma_f32_16x16x32_bf16 v[8:11], v[168:171], v[206:209], v[8:11]
	v_mfma_f32_16x16x32_bf16 v[60:63], v[164:167], v[180:183], v[60:63]
	v_mfma_f32_16x16x32_bf16 v[56:59], v[172:175], v[180:183], v[56:59]
	v_mfma_f32_16x16x32_bf16 v[44:47], v[164:167], v[194:197], v[44:47]
	v_mfma_f32_16x16x32_bf16 v[40:43], v[172:175], v[194:197], v[40:43]
	v_mfma_f32_16x16x32_bf16 v[28:31], v[164:167], v[202:205], v[28:31]
	v_mfma_f32_16x16x32_bf16 v[24:27], v[172:175], v[202:205], v[24:27]
	v_mfma_f32_16x16x32_bf16 v[12:15], v[164:167], v[210:213], v[12:15]
	v_mfma_f32_16x16x32_bf16 v[8:11], v[172:175], v[210:213], v[8:11]
	s_setprio 0
	s_barrier
	s_add_i32 s4, s5, s53
	s_mov_b32 m0, s4
	s_add_u32 s0, s42, 0x160080
	s_addc_u32 s1, s43, 0
	global_load_lds_dwordx4 v130, s[0:1]
	s_add_i32 m0, s4, 0x2000
	s_nop 0
	global_load_lds_dwordx4 v134, s[0:1]
	s_waitcnt vmcnt(6)
	s_barrier
	s_setprio 1
	v_mfma_f32_16x16x32_bf16 v[52:55], v[214:217], v[176:179], v[52:55]
	v_mfma_f32_16x16x32_bf16 v[48:51], v[222:225], v[176:179], v[48:51]
	v_mfma_f32_16x16x32_bf16 v[36:39], v[214:217], v[188:191], v[36:39]
	v_mfma_f32_16x16x32_bf16 v[32:35], v[222:225], v[188:191], v[32:35]
	v_mfma_f32_16x16x32_bf16 v[20:23], v[214:217], v[198:201], v[20:23]
	v_mfma_f32_16x16x32_bf16 v[16:19], v[222:225], v[198:201], v[16:19]
	v_mfma_f32_16x16x32_bf16 v[4:7], v[214:217], v[206:209], v[4:7]
	v_mfma_f32_16x16x32_bf16 v[0:3], v[222:225], v[206:209], v[0:3]
	v_mfma_f32_16x16x32_bf16 v[52:55], v[218:221], v[180:183], v[52:55]
	v_mfma_f32_16x16x32_bf16 v[48:51], v[226:229], v[180:183], v[48:51]
	v_mfma_f32_16x16x32_bf16 v[36:39], v[218:221], v[194:197], v[36:39]
	v_mfma_f32_16x16x32_bf16 v[32:35], v[226:229], v[194:197], v[32:35]
	v_mfma_f32_16x16x32_bf16 v[20:23], v[218:221], v[202:205], v[20:23]
	v_mfma_f32_16x16x32_bf16 v[16:19], v[226:229], v[202:205], v[16:19]
	v_mfma_f32_16x16x32_bf16 v[4:7], v[218:221], v[210:213], v[4:7]
	v_mfma_f32_16x16x32_bf16 v[0:3], v[226:229], v[210:213], v[0:3]
	s_setprio 0
	s_add_i32 s69, s69, 2
	s_add_u32 s40, s40, 0x100
	s_addc_u32 s41, s41, 0
	s_add_u32 s35, s35, 0x100
	s_addc_u32 s68, s68, 0
	s_cmpk_gt_u32 s69, 0x55
	s_barrier
	s_cbranch_scc0 .LBB0_297

;     DI size_t aoff(const Unit& u, size_t tstep) const { return (size_t)u.pm * tstep; }
;     DI size_t boff(const Unit& u, size_t tstep) const { return (size_t)u.pn * tstep; }
;     DI bool next(int i, Unit& u) const { const long L = (long)i * G + c; if (L >= np) return false; u.pm = pmv; u.pn = (int)(L % nN); u.ks = (int)(L / nN); return true; }
;     DI size_t aoff(const Unit& u, size_t) const { return (size_t)u.ks * kbytes; }
;     DI size_t boff(const Unit& u, size_t tstep) const { return (size_t)u.pn * tstep + (size_t)u.ks * kbytes; }
;     DI bool next(int i, Unit& u) const { Unit t; if (!S.next(i / 3, t)) return false; u.pm = t.pm; u.pn = t.pn; u.ks = i % 3; return true; }
;     DI size_t aoff(const Unit& u, size_t tstep) const { return (u.ks < 2 ? offU : offOA) + (size_t)u.pm * tstep; }
; #define PG8_WAIT_V(n) asm volatile("s_waitcnt vmcnt(" #n ")" ::: "memory")
; template <class Epi, class Sched>
; DI void gemm_phase(LAS unsigned char* lds, const Gemm g, const Sched& S, const Epi& E) {
;     ...
;         const bool has_next = S.next(ui + 1, nxt);
;         const char* nA = has_next ? (const char*)g.A + S.aoff(nxt, tstep) : cA; const char* nB = has_next ? (const char*)g.Bt + S.boff(nxt, tstep) : cB;
;         for (int t = 0; t < nt; t += 2) {
;             if constexpr (Epi::HAS_MID) { if (t == E.mid_t(nt)) { int fr3 = fr, fq3 = fq; asm volatile("" : "+v"(fr3), "+v"(fq3)); E.mid(acc, cur, wr, wc, fr3, fq3); } }
;             const bool last = (t == nt - 2);
;             const char* a1 = cA + (size_t)(t + 1) * kstep;
;             const char* a2 = last ? nA : cA + (size_t)(t + 2) * kstep; const char* b2 = last ? nB : cB + (size_t)(t + 2) * kstep;
;             const char* a3 = a2 + kstep; const char* b3 = b2 + kstep;
;             PG8_LDB(B0, 0, 0); PG8_SCHED; PG8_LDA(At, 0, 0); PG8_STAGE(PG8_SA(1, 1), a1 + hstep, voffA);
;             PG8_WAIT_L(8); PG8_BAR; PG8_WAIT_L(0); PG8_MMA(0, 0, At, B0); PG8_BAR; PG8_SCHED;
;             PG8_LDB(B1, 0, 1); PG8_STAGE(PG8_SB(0, 0), b2, voffB);
;             PG8_BAR; PG8_WAIT_L(0); PG8_MMA(0, 1, At, B1); PG8_BAR;
;             PG8_LDA(At, 0, 1); PG8_STAGE(PG8_SA(0, 0), a2, voffA);
;             PG8_BAR; PG8_WAIT_L(0); PG8_MMA(1, 0, At, B0); PG8_BAR; PG8_SCHED;
;             PG8_STAGE(PG8_SB(0, 1), b2 + hstep, voffB);
;             PG8_WAIT_V(6); PG8_BAR; PG8_MMA(1, 1, At, B1); PG8_BAR;
.LBB0_325:
	s_add_u32 s28, s40, s28
	s_addc_u32 s29, s41, s29
	s_and_b64 s[0:1], s[8:9], exec
	s_cselect_b32 s15, s29, s39
	s_cselect_b32 s17, s28, s38
	s_add_u32 s8, s38, 0x160080
	s_addc_u32 s9, s39, 0
	s_add_u32 s66, s36, 0x100
	v_mov_b32_e32 v0, 0
	s_addc_u32 s67, s37, 0
	s_mov_b32 s68, -2
	ds_read_b128 v[150:153], v141
	ds_read_b128 v[154:157], v141 offset:1024
	ds_read_b128 v[162:165], v141 offset:2048
	ds_read_b128 v[166:169], v141 offset:3072
	s_add_u32 s0, s8, 0xffea0080
	s_addc_u32 s1, s9, -1
	s_cmp_eq_u32 s68, 4
	s_cselect_b32 s39, s15, s1
	s_cselect_b32 s38, s17, s0
	s_cselect_b32 s37, s19, s67
	s_cselect_b32 s36, s18, s66
	s_mov_b32 m0, s58
	ds_read_b128 v[170:173], v142
	ds_read_b128 v[174:177], v142 offset:1024
	ds_read_b128 v[178:181], v142 offset:2048
	ds_read_b128 v[188:191], v142 offset:3072
	ds_read_b128 v[194:197], v142 offset:4096
	ds_read_b128 v[198:201], v142 offset:5120
	ds_read_b128 v[202:205], v142 offset:6144
	global_load_lds_dwordx4 v132, s[8:9]
	s_mov_b32 m0, s59
	ds_read_b128 v[206:209], v142 offset:7168
	global_load_lds_dwordx4 v134, s[8:9]
	s_waitcnt lgkmcnt(8)
	s_barrier
	s_waitcnt lgkmcnt(0)
	s_setprio 1
	v_mfma_f32_16x16x32_bf16 v[124:127], v[150:153], v[170:173], 0
	v_mfma_f32_16x16x32_bf16 v[120:123], v[162:165], v[170:173], 0
	v_mfma_f32_16x16x32_bf16 v[116:119], v[150:153], v[178:181], 0
	v_mfma_f32_16x16x32_bf16 v[112:115], v[162:165], v[178:181], 0
	v_mfma_f32_16x16x32_bf16 v[104:107], v[150:153], v[194:197], 0
	v_mfma_f32_16x16x32_bf16 v[96:99], v[162:165], v[194:197], 0
	v_mfma_f32_16x16x32_bf16 v[88:91], v[150:153], v[202:205], 0
	v_mfma_f32_16x16x32_bf16 v[80:83], v[162:165], v[202:205], 0
	v_mfma_f32_16x16x32_bf16 v[124:127], v[154:157], v[174:177], v[124:127]
	v_mfma_f32_16x16x32_bf16 v[120:123], v[166:169], v[174:177], v[120:123]
	v_mfma_f32_16x16x32_bf16 v[116:119], v[154:157], v[188:191], v[116:119]
	v_mfma_f32_16x16x32_bf16 v[112:115], v[166:169], v[188:191], v[112:115]
	v_mfma_f32_16x16x32_bf16 v[104:107], v[154:157], v[198:201], v[104:107]
	v_mfma_f32_16x16x32_bf16 v[96:99], v[166:169], v[198:201], v[96:99]
	v_mfma_f32_16x16x32_bf16 v[88:91], v[154:157], v[206:209], v[88:91]
	v_mfma_f32_16x16x32_bf16 v[80:83], v[166:169], v[206:209], v[80:83]
	s_setprio 0
	s_barrier
	s_mov_b32 m0, s60
	ds_read_b128 v[210:213], v143
	ds_read_b128 v[214:217], v143 offset:1024
	ds_read_b128 v[218:221], v143 offset:2048
	global_load_lds_dwordx4 v130, s[36:37]
	s_mov_b32 m0, s61
	ds_read_b128 v[222:225], v143 offset:3072
	global_load_lds_dwordx4 v128, s[36:37]
	s_barrier
	s_waitcnt lgkmcnt(0)
	s_setprio 1
	v_mfma_f32_16x16x32_bf16 v[108:111], v[210:213], v[170:173], 0
	v_mfma_f32_16x16x32_bf16 v[100:103], v[218:221], v[170:173], 0
	v_mfma_f32_16x16x32_bf16 v[92:95], v[210:213], v[178:181], 0
	v_mfma_f32_16x16x32_bf16 v[84:87], v[218:221], v[178:181], 0
	v_mfma_f32_16x16x32_bf16 v[76:79], v[210:213], v[194:197], 0
	v_mfma_f32_16x16x32_bf16 v[72:75], v[218:221], v[194:197], 0
	v_mfma_f32_16x16x32_bf16 v[68:71], v[210:213], v[202:205], 0
	v_mfma_f32_16x16x32_bf16 v[64:67], v[218:221], v[202:205], 0
	v_mfma_f32_16x16x32_bf16 v[108:111], v[214:217], v[174:177], v[108:111]
	v_mfma_f32_16x16x32_bf16 v[100:103], v[222:225], v[174:177], v[100:103]
	v_mfma_f32_16x16x32_bf16 v[92:95], v[214:217], v[188:191], v[92:95]
	v_mfma_f32_16x16x32_bf16 v[84:87], v[222:225], v[188:191], v[84:87]
	v_mfma_f32_16x16x32_bf16 v[76:79], v[214:217], v[198:201], v[76:79]
	v_mfma_f32_16x16x32_bf16 v[72:75], v[222:225], v[198:201], v[72:75]
	v_mfma_f32_16x16x32_bf16 v[68:71], v[214:217], v[206:209], v[68:71]
	v_mfma_f32_16x16x32_bf16 v[64:67], v[222:225], v[206:209], v[64:67]
	s_setprio 0
	s_mov_b32 m0, s42
	s_barrier
	ds_read_b128 v[170:173], v142 offset:16384
	ds_read_b128 v[174:177], v142 offset:17408
	ds_read_b128 v[178:181], v142 offset:18432
	ds_read_b128 v[188:191], v142 offset:19456
	ds_read_b128 v[194:197], v142 offset:20480
	ds_read_b128 v[198:201], v142 offset:21504
	ds_read_b128 v[202:205], v142 offset:22528
	global_load_lds_dwordx4 v130, s[38:39]
	s_mov_b32 m0, s43
	ds_read_b128 v[206:209], v142 offset:23552
	global_load_lds_dwordx4 v128, s[38:39]
	s_barrier
	s_waitcnt lgkmcnt(0)
	s_setprio 1
	v_mfma_f32_16x16x32_bf16 v[60:63], v[150:153], v[170:173], 0
	v_mfma_f32_16x16x32_bf16 v[56:59], v[162:165], v[170:173], 0
	v_mfma_f32_16x16x32_bf16 v[52:55], v[150:153], v[178:181], 0
	v_mfma_f32_16x16x32_bf16 v[48:51], v[162:165], v[178:181], 0
	v_mfma_f32_16x16x32_bf16 v[40:43], v[150:153], v[194:197], 0
	v_mfma_f32_16x16x32_bf16 v[32:35], v[162:165], v[194:197], 0
	v_mfma_f32_16x16x32_bf16 v[24:27], v[150:153], v[202:205], 0
	v_mfma_f32_16x16x32_bf16 v[16:19], v[162:165], v[202:205], 0
	v_mfma_f32_16x16x32_bf16 v[60:63], v[154:157], v[174:177], v[60:63]
	v_mfma_f32_16x16x32_bf16 v[56:59], v[166:169], v[174:177], v[56:59]
	v_mfma_f32_16x16x32_bf16 v[52:55], v[154:157], v[188:191], v[52:55]
	v_mfma_f32_16x16x32_bf16 v[48:51], v[166:169], v[188:191], v[48:51]
	v_mfma_f32_16x16x32_bf16 v[40:43], v[154:157], v[198:201], v[40:43]
	v_mfma_f32_16x16x32_bf16 v[32:35], v[166:169], v[198:201], v[32:35]
	v_mfma_f32_16x16x32_bf16 v[24:27], v[154:157], v[206:209], v[24:27]
	v_mfma_f32_16x16x32_bf16 v[16:19], v[166:169], v[206:209], v[16:19]
	s_setprio 0
	s_barrier
	s_add_u32 s0, s36, 0x160000
	s_addc_u32 s1, s37, 0
	s_mov_b32 m0, s62
	s_nop 0
	global_load_lds_dwordx4 v130, s[0:1]
	s_mov_b32 m0, s63
	s_nop 0
	global_load_lds_dwordx4 v128, s[0:1]
	s_waitcnt vmcnt(6)
	s_barrier
; #define PG8_STAGE(bufoff, gbase, voff) do { _Pragma("unroll") for (int _i = 0; _i < 2; ++_i) \
;         __builtin_amdgcn_global_load_lds((const unsigned*)((const char*)(gbase) + (voff)[_i]), (LAS unsigned*)(lds + (bufoff) + ldsw + _i * 8192), 16, 0, 0); } while (0)
; #define PG8_LDA(dst, b, h) do { _Pragma("unroll") for (int m = 0; m < 4; ++m) _Pragma("unroll") for (int k = 0; k < 2; ++k) dst[m][k] = *(const LAS bf16x8*)(lds + PG8_SA(b, h) + aoff + m * 2048 + k * 1024); } while (0)
; #define PG8_LDB(dst, b, h) do { _Pragma("unroll") for (int n = 0; n < 2; ++n) _Pragma("unroll") for (int k = 0; k < 2; ++k) dst[n][k] = *(const LAS bf16x8*)(lds + PG8_SB(b, h) + boff + n * 2048 + k * 1024); } while (0)
; #define PG8_MMA(ai, bj, At, Bt) do { __builtin_amdgcn_s_setprio(1); _Pragma("unroll") for (int m = 0; m < 4; ++m) _Pragma("unroll") for (int n = 0; n < 2; ++n) _Pragma("unroll") for (int k = 0; k < 2; ++k) \
;         acc[ai][bj][m][n] = __builtin_amdgcn_mfma_f32_16x16x32_bf16(Bt[n][k], At[m][k], acc[ai][bj][m][n], 0, 0, 0); __builtin_amdgcn_s_setprio(0); } while (0)
; #define PG8_WAIT_V(n) asm volatile("s_waitcnt vmcnt(" #n ")" ::: "memory")
; #define PG8_WAIT_L(n) asm volatile("s_waitcnt lgkmcnt(" #n ")" ::: "memory")
; #define PG8_BAR __builtin_amdgcn_s_barrier()
; #define PG8_SCHED __builtin_amdgcn_sched_barrier(0)
; template <class Epi, class Sched>
; DI void gemm_phase(LAS unsigned char* lds, const Gemm g, const Sched& S, const Epi& E) {
;     ...
;             PG8_WAIT_V(6); PG8_BAR; PG8_MMA(1, 1, At, B1); PG8_BAR;
;             PG8_LDB(B0, 1, 0); PG8_SCHED; PG8_LDA(At, 1, 0); PG8_STAGE(PG8_SA(0, 1), a2 + hstep, voffA);
;             PG8_WAIT_L(8); PG8_BAR; PG8_WAIT_L(0); PG8_MMA(0, 0, At, B0); PG8_BAR; PG8_SCHED;
;             PG8_LDB(B1, 1, 1); PG8_STAGE(PG8_SB(1, 0), b3, voffB);
;             PG8_BAR; PG8_WAIT_L(0); PG8_MMA(0, 1, At, B1); PG8_BAR;
;             PG8_LDA(At, 1, 1); PG8_STAGE(PG8_SA(1, 0), a3, voffA);
;             PG8_BAR; PG8_WAIT_L(0); PG8_MMA(1, 0, At, B0); PG8_BAR; PG8_SCHED;
	s_setprio 1
	v_mfma_f32_16x16x32_bf16 v[44:47], v[210:213], v[170:173], 0
	v_mfma_f32_16x16x32_bf16 v[36:39], v[218:221], v[170:173], 0
	v_mfma_f32_16x16x32_bf16 v[28:31], v[210:213], v[178:181], 0
	v_mfma_f32_16x16x32_bf16 v[20:23], v[218:221], v[178:181], 0
	v_mfma_f32_16x16x32_bf16 v[12:15], v[210:213], v[194:197], 0
	v_mfma_f32_16x16x32_bf16 v[8:11], v[218:221], v[194:197], 0
	v_mfma_f32_16x16x32_bf16 v[4:7], v[210:213], v[202:205], 0
	v_mfma_f32_16x16x32_bf16 v[0:3], v[218:221], v[202:205], 0
	v_mfma_f32_16x16x32_bf16 v[44:47], v[214:217], v[174:177], v[44:47]
	v_mfma_f32_16x16x32_bf16 v[36:39], v[222:225], v[174:177], v[36:39]
	v_mfma_f32_16x16x32_bf16 v[28:31], v[214:217], v[188:191], v[28:31]
	v_mfma_f32_16x16x32_bf16 v[20:23], v[222:225], v[188:191], v[20:23]
	v_mfma_f32_16x16x32_bf16 v[12:15], v[214:217], v[198:201], v[12:15]
	v_mfma_f32_16x16x32_bf16 v[8:11], v[222:225], v[198:201], v[8:11]
	v_mfma_f32_16x16x32_bf16 v[4:7], v[214:217], v[206:209], v[4:7]
	v_mfma_f32_16x16x32_bf16 v[0:3], v[222:225], v[206:209], v[0:3]
	s_setprio 0
	s_barrier
	ds_read_b128 v[150:153], v144
	ds_read_b128 v[154:157], v144 offset:1024
	ds_read_b128 v[162:165], v144 offset:2048
	ds_read_b128 v[166:169], v144 offset:3072
	s_add_u32 s0, s38, 0x160000
	s_addc_u32 s1, s39, 0
	s_mov_b32 m0, s44
	ds_read_b128 v[170:173], v142 offset:32768
	ds_read_b128 v[174:177], v142 offset:33792
	ds_read_b128 v[178:181], v142 offset:34816
	ds_read_b128 v[188:191], v142 offset:35840
	ds_read_b128 v[194:197], v142 offset:36864
	ds_read_b128 v[198:201], v142 offset:37888
	ds_read_b128 v[202:205], v142 offset:38912
	global_load_lds_dwordx4 v130, s[0:1]
	s_mov_b32 m0, s45
	ds_read_b128 v[206:209], v142 offset:39936
	global_load_lds_dwordx4 v128, s[0:1]
	s_waitcnt lgkmcnt(8)
	s_barrier
	s_waitcnt lgkmcnt(0)
	s_setprio 1
	v_mfma_f32_16x16x32_bf16 v[124:127], v[150:153], v[170:173], v[124:127]
	v_mfma_f32_16x16x32_bf16 v[120:123], v[162:165], v[170:173], v[120:123]
	v_mfma_f32_16x16x32_bf16 v[116:119], v[150:153], v[178:181], v[116:119]
	v_mfma_f32_16x16x32_bf16 v[112:115], v[162:165], v[178:181], v[112:115]
	v_mfma_f32_16x16x32_bf16 v[104:107], v[150:153], v[194:197], v[104:107]
	v_mfma_f32_16x16x32_bf16 v[96:99], v[162:165], v[194:197], v[96:99]
	v_mfma_f32_16x16x32_bf16 v[88:91], v[150:153], v[202:205], v[88:91]
	v_mfma_f32_16x16x32_bf16 v[80:83], v[162:165], v[202:205], v[80:83]
	v_mfma_f32_16x16x32_bf16 v[124:127], v[154:157], v[174:177], v[124:127]
	v_mfma_f32_16x16x32_bf16 v[120:123], v[166:169], v[174:177], v[120:123]
	v_mfma_f32_16x16x32_bf16 v[116:119], v[154:157], v[188:191], v[116:119]
	v_mfma_f32_16x16x32_bf16 v[112:115], v[166:169], v[188:191], v[112:115]
	v_mfma_f32_16x16x32_bf16 v[104:107], v[154:157], v[198:201], v[104:107]
	v_mfma_f32_16x16x32_bf16 v[96:99], v[166:169], v[198:201], v[96:99]
	v_mfma_f32_16x16x32_bf16 v[88:91], v[154:157], v[206:209], v[88:91]
	v_mfma_f32_16x16x32_bf16 v[80:83], v[166:169], v[206:209], v[80:83]
	s_setprio 0
	s_barrier
	s_add_i32 s4, 0, 0x1c000
	s_add_i32 s0, s64, s35
	v_add_u32_e32 v145, s4, v140
	s_add_i32 m0, s0, 0xffffff80
	ds_read_b128 v[210:213], v145
	ds_read_b128 v[214:217], v145 offset:1024
	ds_read_b128 v[218:221], v145 offset:2048
	global_load_lds_dwordx4 v130, s[36:37] offset:128
	s_add_i32 m0, s0, 0x1f80
	ds_read_b128 v[222:225], v145 offset:3072
	global_load_lds_dwordx4 v128, s[36:37] offset:128
	s_barrier
	s_waitcnt lgkmcnt(0)
	s_setprio 1
	v_mfma_f32_16x16x32_bf16 v[108:111], v[210:213], v[170:173], v[108:111]
	v_mfma_f32_16x16x32_bf16 v[100:103], v[218:221], v[170:173], v[100:103]
	v_mfma_f32_16x16x32_bf16 v[92:95], v[210:213], v[178:181], v[92:95]
	v_mfma_f32_16x16x32_bf16 v[84:87], v[218:221], v[178:181], v[84:87]
	v_mfma_f32_16x16x32_bf16 v[76:79], v[210:213], v[194:197], v[76:79]
	v_mfma_f32_16x16x32_bf16 v[72:75], v[218:221], v[194:197], v[72:75]
	v_mfma_f32_16x16x32_bf16 v[68:71], v[210:213], v[202:205], v[68:71]
	v_mfma_f32_16x16x32_bf16 v[64:67], v[218:221], v[202:205], v[64:67]
	v_mfma_f32_16x16x32_bf16 v[108:111], v[214:217], v[174:177], v[108:111]
	v_mfma_f32_16x16x32_bf16 v[100:103], v[222:225], v[174:177], v[100:103]
	v_mfma_f32_16x16x32_bf16 v[92:95], v[214:217], v[188:191], v[92:95]
	v_mfma_f32_16x16x32_bf16 v[84:87], v[222:225], v[188:191], v[84:87]
	v_mfma_f32_16x16x32_bf16 v[76:79], v[214:217], v[198:201], v[76:79]
	v_mfma_f32_16x16x32_bf16 v[72:75], v[222:225], v[198:201], v[72:75]
	v_mfma_f32_16x16x32_bf16 v[68:71], v[214:217], v[206:209], v[68:71]
	v_mfma_f32_16x16x32_bf16 v[64:67], v[222:225], v[206:209], v[64:67]
	s_setprio 0
	s_add_i32 m0, s56, 0xffffff80
	s_barrier
	ds_read_b128 v[170:173], v142 offset:49152
	ds_read_b128 v[174:177], v142 offset:50176
	ds_read_b128 v[178:181], v142 offset:51200
	ds_read_b128 v[188:191], v142 offset:52224
	ds_read_b128 v[194:197], v142 offset:53248
	ds_read_b128 v[198:201], v142 offset:54272
	ds_read_b128 v[202:205], v142 offset:55296
	global_load_lds_dwordx4 v130, s[38:39] offset:128
	s_add_i32 m0, s57, 0xffffff80
	ds_read_b128 v[206:209], v142 offset:56320
	global_load_lds_dwordx4 v128, s[38:39] offset:128
	s_barrier
; #define PG8_STAGE(bufoff, gbase, voff) do { _Pragma("unroll") for (int _i = 0; _i < 2; ++_i) \
;         __builtin_amdgcn_global_load_lds((const unsigned*)((const char*)(gbase) + (voff)[_i]), (LAS unsigned*)(lds + (bufoff) + ldsw + _i * 8192), 16, 0, 0); } while (0)
; #define PG8_LDA(dst, b, h) do { _Pragma("unroll") for (int m = 0; m < 4; ++m) _Pragma("unroll") for (int k = 0; k < 2; ++k) dst[m][k] = *(const LAS bf16x8*)(lds + PG8_SA(b, h) + aoff + m * 2048 + k * 1024); } while (0)
; #define PG8_LDB(dst, b, h) do { _Pragma("unroll") for (int n = 0; n < 2; ++n) _Pragma("unroll") for (int k = 0; k < 2; ++k) dst[n][k] = *(const LAS bf16x8*)(lds + PG8_SB(b, h) + boff + n * 2048 + k * 1024); } while (0)
; #define PG8_MMA(ai, bj, At, Bt) do { __builtin_amdgcn_s_setprio(1); _Pragma("unroll") for (int m = 0; m < 4; ++m) _Pragma("unroll") for (int n = 0; n < 2; ++n) _Pragma("unroll") for (int k = 0; k < 2; ++k) \
;         acc[ai][bj][m][n] = __builtin_amdgcn_mfma_f32_16x16x32_bf16(Bt[n][k], At[m][k], acc[ai][bj][m][n], 0, 0, 0); __builtin_amdgcn_s_setprio(0); } while (0)
; #define PG8_WAIT_V(n) asm volatile("s_waitcnt vmcnt(" #n ")" ::: "memory")
; #define PG8_WAIT_L(n) asm volatile("s_waitcnt lgkmcnt(" #n ")" ::: "memory")
; #define PG8_BAR __builtin_amdgcn_s_barrier()
; #define PG8_SCHED __builtin_amdgcn_sched_barrier(0)
; template <class Epi, class Sched>
; DI void gemm_phase(LAS unsigned char* lds, const Gemm g, const Sched& S, const Epi& E) {
;     ...
;             PG8_LDB(B0, 0, 0); PG8_SCHED; PG8_LDA(At, 0, 0); PG8_STAGE(PG8_SA(1, 1), a1 + hstep, voffA);
;             PG8_WAIT_L(8); PG8_BAR; PG8_WAIT_L(0); PG8_MMA(0, 0, At, B0); PG8_BAR; PG8_SCHED;
;             PG8_LDB(B1, 0, 1); PG8_STAGE(PG8_SB(0, 0), b2, voffB);
;             PG8_BAR; PG8_WAIT_L(0); PG8_MMA(0, 1, At, B1); PG8_BAR;
;     ...
;             PG8_BAR; PG8_WAIT_L(0); PG8_MMA(1, 0, At, B0); PG8_BAR; PG8_SCHED;
;             PG8_STAGE(PG8_SB(1, 1), b3 + hstep, voffB);
;             PG8_WAIT_V(6); PG8_BAR; PG8_MMA(1, 1, At, B1); PG8_BAR;
	s_waitcnt lgkmcnt(0)
	s_setprio 1
	v_mfma_f32_16x16x32_bf16 v[60:63], v[150:153], v[170:173], v[60:63]
	v_mfma_f32_16x16x32_bf16 v[56:59], v[162:165], v[170:173], v[56:59]
	v_mfma_f32_16x16x32_bf16 v[52:55], v[150:153], v[178:181], v[52:55]
	v_mfma_f32_16x16x32_bf16 v[48:51], v[162:165], v[178:181], v[48:51]
	v_mfma_f32_16x16x32_bf16 v[40:43], v[150:153], v[194:197], v[40:43]
	v_mfma_f32_16x16x32_bf16 v[32:35], v[162:165], v[194:197], v[32:35]
	v_mfma_f32_16x16x32_bf16 v[24:27], v[150:153], v[202:205], v[24:27]
	v_mfma_f32_16x16x32_bf16 v[16:19], v[162:165], v[202:205], v[16:19]
	v_mfma_f32_16x16x32_bf16 v[60:63], v[154:157], v[174:177], v[60:63]
	v_mfma_f32_16x16x32_bf16 v[56:59], v[166:169], v[174:177], v[56:59]
	v_mfma_f32_16x16x32_bf16 v[52:55], v[154:157], v[188:191], v[52:55]
	v_mfma_f32_16x16x32_bf16 v[48:51], v[166:169], v[188:191], v[48:51]
	v_mfma_f32_16x16x32_bf16 v[40:43], v[154:157], v[198:201], v[40:43]
	v_mfma_f32_16x16x32_bf16 v[32:35], v[166:169], v[198:201], v[32:35]
	v_mfma_f32_16x16x32_bf16 v[24:27], v[154:157], v[206:209], v[24:27]
	v_mfma_f32_16x16x32_bf16 v[16:19], v[166:169], v[206:209], v[16:19]
	s_setprio 0
	s_barrier
	s_add_i32 s4, s4, s35
	s_mov_b32 m0, s4
	s_add_u32 s0, s36, 0x160080
	s_addc_u32 s1, s37, 0
	global_load_lds_dwordx4 v130, s[0:1]
	s_add_i32 m0, s4, 0x2000
	s_nop 0
	global_load_lds_dwordx4 v128, s[0:1]
	s_waitcnt vmcnt(6)
	s_barrier
	s_setprio 1
	v_mfma_f32_16x16x32_bf16 v[44:47], v[210:213], v[170:173], v[44:47]
	v_mfma_f32_16x16x32_bf16 v[36:39], v[218:221], v[170:173], v[36:39]
	v_mfma_f32_16x16x32_bf16 v[28:31], v[210:213], v[178:181], v[28:31]
	v_mfma_f32_16x16x32_bf16 v[20:23], v[218:221], v[178:181], v[20:23]
	v_mfma_f32_16x16x32_bf16 v[12:15], v[210:213], v[194:197], v[12:15]
	v_mfma_f32_16x16x32_bf16 v[8:11], v[218:221], v[194:197], v[8:11]
	v_mfma_f32_16x16x32_bf16 v[4:7], v[210:213], v[202:205], v[4:7]
	v_mfma_f32_16x16x32_bf16 v[0:3], v[218:221], v[202:205], v[0:3]
	v_mfma_f32_16x16x32_bf16 v[44:47], v[214:217], v[174:177], v[44:47]
	v_mfma_f32_16x16x32_bf16 v[36:39], v[222:225], v[174:177], v[36:39]
	v_mfma_f32_16x16x32_bf16 v[28:31], v[214:217], v[188:191], v[28:31]
	v_mfma_f32_16x16x32_bf16 v[20:23], v[222:225], v[188:191], v[20:23]
	v_mfma_f32_16x16x32_bf16 v[12:15], v[214:217], v[198:201], v[12:15]
	v_mfma_f32_16x16x32_bf16 v[8:11], v[222:225], v[198:201], v[8:11]
	v_mfma_f32_16x16x32_bf16 v[4:7], v[214:217], v[206:209], v[4:7]
	v_mfma_f32_16x16x32_bf16 v[0:3], v[222:225], v[206:209], v[0:3]
	s_setprio 0
	s_add_i32 s68, s68, 2
	s_add_u32 s8, s8, 0x100
	s_addc_u32 s9, s9, 0
	s_add_u32 s66, s66, 0x100
	s_addc_u32 s67, s67, 0
	s_cmp_gt_u32 s68, 5
	s_barrier
	s_cbranch_scc0 .LBB0_326
	s_branch .Lpeel_done_326
.LBB0_326:
	ds_read_b128 v[150:153], v141
	ds_read_b128 v[154:157], v141 offset:1024
	ds_read_b128 v[162:165], v141 offset:2048
	ds_read_b128 v[166:169], v141 offset:3072
	s_add_u32 s0, s8, 0xffea0080
	s_addc_u32 s1, s9, -1
	s_cmp_eq_u32 s68, 4
	s_cselect_b32 s39, s15, s1
	s_cselect_b32 s38, s17, s0
	s_cselect_b32 s37, s19, s67
	s_cselect_b32 s36, s18, s66
	s_mov_b32 m0, s58
	ds_read_b128 v[170:173], v142
	ds_read_b128 v[174:177], v142 offset:1024
	ds_read_b128 v[178:181], v142 offset:2048
	ds_read_b128 v[188:191], v142 offset:3072
	ds_read_b128 v[194:197], v142 offset:4096
	ds_read_b128 v[198:201], v142 offset:5120
	ds_read_b128 v[202:205], v142 offset:6144
	global_load_lds_dwordx4 v132, s[8:9]
	s_mov_b32 m0, s59
	ds_read_b128 v[206:209], v142 offset:7168
	global_load_lds_dwordx4 v134, s[8:9]
	s_waitcnt lgkmcnt(8)
	s_barrier
	s_waitcnt lgkmcnt(0)
	s_setprio 1
	v_mfma_f32_16x16x32_bf16 v[124:127], v[150:153], v[170:173], v[124:127]
	v_mfma_f32_16x16x32_bf16 v[120:123], v[162:165], v[170:173], v[120:123]
	v_mfma_f32_16x16x32_bf16 v[116:119], v[150:153], v[178:181], v[116:119]
	v_mfma_f32_16x16x32_bf16 v[112:115], v[162:165], v[178:181], v[112:115]
	v_mfma_f32_16x16x32_bf16 v[104:107], v[150:153], v[194:197], v[104:107]
	v_mfma_f32_16x16x32_bf16 v[96:99], v[162:165], v[194:197], v[96:99]
	v_mfma_f32_16x16x32_bf16 v[88:91], v[150:153], v[202:205], v[88:91]
	v_mfma_f32_16x16x32_bf16 v[80:83], v[162:165], v[202:205], v[80:83]
	v_mfma_f32_16x16x32_bf16 v[124:127], v[154:157], v[174:177], v[124:127]
	v_mfma_f32_16x16x32_bf16 v[120:123], v[166:169], v[174:177], v[120:123]
	v_mfma_f32_16x16x32_bf16 v[116:119], v[154:157], v[188:191], v[116:119]
	v_mfma_f32_16x16x32_bf16 v[112:115], v[166:169], v[188:191], v[112:115]
	v_mfma_f32_16x16x32_bf16 v[104:107], v[154:157], v[198:201], v[104:107]
	v_mfma_f32_16x16x32_bf16 v[96:99], v[166:169], v[198:201], v[96:99]
	v_mfma_f32_16x16x32_bf16 v[88:91], v[154:157], v[206:209], v[88:91]
	v_mfma_f32_16x16x32_bf16 v[80:83], v[166:169], v[206:209], v[80:83]
	s_setprio 0
	s_barrier
	s_mov_b32 m0, s60
	ds_read_b128 v[210:213], v143
	ds_read_b128 v[214:217], v143 offset:1024
	ds_read_b128 v[218:221], v143 offset:2048
	global_load_lds_dwordx4 v130, s[36:37]
	s_mov_b32 m0, s61
	ds_read_b128 v[222:225], v143 offset:3072
	global_load_lds_dwordx4 v128, s[36:37]
	s_barrier
; #define PG8_STAGE(bufoff, gbase, voff) do { _Pragma("unroll") for (int _i = 0; _i < 2; ++_i) \
;         __builtin_amdgcn_global_load_lds((const unsigned*)((const char*)(gbase) + (voff)[_i]), (LAS unsigned*)(lds + (bufoff) + ldsw + _i * 8192), 16, 0, 0); } while (0)
; #define PG8_LDA(dst, b, h) do { _Pragma("unroll") for (int m = 0; m < 4; ++m) _Pragma("unroll") for (int k = 0; k < 2; ++k) dst[m][k] = *(const LAS bf16x8*)(lds + PG8_SA(b, h) + aoff + m * 2048 + k * 1024); } while (0)
; #define PG8_LDB(dst, b, h) do { _Pragma("unroll") for (int n = 0; n < 2; ++n) _Pragma("unroll") for (int k = 0; k < 2; ++k) dst[n][k] = *(const LAS bf16x8*)(lds + PG8_SB(b, h) + boff + n * 2048 + k * 1024); } while (0)
; #define PG8_MMA(ai, bj, At, Bt) do { __builtin_amdgcn_s_setprio(1); _Pragma("unroll") for (int m = 0; m < 4; ++m) _Pragma("unroll") for (int n = 0; n < 2; ++n) _Pragma("unroll") for (int k = 0; k < 2; ++k) \
;         acc[ai][bj][m][n] = __builtin_amdgcn_mfma_f32_16x16x32_bf16(Bt[n][k], At[m][k], acc[ai][bj][m][n], 0, 0, 0); __builtin_amdgcn_s_setprio(0); } while (0)
; #define PG8_WAIT_V(n) asm volatile("s_waitcnt vmcnt(" #n ")" ::: "memory")
; #define PG8_WAIT_L(n) asm volatile("s_waitcnt lgkmcnt(" #n ")" ::: "memory")
; #define PG8_BAR __builtin_amdgcn_s_barrier()
; #define PG8_SCHED __builtin_amdgcn_sched_barrier(0)
; template <class Epi, class Sched>
; DI void gemm_phase(LAS unsigned char* lds, const Gemm g, const Sched& S, const Epi& E) {
;     ...
;             PG8_BAR; PG8_WAIT_L(0); PG8_MMA(0, 1, At, B1); PG8_BAR;
;             PG8_LDA(At, 0, 1); PG8_STAGE(PG8_SA(0, 0), a2, voffA);
;             PG8_BAR; PG8_WAIT_L(0); PG8_MMA(1, 0, At, B0); PG8_BAR; PG8_SCHED;
;             PG8_STAGE(PG8_SB(0, 1), b2 + hstep, voffB);
;             PG8_WAIT_V(6); PG8_BAR; PG8_MMA(1, 1, At, B1); PG8_BAR;
;             PG8_LDB(B0, 1, 0); PG8_SCHED; PG8_LDA(At, 1, 0); PG8_STAGE(PG8_SA(0, 1), a2 + hstep, voffA);
;             PG8_WAIT_L(8); PG8_BAR; PG8_WAIT_L(0); PG8_MMA(0, 0, At, B0); PG8_BAR; PG8_SCHED;
;             PG8_LDB(B1, 1, 1); PG8_STAGE(PG8_SB(1, 0), b3, voffB);
	s_waitcnt lgkmcnt(0)
	s_setprio 1
	v_mfma_f32_16x16x32_bf16 v[108:111], v[210:213], v[170:173], v[108:111]
	v_mfma_f32_16x16x32_bf16 v[100:103], v[218:221], v[170:173], v[100:103]
	v_mfma_f32_16x16x32_bf16 v[92:95], v[210:213], v[178:181], v[92:95]
	v_mfma_f32_16x16x32_bf16 v[84:87], v[218:221], v[178:181], v[84:87]
	v_mfma_f32_16x16x32_bf16 v[76:79], v[210:213], v[194:197], v[76:79]
	v_mfma_f32_16x16x32_bf16 v[72:75], v[218:221], v[194:197], v[72:75]
	v_mfma_f32_16x16x32_bf16 v[68:71], v[210:213], v[202:205], v[68:71]
	v_mfma_f32_16x16x32_bf16 v[64:67], v[218:221], v[202:205], v[64:67]
	v_mfma_f32_16x16x32_bf16 v[108:111], v[214:217], v[174:177], v[108:111]
	v_mfma_f32_16x16x32_bf16 v[100:103], v[222:225], v[174:177], v[100:103]
	v_mfma_f32_16x16x32_bf16 v[92:95], v[214:217], v[188:191], v[92:95]
	v_mfma_f32_16x16x32_bf16 v[84:87], v[222:225], v[188:191], v[84:87]
	v_mfma_f32_16x16x32_bf16 v[76:79], v[214:217], v[198:201], v[76:79]
	v_mfma_f32_16x16x32_bf16 v[72:75], v[222:225], v[198:201], v[72:75]
	v_mfma_f32_16x16x32_bf16 v[68:71], v[214:217], v[206:209], v[68:71]
	v_mfma_f32_16x16x32_bf16 v[64:67], v[222:225], v[206:209], v[64:67]
	s_setprio 0
	s_mov_b32 m0, s42
	s_barrier
	ds_read_b128 v[170:173], v142 offset:16384
	ds_read_b128 v[174:177], v142 offset:17408
	ds_read_b128 v[178:181], v142 offset:18432
	ds_read_b128 v[188:191], v142 offset:19456
	ds_read_b128 v[194:197], v142 offset:20480
	ds_read_b128 v[198:201], v142 offset:21504
	ds_read_b128 v[202:205], v142 offset:22528
	global_load_lds_dwordx4 v130, s[38:39]
	s_mov_b32 m0, s43
	ds_read_b128 v[206:209], v142 offset:23552
	global_load_lds_dwordx4 v128, s[38:39]
	s_barrier
	s_waitcnt lgkmcnt(0)
	s_setprio 1
	v_mfma_f32_16x16x32_bf16 v[60:63], v[150:153], v[170:173], v[60:63]
	v_mfma_f32_16x16x32_bf16 v[56:59], v[162:165], v[170:173], v[56:59]
	v_mfma_f32_16x16x32_bf16 v[52:55], v[150:153], v[178:181], v[52:55]
	v_mfma_f32_16x16x32_bf16 v[48:51], v[162:165], v[178:181], v[48:51]
	v_mfma_f32_16x16x32_bf16 v[40:43], v[150:153], v[194:197], v[40:43]
	v_mfma_f32_16x16x32_bf16 v[32:35], v[162:165], v[194:197], v[32:35]
	v_mfma_f32_16x16x32_bf16 v[24:27], v[150:153], v[202:205], v[24:27]
	v_mfma_f32_16x16x32_bf16 v[16:19], v[162:165], v[202:205], v[16:19]
	v_mfma_f32_16x16x32_bf16 v[60:63], v[154:157], v[174:177], v[60:63]
	v_mfma_f32_16x16x32_bf16 v[56:59], v[166:169], v[174:177], v[56:59]
	v_mfma_f32_16x16x32_bf16 v[52:55], v[154:157], v[188:191], v[52:55]
	v_mfma_f32_16x16x32_bf16 v[48:51], v[166:169], v[188:191], v[48:51]
	v_mfma_f32_16x16x32_bf16 v[40:43], v[154:157], v[198:201], v[40:43]
	v_mfma_f32_16x16x32_bf16 v[32:35], v[166:169], v[198:201], v[32:35]
	v_mfma_f32_16x16x32_bf16 v[24:27], v[154:157], v[206:209], v[24:27]
	v_mfma_f32_16x16x32_bf16 v[16:19], v[166:169], v[206:209], v[16:19]
	s_setprio 0
	s_barrier
	s_add_u32 s0, s36, 0x160000
	s_addc_u32 s1, s37, 0
	s_mov_b32 m0, s62
	s_nop 0
	global_load_lds_dwordx4 v130, s[0:1]
	s_mov_b32 m0, s63
	s_nop 0
	global_load_lds_dwordx4 v128, s[0:1]
	s_waitcnt vmcnt(6)
	s_barrier
	s_setprio 1
	v_mfma_f32_16x16x32_bf16 v[44:47], v[210:213], v[170:173], v[44:47]
	v_mfma_f32_16x16x32_bf16 v[36:39], v[218:221], v[170:173], v[36:39]
	v_mfma_f32_16x16x32_bf16 v[28:31], v[210:213], v[178:181], v[28:31]
	v_mfma_f32_16x16x32_bf16 v[20:23], v[218:221], v[178:181], v[20:23]
	v_mfma_f32_16x16x32_bf16 v[12:15], v[210:213], v[194:197], v[12:15]
	v_mfma_f32_16x16x32_bf16 v[8:11], v[218:221], v[194:197], v[8:11]
	v_mfma_f32_16x16x32_bf16 v[4:7], v[210:213], v[202:205], v[4:7]
	v_mfma_f32_16x16x32_bf16 v[0:3], v[218:221], v[202:205], v[0:3]
	v_mfma_f32_16x16x32_bf16 v[44:47], v[214:217], v[174:177], v[44:47]
	v_mfma_f32_16x16x32_bf16 v[36:39], v[222:225], v[174:177], v[36:39]
	v_mfma_f32_16x16x32_bf16 v[28:31], v[214:217], v[188:191], v[28:31]
	v_mfma_f32_16x16x32_bf16 v[20:23], v[222:225], v[188:191], v[20:23]
	v_mfma_f32_16x16x32_bf16 v[12:15], v[214:217], v[198:201], v[12:15]
	v_mfma_f32_16x16x32_bf16 v[8:11], v[222:225], v[198:201], v[8:11]
	v_mfma_f32_16x16x32_bf16 v[4:7], v[214:217], v[206:209], v[4:7]
	v_mfma_f32_16x16x32_bf16 v[0:3], v[222:225], v[206:209], v[0:3]
	s_setprio 0
	s_barrier
	ds_read_b128 v[150:153], v144
	ds_read_b128 v[154:157], v144 offset:1024
	ds_read_b128 v[162:165], v144 offset:2048
	ds_read_b128 v[166:169], v144 offset:3072
	s_add_u32 s0, s38, 0x160000
	s_addc_u32 s1, s39, 0
	s_mov_b32 m0, s44
	ds_read_b128 v[170:173], v142 offset:32768
	ds_read_b128 v[174:177], v142 offset:33792
	ds_read_b128 v[178:181], v142 offset:34816
	ds_read_b128 v[188:191], v142 offset:35840
	ds_read_b128 v[194:197], v142 offset:36864
	ds_read_b128 v[198:201], v142 offset:37888
	ds_read_b128 v[202:205], v142 offset:38912
	global_load_lds_dwordx4 v130, s[0:1]
	s_mov_b32 m0, s45
	ds_read_b128 v[206:209], v142 offset:39936
	global_load_lds_dwordx4 v128, s[0:1]
	s_waitcnt lgkmcnt(8)
	s_barrier
; #define PG8_STAGE(bufoff, gbase, voff) do { _Pragma("unroll") for (int _i = 0; _i < 2; ++_i) \
;         __builtin_amdgcn_global_load_lds((const unsigned*)((const char*)(gbase) + (voff)[_i]), (LAS unsigned*)(lds + (bufoff) + ldsw + _i * 8192), 16, 0, 0); } while (0)
; #define PG8_LDA(dst, b, h) do { _Pragma("unroll") for (int m = 0; m < 4; ++m) _Pragma("unroll") for (int k = 0; k < 2; ++k) dst[m][k] = *(const LAS bf16x8*)(lds + PG8_SA(b, h) + aoff + m * 2048 + k * 1024); } while (0)
; #define PG8_LDB(dst, b, h) do { _Pragma("unroll") for (int n = 0; n < 2; ++n) _Pragma("unroll") for (int k = 0; k < 2; ++k) dst[n][k] = *(const LAS bf16x8*)(lds + PG8_SB(b, h) + boff + n * 2048 + k * 1024); } while (0)
; #define PG8_MMA(ai, bj, At, Bt) do { __builtin_amdgcn_s_setprio(1); _Pragma("unroll") for (int m = 0; m < 4; ++m) _Pragma("unroll") for (int n = 0; n < 2; ++n) _Pragma("unroll") for (int k = 0; k < 2; ++k) \
;         acc[ai][bj][m][n] = __builtin_amdgcn_mfma_f32_16x16x32_bf16(Bt[n][k], At[m][k], acc[ai][bj][m][n], 0, 0, 0); __builtin_amdgcn_s_setprio(0); } while (0)
; #define PG8_WAIT_V(n) asm volatile("s_waitcnt vmcnt(" #n ")" ::: "memory")
; #define PG8_WAIT_L(n) asm volatile("s_waitcnt lgkmcnt(" #n ")" ::: "memory")
; #define PG8_BAR __builtin_amdgcn_s_barrier()
; #define PG8_SCHED __builtin_amdgcn_sched_barrier(0)
; template <class Epi, class Sched>
; DI void gemm_phase(LAS unsigned char* lds, const Gemm g, const Sched& S, const Epi& E) {
;     ...
;             PG8_LDB(B1, 1, 1); PG8_STAGE(PG8_SB(1, 0), b3, voffB);
;             PG8_BAR; PG8_WAIT_L(0); PG8_MMA(0, 1, At, B1); PG8_BAR;
;             PG8_LDA(At, 1, 1); PG8_STAGE(PG8_SA(1, 0), a3, voffA);
;             PG8_BAR; PG8_WAIT_L(0); PG8_MMA(1, 0, At, B0); PG8_BAR; PG8_SCHED;
;             PG8_STAGE(PG8_SB(1, 1), b3 + hstep, voffB);
;             PG8_WAIT_V(6); PG8_BAR; PG8_MMA(1, 1, At, B1); PG8_BAR;
	s_waitcnt lgkmcnt(0)
	s_setprio 1
	v_mfma_f32_16x16x32_bf16 v[124:127], v[150:153], v[170:173], v[124:127]
	v_mfma_f32_16x16x32_bf16 v[120:123], v[162:165], v[170:173], v[120:123]
	v_mfma_f32_16x16x32_bf16 v[116:119], v[150:153], v[178:181], v[116:119]
	v_mfma_f32_16x16x32_bf16 v[112:115], v[162:165], v[178:181], v[112:115]
	v_mfma_f32_16x16x32_bf16 v[104:107], v[150:153], v[194:197], v[104:107]
	v_mfma_f32_16x16x32_bf16 v[96:99], v[162:165], v[194:197], v[96:99]
	v_mfma_f32_16x16x32_bf16 v[88:91], v[150:153], v[202:205], v[88:91]
	v_mfma_f32_16x16x32_bf16 v[80:83], v[162:165], v[202:205], v[80:83]
	v_mfma_f32_16x16x32_bf16 v[124:127], v[154:157], v[174:177], v[124:127]
	v_mfma_f32_16x16x32_bf16 v[120:123], v[166:169], v[174:177], v[120:123]
	v_mfma_f32_16x16x32_bf16 v[116:119], v[154:157], v[188:191], v[116:119]
	v_mfma_f32_16x16x32_bf16 v[112:115], v[166:169], v[188:191], v[112:115]
	v_mfma_f32_16x16x32_bf16 v[104:107], v[154:157], v[198:201], v[104:107]
	v_mfma_f32_16x16x32_bf16 v[96:99], v[166:169], v[198:201], v[96:99]
	v_mfma_f32_16x16x32_bf16 v[88:91], v[154:157], v[206:209], v[88:91]
	v_mfma_f32_16x16x32_bf16 v[80:83], v[166:169], v[206:209], v[80:83]
	s_setprio 0
	s_barrier
	s_add_i32 s4, 0, 0x1c000
	s_add_i32 s0, s64, s35
	v_add_u32_e32 v145, s4, v140
	s_add_i32 m0, s0, 0xffffff80
	ds_read_b128 v[210:213], v145
	ds_read_b128 v[214:217], v145 offset:1024
	ds_read_b128 v[218:221], v145 offset:2048
	global_load_lds_dwordx4 v130, s[36:37] offset:128
	s_add_i32 m0, s0, 0x1f80
	ds_read_b128 v[222:225], v145 offset:3072
	global_load_lds_dwordx4 v128, s[36:37] offset:128
	s_barrier
	s_waitcnt lgkmcnt(0)
	s_setprio 1
	v_mfma_f32_16x16x32_bf16 v[108:111], v[210:213], v[170:173], v[108:111]
	v_mfma_f32_16x16x32_bf16 v[100:103], v[218:221], v[170:173], v[100:103]
	v_mfma_f32_16x16x32_bf16 v[92:95], v[210:213], v[178:181], v[92:95]
	v_mfma_f32_16x16x32_bf16 v[84:87], v[218:221], v[178:181], v[84:87]
	v_mfma_f32_16x16x32_bf16 v[76:79], v[210:213], v[194:197], v[76:79]
	v_mfma_f32_16x16x32_bf16 v[72:75], v[218:221], v[194:197], v[72:75]
	v_mfma_f32_16x16x32_bf16 v[68:71], v[210:213], v[202:205], v[68:71]
	v_mfma_f32_16x16x32_bf16 v[64:67], v[218:221], v[202:205], v[64:67]
	v_mfma_f32_16x16x32_bf16 v[108:111], v[214:217], v[174:177], v[108:111]
	v_mfma_f32_16x16x32_bf16 v[100:103], v[222:225], v[174:177], v[100:103]
	v_mfma_f32_16x16x32_bf16 v[92:95], v[214:217], v[188:191], v[92:95]
	v_mfma_f32_16x16x32_bf16 v[84:87], v[222:225], v[188:191], v[84:87]
	v_mfma_f32_16x16x32_bf16 v[76:79], v[214:217], v[198:201], v[76:79]
	v_mfma_f32_16x16x32_bf16 v[72:75], v[222:225], v[198:201], v[72:75]
	v_mfma_f32_16x16x32_bf16 v[68:71], v[214:217], v[206:209], v[68:71]
	v_mfma_f32_16x16x32_bf16 v[64:67], v[222:225], v[206:209], v[64:67]
	s_setprio 0
	s_add_i32 m0, s56, 0xffffff80
	s_barrier
	ds_read_b128 v[170:173], v142 offset:49152
	ds_read_b128 v[174:177], v142 offset:50176
	ds_read_b128 v[178:181], v142 offset:51200
	ds_read_b128 v[188:191], v142 offset:52224
	ds_read_b128 v[194:197], v142 offset:53248
	ds_read_b128 v[198:201], v142 offset:54272
	ds_read_b128 v[202:205], v142 offset:55296
	global_load_lds_dwordx4 v130, s[38:39] offset:128
	s_add_i32 m0, s57, 0xffffff80
	ds_read_b128 v[206:209], v142 offset:56320
	global_load_lds_dwordx4 v128, s[38:39] offset:128
	s_barrier
	s_waitcnt lgkmcnt(0)
	s_setprio 1
	v_mfma_f32_16x16x32_bf16 v[60:63], v[150:153], v[170:173], v[60:63]
	v_mfma_f32_16x16x32_bf16 v[56:59], v[162:165], v[170:173], v[56:59]
	v_mfma_f32_16x16x32_bf16 v[52:55], v[150:153], v[178:181], v[52:55]
	v_mfma_f32_16x16x32_bf16 v[48:51], v[162:165], v[178:181], v[48:51]
	v_mfma_f32_16x16x32_bf16 v[40:43], v[150:153], v[194:197], v[40:43]
	v_mfma_f32_16x16x32_bf16 v[32:35], v[162:165], v[194:197], v[32:35]
	v_mfma_f32_16x16x32_bf16 v[24:27], v[150:153], v[202:205], v[24:27]
	v_mfma_f32_16x16x32_bf16 v[16:19], v[162:165], v[202:205], v[16:19]
	v_mfma_f32_16x16x32_bf16 v[60:63], v[154:157], v[174:177], v[60:63]
	v_mfma_f32_16x16x32_bf16 v[56:59], v[166:169], v[174:177], v[56:59]
	v_mfma_f32_16x16x32_bf16 v[52:55], v[154:157], v[188:191], v[52:55]
	v_mfma_f32_16x16x32_bf16 v[48:51], v[166:169], v[188:191], v[48:51]
	v_mfma_f32_16x16x32_bf16 v[40:43], v[154:157], v[198:201], v[40:43]
	v_mfma_f32_16x16x32_bf16 v[32:35], v[166:169], v[198:201], v[32:35]
	v_mfma_f32_16x16x32_bf16 v[24:27], v[154:157], v[206:209], v[24:27]
	v_mfma_f32_16x16x32_bf16 v[16:19], v[166:169], v[206:209], v[16:19]
	s_setprio 0
	s_barrier
	s_add_i32 s4, s4, s35
	s_mov_b32 m0, s4
	s_add_u32 s0, s36, 0x160080
	s_addc_u32 s1, s37, 0
	global_load_lds_dwordx4 v130, s[0:1]
	s_add_i32 m0, s4, 0x2000
	s_nop 0
	global_load_lds_dwordx4 v128, s[0:1]
	s_waitcnt vmcnt(6)
	s_barrier
	s_setprio 1
	v_mfma_f32_16x16x32_bf16 v[44:47], v[210:213], v[170:173], v[44:47]
	v_mfma_f32_16x16x32_bf16 v[36:39], v[218:221], v[170:173], v[36:39]
	v_mfma_f32_16x16x32_bf16 v[28:31], v[210:213], v[178:181], v[28:31]
	v_mfma_f32_16x16x32_bf16 v[20:23], v[218:221], v[178:181], v[20:23]
	v_mfma_f32_16x16x32_bf16 v[12:15], v[210:213], v[194:197], v[12:15]
	v_mfma_f32_16x16x32_bf16 v[8:11], v[218:221], v[194:197], v[8:11]
	v_mfma_f32_16x16x32_bf16 v[4:7], v[210:213], v[202:205], v[4:7]
	v_mfma_f32_16x16x32_bf16 v[0:3], v[218:221], v[202:205], v[0:3]
	v_mfma_f32_16x16x32_bf16 v[44:47], v[214:217], v[174:177], v[44:47]
	v_mfma_f32_16x16x32_bf16 v[36:39], v[222:225], v[174:177], v[36:39]
	v_mfma_f32_16x16x32_bf16 v[28:31], v[214:217], v[188:191], v[28:31]
	v_mfma_f32_16x16x32_bf16 v[20:23], v[222:225], v[188:191], v[20:23]
	v_mfma_f32_16x16x32_bf16 v[12:15], v[214:217], v[198:201], v[12:15]
	v_mfma_f32_16x16x32_bf16 v[8:11], v[222:225], v[198:201], v[8:11]
	v_mfma_f32_16x16x32_bf16 v[4:7], v[214:217], v[206:209], v[4:7]
	v_mfma_f32_16x16x32_bf16 v[0:3], v[222:225], v[206:209], v[0:3]
	s_setprio 0
	s_add_i32 s68, s68, 2
	s_add_u32 s8, s8, 0x100
	s_addc_u32 s9, s9, 0
	s_add_u32 s66, s66, 0x100
	s_addc_u32 s67, s67, 0
	s_cmp_gt_u32 s68, 5
	s_barrier
	s_cbranch_scc0 .LBB0_326

;     DI size_t aoff(const Unit& u, size_t tstep) const { return (size_t)u.pm * tstep; }
;     DI size_t boff(const Unit& u, size_t tstep) const { return (size_t)u.pn * tstep; }
;     DI bool next(int i, Unit& u) const { const long L = (long)i * G + c; if (L >= np) return false; u.pm = pmv; u.pn = (int)(L % nN); u.ks = (int)(L / nN); return true; }
;     DI size_t aoff(const Unit& u, size_t) const { return (size_t)u.ks * kbytes; }
;     DI size_t boff(const Unit& u, size_t tstep) const { return (size_t)u.pn * tstep + (size_t)u.ks * kbytes; }
;     DI bool next(int i, Unit& u) const { Unit t; if (!S.next(i / 3, t)) return false; u.pm = t.pm; u.pn = t.pn; u.ks = i % 3; return true; }
;     DI size_t aoff(const Unit& u, size_t tstep) const { return (u.ks < 2 ? offU : offOA) + (size_t)u.pm * tstep; }
; #define PG8_LDA(dst, b, h) do { _Pragma("unroll") for (int m = 0; m < 4; ++m) _Pragma("unroll") for (int k = 0; k < 2; ++k) dst[m][k] = *(const LAS bf16x8*)(lds + PG8_SA(b, h) + aoff + m * 2048 + k * 1024); } while (0)
; template <class Epi, class Sched>
; DI void gemm_phase(LAS unsigned char* lds, const Gemm g, const Sched& S, const Epi& E) {
;     ...
;         const bool has_next = S.next(ui + 1, nxt);
;         const char* nA = has_next ? (const char*)g.A + S.aoff(nxt, tstep) : cA; const char* nB = has_next ? (const char*)g.Bt + S.boff(nxt, tstep) : cB;
;         for (int t = 0; t < nt; t += 2) {
;             if constexpr (Epi::HAS_MID) { if (t == E.mid_t(nt)) { int fr3 = fr, fq3 = fq; asm volatile("" : "+v"(fr3), "+v"(fq3)); E.mid(acc, cur, wr, wc, fr3, fq3); } }
;             const bool last = (t == nt - 2);
;             const char* a1 = cA + (size_t)(t + 1) * kstep;
;             const char* a2 = last ? nA : cA + (size_t)(t + 2) * kstep; const char* b2 = last ? nB : cB + (size_t)(t + 2) * kstep;
;             const char* a3 = a2 + kstep; const char* b3 = b2 + kstep;
;             PG8_LDB(B0, 0, 0); PG8_SCHED; PG8_LDA(At, 0, 0); PG8_STAGE(PG8_SA(1, 1), a1 + hstep, voffA);
;             PG8_WAIT_L(8); PG8_BAR; PG8_WAIT_L(0); PG8_MMA(0, 0, At, B0); PG8_BAR; PG8_SCHED;
;             PG8_LDB(B1, 0, 1); PG8_STAGE(PG8_SB(0, 0), b2, voffB);
;             PG8_BAR; PG8_WAIT_L(0); PG8_MMA(0, 1, At, B1); PG8_BAR;
;             PG8_LDA(At, 0, 1); PG8_STAGE(PG8_SA(0, 0), a2, voffA);
;             PG8_BAR; PG8_WAIT_L(0); PG8_MMA(1, 0, At, B0); PG8_BAR; PG8_SCHED;
.LBB0_526:
	s_ashr_i32 s51, s50, 31
	s_lshl_b64 s[0:1], s[50:51], 20
	s_add_u32 s52, s70, s0
	v_cmp_lt_i64_e32 vcc, s[12:13], v[142:143]
	s_addc_u32 s53, s71, s1
	s_and_b64 s[0:1], vcc, exec
	s_cselect_b32 s14, s53, s9
	s_cselect_b32 s15, s52, s8
	s_ashr_i32 s49, s48, 31
	s_lshl_b64 s[0:1], s[48:49], 20
	s_add_u32 s54, s72, s0
	s_addc_u32 s55, s73, s1
	s_and_b64 s[0:1], vcc, exec
	s_cselect_b32 s16, s55, s11
	s_cselect_b32 s17, s54, s10
	s_add_u32 s8, s8, 0x80080
	s_addc_u32 s9, s9, 0
	s_add_u32 s28, s10, 0x100
	v_mov_b32_e32 v0, 0
	s_addc_u32 s34, s11, 0
	s_mov_b32 s35, -2
	ds_read_b128 v[146:149], v164
	ds_read_b128 v[150:153], v164 offset:1024
	ds_read_b128 v[154:157], v164 offset:2048
	ds_read_b128 v[170:173], v164 offset:3072
	s_add_u32 s0, s8, 0xfff80080
	s_addc_u32 s1, s9, -1
	s_cmp_eq_u32 s35, 28
	s_cselect_b32 s13, s14, s1
	s_cselect_b32 s12, s15, s0
	s_cselect_b32 s11, s16, s34
	s_cselect_b32 s10, s17, s28
	s_add_i32 m0, s59, 0xc000
	ds_read_b128 v[174:177], v165
	ds_read_b128 v[178:181], v165 offset:1024
	ds_read_b128 v[188:191], v165 offset:2048
	ds_read_b128 v[194:197], v165 offset:3072
	ds_read_b128 v[198:201], v165 offset:4096
	ds_read_b128 v[202:205], v165 offset:5120
	ds_read_b128 v[206:209], v165 offset:6144
	global_load_lds_dwordx4 v138, s[8:9]
	s_add_i32 m0, s59, 0xe000
	ds_read_b128 v[210:213], v165 offset:7168
	global_load_lds_dwordx4 v140, s[8:9]
	s_waitcnt lgkmcnt(8)
	s_barrier
	s_waitcnt lgkmcnt(0)
	s_setprio 1
	v_mfma_f32_16x16x32_bf16 v[124:127], v[146:149], v[174:177], 0
	v_mfma_f32_16x16x32_bf16 v[120:123], v[154:157], v[174:177], 0
	v_mfma_f32_16x16x32_bf16 v[108:111], v[146:149], v[188:191], 0
	v_mfma_f32_16x16x32_bf16 v[104:107], v[154:157], v[188:191], 0
	v_mfma_f32_16x16x32_bf16 v[92:95], v[146:149], v[198:201], 0
	v_mfma_f32_16x16x32_bf16 v[88:91], v[154:157], v[198:201], 0
	v_mfma_f32_16x16x32_bf16 v[76:79], v[146:149], v[206:209], 0
	v_mfma_f32_16x16x32_bf16 v[72:75], v[154:157], v[206:209], 0
	v_mfma_f32_16x16x32_bf16 v[124:127], v[150:153], v[178:181], v[124:127]
	v_mfma_f32_16x16x32_bf16 v[120:123], v[170:173], v[178:181], v[120:123]
	v_mfma_f32_16x16x32_bf16 v[108:111], v[150:153], v[194:197], v[108:111]
	v_mfma_f32_16x16x32_bf16 v[104:107], v[170:173], v[194:197], v[104:107]
	v_mfma_f32_16x16x32_bf16 v[92:95], v[150:153], v[202:205], v[92:95]
	v_mfma_f32_16x16x32_bf16 v[88:91], v[170:173], v[202:205], v[88:91]
	v_mfma_f32_16x16x32_bf16 v[76:79], v[150:153], v[210:213], v[76:79]
	v_mfma_f32_16x16x32_bf16 v[72:75], v[170:173], v[210:213], v[72:75]
	s_setprio 0
	s_barrier
	s_add_i32 s0, s47, s74
	s_mov_b32 m0, s0
	ds_read_b128 v[214:217], v166
	ds_read_b128 v[218:221], v166 offset:1024
	ds_read_b128 v[222:225], v166 offset:2048
	global_load_lds_dwordx4 v130, s[10:11]
	s_add_i32 m0, s0, 0x2000
	ds_read_b128 v[226:229], v166 offset:3072
	global_load_lds_dwordx4 v134, s[10:11]
	s_barrier
	s_waitcnt lgkmcnt(0)
	s_setprio 1
	v_mfma_f32_16x16x32_bf16 v[116:119], v[214:217], v[174:177], 0
	v_mfma_f32_16x16x32_bf16 v[112:115], v[222:225], v[174:177], 0
	v_mfma_f32_16x16x32_bf16 v[100:103], v[214:217], v[188:191], 0
	v_mfma_f32_16x16x32_bf16 v[96:99], v[222:225], v[188:191], 0
	v_mfma_f32_16x16x32_bf16 v[84:87], v[214:217], v[198:201], 0
	v_mfma_f32_16x16x32_bf16 v[80:83], v[222:225], v[198:201], 0
	v_mfma_f32_16x16x32_bf16 v[68:71], v[214:217], v[206:209], 0
	v_mfma_f32_16x16x32_bf16 v[64:67], v[222:225], v[206:209], 0
	v_mfma_f32_16x16x32_bf16 v[116:119], v[218:221], v[178:181], v[116:119]
	v_mfma_f32_16x16x32_bf16 v[112:115], v[226:229], v[178:181], v[112:115]
	v_mfma_f32_16x16x32_bf16 v[100:103], v[218:221], v[194:197], v[100:103]
	v_mfma_f32_16x16x32_bf16 v[96:99], v[226:229], v[194:197], v[96:99]
	v_mfma_f32_16x16x32_bf16 v[84:87], v[218:221], v[202:205], v[84:87]
	v_mfma_f32_16x16x32_bf16 v[80:83], v[226:229], v[202:205], v[80:83]
	v_mfma_f32_16x16x32_bf16 v[68:71], v[218:221], v[210:213], v[68:71]
	v_mfma_f32_16x16x32_bf16 v[64:67], v[226:229], v[210:213], v[64:67]
	s_setprio 0
	s_mov_b32 m0, s59
	s_barrier
	ds_read_b128 v[174:177], v165 offset:16384
	ds_read_b128 v[178:181], v165 offset:17408
	ds_read_b128 v[188:191], v165 offset:18432
	ds_read_b128 v[194:197], v165 offset:19456
	ds_read_b128 v[198:201], v165 offset:20480
	ds_read_b128 v[202:205], v165 offset:21504
	ds_read_b128 v[206:209], v165 offset:22528
	global_load_lds_dwordx4 v128, s[12:13]
	s_mov_b32 m0, s75
	ds_read_b128 v[210:213], v165 offset:23552
	global_load_lds_dwordx4 v132, s[12:13]
	s_barrier
	s_waitcnt lgkmcnt(0)
	s_setprio 1
	v_mfma_f32_16x16x32_bf16 v[60:63], v[146:149], v[174:177], 0
	v_mfma_f32_16x16x32_bf16 v[56:59], v[154:157], v[174:177], 0
	v_mfma_f32_16x16x32_bf16 v[44:47], v[146:149], v[188:191], 0
	v_mfma_f32_16x16x32_bf16 v[40:43], v[154:157], v[188:191], 0
	v_mfma_f32_16x16x32_bf16 v[28:31], v[146:149], v[198:201], 0
	v_mfma_f32_16x16x32_bf16 v[24:27], v[154:157], v[198:201], 0
	v_mfma_f32_16x16x32_bf16 v[12:15], v[146:149], v[206:209], 0
	v_mfma_f32_16x16x32_bf16 v[8:11], v[154:157], v[206:209], 0
	v_mfma_f32_16x16x32_bf16 v[60:63], v[150:153], v[178:181], v[60:63]
	v_mfma_f32_16x16x32_bf16 v[56:59], v[170:173], v[178:181], v[56:59]
	v_mfma_f32_16x16x32_bf16 v[44:47], v[150:153], v[194:197], v[44:47]
	v_mfma_f32_16x16x32_bf16 v[40:43], v[170:173], v[194:197], v[40:43]
	v_mfma_f32_16x16x32_bf16 v[28:31], v[150:153], v[202:205], v[28:31]
	v_mfma_f32_16x16x32_bf16 v[24:27], v[170:173], v[202:205], v[24:27]
	v_mfma_f32_16x16x32_bf16 v[12:15], v[150:153], v[210:213], v[12:15]
	v_mfma_f32_16x16x32_bf16 v[8:11], v[170:173], v[210:213], v[8:11]
	s_setprio 0
	s_barrier
; #define PG8_STAGE(bufoff, gbase, voff) do { _Pragma("unroll") for (int _i = 0; _i < 2; ++_i) \
;         __builtin_amdgcn_global_load_lds((const unsigned*)((const char*)(gbase) + (voff)[_i]), (LAS unsigned*)(lds + (bufoff) + ldsw + _i * 8192), 16, 0, 0); } while (0)
; #define PG8_LDA(dst, b, h) do { _Pragma("unroll") for (int m = 0; m < 4; ++m) _Pragma("unroll") for (int k = 0; k < 2; ++k) dst[m][k] = *(const LAS bf16x8*)(lds + PG8_SA(b, h) + aoff + m * 2048 + k * 1024); } while (0)
; #define PG8_LDB(dst, b, h) do { _Pragma("unroll") for (int n = 0; n < 2; ++n) _Pragma("unroll") for (int k = 0; k < 2; ++k) dst[n][k] = *(const LAS bf16x8*)(lds + PG8_SB(b, h) + boff + n * 2048 + k * 1024); } while (0)
; #define PG8_MMA(ai, bj, At, Bt) do { __builtin_amdgcn_s_setprio(1); _Pragma("unroll") for (int m = 0; m < 4; ++m) _Pragma("unroll") for (int n = 0; n < 2; ++n) _Pragma("unroll") for (int k = 0; k < 2; ++k) \
;         acc[ai][bj][m][n] = __builtin_amdgcn_mfma_f32_16x16x32_bf16(Bt[n][k], At[m][k], acc[ai][bj][m][n], 0, 0, 0); __builtin_amdgcn_s_setprio(0); } while (0)
; #define PG8_WAIT_V(n) asm volatile("s_waitcnt vmcnt(" #n ")" ::: "memory")
; #define PG8_WAIT_L(n) asm volatile("s_waitcnt lgkmcnt(" #n ")" ::: "memory")
; #define PG8_BAR __builtin_amdgcn_s_barrier()
; #define PG8_SCHED __builtin_amdgcn_sched_barrier(0)
; template <class Epi, class Sched>
; DI void gemm_phase(LAS unsigned char* lds, const Gemm g, const Sched& S, const Epi& E) {
;     ...
;             PG8_STAGE(PG8_SB(0, 1), b2 + hstep, voffB);
;             PG8_WAIT_V(6); PG8_BAR; PG8_MMA(1, 1, At, B1); PG8_BAR;
;             PG8_LDB(B0, 1, 0); PG8_SCHED; PG8_LDA(At, 1, 0); PG8_STAGE(PG8_SA(0, 1), a2 + hstep, voffA);
;             PG8_WAIT_L(8); PG8_BAR; PG8_WAIT_L(0); PG8_MMA(0, 0, At, B0); PG8_BAR; PG8_SCHED;
;             PG8_LDB(B1, 1, 1); PG8_STAGE(PG8_SB(1, 0), b3, voffB);
;             PG8_BAR; PG8_WAIT_L(0); PG8_MMA(0, 1, At, B1); PG8_BAR;
;             PG8_LDA(At, 1, 1); PG8_STAGE(PG8_SA(1, 0), a3, voffA);
;             PG8_BAR; PG8_WAIT_L(0); PG8_MMA(1, 0, At, B0); PG8_BAR; PG8_SCHED;
	s_add_i32 s4, s87, s74
	s_mov_b32 m0, s4
	s_add_u32 s0, s10, 0x80000
	s_addc_u32 s1, s11, 0
	global_load_lds_dwordx4 v130, s[0:1]
	s_add_i32 m0, s4, 0x2000
	s_nop 0
	global_load_lds_dwordx4 v134, s[0:1]
	s_waitcnt vmcnt(6)
	s_barrier
	s_setprio 1
	v_mfma_f32_16x16x32_bf16 v[52:55], v[214:217], v[174:177], 0
	v_mfma_f32_16x16x32_bf16 v[48:51], v[222:225], v[174:177], 0
	v_mfma_f32_16x16x32_bf16 v[36:39], v[214:217], v[188:191], 0
	v_mfma_f32_16x16x32_bf16 v[32:35], v[222:225], v[188:191], 0
	v_mfma_f32_16x16x32_bf16 v[20:23], v[214:217], v[198:201], 0
	v_mfma_f32_16x16x32_bf16 v[16:19], v[222:225], v[198:201], 0
	v_mfma_f32_16x16x32_bf16 v[4:7], v[214:217], v[206:209], 0
	v_mfma_f32_16x16x32_bf16 v[0:3], v[222:225], v[206:209], 0
	v_mfma_f32_16x16x32_bf16 v[52:55], v[218:221], v[178:181], v[52:55]
	v_mfma_f32_16x16x32_bf16 v[48:51], v[226:229], v[178:181], v[48:51]
	v_mfma_f32_16x16x32_bf16 v[36:39], v[218:221], v[194:197], v[36:39]
	v_mfma_f32_16x16x32_bf16 v[32:35], v[226:229], v[194:197], v[32:35]
	v_mfma_f32_16x16x32_bf16 v[20:23], v[218:221], v[202:205], v[20:23]
	v_mfma_f32_16x16x32_bf16 v[16:19], v[226:229], v[202:205], v[16:19]
	v_mfma_f32_16x16x32_bf16 v[4:7], v[218:221], v[210:213], v[4:7]
	v_mfma_f32_16x16x32_bf16 v[0:3], v[226:229], v[210:213], v[0:3]
	s_setprio 0
	s_add_i32 s4, 0, 0x18000
	v_add_u32_e32 v158, s4, v163
	s_barrier
	ds_read_b128 v[146:149], v158
	ds_read_b128 v[150:153], v158 offset:1024
	ds_read_b128 v[154:157], v158 offset:2048
	ds_read_b128 v[170:173], v158 offset:3072
	s_add_u32 s0, s12, 0x80000
	s_addc_u32 s1, s13, 0
	s_mov_b32 m0, s76
	ds_read_b128 v[174:177], v165 offset:32768
	ds_read_b128 v[178:181], v165 offset:33792
	ds_read_b128 v[188:191], v165 offset:34816
	ds_read_b128 v[194:197], v165 offset:35840
	ds_read_b128 v[198:201], v165 offset:36864
	ds_read_b128 v[202:205], v165 offset:37888
	ds_read_b128 v[206:209], v165 offset:38912
	global_load_lds_dwordx4 v128, s[0:1]
	s_mov_b32 m0, s77
	ds_read_b128 v[210:213], v165 offset:39936
	global_load_lds_dwordx4 v132, s[0:1]
	s_waitcnt lgkmcnt(8)
	s_barrier
	s_waitcnt lgkmcnt(0)
	s_setprio 1
	v_mfma_f32_16x16x32_bf16 v[124:127], v[146:149], v[174:177], v[124:127]
	v_mfma_f32_16x16x32_bf16 v[120:123], v[154:157], v[174:177], v[120:123]
	v_mfma_f32_16x16x32_bf16 v[108:111], v[146:149], v[188:191], v[108:111]
	v_mfma_f32_16x16x32_bf16 v[104:107], v[154:157], v[188:191], v[104:107]
	v_mfma_f32_16x16x32_bf16 v[92:95], v[146:149], v[198:201], v[92:95]
	v_mfma_f32_16x16x32_bf16 v[88:91], v[154:157], v[198:201], v[88:91]
	v_mfma_f32_16x16x32_bf16 v[76:79], v[146:149], v[206:209], v[76:79]
	v_mfma_f32_16x16x32_bf16 v[72:75], v[154:157], v[206:209], v[72:75]
	v_mfma_f32_16x16x32_bf16 v[124:127], v[150:153], v[178:181], v[124:127]
	v_mfma_f32_16x16x32_bf16 v[120:123], v[170:173], v[178:181], v[120:123]
	v_mfma_f32_16x16x32_bf16 v[108:111], v[150:153], v[194:197], v[108:111]
	v_mfma_f32_16x16x32_bf16 v[104:107], v[170:173], v[194:197], v[104:107]
	v_mfma_f32_16x16x32_bf16 v[92:95], v[150:153], v[202:205], v[92:95]
	v_mfma_f32_16x16x32_bf16 v[88:91], v[170:173], v[202:205], v[88:91]
	v_mfma_f32_16x16x32_bf16 v[76:79], v[150:153], v[210:213], v[76:79]
	v_mfma_f32_16x16x32_bf16 v[72:75], v[170:173], v[210:213], v[72:75]
	s_setprio 0
	s_barrier
	s_add_i32 s5, 0, 0x1c000
	s_add_i32 s0, s4, s74
	v_add_u32_e32 v159, s5, v163
	s_add_i32 m0, s0, 0xffffff80
	ds_read_b128 v[214:217], v159
	ds_read_b128 v[218:221], v159 offset:1024
	ds_read_b128 v[222:225], v159 offset:2048
	global_load_lds_dwordx4 v130, s[10:11] offset:128
	s_add_i32 m0, s0, 0x1f80
	ds_read_b128 v[226:229], v159 offset:3072
	global_load_lds_dwordx4 v134, s[10:11] offset:128
	s_barrier
	s_waitcnt lgkmcnt(0)
	s_setprio 1
	v_mfma_f32_16x16x32_bf16 v[116:119], v[214:217], v[174:177], v[116:119]
	v_mfma_f32_16x16x32_bf16 v[112:115], v[222:225], v[174:177], v[112:115]
	v_mfma_f32_16x16x32_bf16 v[100:103], v[214:217], v[188:191], v[100:103]
	v_mfma_f32_16x16x32_bf16 v[96:99], v[222:225], v[188:191], v[96:99]
	v_mfma_f32_16x16x32_bf16 v[84:87], v[214:217], v[198:201], v[84:87]
	v_mfma_f32_16x16x32_bf16 v[80:83], v[222:225], v[198:201], v[80:83]
	v_mfma_f32_16x16x32_bf16 v[68:71], v[214:217], v[206:209], v[68:71]
	v_mfma_f32_16x16x32_bf16 v[64:67], v[222:225], v[206:209], v[64:67]
	v_mfma_f32_16x16x32_bf16 v[116:119], v[218:221], v[178:181], v[116:119]
	v_mfma_f32_16x16x32_bf16 v[112:115], v[226:229], v[178:181], v[112:115]
	v_mfma_f32_16x16x32_bf16 v[100:103], v[218:221], v[194:197], v[100:103]
	v_mfma_f32_16x16x32_bf16 v[96:99], v[226:229], v[194:197], v[96:99]
	v_mfma_f32_16x16x32_bf16 v[84:87], v[218:221], v[202:205], v[84:87]
	v_mfma_f32_16x16x32_bf16 v[80:83], v[226:229], v[202:205], v[80:83]
	v_mfma_f32_16x16x32_bf16 v[68:71], v[218:221], v[210:213], v[68:71]
	v_mfma_f32_16x16x32_bf16 v[64:67], v[226:229], v[210:213], v[64:67]
	s_setprio 0
	s_add_i32 m0, s97, 0xffffff80
	s_barrier
	ds_read_b128 v[174:177], v165 offset:49152
	ds_read_b128 v[178:181], v165 offset:50176
	ds_read_b128 v[188:191], v165 offset:51200
	ds_read_b128 v[194:197], v165 offset:52224
	ds_read_b128 v[198:201], v165 offset:53248
	ds_read_b128 v[202:205], v165 offset:54272
	ds_read_b128 v[206:209], v165 offset:55296
	global_load_lds_dwordx4 v128, s[12:13] offset:128
	s_add_i32 m0, s84, 0xffffff80
	ds_read_b128 v[210:213], v165 offset:56320
	global_load_lds_dwordx4 v132, s[12:13] offset:128
	s_barrier
; #define PG8_STAGE(bufoff, gbase, voff) do { _Pragma("unroll") for (int _i = 0; _i < 2; ++_i) \
;         __builtin_amdgcn_global_load_lds((const unsigned*)((const char*)(gbase) + (voff)[_i]), (LAS unsigned*)(lds + (bufoff) + ldsw + _i * 8192), 16, 0, 0); } while (0)
; #define PG8_LDA(dst, b, h) do { _Pragma("unroll") for (int m = 0; m < 4; ++m) _Pragma("unroll") for (int k = 0; k < 2; ++k) dst[m][k] = *(const LAS bf16x8*)(lds + PG8_SA(b, h) + aoff + m * 2048 + k * 1024); } while (0)
; #define PG8_LDB(dst, b, h) do { _Pragma("unroll") for (int n = 0; n < 2; ++n) _Pragma("unroll") for (int k = 0; k < 2; ++k) dst[n][k] = *(const LAS bf16x8*)(lds + PG8_SB(b, h) + boff + n * 2048 + k * 1024); } while (0)
; #define PG8_MMA(ai, bj, At, Bt) do { __builtin_amdgcn_s_setprio(1); _Pragma("unroll") for (int m = 0; m < 4; ++m) _Pragma("unroll") for (int n = 0; n < 2; ++n) _Pragma("unroll") for (int k = 0; k < 2; ++k) \
;         acc[ai][bj][m][n] = __builtin_amdgcn_mfma_f32_16x16x32_bf16(Bt[n][k], At[m][k], acc[ai][bj][m][n], 0, 0, 0); __builtin_amdgcn_s_setprio(0); } while (0)
; #define PG8_WAIT_V(n) asm volatile("s_waitcnt vmcnt(" #n ")" ::: "memory")
; #define PG8_WAIT_L(n) asm volatile("s_waitcnt lgkmcnt(" #n ")" ::: "memory")
; #define PG8_BAR __builtin_amdgcn_s_barrier()
; #define PG8_SCHED __builtin_amdgcn_sched_barrier(0)
; template <class Epi, class Sched>
; DI void gemm_phase(LAS unsigned char* lds, const Gemm g, const Sched& S, const Epi& E) {
;     ...
;             PG8_LDB(B0, 0, 0); PG8_SCHED; PG8_LDA(At, 0, 0); PG8_STAGE(PG8_SA(1, 1), a1 + hstep, voffA);
;             PG8_WAIT_L(8); PG8_BAR; PG8_WAIT_L(0); PG8_MMA(0, 0, At, B0); PG8_BAR; PG8_SCHED;
;             PG8_LDB(B1, 0, 1); PG8_STAGE(PG8_SB(0, 0), b2, voffB);
;             PG8_BAR; PG8_WAIT_L(0); PG8_MMA(0, 1, At, B1); PG8_BAR;
;             PG8_LDA(At, 0, 1); PG8_STAGE(PG8_SA(0, 0), a2, voffA);
;             PG8_BAR; PG8_WAIT_L(0); PG8_MMA(1, 0, At, B0); PG8_BAR; PG8_SCHED;
;     ...
;             PG8_BAR; PG8_WAIT_L(0); PG8_MMA(1, 0, At, B0); PG8_BAR; PG8_SCHED;
;             PG8_STAGE(PG8_SB(1, 1), b3 + hstep, voffB);
;             PG8_WAIT_V(6); PG8_BAR; PG8_MMA(1, 1, At, B1); PG8_BAR;
	s_waitcnt lgkmcnt(0)
	s_setprio 1
	v_mfma_f32_16x16x32_bf16 v[60:63], v[146:149], v[174:177], v[60:63]
	v_mfma_f32_16x16x32_bf16 v[56:59], v[154:157], v[174:177], v[56:59]
	v_mfma_f32_16x16x32_bf16 v[44:47], v[146:149], v[188:191], v[44:47]
	v_mfma_f32_16x16x32_bf16 v[40:43], v[154:157], v[188:191], v[40:43]
	v_mfma_f32_16x16x32_bf16 v[28:31], v[146:149], v[198:201], v[28:31]
	v_mfma_f32_16x16x32_bf16 v[24:27], v[154:157], v[198:201], v[24:27]
	v_mfma_f32_16x16x32_bf16 v[12:15], v[146:149], v[206:209], v[12:15]
	v_mfma_f32_16x16x32_bf16 v[8:11], v[154:157], v[206:209], v[8:11]
	v_mfma_f32_16x16x32_bf16 v[60:63], v[150:153], v[178:181], v[60:63]
	v_mfma_f32_16x16x32_bf16 v[56:59], v[170:173], v[178:181], v[56:59]
	v_mfma_f32_16x16x32_bf16 v[44:47], v[150:153], v[194:197], v[44:47]
	v_mfma_f32_16x16x32_bf16 v[40:43], v[170:173], v[194:197], v[40:43]
	v_mfma_f32_16x16x32_bf16 v[28:31], v[150:153], v[202:205], v[28:31]
	v_mfma_f32_16x16x32_bf16 v[24:27], v[170:173], v[202:205], v[24:27]
	v_mfma_f32_16x16x32_bf16 v[12:15], v[150:153], v[210:213], v[12:15]
	v_mfma_f32_16x16x32_bf16 v[8:11], v[170:173], v[210:213], v[8:11]
	s_setprio 0
	s_barrier
	s_add_i32 s4, s5, s74
	s_mov_b32 m0, s4
	s_add_u32 s0, s10, 0x80080
	s_addc_u32 s1, s11, 0
	global_load_lds_dwordx4 v130, s[0:1]
	v_lshl_add_u64 v[146:147], s[0:1], 0, v[134:135]
	s_add_i32 m0, s4, 0x2000
	s_nop 0
	global_load_lds_dwordx4 v134, s[0:1]
	s_waitcnt vmcnt(6)
	s_barrier
	s_setprio 1
	v_mfma_f32_16x16x32_bf16 v[52:55], v[214:217], v[174:177], v[52:55]
	v_mfma_f32_16x16x32_bf16 v[48:51], v[222:225], v[174:177], v[48:51]
	v_mfma_f32_16x16x32_bf16 v[36:39], v[214:217], v[188:191], v[36:39]
	v_mfma_f32_16x16x32_bf16 v[32:35], v[222:225], v[188:191], v[32:35]
	v_mfma_f32_16x16x32_bf16 v[20:23], v[214:217], v[198:201], v[20:23]
	v_mfma_f32_16x16x32_bf16 v[16:19], v[222:225], v[198:201], v[16:19]
	v_mfma_f32_16x16x32_bf16 v[4:7], v[214:217], v[206:209], v[4:7]
	v_mfma_f32_16x16x32_bf16 v[0:3], v[222:225], v[206:209], v[0:3]
	v_mfma_f32_16x16x32_bf16 v[52:55], v[218:221], v[178:181], v[52:55]
	v_mfma_f32_16x16x32_bf16 v[48:51], v[226:229], v[178:181], v[48:51]
	v_mfma_f32_16x16x32_bf16 v[36:39], v[218:221], v[194:197], v[36:39]
	v_mfma_f32_16x16x32_bf16 v[32:35], v[226:229], v[194:197], v[32:35]
	v_mfma_f32_16x16x32_bf16 v[20:23], v[218:221], v[202:205], v[20:23]
	v_mfma_f32_16x16x32_bf16 v[16:19], v[226:229], v[202:205], v[16:19]
	v_mfma_f32_16x16x32_bf16 v[4:7], v[218:221], v[210:213], v[4:7]
	v_mfma_f32_16x16x32_bf16 v[0:3], v[226:229], v[210:213], v[0:3]
	s_setprio 0
	s_add_i32 s35, s35, 2
	s_add_u32 s8, s8, 0x100
	s_addc_u32 s9, s9, 0
	s_add_u32 s28, s28, 0x100
	s_addc_u32 s34, s34, 0
	s_cmp_gt_u32 s35, 29
	s_barrier
	s_cbranch_scc0 .LBB0_527
	s_branch .Lpeel_done_527
.LBB0_527:
	ds_read_b128 v[146:149], v164
	ds_read_b128 v[150:153], v164 offset:1024
	ds_read_b128 v[154:157], v164 offset:2048
	ds_read_b128 v[170:173], v164 offset:3072
	s_add_u32 s0, s8, 0xfff80080
	s_addc_u32 s1, s9, -1
	s_cmp_eq_u32 s35, 28
	s_cselect_b32 s13, s14, s1
	s_cselect_b32 s12, s15, s0
	s_cselect_b32 s11, s16, s34
	s_cselect_b32 s10, s17, s28
	s_add_i32 m0, s59, 0xc000
	ds_read_b128 v[174:177], v165
	ds_read_b128 v[178:181], v165 offset:1024
	ds_read_b128 v[188:191], v165 offset:2048
	ds_read_b128 v[194:197], v165 offset:3072
	ds_read_b128 v[198:201], v165 offset:4096
	ds_read_b128 v[202:205], v165 offset:5120
	ds_read_b128 v[206:209], v165 offset:6144
	global_load_lds_dwordx4 v138, s[8:9]
	s_add_i32 m0, s59, 0xe000
	ds_read_b128 v[210:213], v165 offset:7168
	global_load_lds_dwordx4 v140, s[8:9]
	s_waitcnt lgkmcnt(8)
	s_barrier
	s_waitcnt lgkmcnt(0)
	s_setprio 1
	v_mfma_f32_16x16x32_bf16 v[124:127], v[146:149], v[174:177], v[124:127]
	v_mfma_f32_16x16x32_bf16 v[120:123], v[154:157], v[174:177], v[120:123]
	v_mfma_f32_16x16x32_bf16 v[108:111], v[146:149], v[188:191], v[108:111]
	v_mfma_f32_16x16x32_bf16 v[104:107], v[154:157], v[188:191], v[104:107]
	v_mfma_f32_16x16x32_bf16 v[92:95], v[146:149], v[198:201], v[92:95]
	v_mfma_f32_16x16x32_bf16 v[88:91], v[154:157], v[198:201], v[88:91]
	v_mfma_f32_16x16x32_bf16 v[76:79], v[146:149], v[206:209], v[76:79]
	v_mfma_f32_16x16x32_bf16 v[72:75], v[154:157], v[206:209], v[72:75]
	v_mfma_f32_16x16x32_bf16 v[124:127], v[150:153], v[178:181], v[124:127]
	v_mfma_f32_16x16x32_bf16 v[120:123], v[170:173], v[178:181], v[120:123]
	v_mfma_f32_16x16x32_bf16 v[108:111], v[150:153], v[194:197], v[108:111]
	v_mfma_f32_16x16x32_bf16 v[104:107], v[170:173], v[194:197], v[104:107]
	v_mfma_f32_16x16x32_bf16 v[92:95], v[150:153], v[202:205], v[92:95]
	v_mfma_f32_16x16x32_bf16 v[88:91], v[170:173], v[202:205], v[88:91]
	v_mfma_f32_16x16x32_bf16 v[76:79], v[150:153], v[210:213], v[76:79]
	v_mfma_f32_16x16x32_bf16 v[72:75], v[170:173], v[210:213], v[72:75]
	s_setprio 0
	s_barrier
	s_add_i32 s0, s47, s74
	s_mov_b32 m0, s0
	ds_read_b128 v[214:217], v166
	ds_read_b128 v[218:221], v166 offset:1024
	ds_read_b128 v[222:225], v166 offset:2048
	global_load_lds_dwordx4 v130, s[10:11]
	s_add_i32 m0, s0, 0x2000
	ds_read_b128 v[226:229], v166 offset:3072
	global_load_lds_dwordx4 v134, s[10:11]
	s_barrier
; #define PG8_STAGE(bufoff, gbase, voff) do { _Pragma("unroll") for (int _i = 0; _i < 2; ++_i) \
;         __builtin_amdgcn_global_load_lds((const unsigned*)((const char*)(gbase) + (voff)[_i]), (LAS unsigned*)(lds + (bufoff) + ldsw + _i * 8192), 16, 0, 0); } while (0)
; #define PG8_LDA(dst, b, h) do { _Pragma("unroll") for (int m = 0; m < 4; ++m) _Pragma("unroll") for (int k = 0; k < 2; ++k) dst[m][k] = *(const LAS bf16x8*)(lds + PG8_SA(b, h) + aoff + m * 2048 + k * 1024); } while (0)
; #define PG8_LDB(dst, b, h) do { _Pragma("unroll") for (int n = 0; n < 2; ++n) _Pragma("unroll") for (int k = 0; k < 2; ++k) dst[n][k] = *(const LAS bf16x8*)(lds + PG8_SB(b, h) + boff + n * 2048 + k * 1024); } while (0)
; #define PG8_MMA(ai, bj, At, Bt) do { __builtin_amdgcn_s_setprio(1); _Pragma("unroll") for (int m = 0; m < 4; ++m) _Pragma("unroll") for (int n = 0; n < 2; ++n) _Pragma("unroll") for (int k = 0; k < 2; ++k) \
;         acc[ai][bj][m][n] = __builtin_amdgcn_mfma_f32_16x16x32_bf16(Bt[n][k], At[m][k], acc[ai][bj][m][n], 0, 0, 0); __builtin_amdgcn_s_setprio(0); } while (0)
; #define PG8_WAIT_V(n) asm volatile("s_waitcnt vmcnt(" #n ")" ::: "memory")
; #define PG8_WAIT_L(n) asm volatile("s_waitcnt lgkmcnt(" #n ")" ::: "memory")
; #define PG8_BAR __builtin_amdgcn_s_barrier()
; #define PG8_SCHED __builtin_amdgcn_sched_barrier(0)
; template <class Epi, class Sched>
; DI void gemm_phase(LAS unsigned char* lds, const Gemm g, const Sched& S, const Epi& E) {
;     ...
;             PG8_BAR; PG8_WAIT_L(0); PG8_MMA(0, 1, At, B1); PG8_BAR;
;             PG8_LDA(At, 0, 1); PG8_STAGE(PG8_SA(0, 0), a2, voffA);
;             PG8_BAR; PG8_WAIT_L(0); PG8_MMA(1, 0, At, B0); PG8_BAR; PG8_SCHED;
;             PG8_STAGE(PG8_SB(0, 1), b2 + hstep, voffB);
;             PG8_WAIT_V(6); PG8_BAR; PG8_MMA(1, 1, At, B1); PG8_BAR;
;             PG8_LDB(B0, 1, 0); PG8_SCHED; PG8_LDA(At, 1, 0); PG8_STAGE(PG8_SA(0, 1), a2 + hstep, voffA);
	s_waitcnt lgkmcnt(0)
	s_setprio 1
	v_mfma_f32_16x16x32_bf16 v[116:119], v[214:217], v[174:177], v[116:119]
	v_mfma_f32_16x16x32_bf16 v[112:115], v[222:225], v[174:177], v[112:115]
	v_mfma_f32_16x16x32_bf16 v[100:103], v[214:217], v[188:191], v[100:103]
	v_mfma_f32_16x16x32_bf16 v[96:99], v[222:225], v[188:191], v[96:99]
	v_mfma_f32_16x16x32_bf16 v[84:87], v[214:217], v[198:201], v[84:87]
	v_mfma_f32_16x16x32_bf16 v[80:83], v[222:225], v[198:201], v[80:83]
	v_mfma_f32_16x16x32_bf16 v[68:71], v[214:217], v[206:209], v[68:71]
	v_mfma_f32_16x16x32_bf16 v[64:67], v[222:225], v[206:209], v[64:67]
	v_mfma_f32_16x16x32_bf16 v[116:119], v[218:221], v[178:181], v[116:119]
	v_mfma_f32_16x16x32_bf16 v[112:115], v[226:229], v[178:181], v[112:115]
	v_mfma_f32_16x16x32_bf16 v[100:103], v[218:221], v[194:197], v[100:103]
	v_mfma_f32_16x16x32_bf16 v[96:99], v[226:229], v[194:197], v[96:99]
	v_mfma_f32_16x16x32_bf16 v[84:87], v[218:221], v[202:205], v[84:87]
	v_mfma_f32_16x16x32_bf16 v[80:83], v[226:229], v[202:205], v[80:83]
	v_mfma_f32_16x16x32_bf16 v[68:71], v[218:221], v[210:213], v[68:71]
	v_mfma_f32_16x16x32_bf16 v[64:67], v[226:229], v[210:213], v[64:67]
	s_setprio 0
	s_mov_b32 m0, s59
	s_barrier
	ds_read_b128 v[174:177], v165 offset:16384
	ds_read_b128 v[178:181], v165 offset:17408
	ds_read_b128 v[188:191], v165 offset:18432
	ds_read_b128 v[194:197], v165 offset:19456
	ds_read_b128 v[198:201], v165 offset:20480
	ds_read_b128 v[202:205], v165 offset:21504
	ds_read_b128 v[206:209], v165 offset:22528
	global_load_lds_dwordx4 v128, s[12:13]
	s_mov_b32 m0, s75
	ds_read_b128 v[210:213], v165 offset:23552
	global_load_lds_dwordx4 v132, s[12:13]
	s_barrier
	s_waitcnt lgkmcnt(0)
	s_setprio 1
	v_mfma_f32_16x16x32_bf16 v[60:63], v[146:149], v[174:177], v[60:63]
	v_mfma_f32_16x16x32_bf16 v[56:59], v[154:157], v[174:177], v[56:59]
	v_mfma_f32_16x16x32_bf16 v[44:47], v[146:149], v[188:191], v[44:47]
	v_mfma_f32_16x16x32_bf16 v[40:43], v[154:157], v[188:191], v[40:43]
	v_mfma_f32_16x16x32_bf16 v[28:31], v[146:149], v[198:201], v[28:31]
	v_mfma_f32_16x16x32_bf16 v[24:27], v[154:157], v[198:201], v[24:27]
	v_mfma_f32_16x16x32_bf16 v[12:15], v[146:149], v[206:209], v[12:15]
	v_mfma_f32_16x16x32_bf16 v[8:11], v[154:157], v[206:209], v[8:11]
	v_mfma_f32_16x16x32_bf16 v[60:63], v[150:153], v[178:181], v[60:63]
	v_mfma_f32_16x16x32_bf16 v[56:59], v[170:173], v[178:181], v[56:59]
	v_mfma_f32_16x16x32_bf16 v[44:47], v[150:153], v[194:197], v[44:47]
	v_mfma_f32_16x16x32_bf16 v[40:43], v[170:173], v[194:197], v[40:43]
	v_mfma_f32_16x16x32_bf16 v[28:31], v[150:153], v[202:205], v[28:31]
	v_mfma_f32_16x16x32_bf16 v[24:27], v[170:173], v[202:205], v[24:27]
	v_mfma_f32_16x16x32_bf16 v[12:15], v[150:153], v[210:213], v[12:15]
	v_mfma_f32_16x16x32_bf16 v[8:11], v[170:173], v[210:213], v[8:11]
	s_setprio 0
	s_barrier
	s_add_i32 s4, s87, s74
	s_mov_b32 m0, s4
	s_add_u32 s0, s10, 0x80000
	s_addc_u32 s1, s11, 0
	global_load_lds_dwordx4 v130, s[0:1]
	s_add_i32 m0, s4, 0x2000
	s_nop 0
	global_load_lds_dwordx4 v134, s[0:1]
	s_waitcnt vmcnt(6)
	s_barrier
	s_setprio 1
	v_mfma_f32_16x16x32_bf16 v[52:55], v[214:217], v[174:177], v[52:55]
	v_mfma_f32_16x16x32_bf16 v[48:51], v[222:225], v[174:177], v[48:51]
	v_mfma_f32_16x16x32_bf16 v[36:39], v[214:217], v[188:191], v[36:39]
	v_mfma_f32_16x16x32_bf16 v[32:35], v[222:225], v[188:191], v[32:35]
	v_mfma_f32_16x16x32_bf16 v[20:23], v[214:217], v[198:201], v[20:23]
	v_mfma_f32_16x16x32_bf16 v[16:19], v[222:225], v[198:201], v[16:19]
	v_mfma_f32_16x16x32_bf16 v[4:7], v[214:217], v[206:209], v[4:7]
	v_mfma_f32_16x16x32_bf16 v[0:3], v[222:225], v[206:209], v[0:3]
	v_mfma_f32_16x16x32_bf16 v[52:55], v[218:221], v[178:181], v[52:55]
	v_mfma_f32_16x16x32_bf16 v[48:51], v[226:229], v[178:181], v[48:51]
	v_mfma_f32_16x16x32_bf16 v[36:39], v[218:221], v[194:197], v[36:39]
	v_mfma_f32_16x16x32_bf16 v[32:35], v[226:229], v[194:197], v[32:35]
	v_mfma_f32_16x16x32_bf16 v[20:23], v[218:221], v[202:205], v[20:23]
	v_mfma_f32_16x16x32_bf16 v[16:19], v[226:229], v[202:205], v[16:19]
	v_mfma_f32_16x16x32_bf16 v[4:7], v[218:221], v[210:213], v[4:7]
	v_mfma_f32_16x16x32_bf16 v[0:3], v[226:229], v[210:213], v[0:3]
	s_setprio 0
	s_add_i32 s4, 0, 0x18000
	s_barrier
	ds_read_b128 v[146:149], v158
	ds_read_b128 v[150:153], v158 offset:1024
	ds_read_b128 v[154:157], v158 offset:2048
	ds_read_b128 v[170:173], v158 offset:3072
	s_add_u32 s0, s12, 0x80000
	s_addc_u32 s1, s13, 0
	s_mov_b32 m0, s76
	ds_read_b128 v[174:177], v165 offset:32768
	ds_read_b128 v[178:181], v165 offset:33792
	ds_read_b128 v[188:191], v165 offset:34816
	ds_read_b128 v[194:197], v165 offset:35840
	ds_read_b128 v[198:201], v165 offset:36864
	ds_read_b128 v[202:205], v165 offset:37888
	ds_read_b128 v[206:209], v165 offset:38912
	global_load_lds_dwordx4 v128, s[0:1]
	s_mov_b32 m0, s77
	ds_read_b128 v[210:213], v165 offset:39936
	global_load_lds_dwordx4 v132, s[0:1]
	s_waitcnt lgkmcnt(8)
	s_barrier
; #define PG8_STAGE(bufoff, gbase, voff) do { _Pragma("unroll") for (int _i = 0; _i < 2; ++_i) \
;         __builtin_amdgcn_global_load_lds((const unsigned*)((const char*)(gbase) + (voff)[_i]), (LAS unsigned*)(lds + (bufoff) + ldsw + _i * 8192), 16, 0, 0); } while (0)
; #define PG8_LDA(dst, b, h) do { _Pragma("unroll") for (int m = 0; m < 4; ++m) _Pragma("unroll") for (int k = 0; k < 2; ++k) dst[m][k] = *(const LAS bf16x8*)(lds + PG8_SA(b, h) + aoff + m * 2048 + k * 1024); } while (0)
; #define PG8_LDB(dst, b, h) do { _Pragma("unroll") for (int n = 0; n < 2; ++n) _Pragma("unroll") for (int k = 0; k < 2; ++k) dst[n][k] = *(const LAS bf16x8*)(lds + PG8_SB(b, h) + boff + n * 2048 + k * 1024); } while (0)
; #define PG8_MMA(ai, bj, At, Bt) do { __builtin_amdgcn_s_setprio(1); _Pragma("unroll") for (int m = 0; m < 4; ++m) _Pragma("unroll") for (int n = 0; n < 2; ++n) _Pragma("unroll") for (int k = 0; k < 2; ++k) \
;         acc[ai][bj][m][n] = __builtin_amdgcn_mfma_f32_16x16x32_bf16(Bt[n][k], At[m][k], acc[ai][bj][m][n], 0, 0, 0); __builtin_amdgcn_s_setprio(0); } while (0)
; #define PG8_WAIT_V(n) asm volatile("s_waitcnt vmcnt(" #n ")" ::: "memory")
; #define PG8_WAIT_L(n) asm volatile("s_waitcnt lgkmcnt(" #n ")" ::: "memory")
; #define PG8_BAR __builtin_amdgcn_s_barrier()
; #define PG8_SCHED __builtin_amdgcn_sched_barrier(0)
; template <class Epi, class Sched>
; DI void gemm_phase(LAS unsigned char* lds, const Gemm g, const Sched& S, const Epi& E) {
;     ...
;             PG8_WAIT_L(8); PG8_BAR; PG8_WAIT_L(0); PG8_MMA(0, 0, At, B0); PG8_BAR; PG8_SCHED;
;             PG8_LDB(B1, 1, 1); PG8_STAGE(PG8_SB(1, 0), b3, voffB);
;             PG8_BAR; PG8_WAIT_L(0); PG8_MMA(0, 1, At, B1); PG8_BAR;
;             PG8_LDA(At, 1, 1); PG8_STAGE(PG8_SA(1, 0), a3, voffA);
;             PG8_BAR; PG8_WAIT_L(0); PG8_MMA(1, 0, At, B0); PG8_BAR; PG8_SCHED;
;             PG8_STAGE(PG8_SB(1, 1), b3 + hstep, voffB);
;             PG8_WAIT_V(6); PG8_BAR; PG8_MMA(1, 1, At, B1); PG8_BAR;
	s_waitcnt lgkmcnt(0)
	s_setprio 1
	v_mfma_f32_16x16x32_bf16 v[124:127], v[146:149], v[174:177], v[124:127]
	v_mfma_f32_16x16x32_bf16 v[120:123], v[154:157], v[174:177], v[120:123]
	v_mfma_f32_16x16x32_bf16 v[108:111], v[146:149], v[188:191], v[108:111]
	v_mfma_f32_16x16x32_bf16 v[104:107], v[154:157], v[188:191], v[104:107]
	v_mfma_f32_16x16x32_bf16 v[92:95], v[146:149], v[198:201], v[92:95]
	v_mfma_f32_16x16x32_bf16 v[88:91], v[154:157], v[198:201], v[88:91]
	v_mfma_f32_16x16x32_bf16 v[76:79], v[146:149], v[206:209], v[76:79]
	v_mfma_f32_16x16x32_bf16 v[72:75], v[154:157], v[206:209], v[72:75]
	v_mfma_f32_16x16x32_bf16 v[124:127], v[150:153], v[178:181], v[124:127]
	v_mfma_f32_16x16x32_bf16 v[120:123], v[170:173], v[178:181], v[120:123]
	v_mfma_f32_16x16x32_bf16 v[108:111], v[150:153], v[194:197], v[108:111]
	v_mfma_f32_16x16x32_bf16 v[104:107], v[170:173], v[194:197], v[104:107]
	v_mfma_f32_16x16x32_bf16 v[92:95], v[150:153], v[202:205], v[92:95]
	v_mfma_f32_16x16x32_bf16 v[88:91], v[170:173], v[202:205], v[88:91]
	v_mfma_f32_16x16x32_bf16 v[76:79], v[150:153], v[210:213], v[76:79]
	v_mfma_f32_16x16x32_bf16 v[72:75], v[170:173], v[210:213], v[72:75]
	s_setprio 0
	s_barrier
	s_add_i32 s5, 0, 0x1c000
	s_add_i32 s0, s4, s74
	s_add_i32 m0, s0, 0xffffff80
	ds_read_b128 v[214:217], v159
	ds_read_b128 v[218:221], v159 offset:1024
	ds_read_b128 v[222:225], v159 offset:2048
	global_load_lds_dwordx4 v130, s[10:11] offset:128
	s_add_i32 m0, s0, 0x1f80
	ds_read_b128 v[226:229], v159 offset:3072
	global_load_lds_dwordx4 v134, s[10:11] offset:128
	s_barrier
	s_waitcnt lgkmcnt(0)
	s_setprio 1
	v_mfma_f32_16x16x32_bf16 v[116:119], v[214:217], v[174:177], v[116:119]
	v_mfma_f32_16x16x32_bf16 v[112:115], v[222:225], v[174:177], v[112:115]
	v_mfma_f32_16x16x32_bf16 v[100:103], v[214:217], v[188:191], v[100:103]
	v_mfma_f32_16x16x32_bf16 v[96:99], v[222:225], v[188:191], v[96:99]
	v_mfma_f32_16x16x32_bf16 v[84:87], v[214:217], v[198:201], v[84:87]
	v_mfma_f32_16x16x32_bf16 v[80:83], v[222:225], v[198:201], v[80:83]
	v_mfma_f32_16x16x32_bf16 v[68:71], v[214:217], v[206:209], v[68:71]
	v_mfma_f32_16x16x32_bf16 v[64:67], v[222:225], v[206:209], v[64:67]
	v_mfma_f32_16x16x32_bf16 v[116:119], v[218:221], v[178:181], v[116:119]
	v_mfma_f32_16x16x32_bf16 v[112:115], v[226:229], v[178:181], v[112:115]
	v_mfma_f32_16x16x32_bf16 v[100:103], v[218:221], v[194:197], v[100:103]
	v_mfma_f32_16x16x32_bf16 v[96:99], v[226:229], v[194:197], v[96:99]
	v_mfma_f32_16x16x32_bf16 v[84:87], v[218:221], v[202:205], v[84:87]
	v_mfma_f32_16x16x32_bf16 v[80:83], v[226:229], v[202:205], v[80:83]
	v_mfma_f32_16x16x32_bf16 v[68:71], v[218:221], v[210:213], v[68:71]
	v_mfma_f32_16x16x32_bf16 v[64:67], v[226:229], v[210:213], v[64:67]
	s_setprio 0
	s_add_i32 m0, s97, 0xffffff80
	s_barrier
	ds_read_b128 v[174:177], v165 offset:49152
	ds_read_b128 v[178:181], v165 offset:50176
	ds_read_b128 v[188:191], v165 offset:51200
	ds_read_b128 v[194:197], v165 offset:52224
	ds_read_b128 v[198:201], v165 offset:53248
	ds_read_b128 v[202:205], v165 offset:54272
	ds_read_b128 v[206:209], v165 offset:55296
	global_load_lds_dwordx4 v128, s[12:13] offset:128
	s_add_i32 m0, s84, 0xffffff80
	ds_read_b128 v[210:213], v165 offset:56320
	global_load_lds_dwordx4 v132, s[12:13] offset:128
	s_barrier
	s_waitcnt lgkmcnt(0)
	s_setprio 1
	v_mfma_f32_16x16x32_bf16 v[60:63], v[146:149], v[174:177], v[60:63]
	v_mfma_f32_16x16x32_bf16 v[56:59], v[154:157], v[174:177], v[56:59]
	v_mfma_f32_16x16x32_bf16 v[44:47], v[146:149], v[188:191], v[44:47]
	v_mfma_f32_16x16x32_bf16 v[40:43], v[154:157], v[188:191], v[40:43]
	v_mfma_f32_16x16x32_bf16 v[28:31], v[146:149], v[198:201], v[28:31]
	v_mfma_f32_16x16x32_bf16 v[24:27], v[154:157], v[198:201], v[24:27]
	v_mfma_f32_16x16x32_bf16 v[12:15], v[146:149], v[206:209], v[12:15]
	v_mfma_f32_16x16x32_bf16 v[8:11], v[154:157], v[206:209], v[8:11]
	v_mfma_f32_16x16x32_bf16 v[60:63], v[150:153], v[178:181], v[60:63]
	v_mfma_f32_16x16x32_bf16 v[56:59], v[170:173], v[178:181], v[56:59]
	v_mfma_f32_16x16x32_bf16 v[44:47], v[150:153], v[194:197], v[44:47]
	v_mfma_f32_16x16x32_bf16 v[40:43], v[170:173], v[194:197], v[40:43]
	v_mfma_f32_16x16x32_bf16 v[28:31], v[150:153], v[202:205], v[28:31]
	v_mfma_f32_16x16x32_bf16 v[24:27], v[170:173], v[202:205], v[24:27]
	v_mfma_f32_16x16x32_bf16 v[12:15], v[150:153], v[210:213], v[12:15]
	v_mfma_f32_16x16x32_bf16 v[8:11], v[170:173], v[210:213], v[8:11]
	s_setprio 0
	s_barrier
	s_add_i32 s4, s5, s74
	s_mov_b32 m0, s4
	s_add_u32 s0, s10, 0x80080
	s_addc_u32 s1, s11, 0
	global_load_lds_dwordx4 v130, s[0:1]
	v_lshl_add_u64 v[146:147], s[0:1], 0, v[134:135]
	s_add_i32 m0, s4, 0x2000
	s_nop 0
	global_load_lds_dwordx4 v134, s[0:1]
	s_waitcnt vmcnt(6)
	s_barrier
	s_setprio 1
	v_mfma_f32_16x16x32_bf16 v[52:55], v[214:217], v[174:177], v[52:55]
	v_mfma_f32_16x16x32_bf16 v[48:51], v[222:225], v[174:177], v[48:51]
	v_mfma_f32_16x16x32_bf16 v[36:39], v[214:217], v[188:191], v[36:39]
	v_mfma_f32_16x16x32_bf16 v[32:35], v[222:225], v[188:191], v[32:35]
	v_mfma_f32_16x16x32_bf16 v[20:23], v[214:217], v[198:201], v[20:23]
	v_mfma_f32_16x16x32_bf16 v[16:19], v[222:225], v[198:201], v[16:19]
	v_mfma_f32_16x16x32_bf16 v[4:7], v[214:217], v[206:209], v[4:7]
	v_mfma_f32_16x16x32_bf16 v[0:3], v[222:225], v[206:209], v[0:3]
	v_mfma_f32_16x16x32_bf16 v[52:55], v[218:221], v[178:181], v[52:55]
	v_mfma_f32_16x16x32_bf16 v[48:51], v[226:229], v[178:181], v[48:51]
	v_mfma_f32_16x16x32_bf16 v[36:39], v[218:221], v[194:197], v[36:39]
	v_mfma_f32_16x16x32_bf16 v[32:35], v[226:229], v[194:197], v[32:35]
	v_mfma_f32_16x16x32_bf16 v[20:23], v[218:221], v[202:205], v[20:23]
	v_mfma_f32_16x16x32_bf16 v[16:19], v[226:229], v[202:205], v[16:19]
	v_mfma_f32_16x16x32_bf16 v[4:7], v[218:221], v[210:213], v[4:7]
	v_mfma_f32_16x16x32_bf16 v[0:3], v[226:229], v[210:213], v[0:3]
	s_setprio 0
	s_add_i32 s35, s35, 2
	s_add_u32 s8, s8, 0x100
	s_addc_u32 s9, s9, 0
	s_add_u32 s28, s28, 0x100
	s_addc_u32 s34, s34, 0
	s_cmp_gt_u32 s35, 29
	s_barrier
	s_cbranch_scc0 .LBB0_527

;     DI size_t aoff(const Unit& u, size_t tstep) const { return (size_t)u.pm * tstep; }
;     DI size_t boff(const Unit& u, size_t tstep) const { return (size_t)u.pn * tstep; }
;     DI bool next(int i, Unit& u) const { const long L = (long)i * G + c; if (L >= np) return false; u.pm = pmv; u.pn = (int)(L % nN); u.ks = (int)(L / nN); return true; }
;     DI size_t aoff(const Unit& u, size_t) const { return (size_t)u.ks * kbytes; }
;     DI size_t boff(const Unit& u, size_t tstep) const { return (size_t)u.pn * tstep + (size_t)u.ks * kbytes; }
;     DI bool next(int i, Unit& u) const { Unit t; if (!S.next(i / 3, t)) return false; u.pm = t.pm; u.pn = t.pn; u.ks = i % 3; return true; }
;     DI size_t aoff(const Unit& u, size_t tstep) const { return (u.ks < 2 ? offU : offOA) + (size_t)u.pm * tstep; }
; #define PG8_WAIT_V(n) asm volatile("s_waitcnt vmcnt(" #n ")" ::: "memory")
; template <class Epi, class Sched>
; DI void gemm_phase(LAS unsigned char* lds, const Gemm g, const Sched& S, const Epi& E) {
;     ...
;         const bool has_next = S.next(ui + 1, nxt);
;         const char* nA = has_next ? (const char*)g.A + S.aoff(nxt, tstep) : cA; const char* nB = has_next ? (const char*)g.Bt + S.boff(nxt, tstep) : cB;
;         for (int t = 0; t < nt; t += 2) {
;             if constexpr (Epi::HAS_MID) { if (t == E.mid_t(nt)) { int fr3 = fr, fq3 = fq; asm volatile("" : "+v"(fr3), "+v"(fq3)); E.mid(acc, cur, wr, wc, fr3, fq3); } }
;             const bool last = (t == nt - 2);
;             const char* a1 = cA + (size_t)(t + 1) * kstep;
;             const char* a2 = last ? nA : cA + (size_t)(t + 2) * kstep; const char* b2 = last ? nB : cB + (size_t)(t + 2) * kstep;
;             const char* a3 = a2 + kstep; const char* b3 = b2 + kstep;
;             PG8_LDB(B0, 0, 0); PG8_SCHED; PG8_LDA(At, 0, 0); PG8_STAGE(PG8_SA(1, 1), a1 + hstep, voffA);
;             PG8_WAIT_L(8); PG8_BAR; PG8_WAIT_L(0); PG8_MMA(0, 0, At, B0); PG8_BAR; PG8_SCHED;
;             PG8_LDB(B1, 0, 1); PG8_STAGE(PG8_SB(0, 0), b2, voffB);
;             PG8_BAR; PG8_WAIT_L(0); PG8_MMA(0, 1, At, B1); PG8_BAR;
;             PG8_LDA(At, 0, 1); PG8_STAGE(PG8_SA(0, 0), a2, voffA);
;             PG8_BAR; PG8_WAIT_L(0); PG8_MMA(1, 0, At, B0); PG8_BAR; PG8_SCHED;
;             PG8_STAGE(PG8_SB(0, 1), b2 + hstep, voffB);
;             PG8_WAIT_V(6); PG8_BAR; PG8_MMA(1, 1, At, B1); PG8_BAR;
.LBB0_937:
	s_add_u32 s8, s38, 0x30080
	s_addc_u32 s9, s39, 0
	s_add_u32 s35, s36, 0x100
	v_mov_b32_e32 v0, 0
	s_addc_u32 s40, s37, 0
	s_mov_b32 s41, -2
	ds_read_b128 v[144:147], v165
	ds_read_b128 v[168:171], v165 offset:1024
	ds_read_b128 v[172:175], v165 offset:2048
	ds_read_b128 v[176:179], v165 offset:3072
	s_add_u32 s0, s8, 0xfffd0080
	s_addc_u32 s1, s9, -1
	s_cmp_eq_u32 s41, 8
	s_cselect_b32 s39, s31, s1
	s_cselect_b32 s38, s30, s0
	s_cselect_b32 s37, s11, s40
	s_cselect_b32 s36, s10, s35
	s_add_i32 m0, s51, 0xc000
	ds_read_b128 v[180:183], v166
	ds_read_b128 v[188:191], v166 offset:1024
	ds_read_b128 v[194:197], v166 offset:2048
	ds_read_b128 v[198:201], v166 offset:3072
	ds_read_b128 v[202:205], v166 offset:4096
	ds_read_b128 v[206:209], v166 offset:5120
	ds_read_b128 v[210:213], v166 offset:6144
	global_load_lds_dwordx4 v136, s[8:9]
	s_add_i32 m0, s51, 0xe000
	ds_read_b128 v[214:217], v166 offset:7168
	global_load_lds_dwordx4 v138, s[8:9]
	s_waitcnt lgkmcnt(8)
	s_barrier
	s_waitcnt lgkmcnt(0)
	s_setprio 1
	v_mfma_f32_16x16x32_bf16 v[124:127], v[144:147], v[180:183], 0
	v_mfma_f32_16x16x32_bf16 v[120:123], v[172:175], v[180:183], 0
	v_mfma_f32_16x16x32_bf16 v[108:111], v[144:147], v[194:197], 0
	v_mfma_f32_16x16x32_bf16 v[104:107], v[172:175], v[194:197], 0
	v_mfma_f32_16x16x32_bf16 v[92:95], v[144:147], v[202:205], 0
	v_mfma_f32_16x16x32_bf16 v[88:91], v[172:175], v[202:205], 0
	v_mfma_f32_16x16x32_bf16 v[76:79], v[144:147], v[210:213], 0
	v_mfma_f32_16x16x32_bf16 v[72:75], v[172:175], v[210:213], 0
	v_mfma_f32_16x16x32_bf16 v[124:127], v[168:171], v[188:191], v[124:127]
	v_mfma_f32_16x16x32_bf16 v[120:123], v[176:179], v[188:191], v[120:123]
	v_mfma_f32_16x16x32_bf16 v[108:111], v[168:171], v[198:201], v[108:111]
	v_mfma_f32_16x16x32_bf16 v[104:107], v[176:179], v[198:201], v[104:107]
	v_mfma_f32_16x16x32_bf16 v[92:95], v[168:171], v[206:209], v[92:95]
	v_mfma_f32_16x16x32_bf16 v[88:91], v[176:179], v[206:209], v[88:91]
	v_mfma_f32_16x16x32_bf16 v[76:79], v[168:171], v[214:217], v[76:79]
	v_mfma_f32_16x16x32_bf16 v[72:75], v[176:179], v[214:217], v[72:75]
	s_setprio 0
	s_barrier
	s_add_i32 s0, s61, s50
	s_mov_b32 m0, s0
	ds_read_b128 v[218:221], v167
	ds_read_b128 v[222:225], v167 offset:1024
	ds_read_b128 v[226:229], v167 offset:2048
	global_load_lds_dwordx4 v130, s[36:37]
	s_add_i32 m0, s0, 0x2000
	ds_read_b128 v[230:233], v167 offset:3072
	global_load_lds_dwordx4 v134, s[36:37]
	s_barrier
	s_waitcnt lgkmcnt(0)
	s_setprio 1
	v_mfma_f32_16x16x32_bf16 v[116:119], v[218:221], v[180:183], 0
	v_mfma_f32_16x16x32_bf16 v[112:115], v[226:229], v[180:183], 0
	v_mfma_f32_16x16x32_bf16 v[100:103], v[218:221], v[194:197], 0
	v_mfma_f32_16x16x32_bf16 v[96:99], v[226:229], v[194:197], 0
	v_mfma_f32_16x16x32_bf16 v[84:87], v[218:221], v[202:205], 0
	v_mfma_f32_16x16x32_bf16 v[80:83], v[226:229], v[202:205], 0
	v_mfma_f32_16x16x32_bf16 v[68:71], v[218:221], v[210:213], 0
	v_mfma_f32_16x16x32_bf16 v[64:67], v[226:229], v[210:213], 0
	v_mfma_f32_16x16x32_bf16 v[116:119], v[222:225], v[188:191], v[116:119]
	v_mfma_f32_16x16x32_bf16 v[112:115], v[230:233], v[188:191], v[112:115]
	v_mfma_f32_16x16x32_bf16 v[100:103], v[222:225], v[198:201], v[100:103]
	v_mfma_f32_16x16x32_bf16 v[96:99], v[230:233], v[198:201], v[96:99]
	v_mfma_f32_16x16x32_bf16 v[84:87], v[222:225], v[206:209], v[84:87]
	v_mfma_f32_16x16x32_bf16 v[80:83], v[230:233], v[206:209], v[80:83]
	v_mfma_f32_16x16x32_bf16 v[68:71], v[222:225], v[214:217], v[68:71]
	v_mfma_f32_16x16x32_bf16 v[64:67], v[230:233], v[214:217], v[64:67]
	s_setprio 0
	s_mov_b32 m0, s51
	s_barrier
	ds_read_b128 v[180:183], v166 offset:16384
	ds_read_b128 v[188:191], v166 offset:17408
	ds_read_b128 v[194:197], v166 offset:18432
	ds_read_b128 v[198:201], v166 offset:19456
	ds_read_b128 v[202:205], v166 offset:20480
	ds_read_b128 v[206:209], v166 offset:21504
	ds_read_b128 v[210:213], v166 offset:22528
	global_load_lds_dwordx4 v128, s[38:39]
	s_mov_b32 m0, s52
	ds_read_b128 v[214:217], v166 offset:23552
	global_load_lds_dwordx4 v132, s[38:39]
	s_barrier
	s_waitcnt lgkmcnt(0)
	s_setprio 1
	v_mfma_f32_16x16x32_bf16 v[60:63], v[144:147], v[180:183], 0
	v_mfma_f32_16x16x32_bf16 v[56:59], v[172:175], v[180:183], 0
	v_mfma_f32_16x16x32_bf16 v[44:47], v[144:147], v[194:197], 0
	v_mfma_f32_16x16x32_bf16 v[40:43], v[172:175], v[194:197], 0
	v_mfma_f32_16x16x32_bf16 v[28:31], v[144:147], v[202:205], 0
	v_mfma_f32_16x16x32_bf16 v[24:27], v[172:175], v[202:205], 0
	v_mfma_f32_16x16x32_bf16 v[12:15], v[144:147], v[210:213], 0
	v_mfma_f32_16x16x32_bf16 v[8:11], v[172:175], v[210:213], 0
	v_mfma_f32_16x16x32_bf16 v[60:63], v[168:171], v[188:191], v[60:63]
	v_mfma_f32_16x16x32_bf16 v[56:59], v[176:179], v[188:191], v[56:59]
	v_mfma_f32_16x16x32_bf16 v[44:47], v[168:171], v[198:201], v[44:47]
	v_mfma_f32_16x16x32_bf16 v[40:43], v[176:179], v[198:201], v[40:43]
	v_mfma_f32_16x16x32_bf16 v[28:31], v[168:171], v[206:209], v[28:31]
	v_mfma_f32_16x16x32_bf16 v[24:27], v[176:179], v[206:209], v[24:27]
	v_mfma_f32_16x16x32_bf16 v[12:15], v[168:171], v[214:217], v[12:15]
	v_mfma_f32_16x16x32_bf16 v[8:11], v[176:179], v[214:217], v[8:11]
	s_setprio 0
	s_barrier
	s_add_i32 s4, s62, s50
	s_mov_b32 m0, s4
	s_add_u32 s0, s36, 0x30000
	s_addc_u32 s1, s37, 0
	global_load_lds_dwordx4 v130, s[0:1]
	s_add_i32 m0, s4, 0x2000
	s_nop 0
	global_load_lds_dwordx4 v134, s[0:1]
	s_waitcnt vmcnt(6)
	s_barrier
; #define PG8_STAGE(bufoff, gbase, voff) do { _Pragma("unroll") for (int _i = 0; _i < 2; ++_i) \
;         __builtin_amdgcn_global_load_lds((const unsigned*)((const char*)(gbase) + (voff)[_i]), (LAS unsigned*)(lds + (bufoff) + ldsw + _i * 8192), 16, 0, 0); } while (0)
; #define PG8_LDA(dst, b, h) do { _Pragma("unroll") for (int m = 0; m < 4; ++m) _Pragma("unroll") for (int k = 0; k < 2; ++k) dst[m][k] = *(const LAS bf16x8*)(lds + PG8_SA(b, h) + aoff + m * 2048 + k * 1024); } while (0)
; #define PG8_LDB(dst, b, h) do { _Pragma("unroll") for (int n = 0; n < 2; ++n) _Pragma("unroll") for (int k = 0; k < 2; ++k) dst[n][k] = *(const LAS bf16x8*)(lds + PG8_SB(b, h) + boff + n * 2048 + k * 1024); } while (0)
; #define PG8_MMA(ai, bj, At, Bt) do { __builtin_amdgcn_s_setprio(1); _Pragma("unroll") for (int m = 0; m < 4; ++m) _Pragma("unroll") for (int n = 0; n < 2; ++n) _Pragma("unroll") for (int k = 0; k < 2; ++k) \
;         acc[ai][bj][m][n] = __builtin_amdgcn_mfma_f32_16x16x32_bf16(Bt[n][k], At[m][k], acc[ai][bj][m][n], 0, 0, 0); __builtin_amdgcn_s_setprio(0); } while (0)
; #define PG8_WAIT_V(n) asm volatile("s_waitcnt vmcnt(" #n ")" ::: "memory")
; #define PG8_WAIT_L(n) asm volatile("s_waitcnt lgkmcnt(" #n ")" ::: "memory")
; #define PG8_BAR __builtin_amdgcn_s_barrier()
; #define PG8_SCHED __builtin_amdgcn_sched_barrier(0)
; template <class Epi, class Sched>
; DI void gemm_phase(LAS unsigned char* lds, const Gemm g, const Sched& S, const Epi& E) {
;     ...
;             PG8_WAIT_V(6); PG8_BAR; PG8_MMA(1, 1, At, B1); PG8_BAR;
;             PG8_LDB(B0, 1, 0); PG8_SCHED; PG8_LDA(At, 1, 0); PG8_STAGE(PG8_SA(0, 1), a2 + hstep, voffA);
;             PG8_WAIT_L(8); PG8_BAR; PG8_WAIT_L(0); PG8_MMA(0, 0, At, B0); PG8_BAR; PG8_SCHED;
;             PG8_LDB(B1, 1, 1); PG8_STAGE(PG8_SB(1, 0), b3, voffB);
;             PG8_BAR; PG8_WAIT_L(0); PG8_MMA(0, 1, At, B1); PG8_BAR;
;             PG8_LDA(At, 1, 1); PG8_STAGE(PG8_SA(1, 0), a3, voffA);
	s_setprio 1
	v_mfma_f32_16x16x32_bf16 v[52:55], v[218:221], v[180:183], 0
	v_mfma_f32_16x16x32_bf16 v[48:51], v[226:229], v[180:183], 0
	v_mfma_f32_16x16x32_bf16 v[36:39], v[218:221], v[194:197], 0
	v_mfma_f32_16x16x32_bf16 v[32:35], v[226:229], v[194:197], 0
	v_mfma_f32_16x16x32_bf16 v[20:23], v[218:221], v[202:205], 0
	v_mfma_f32_16x16x32_bf16 v[16:19], v[226:229], v[202:205], 0
	v_mfma_f32_16x16x32_bf16 v[4:7], v[218:221], v[210:213], 0
	v_mfma_f32_16x16x32_bf16 v[0:3], v[226:229], v[210:213], 0
	v_mfma_f32_16x16x32_bf16 v[52:55], v[222:225], v[188:191], v[52:55]
	v_mfma_f32_16x16x32_bf16 v[48:51], v[230:233], v[188:191], v[48:51]
	v_mfma_f32_16x16x32_bf16 v[36:39], v[222:225], v[198:201], v[36:39]
	v_mfma_f32_16x16x32_bf16 v[32:35], v[230:233], v[198:201], v[32:35]
	v_mfma_f32_16x16x32_bf16 v[20:23], v[222:225], v[206:209], v[20:23]
	v_mfma_f32_16x16x32_bf16 v[16:19], v[230:233], v[206:209], v[16:19]
	v_mfma_f32_16x16x32_bf16 v[4:7], v[222:225], v[214:217], v[4:7]
	v_mfma_f32_16x16x32_bf16 v[0:3], v[230:233], v[214:217], v[0:3]
	s_setprio 0
	s_add_i32 s4, 0, 0x18000
	v_add_u32_e32 v148, s4, v164
	s_barrier
	ds_read_b128 v[144:147], v148
	ds_read_b128 v[168:171], v148 offset:1024
	ds_read_b128 v[172:175], v148 offset:2048
	ds_read_b128 v[176:179], v148 offset:3072
	s_add_u32 s0, s38, 0x30000
	s_addc_u32 s1, s39, 0
	s_mov_b32 m0, s53
	ds_read_b128 v[180:183], v166 offset:32768
	ds_read_b128 v[188:191], v166 offset:33792
	ds_read_b128 v[194:197], v166 offset:34816
	ds_read_b128 v[198:201], v166 offset:35840
	ds_read_b128 v[202:205], v166 offset:36864
	ds_read_b128 v[206:209], v166 offset:37888
	ds_read_b128 v[210:213], v166 offset:38912
	global_load_lds_dwordx4 v128, s[0:1]
	s_mov_b32 m0, s54
	ds_read_b128 v[214:217], v166 offset:39936
	global_load_lds_dwordx4 v132, s[0:1]
	s_waitcnt lgkmcnt(8)
	s_barrier
	s_waitcnt lgkmcnt(0)
	s_setprio 1
	v_mfma_f32_16x16x32_bf16 v[124:127], v[144:147], v[180:183], v[124:127]
	v_mfma_f32_16x16x32_bf16 v[120:123], v[172:175], v[180:183], v[120:123]
	v_mfma_f32_16x16x32_bf16 v[108:111], v[144:147], v[194:197], v[108:111]
	v_mfma_f32_16x16x32_bf16 v[104:107], v[172:175], v[194:197], v[104:107]
	v_mfma_f32_16x16x32_bf16 v[92:95], v[144:147], v[202:205], v[92:95]
	v_mfma_f32_16x16x32_bf16 v[88:91], v[172:175], v[202:205], v[88:91]
	v_mfma_f32_16x16x32_bf16 v[76:79], v[144:147], v[210:213], v[76:79]
	v_mfma_f32_16x16x32_bf16 v[72:75], v[172:175], v[210:213], v[72:75]
	v_mfma_f32_16x16x32_bf16 v[124:127], v[168:171], v[188:191], v[124:127]
	v_mfma_f32_16x16x32_bf16 v[120:123], v[176:179], v[188:191], v[120:123]
	v_mfma_f32_16x16x32_bf16 v[108:111], v[168:171], v[198:201], v[108:111]
	v_mfma_f32_16x16x32_bf16 v[104:107], v[176:179], v[198:201], v[104:107]
	v_mfma_f32_16x16x32_bf16 v[92:95], v[168:171], v[206:209], v[92:95]
	v_mfma_f32_16x16x32_bf16 v[88:91], v[176:179], v[206:209], v[88:91]
	v_mfma_f32_16x16x32_bf16 v[76:79], v[168:171], v[214:217], v[76:79]
	v_mfma_f32_16x16x32_bf16 v[72:75], v[176:179], v[214:217], v[72:75]
	s_setprio 0
	s_barrier
	s_add_i32 s5, 0, 0x1c000
	s_add_i32 s0, s4, s50
	v_add_u32_e32 v149, s5, v164
	s_add_i32 m0, s0, 0xffffff80
	ds_read_b128 v[218:221], v149
	ds_read_b128 v[222:225], v149 offset:1024
	ds_read_b128 v[226:229], v149 offset:2048
	global_load_lds_dwordx4 v130, s[36:37] offset:128
	s_add_i32 m0, s0, 0x1f80
	ds_read_b128 v[230:233], v149 offset:3072
	global_load_lds_dwordx4 v134, s[36:37] offset:128
	s_barrier
	s_waitcnt lgkmcnt(0)
	s_setprio 1
	v_mfma_f32_16x16x32_bf16 v[116:119], v[218:221], v[180:183], v[116:119]
	v_mfma_f32_16x16x32_bf16 v[112:115], v[226:229], v[180:183], v[112:115]
	v_mfma_f32_16x16x32_bf16 v[100:103], v[218:221], v[194:197], v[100:103]
	v_mfma_f32_16x16x32_bf16 v[96:99], v[226:229], v[194:197], v[96:99]
	v_mfma_f32_16x16x32_bf16 v[84:87], v[218:221], v[202:205], v[84:87]
	v_mfma_f32_16x16x32_bf16 v[80:83], v[226:229], v[202:205], v[80:83]
	v_mfma_f32_16x16x32_bf16 v[68:71], v[218:221], v[210:213], v[68:71]
	v_mfma_f32_16x16x32_bf16 v[64:67], v[226:229], v[210:213], v[64:67]
	v_mfma_f32_16x16x32_bf16 v[116:119], v[222:225], v[188:191], v[116:119]
	v_mfma_f32_16x16x32_bf16 v[112:115], v[230:233], v[188:191], v[112:115]
	v_mfma_f32_16x16x32_bf16 v[100:103], v[222:225], v[198:201], v[100:103]
	v_mfma_f32_16x16x32_bf16 v[96:99], v[230:233], v[198:201], v[96:99]
	v_mfma_f32_16x16x32_bf16 v[84:87], v[222:225], v[206:209], v[84:87]
	v_mfma_f32_16x16x32_bf16 v[80:83], v[230:233], v[206:209], v[80:83]
	v_mfma_f32_16x16x32_bf16 v[68:71], v[222:225], v[214:217], v[68:71]
	v_mfma_f32_16x16x32_bf16 v[64:67], v[230:233], v[214:217], v[64:67]
	s_setprio 0
	s_add_i32 m0, s57, 0xffffff80
	s_barrier
	ds_read_b128 v[180:183], v166 offset:49152
	ds_read_b128 v[188:191], v166 offset:50176
	ds_read_b128 v[194:197], v166 offset:51200
	ds_read_b128 v[198:201], v166 offset:52224
	ds_read_b128 v[202:205], v166 offset:53248
	ds_read_b128 v[206:209], v166 offset:54272
	ds_read_b128 v[210:213], v166 offset:55296
	global_load_lds_dwordx4 v128, s[38:39] offset:128
	s_add_i32 m0, s58, 0xffffff80
	ds_read_b128 v[214:217], v166 offset:56320
	global_load_lds_dwordx4 v132, s[38:39] offset:128
	s_barrier
; #define PG8_STAGE(bufoff, gbase, voff) do { _Pragma("unroll") for (int _i = 0; _i < 2; ++_i) \
;         __builtin_amdgcn_global_load_lds((const unsigned*)((const char*)(gbase) + (voff)[_i]), (LAS unsigned*)(lds + (bufoff) + ldsw + _i * 8192), 16, 0, 0); } while (0)
; #define PG8_LDA(dst, b, h) do { _Pragma("unroll") for (int m = 0; m < 4; ++m) _Pragma("unroll") for (int k = 0; k < 2; ++k) dst[m][k] = *(const LAS bf16x8*)(lds + PG8_SA(b, h) + aoff + m * 2048 + k * 1024); } while (0)
; #define PG8_LDB(dst, b, h) do { _Pragma("unroll") for (int n = 0; n < 2; ++n) _Pragma("unroll") for (int k = 0; k < 2; ++k) dst[n][k] = *(const LAS bf16x8*)(lds + PG8_SB(b, h) + boff + n * 2048 + k * 1024); } while (0)
; #define PG8_MMA(ai, bj, At, Bt) do { __builtin_amdgcn_s_setprio(1); _Pragma("unroll") for (int m = 0; m < 4; ++m) _Pragma("unroll") for (int n = 0; n < 2; ++n) _Pragma("unroll") for (int k = 0; k < 2; ++k) \
;         acc[ai][bj][m][n] = __builtin_amdgcn_mfma_f32_16x16x32_bf16(Bt[n][k], At[m][k], acc[ai][bj][m][n], 0, 0, 0); __builtin_amdgcn_s_setprio(0); } while (0)
; #define PG8_WAIT_V(n) asm volatile("s_waitcnt vmcnt(" #n ")" ::: "memory")
; #define PG8_WAIT_L(n) asm volatile("s_waitcnt lgkmcnt(" #n ")" ::: "memory")
; #define PG8_BAR __builtin_amdgcn_s_barrier()
; #define PG8_SCHED __builtin_amdgcn_sched_barrier(0)
; template <class Epi, class Sched>
; DI void gemm_phase(LAS unsigned char* lds, const Gemm g, const Sched& S, const Epi& E) {
;     ...
;             PG8_LDB(B0, 0, 0); PG8_SCHED; PG8_LDA(At, 0, 0); PG8_STAGE(PG8_SA(1, 1), a1 + hstep, voffA);
;             PG8_WAIT_L(8); PG8_BAR; PG8_WAIT_L(0); PG8_MMA(0, 0, At, B0); PG8_BAR; PG8_SCHED;
;             PG8_LDB(B1, 0, 1); PG8_STAGE(PG8_SB(0, 0), b2, voffB);
;     ...
;             PG8_BAR; PG8_WAIT_L(0); PG8_MMA(1, 0, At, B0); PG8_BAR; PG8_SCHED;
;             PG8_STAGE(PG8_SB(1, 1), b3 + hstep, voffB);
;             PG8_WAIT_V(6); PG8_BAR; PG8_MMA(1, 1, At, B1); PG8_BAR;
	s_waitcnt lgkmcnt(0)
	s_setprio 1
	v_mfma_f32_16x16x32_bf16 v[60:63], v[144:147], v[180:183], v[60:63]
	v_mfma_f32_16x16x32_bf16 v[56:59], v[172:175], v[180:183], v[56:59]
	v_mfma_f32_16x16x32_bf16 v[44:47], v[144:147], v[194:197], v[44:47]
	v_mfma_f32_16x16x32_bf16 v[40:43], v[172:175], v[194:197], v[40:43]
	v_mfma_f32_16x16x32_bf16 v[28:31], v[144:147], v[202:205], v[28:31]
	v_mfma_f32_16x16x32_bf16 v[24:27], v[172:175], v[202:205], v[24:27]
	v_mfma_f32_16x16x32_bf16 v[12:15], v[144:147], v[210:213], v[12:15]
	v_mfma_f32_16x16x32_bf16 v[8:11], v[172:175], v[210:213], v[8:11]
	v_mfma_f32_16x16x32_bf16 v[60:63], v[168:171], v[188:191], v[60:63]
	v_mfma_f32_16x16x32_bf16 v[56:59], v[176:179], v[188:191], v[56:59]
	v_mfma_f32_16x16x32_bf16 v[44:47], v[168:171], v[198:201], v[44:47]
	v_mfma_f32_16x16x32_bf16 v[40:43], v[176:179], v[198:201], v[40:43]
	v_mfma_f32_16x16x32_bf16 v[28:31], v[168:171], v[206:209], v[28:31]
	v_mfma_f32_16x16x32_bf16 v[24:27], v[176:179], v[206:209], v[24:27]
	v_mfma_f32_16x16x32_bf16 v[12:15], v[168:171], v[214:217], v[12:15]
	v_mfma_f32_16x16x32_bf16 v[8:11], v[176:179], v[214:217], v[8:11]
	s_setprio 0
	s_barrier
	s_add_i32 s4, s5, s50
	s_mov_b32 m0, s4
	s_add_u32 s0, s36, 0x30080
	s_addc_u32 s1, s37, 0
	global_load_lds_dwordx4 v130, s[0:1]
	s_add_i32 m0, s4, 0x2000
	s_nop 0
	global_load_lds_dwordx4 v134, s[0:1]
	s_waitcnt vmcnt(6)
	s_barrier
	s_setprio 1
	v_mfma_f32_16x16x32_bf16 v[52:55], v[218:221], v[180:183], v[52:55]
	v_mfma_f32_16x16x32_bf16 v[48:51], v[226:229], v[180:183], v[48:51]
	v_mfma_f32_16x16x32_bf16 v[36:39], v[218:221], v[194:197], v[36:39]
	v_mfma_f32_16x16x32_bf16 v[32:35], v[226:229], v[194:197], v[32:35]
	v_mfma_f32_16x16x32_bf16 v[20:23], v[218:221], v[202:205], v[20:23]
	v_mfma_f32_16x16x32_bf16 v[16:19], v[226:229], v[202:205], v[16:19]
	v_mfma_f32_16x16x32_bf16 v[4:7], v[218:221], v[210:213], v[4:7]
	v_mfma_f32_16x16x32_bf16 v[0:3], v[226:229], v[210:213], v[0:3]
	v_mfma_f32_16x16x32_bf16 v[52:55], v[222:225], v[188:191], v[52:55]
	v_mfma_f32_16x16x32_bf16 v[48:51], v[230:233], v[188:191], v[48:51]
	v_mfma_f32_16x16x32_bf16 v[36:39], v[222:225], v[198:201], v[36:39]
	v_mfma_f32_16x16x32_bf16 v[32:35], v[230:233], v[198:201], v[32:35]
	v_mfma_f32_16x16x32_bf16 v[20:23], v[222:225], v[206:209], v[20:23]
	v_mfma_f32_16x16x32_bf16 v[16:19], v[230:233], v[206:209], v[16:19]
	v_mfma_f32_16x16x32_bf16 v[4:7], v[222:225], v[214:217], v[4:7]
	v_mfma_f32_16x16x32_bf16 v[0:3], v[230:233], v[214:217], v[0:3]
	s_setprio 0
	s_add_i32 s41, s41, 2
	s_add_u32 s8, s8, 0x100
	s_addc_u32 s9, s9, 0
	s_add_u32 s35, s35, 0x100
	s_addc_u32 s40, s40, 0
	s_cmp_gt_u32 s41, 9
	s_barrier
	s_cbranch_scc0 .LBB0_938
	s_branch .Lpeel_done_938
.LBB0_938:
	ds_read_b128 v[144:147], v165
	ds_read_b128 v[168:171], v165 offset:1024
	ds_read_b128 v[172:175], v165 offset:2048
	ds_read_b128 v[176:179], v165 offset:3072
	s_add_u32 s0, s8, 0xfffd0080
	s_addc_u32 s1, s9, -1
	s_cmp_eq_u32 s41, 8
	s_cselect_b32 s39, s31, s1
	s_cselect_b32 s38, s30, s0
	s_cselect_b32 s37, s11, s40
	s_cselect_b32 s36, s10, s35
	s_add_i32 m0, s51, 0xc000
	ds_read_b128 v[180:183], v166
	ds_read_b128 v[188:191], v166 offset:1024
	ds_read_b128 v[194:197], v166 offset:2048
	ds_read_b128 v[198:201], v166 offset:3072
	ds_read_b128 v[202:205], v166 offset:4096
	ds_read_b128 v[206:209], v166 offset:5120
	ds_read_b128 v[210:213], v166 offset:6144
	global_load_lds_dwordx4 v136, s[8:9]
	s_add_i32 m0, s51, 0xe000
	ds_read_b128 v[214:217], v166 offset:7168
	global_load_lds_dwordx4 v138, s[8:9]
	s_waitcnt lgkmcnt(8)
	s_barrier
	s_waitcnt lgkmcnt(0)
	s_setprio 1
	v_mfma_f32_16x16x32_bf16 v[124:127], v[144:147], v[180:183], v[124:127]
	v_mfma_f32_16x16x32_bf16 v[120:123], v[172:175], v[180:183], v[120:123]
	v_mfma_f32_16x16x32_bf16 v[108:111], v[144:147], v[194:197], v[108:111]
	v_mfma_f32_16x16x32_bf16 v[104:107], v[172:175], v[194:197], v[104:107]
	v_mfma_f32_16x16x32_bf16 v[92:95], v[144:147], v[202:205], v[92:95]
	v_mfma_f32_16x16x32_bf16 v[88:91], v[172:175], v[202:205], v[88:91]
	v_mfma_f32_16x16x32_bf16 v[76:79], v[144:147], v[210:213], v[76:79]
	v_mfma_f32_16x16x32_bf16 v[72:75], v[172:175], v[210:213], v[72:75]
	v_mfma_f32_16x16x32_bf16 v[124:127], v[168:171], v[188:191], v[124:127]
	v_mfma_f32_16x16x32_bf16 v[120:123], v[176:179], v[188:191], v[120:123]
	v_mfma_f32_16x16x32_bf16 v[108:111], v[168:171], v[198:201], v[108:111]
	v_mfma_f32_16x16x32_bf16 v[104:107], v[176:179], v[198:201], v[104:107]
	v_mfma_f32_16x16x32_bf16 v[92:95], v[168:171], v[206:209], v[92:95]
	v_mfma_f32_16x16x32_bf16 v[88:91], v[176:179], v[206:209], v[88:91]
	v_mfma_f32_16x16x32_bf16 v[76:79], v[168:171], v[214:217], v[76:79]
	v_mfma_f32_16x16x32_bf16 v[72:75], v[176:179], v[214:217], v[72:75]
	s_setprio 0
	s_barrier
	s_add_i32 s0, s61, s50
	s_mov_b32 m0, s0
	ds_read_b128 v[218:221], v167
	ds_read_b128 v[222:225], v167 offset:1024
	ds_read_b128 v[226:229], v167 offset:2048
	global_load_lds_dwordx4 v130, s[36:37]
	s_add_i32 m0, s0, 0x2000
	ds_read_b128 v[230:233], v167 offset:3072
	global_load_lds_dwordx4 v134, s[36:37]
	s_barrier
; #define PG8_STAGE(bufoff, gbase, voff) do { _Pragma("unroll") for (int _i = 0; _i < 2; ++_i) \
;         __builtin_amdgcn_global_load_lds((const unsigned*)((const char*)(gbase) + (voff)[_i]), (LAS unsigned*)(lds + (bufoff) + ldsw + _i * 8192), 16, 0, 0); } while (0)
; #define PG8_LDA(dst, b, h) do { _Pragma("unroll") for (int m = 0; m < 4; ++m) _Pragma("unroll") for (int k = 0; k < 2; ++k) dst[m][k] = *(const LAS bf16x8*)(lds + PG8_SA(b, h) + aoff + m * 2048 + k * 1024); } while (0)
; #define PG8_LDB(dst, b, h) do { _Pragma("unroll") for (int n = 0; n < 2; ++n) _Pragma("unroll") for (int k = 0; k < 2; ++k) dst[n][k] = *(const LAS bf16x8*)(lds + PG8_SB(b, h) + boff + n * 2048 + k * 1024); } while (0)
; #define PG8_MMA(ai, bj, At, Bt) do { __builtin_amdgcn_s_setprio(1); _Pragma("unroll") for (int m = 0; m < 4; ++m) _Pragma("unroll") for (int n = 0; n < 2; ++n) _Pragma("unroll") for (int k = 0; k < 2; ++k) \
;         acc[ai][bj][m][n] = __builtin_amdgcn_mfma_f32_16x16x32_bf16(Bt[n][k], At[m][k], acc[ai][bj][m][n], 0, 0, 0); __builtin_amdgcn_s_setprio(0); } while (0)
; #define PG8_WAIT_V(n) asm volatile("s_waitcnt vmcnt(" #n ")" ::: "memory")
; #define PG8_WAIT_L(n) asm volatile("s_waitcnt lgkmcnt(" #n ")" ::: "memory")
; #define PG8_BAR __builtin_amdgcn_s_barrier()
; #define PG8_SCHED __builtin_amdgcn_sched_barrier(0)
; template <class Epi, class Sched>
; DI void gemm_phase(LAS unsigned char* lds, const Gemm g, const Sched& S, const Epi& E) {
;     ...
;             PG8_BAR; PG8_WAIT_L(0); PG8_MMA(0, 1, At, B1); PG8_BAR;
;             PG8_LDA(At, 0, 1); PG8_STAGE(PG8_SA(0, 0), a2, voffA);
;             PG8_BAR; PG8_WAIT_L(0); PG8_MMA(1, 0, At, B0); PG8_BAR; PG8_SCHED;
;             PG8_STAGE(PG8_SB(0, 1), b2 + hstep, voffB);
;             PG8_WAIT_V(6); PG8_BAR; PG8_MMA(1, 1, At, B1); PG8_BAR;
;             PG8_LDB(B0, 1, 0); PG8_SCHED; PG8_LDA(At, 1, 0); PG8_STAGE(PG8_SA(0, 1), a2 + hstep, voffA);
	s_waitcnt lgkmcnt(0)
	s_setprio 1
	v_mfma_f32_16x16x32_bf16 v[116:119], v[218:221], v[180:183], v[116:119]
	v_mfma_f32_16x16x32_bf16 v[112:115], v[226:229], v[180:183], v[112:115]
	v_mfma_f32_16x16x32_bf16 v[100:103], v[218:221], v[194:197], v[100:103]
	v_mfma_f32_16x16x32_bf16 v[96:99], v[226:229], v[194:197], v[96:99]
	v_mfma_f32_16x16x32_bf16 v[84:87], v[218:221], v[202:205], v[84:87]
	v_mfma_f32_16x16x32_bf16 v[80:83], v[226:229], v[202:205], v[80:83]
	v_mfma_f32_16x16x32_bf16 v[68:71], v[218:221], v[210:213], v[68:71]
	v_mfma_f32_16x16x32_bf16 v[64:67], v[226:229], v[210:213], v[64:67]
	v_mfma_f32_16x16x32_bf16 v[116:119], v[222:225], v[188:191], v[116:119]
	v_mfma_f32_16x16x32_bf16 v[112:115], v[230:233], v[188:191], v[112:115]
	v_mfma_f32_16x16x32_bf16 v[100:103], v[222:225], v[198:201], v[100:103]
	v_mfma_f32_16x16x32_bf16 v[96:99], v[230:233], v[198:201], v[96:99]
	v_mfma_f32_16x16x32_bf16 v[84:87], v[222:225], v[206:209], v[84:87]
	v_mfma_f32_16x16x32_bf16 v[80:83], v[230:233], v[206:209], v[80:83]
	v_mfma_f32_16x16x32_bf16 v[68:71], v[222:225], v[214:217], v[68:71]
	v_mfma_f32_16x16x32_bf16 v[64:67], v[230:233], v[214:217], v[64:67]
	s_setprio 0
	s_mov_b32 m0, s51
	s_barrier
	ds_read_b128 v[180:183], v166 offset:16384
	ds_read_b128 v[188:191], v166 offset:17408
	ds_read_b128 v[194:197], v166 offset:18432
	ds_read_b128 v[198:201], v166 offset:19456
	ds_read_b128 v[202:205], v166 offset:20480
	ds_read_b128 v[206:209], v166 offset:21504
	ds_read_b128 v[210:213], v166 offset:22528
	global_load_lds_dwordx4 v128, s[38:39]
	s_mov_b32 m0, s52
	ds_read_b128 v[214:217], v166 offset:23552
	global_load_lds_dwordx4 v132, s[38:39]
	s_barrier
	s_waitcnt lgkmcnt(0)
	s_setprio 1
	v_mfma_f32_16x16x32_bf16 v[60:63], v[144:147], v[180:183], v[60:63]
	v_mfma_f32_16x16x32_bf16 v[56:59], v[172:175], v[180:183], v[56:59]
	v_mfma_f32_16x16x32_bf16 v[44:47], v[144:147], v[194:197], v[44:47]
	v_mfma_f32_16x16x32_bf16 v[40:43], v[172:175], v[194:197], v[40:43]
	v_mfma_f32_16x16x32_bf16 v[28:31], v[144:147], v[202:205], v[28:31]
	v_mfma_f32_16x16x32_bf16 v[24:27], v[172:175], v[202:205], v[24:27]
	v_mfma_f32_16x16x32_bf16 v[12:15], v[144:147], v[210:213], v[12:15]
	v_mfma_f32_16x16x32_bf16 v[8:11], v[172:175], v[210:213], v[8:11]
	v_mfma_f32_16x16x32_bf16 v[60:63], v[168:171], v[188:191], v[60:63]
	v_mfma_f32_16x16x32_bf16 v[56:59], v[176:179], v[188:191], v[56:59]
	v_mfma_f32_16x16x32_bf16 v[44:47], v[168:171], v[198:201], v[44:47]
	v_mfma_f32_16x16x32_bf16 v[40:43], v[176:179], v[198:201], v[40:43]
	v_mfma_f32_16x16x32_bf16 v[28:31], v[168:171], v[206:209], v[28:31]
	v_mfma_f32_16x16x32_bf16 v[24:27], v[176:179], v[206:209], v[24:27]
	v_mfma_f32_16x16x32_bf16 v[12:15], v[168:171], v[214:217], v[12:15]
	v_mfma_f32_16x16x32_bf16 v[8:11], v[176:179], v[214:217], v[8:11]
	s_setprio 0
	s_barrier
	s_add_i32 s4, s62, s50
	s_mov_b32 m0, s4
	s_add_u32 s0, s36, 0x30000
	s_addc_u32 s1, s37, 0
	global_load_lds_dwordx4 v130, s[0:1]
	s_add_i32 m0, s4, 0x2000
	s_nop 0
	global_load_lds_dwordx4 v134, s[0:1]
	s_waitcnt vmcnt(6)
	s_barrier
	s_setprio 1
	v_mfma_f32_16x16x32_bf16 v[52:55], v[218:221], v[180:183], v[52:55]
	v_mfma_f32_16x16x32_bf16 v[48:51], v[226:229], v[180:183], v[48:51]
	v_mfma_f32_16x16x32_bf16 v[36:39], v[218:221], v[194:197], v[36:39]
	v_mfma_f32_16x16x32_bf16 v[32:35], v[226:229], v[194:197], v[32:35]
	v_mfma_f32_16x16x32_bf16 v[20:23], v[218:221], v[202:205], v[20:23]
	v_mfma_f32_16x16x32_bf16 v[16:19], v[226:229], v[202:205], v[16:19]
	v_mfma_f32_16x16x32_bf16 v[4:7], v[218:221], v[210:213], v[4:7]
	v_mfma_f32_16x16x32_bf16 v[0:3], v[226:229], v[210:213], v[0:3]
	v_mfma_f32_16x16x32_bf16 v[52:55], v[222:225], v[188:191], v[52:55]
	v_mfma_f32_16x16x32_bf16 v[48:51], v[230:233], v[188:191], v[48:51]
	v_mfma_f32_16x16x32_bf16 v[36:39], v[222:225], v[198:201], v[36:39]
	v_mfma_f32_16x16x32_bf16 v[32:35], v[230:233], v[198:201], v[32:35]
	v_mfma_f32_16x16x32_bf16 v[20:23], v[222:225], v[206:209], v[20:23]
	v_mfma_f32_16x16x32_bf16 v[16:19], v[230:233], v[206:209], v[16:19]
	v_mfma_f32_16x16x32_bf16 v[4:7], v[222:225], v[214:217], v[4:7]
	v_mfma_f32_16x16x32_bf16 v[0:3], v[230:233], v[214:217], v[0:3]
	s_setprio 0
	s_add_i32 s4, 0, 0x18000
	s_barrier
	ds_read_b128 v[144:147], v148
	ds_read_b128 v[168:171], v148 offset:1024
	ds_read_b128 v[172:175], v148 offset:2048
	ds_read_b128 v[176:179], v148 offset:3072
	s_add_u32 s0, s38, 0x30000
	s_addc_u32 s1, s39, 0
	s_mov_b32 m0, s53
	ds_read_b128 v[180:183], v166 offset:32768
	ds_read_b128 v[188:191], v166 offset:33792
	ds_read_b128 v[194:197], v166 offset:34816
	ds_read_b128 v[198:201], v166 offset:35840
	ds_read_b128 v[202:205], v166 offset:36864
	ds_read_b128 v[206:209], v166 offset:37888
	ds_read_b128 v[210:213], v166 offset:38912
	global_load_lds_dwordx4 v128, s[0:1]
	s_mov_b32 m0, s54
	ds_read_b128 v[214:217], v166 offset:39936
	global_load_lds_dwordx4 v132, s[0:1]
	s_waitcnt lgkmcnt(8)
	s_barrier
; #define PG8_STAGE(bufoff, gbase, voff) do { _Pragma("unroll") for (int _i = 0; _i < 2; ++_i) \
;         __builtin_amdgcn_global_load_lds((const unsigned*)((const char*)(gbase) + (voff)[_i]), (LAS unsigned*)(lds + (bufoff) + ldsw + _i * 8192), 16, 0, 0); } while (0)
; #define PG8_LDA(dst, b, h) do { _Pragma("unroll") for (int m = 0; m < 4; ++m) _Pragma("unroll") for (int k = 0; k < 2; ++k) dst[m][k] = *(const LAS bf16x8*)(lds + PG8_SA(b, h) + aoff + m * 2048 + k * 1024); } while (0)
; #define PG8_LDB(dst, b, h) do { _Pragma("unroll") for (int n = 0; n < 2; ++n) _Pragma("unroll") for (int k = 0; k < 2; ++k) dst[n][k] = *(const LAS bf16x8*)(lds + PG8_SB(b, h) + boff + n * 2048 + k * 1024); } while (0)
; #define PG8_MMA(ai, bj, At, Bt) do { __builtin_amdgcn_s_setprio(1); _Pragma("unroll") for (int m = 0; m < 4; ++m) _Pragma("unroll") for (int n = 0; n < 2; ++n) _Pragma("unroll") for (int k = 0; k < 2; ++k) \
;         acc[ai][bj][m][n] = __builtin_amdgcn_mfma_f32_16x16x32_bf16(Bt[n][k], At[m][k], acc[ai][bj][m][n], 0, 0, 0); __builtin_amdgcn_s_setprio(0); } while (0)
; #define PG8_WAIT_V(n) asm volatile("s_waitcnt vmcnt(" #n ")" ::: "memory")
; #define PG8_WAIT_L(n) asm volatile("s_waitcnt lgkmcnt(" #n ")" ::: "memory")
; #define PG8_BAR __builtin_amdgcn_s_barrier()
; #define PG8_SCHED __builtin_amdgcn_sched_barrier(0)
; template <class Epi, class Sched>
; DI void gemm_phase(LAS unsigned char* lds, const Gemm g, const Sched& S, const Epi& E) {
;     ...
;             PG8_WAIT_L(8); PG8_BAR; PG8_WAIT_L(0); PG8_MMA(0, 0, At, B0); PG8_BAR; PG8_SCHED;
;             PG8_LDB(B1, 1, 1); PG8_STAGE(PG8_SB(1, 0), b3, voffB);
;             PG8_BAR; PG8_WAIT_L(0); PG8_MMA(0, 1, At, B1); PG8_BAR;
;             PG8_LDA(At, 1, 1); PG8_STAGE(PG8_SA(1, 0), a3, voffA);
;             PG8_BAR; PG8_WAIT_L(0); PG8_MMA(1, 0, At, B0); PG8_BAR; PG8_SCHED;
;             PG8_STAGE(PG8_SB(1, 1), b3 + hstep, voffB);
;             PG8_WAIT_V(6); PG8_BAR; PG8_MMA(1, 1, At, B1); PG8_BAR;
	s_waitcnt lgkmcnt(0)
	s_setprio 1
	v_mfma_f32_16x16x32_bf16 v[124:127], v[144:147], v[180:183], v[124:127]
	v_mfma_f32_16x16x32_bf16 v[120:123], v[172:175], v[180:183], v[120:123]
	v_mfma_f32_16x16x32_bf16 v[108:111], v[144:147], v[194:197], v[108:111]
	v_mfma_f32_16x16x32_bf16 v[104:107], v[172:175], v[194:197], v[104:107]
	v_mfma_f32_16x16x32_bf16 v[92:95], v[144:147], v[202:205], v[92:95]
	v_mfma_f32_16x16x32_bf16 v[88:91], v[172:175], v[202:205], v[88:91]
	v_mfma_f32_16x16x32_bf16 v[76:79], v[144:147], v[210:213], v[76:79]
	v_mfma_f32_16x16x32_bf16 v[72:75], v[172:175], v[210:213], v[72:75]
	v_mfma_f32_16x16x32_bf16 v[124:127], v[168:171], v[188:191], v[124:127]
	v_mfma_f32_16x16x32_bf16 v[120:123], v[176:179], v[188:191], v[120:123]
	v_mfma_f32_16x16x32_bf16 v[108:111], v[168:171], v[198:201], v[108:111]
	v_mfma_f32_16x16x32_bf16 v[104:107], v[176:179], v[198:201], v[104:107]
	v_mfma_f32_16x16x32_bf16 v[92:95], v[168:171], v[206:209], v[92:95]
	v_mfma_f32_16x16x32_bf16 v[88:91], v[176:179], v[206:209], v[88:91]
	v_mfma_f32_16x16x32_bf16 v[76:79], v[168:171], v[214:217], v[76:79]
	v_mfma_f32_16x16x32_bf16 v[72:75], v[176:179], v[214:217], v[72:75]
	s_setprio 0
	s_barrier
	s_add_i32 s5, 0, 0x1c000
	s_add_i32 s0, s4, s50
	s_add_i32 m0, s0, 0xffffff80
	ds_read_b128 v[218:221], v149
	ds_read_b128 v[222:225], v149 offset:1024
	ds_read_b128 v[226:229], v149 offset:2048
	global_load_lds_dwordx4 v130, s[36:37] offset:128
	s_add_i32 m0, s0, 0x1f80
	ds_read_b128 v[230:233], v149 offset:3072
	global_load_lds_dwordx4 v134, s[36:37] offset:128
	s_barrier
	s_waitcnt lgkmcnt(0)
	s_setprio 1
	v_mfma_f32_16x16x32_bf16 v[116:119], v[218:221], v[180:183], v[116:119]
	v_mfma_f32_16x16x32_bf16 v[112:115], v[226:229], v[180:183], v[112:115]
	v_mfma_f32_16x16x32_bf16 v[100:103], v[218:221], v[194:197], v[100:103]
	v_mfma_f32_16x16x32_bf16 v[96:99], v[226:229], v[194:197], v[96:99]
	v_mfma_f32_16x16x32_bf16 v[84:87], v[218:221], v[202:205], v[84:87]
	v_mfma_f32_16x16x32_bf16 v[80:83], v[226:229], v[202:205], v[80:83]
	v_mfma_f32_16x16x32_bf16 v[68:71], v[218:221], v[210:213], v[68:71]
	v_mfma_f32_16x16x32_bf16 v[64:67], v[226:229], v[210:213], v[64:67]
	v_mfma_f32_16x16x32_bf16 v[116:119], v[222:225], v[188:191], v[116:119]
	v_mfma_f32_16x16x32_bf16 v[112:115], v[230:233], v[188:191], v[112:115]
	v_mfma_f32_16x16x32_bf16 v[100:103], v[222:225], v[198:201], v[100:103]
	v_mfma_f32_16x16x32_bf16 v[96:99], v[230:233], v[198:201], v[96:99]
	v_mfma_f32_16x16x32_bf16 v[84:87], v[222:225], v[206:209], v[84:87]
	v_mfma_f32_16x16x32_bf16 v[80:83], v[230:233], v[206:209], v[80:83]
	v_mfma_f32_16x16x32_bf16 v[68:71], v[222:225], v[214:217], v[68:71]
	v_mfma_f32_16x16x32_bf16 v[64:67], v[230:233], v[214:217], v[64:67]
	s_setprio 0
	s_add_i32 m0, s57, 0xffffff80
	s_barrier
	ds_read_b128 v[180:183], v166 offset:49152
	ds_read_b128 v[188:191], v166 offset:50176
	ds_read_b128 v[194:197], v166 offset:51200
	ds_read_b128 v[198:201], v166 offset:52224
	ds_read_b128 v[202:205], v166 offset:53248
	ds_read_b128 v[206:209], v166 offset:54272
	ds_read_b128 v[210:213], v166 offset:55296
	global_load_lds_dwordx4 v128, s[38:39] offset:128
	s_add_i32 m0, s58, 0xffffff80
	ds_read_b128 v[214:217], v166 offset:56320
	global_load_lds_dwordx4 v132, s[38:39] offset:128
	s_barrier
	s_waitcnt lgkmcnt(0)
	s_setprio 1
	v_mfma_f32_16x16x32_bf16 v[60:63], v[144:147], v[180:183], v[60:63]
	v_mfma_f32_16x16x32_bf16 v[56:59], v[172:175], v[180:183], v[56:59]
	v_mfma_f32_16x16x32_bf16 v[44:47], v[144:147], v[194:197], v[44:47]
	v_mfma_f32_16x16x32_bf16 v[40:43], v[172:175], v[194:197], v[40:43]
	v_mfma_f32_16x16x32_bf16 v[28:31], v[144:147], v[202:205], v[28:31]
	v_mfma_f32_16x16x32_bf16 v[24:27], v[172:175], v[202:205], v[24:27]
	v_mfma_f32_16x16x32_bf16 v[12:15], v[144:147], v[210:213], v[12:15]
	v_mfma_f32_16x16x32_bf16 v[8:11], v[172:175], v[210:213], v[8:11]
	v_mfma_f32_16x16x32_bf16 v[60:63], v[168:171], v[188:191], v[60:63]
	v_mfma_f32_16x16x32_bf16 v[56:59], v[176:179], v[188:191], v[56:59]
	v_mfma_f32_16x16x32_bf16 v[44:47], v[168:171], v[198:201], v[44:47]
	v_mfma_f32_16x16x32_bf16 v[40:43], v[176:179], v[198:201], v[40:43]
	v_mfma_f32_16x16x32_bf16 v[28:31], v[168:171], v[206:209], v[28:31]
	v_mfma_f32_16x16x32_bf16 v[24:27], v[176:179], v[206:209], v[24:27]
	v_mfma_f32_16x16x32_bf16 v[12:15], v[168:171], v[214:217], v[12:15]
	v_mfma_f32_16x16x32_bf16 v[8:11], v[176:179], v[214:217], v[8:11]
	s_setprio 0
	s_barrier
	s_add_i32 s4, s5, s50
	s_mov_b32 m0, s4
	s_add_u32 s0, s36, 0x30080
	s_addc_u32 s1, s37, 0
	global_load_lds_dwordx4 v130, s[0:1]
	s_add_i32 m0, s4, 0x2000
	s_nop 0
	global_load_lds_dwordx4 v134, s[0:1]
	s_waitcnt vmcnt(6)
	s_barrier
	s_setprio 1
	v_mfma_f32_16x16x32_bf16 v[52:55], v[218:221], v[180:183], v[52:55]
	v_mfma_f32_16x16x32_bf16 v[48:51], v[226:229], v[180:183], v[48:51]
	v_mfma_f32_16x16x32_bf16 v[36:39], v[218:221], v[194:197], v[36:39]
	v_mfma_f32_16x16x32_bf16 v[32:35], v[226:229], v[194:197], v[32:35]
	v_mfma_f32_16x16x32_bf16 v[20:23], v[218:221], v[202:205], v[20:23]
	v_mfma_f32_16x16x32_bf16 v[16:19], v[226:229], v[202:205], v[16:19]
	v_mfma_f32_16x16x32_bf16 v[4:7], v[218:221], v[210:213], v[4:7]
	v_mfma_f32_16x16x32_bf16 v[0:3], v[226:229], v[210:213], v[0:3]
	v_mfma_f32_16x16x32_bf16 v[52:55], v[222:225], v[188:191], v[52:55]
	v_mfma_f32_16x16x32_bf16 v[48:51], v[230:233], v[188:191], v[48:51]
	v_mfma_f32_16x16x32_bf16 v[36:39], v[222:225], v[198:201], v[36:39]
	v_mfma_f32_16x16x32_bf16 v[32:35], v[230:233], v[198:201], v[32:35]
	v_mfma_f32_16x16x32_bf16 v[20:23], v[222:225], v[206:209], v[20:23]
	v_mfma_f32_16x16x32_bf16 v[16:19], v[230:233], v[206:209], v[16:19]
	v_mfma_f32_16x16x32_bf16 v[4:7], v[222:225], v[214:217], v[4:7]
	v_mfma_f32_16x16x32_bf16 v[0:3], v[230:233], v[214:217], v[0:3]
	s_setprio 0
	s_add_i32 s41, s41, 2
	s_add_u32 s8, s8, 0x100
	s_addc_u32 s9, s9, 0
	s_add_u32 s35, s35, 0x100
	s_addc_u32 s40, s40, 0
	s_cmp_gt_u32 s41, 9
	s_barrier
	s_cbranch_scc0 .LBB0_938

;     DI size_t aoff(const Unit& u, size_t tstep) const { return (size_t)u.pm * tstep; }
;     DI size_t boff(const Unit& u, size_t tstep) const { return (size_t)u.pn * tstep; }
;     DI bool next(int i, Unit& u) const { const long L = (long)i * G + c; if (L >= np) return false; u.pm = pmv; u.pn = (int)(L % nN); u.ks = (int)(L / nN); return true; }
;     DI size_t aoff(const Unit& u, size_t) const { return (size_t)u.ks * kbytes; }
;     DI size_t boff(const Unit& u, size_t tstep) const { return (size_t)u.pn * tstep + (size_t)u.ks * kbytes; }
;     DI bool next(int i, Unit& u) const { Unit t; if (!S.next(i / 3, t)) return false; u.pm = t.pm; u.pn = t.pn; u.ks = i % 3; return true; }
;     DI size_t aoff(const Unit& u, size_t tstep) const { return (u.ks < 2 ? offU : offOA) + (size_t)u.pm * tstep; }
; #define PG8_LDA(dst, b, h) do { _Pragma("unroll") for (int m = 0; m < 4; ++m) _Pragma("unroll") for (int k = 0; k < 2; ++k) dst[m][k] = *(const LAS bf16x8*)(lds + PG8_SA(b, h) + aoff + m * 2048 + k * 1024); } while (0)
; template <class Epi, class Sched>
; DI void gemm_phase(LAS unsigned char* lds, const Gemm g, const Sched& S, const Epi& E) {
;     ...
;         const bool has_next = S.next(ui + 1, nxt);
;         const char* nA = has_next ? (const char*)g.A + S.aoff(nxt, tstep) : cA; const char* nB = has_next ? (const char*)g.Bt + S.boff(nxt, tstep) : cB;
;         for (int t = 0; t < nt; t += 2) {
;             if constexpr (Epi::HAS_MID) { if (t == E.mid_t(nt)) { int fr3 = fr, fq3 = fq; asm volatile("" : "+v"(fr3), "+v"(fq3)); E.mid(acc, cur, wr, wc, fr3, fq3); } }
;             const bool last = (t == nt - 2);
;             const char* a1 = cA + (size_t)(t + 1) * kstep;
;             const char* a2 = last ? nA : cA + (size_t)(t + 2) * kstep; const char* b2 = last ? nB : cB + (size_t)(t + 2) * kstep;
;             const char* a3 = a2 + kstep; const char* b3 = b2 + kstep;
;             PG8_LDB(B0, 0, 0); PG8_SCHED; PG8_LDA(At, 0, 0); PG8_STAGE(PG8_SA(1, 1), a1 + hstep, voffA);
;             PG8_WAIT_L(8); PG8_BAR; PG8_WAIT_L(0); PG8_MMA(0, 0, At, B0); PG8_BAR; PG8_SCHED;
;             PG8_LDB(B1, 0, 1); PG8_STAGE(PG8_SB(0, 0), b2, voffB);
;             PG8_BAR; PG8_WAIT_L(0); PG8_MMA(0, 1, At, B1); PG8_BAR;
;             PG8_LDA(At, 0, 1); PG8_STAGE(PG8_SA(0, 0), a2, voffA);
;             PG8_BAR; PG8_WAIT_L(0); PG8_MMA(1, 0, At, B0); PG8_BAR; PG8_SCHED;
.LBB0_983:
	s_ashr_i32 s31, s30, 31
	s_lshl_b64 s[0:1], s[30:31], 18
	v_cmp_lt_i64_e32 vcc, s[36:37], v[142:143]
	s_add_u32 s36, s51, s0
	s_addc_u32 s37, s52, s1
	s_and_b64 s[0:1], vcc, exec
	s_cselect_b32 s9, s37, s43
	s_cselect_b32 s31, s36, s42
	s_ashr_i32 s29, s28, 31
	s_lshl_b64 s[0:1], s[28:29], 18
	s_add_u32 s38, s53, s0
	s_addc_u32 s39, s54, s1
	s_and_b64 s[0:1], vcc, exec
	s_cselect_b32 s29, s39, s45
	s_cselect_b32 s34, s38, s44
	s_add_u32 s42, s42, 0x20080
	s_addc_u32 s43, s43, 0
	s_add_u32 s35, s44, 0x100
	v_mov_b32_e32 v0, 0
	s_addc_u32 s41, s45, 0
	s_mov_b32 s79, -2
	ds_read_b128 v[146:149], v156
	ds_read_b128 v[150:153], v156 offset:1024
	ds_read_b128 v[160:163], v156 offset:2048
	ds_read_b128 v[164:167], v156 offset:3072
	s_add_u32 s0, s42, 0xfffe0080
	s_addc_u32 s1, s43, -1
	s_cmp_eq_u32 s79, 4
	s_cselect_b32 s47, s9, s1
	s_cselect_b32 s46, s31, s0
	s_cselect_b32 s45, s29, s41
	s_cselect_b32 s44, s34, s35
	s_add_i32 m0, s55, 0xc000
	ds_read_b128 v[168:171], v158
	ds_read_b128 v[172:175], v158 offset:1024
	ds_read_b128 v[176:179], v158 offset:2048
	ds_read_b128 v[180:183], v158 offset:3072
	ds_read_b128 v[188:191], v158 offset:4096
	ds_read_b128 v[194:197], v158 offset:5120
	ds_read_b128 v[198:201], v158 offset:6144
	global_load_lds_dwordx4 v138, s[42:43]
	s_add_i32 m0, s55, 0xe000
	ds_read_b128 v[202:205], v158 offset:7168
	global_load_lds_dwordx4 v140, s[42:43]
	s_waitcnt lgkmcnt(8)
	s_barrier
	s_waitcnt lgkmcnt(0)
	s_setprio 1
	v_mfma_f32_16x16x32_bf16 v[124:127], v[146:149], v[168:171], 0
	v_mfma_f32_16x16x32_bf16 v[120:123], v[160:163], v[168:171], 0
	v_mfma_f32_16x16x32_bf16 v[108:111], v[146:149], v[176:179], 0
	v_mfma_f32_16x16x32_bf16 v[104:107], v[160:163], v[176:179], 0
	v_mfma_f32_16x16x32_bf16 v[92:95], v[146:149], v[188:191], 0
	v_mfma_f32_16x16x32_bf16 v[88:91], v[160:163], v[188:191], 0
	v_mfma_f32_16x16x32_bf16 v[76:79], v[146:149], v[198:201], 0
	v_mfma_f32_16x16x32_bf16 v[72:75], v[160:163], v[198:201], 0
	v_mfma_f32_16x16x32_bf16 v[124:127], v[150:153], v[172:175], v[124:127]
	v_mfma_f32_16x16x32_bf16 v[120:123], v[164:167], v[172:175], v[120:123]
	v_mfma_f32_16x16x32_bf16 v[108:111], v[150:153], v[180:183], v[108:111]
	v_mfma_f32_16x16x32_bf16 v[104:107], v[164:167], v[180:183], v[104:107]
	v_mfma_f32_16x16x32_bf16 v[92:95], v[150:153], v[194:197], v[92:95]
	v_mfma_f32_16x16x32_bf16 v[88:91], v[164:167], v[194:197], v[88:91]
	v_mfma_f32_16x16x32_bf16 v[76:79], v[150:153], v[202:205], v[76:79]
	v_mfma_f32_16x16x32_bf16 v[72:75], v[164:167], v[202:205], v[72:75]
	s_setprio 0
	s_barrier
	s_add_i32 s0, s66, s50
	s_mov_b32 m0, s0
	ds_read_b128 v[206:209], v159
	ds_read_b128 v[210:213], v159 offset:1024
	ds_read_b128 v[214:217], v159 offset:2048
	global_load_lds_dwordx4 v130, s[44:45]
	s_add_i32 m0, s0, 0x2000
	ds_read_b128 v[218:221], v159 offset:3072
	global_load_lds_dwordx4 v134, s[44:45]
	s_barrier
	s_waitcnt lgkmcnt(0)
	s_setprio 1
	v_mfma_f32_16x16x32_bf16 v[116:119], v[206:209], v[168:171], 0
	v_mfma_f32_16x16x32_bf16 v[112:115], v[214:217], v[168:171], 0
	v_mfma_f32_16x16x32_bf16 v[100:103], v[206:209], v[176:179], 0
	v_mfma_f32_16x16x32_bf16 v[96:99], v[214:217], v[176:179], 0
	v_mfma_f32_16x16x32_bf16 v[84:87], v[206:209], v[188:191], 0
	v_mfma_f32_16x16x32_bf16 v[80:83], v[214:217], v[188:191], 0
	v_mfma_f32_16x16x32_bf16 v[68:71], v[206:209], v[198:201], 0
	v_mfma_f32_16x16x32_bf16 v[64:67], v[214:217], v[198:201], 0
	v_mfma_f32_16x16x32_bf16 v[116:119], v[210:213], v[172:175], v[116:119]
	v_mfma_f32_16x16x32_bf16 v[112:115], v[218:221], v[172:175], v[112:115]
	v_mfma_f32_16x16x32_bf16 v[100:103], v[210:213], v[180:183], v[100:103]
	v_mfma_f32_16x16x32_bf16 v[96:99], v[218:221], v[180:183], v[96:99]
	v_mfma_f32_16x16x32_bf16 v[84:87], v[210:213], v[194:197], v[84:87]
	v_mfma_f32_16x16x32_bf16 v[80:83], v[218:221], v[194:197], v[80:83]
	v_mfma_f32_16x16x32_bf16 v[68:71], v[210:213], v[202:205], v[68:71]
	v_mfma_f32_16x16x32_bf16 v[64:67], v[218:221], v[202:205], v[64:67]
	s_setprio 0
	s_mov_b32 m0, s55
	s_barrier
	ds_read_b128 v[168:171], v158 offset:16384
	ds_read_b128 v[172:175], v158 offset:17408
	ds_read_b128 v[176:179], v158 offset:18432
	ds_read_b128 v[180:183], v158 offset:19456
	ds_read_b128 v[188:191], v158 offset:20480
	ds_read_b128 v[194:197], v158 offset:21504
	ds_read_b128 v[198:201], v158 offset:22528
	global_load_lds_dwordx4 v128, s[46:47]
	s_mov_b32 m0, s56
	ds_read_b128 v[202:205], v158 offset:23552
	global_load_lds_dwordx4 v132, s[46:47]
	s_barrier
	s_waitcnt lgkmcnt(0)
	s_setprio 1
	v_mfma_f32_16x16x32_bf16 v[60:63], v[146:149], v[168:171], 0
	v_mfma_f32_16x16x32_bf16 v[56:59], v[160:163], v[168:171], 0
	v_mfma_f32_16x16x32_bf16 v[44:47], v[146:149], v[176:179], 0
	v_mfma_f32_16x16x32_bf16 v[40:43], v[160:163], v[176:179], 0
	v_mfma_f32_16x16x32_bf16 v[28:31], v[146:149], v[188:191], 0
	v_mfma_f32_16x16x32_bf16 v[24:27], v[160:163], v[188:191], 0
	v_mfma_f32_16x16x32_bf16 v[12:15], v[146:149], v[198:201], 0
	v_mfma_f32_16x16x32_bf16 v[8:11], v[160:163], v[198:201], 0
	v_mfma_f32_16x16x32_bf16 v[60:63], v[150:153], v[172:175], v[60:63]
	v_mfma_f32_16x16x32_bf16 v[56:59], v[164:167], v[172:175], v[56:59]
	v_mfma_f32_16x16x32_bf16 v[44:47], v[150:153], v[180:183], v[44:47]
	v_mfma_f32_16x16x32_bf16 v[40:43], v[164:167], v[180:183], v[40:43]
	v_mfma_f32_16x16x32_bf16 v[28:31], v[150:153], v[194:197], v[28:31]
	v_mfma_f32_16x16x32_bf16 v[24:27], v[164:167], v[194:197], v[24:27]
	v_mfma_f32_16x16x32_bf16 v[12:15], v[150:153], v[202:205], v[12:15]
	v_mfma_f32_16x16x32_bf16 v[8:11], v[164:167], v[202:205], v[8:11]
	s_setprio 0
	s_barrier
; #define PG8_STAGE(bufoff, gbase, voff) do { _Pragma("unroll") for (int _i = 0; _i < 2; ++_i) \
;         __builtin_amdgcn_global_load_lds((const unsigned*)((const char*)(gbase) + (voff)[_i]), (LAS unsigned*)(lds + (bufoff) + ldsw + _i * 8192), 16, 0, 0); } while (0)
; #define PG8_LDA(dst, b, h) do { _Pragma("unroll") for (int m = 0; m < 4; ++m) _Pragma("unroll") for (int k = 0; k < 2; ++k) dst[m][k] = *(const LAS bf16x8*)(lds + PG8_SA(b, h) + aoff + m * 2048 + k * 1024); } while (0)
; #define PG8_LDB(dst, b, h) do { _Pragma("unroll") for (int n = 0; n < 2; ++n) _Pragma("unroll") for (int k = 0; k < 2; ++k) dst[n][k] = *(const LAS bf16x8*)(lds + PG8_SB(b, h) + boff + n * 2048 + k * 1024); } while (0)
; #define PG8_MMA(ai, bj, At, Bt) do { __builtin_amdgcn_s_setprio(1); _Pragma("unroll") for (int m = 0; m < 4; ++m) _Pragma("unroll") for (int n = 0; n < 2; ++n) _Pragma("unroll") for (int k = 0; k < 2; ++k) \
;         acc[ai][bj][m][n] = __builtin_amdgcn_mfma_f32_16x16x32_bf16(Bt[n][k], At[m][k], acc[ai][bj][m][n], 0, 0, 0); __builtin_amdgcn_s_setprio(0); } while (0)
; #define PG8_WAIT_V(n) asm volatile("s_waitcnt vmcnt(" #n ")" ::: "memory")
; #define PG8_WAIT_L(n) asm volatile("s_waitcnt lgkmcnt(" #n ")" ::: "memory")
; #define PG8_BAR __builtin_amdgcn_s_barrier()
; #define PG8_SCHED __builtin_amdgcn_sched_barrier(0)
; template <class Epi, class Sched>
; DI void gemm_phase(LAS unsigned char* lds, const Gemm g, const Sched& S, const Epi& E) {
;     ...
;             PG8_STAGE(PG8_SB(0, 1), b2 + hstep, voffB);
;             PG8_WAIT_V(6); PG8_BAR; PG8_MMA(1, 1, At, B1); PG8_BAR;
;             PG8_LDB(B0, 1, 0); PG8_SCHED; PG8_LDA(At, 1, 0); PG8_STAGE(PG8_SA(0, 1), a2 + hstep, voffA);
;             PG8_WAIT_L(8); PG8_BAR; PG8_WAIT_L(0); PG8_MMA(0, 0, At, B0); PG8_BAR; PG8_SCHED;
;             PG8_LDB(B1, 1, 1); PG8_STAGE(PG8_SB(1, 0), b3, voffB);
;             PG8_BAR; PG8_WAIT_L(0); PG8_MMA(0, 1, At, B1); PG8_BAR;
;             PG8_LDA(At, 1, 1); PG8_STAGE(PG8_SA(1, 0), a3, voffA);
	s_add_i32 s4, s67, s50
	s_mov_b32 m0, s4
	s_add_u32 s0, s44, 0x20000
	s_addc_u32 s1, s45, 0
	global_load_lds_dwordx4 v130, s[0:1]
	s_add_i32 m0, s4, 0x2000
	s_nop 0
	global_load_lds_dwordx4 v134, s[0:1]
	s_waitcnt vmcnt(6)
	s_barrier
	s_setprio 1
	v_mfma_f32_16x16x32_bf16 v[52:55], v[206:209], v[168:171], 0
	v_mfma_f32_16x16x32_bf16 v[48:51], v[214:217], v[168:171], 0
	v_mfma_f32_16x16x32_bf16 v[36:39], v[206:209], v[176:179], 0
	v_mfma_f32_16x16x32_bf16 v[32:35], v[214:217], v[176:179], 0
	v_mfma_f32_16x16x32_bf16 v[20:23], v[206:209], v[188:191], 0
	v_mfma_f32_16x16x32_bf16 v[16:19], v[214:217], v[188:191], 0
	v_mfma_f32_16x16x32_bf16 v[4:7], v[206:209], v[198:201], 0
	v_mfma_f32_16x16x32_bf16 v[0:3], v[214:217], v[198:201], 0
	v_mfma_f32_16x16x32_bf16 v[52:55], v[210:213], v[172:175], v[52:55]
	v_mfma_f32_16x16x32_bf16 v[48:51], v[218:221], v[172:175], v[48:51]
	v_mfma_f32_16x16x32_bf16 v[36:39], v[210:213], v[180:183], v[36:39]
	v_mfma_f32_16x16x32_bf16 v[32:35], v[218:221], v[180:183], v[32:35]
	v_mfma_f32_16x16x32_bf16 v[20:23], v[210:213], v[194:197], v[20:23]
	v_mfma_f32_16x16x32_bf16 v[16:19], v[218:221], v[194:197], v[16:19]
	v_mfma_f32_16x16x32_bf16 v[4:7], v[210:213], v[202:205], v[4:7]
	v_mfma_f32_16x16x32_bf16 v[0:3], v[218:221], v[202:205], v[0:3]
	s_setprio 0
	s_add_i32 s4, 0, 0x18000
	v_add_u32_e32 v222, s4, v157
	s_barrier
	ds_read_b128 v[146:149], v222
	ds_read_b128 v[150:153], v222 offset:1024
	ds_read_b128 v[160:163], v222 offset:2048
	ds_read_b128 v[164:167], v222 offset:3072
	s_add_u32 s0, s46, 0x20000
	s_addc_u32 s1, s47, 0
	s_mov_b32 m0, s57
	ds_read_b128 v[168:171], v158 offset:32768
	ds_read_b128 v[172:175], v158 offset:33792
	ds_read_b128 v[176:179], v158 offset:34816
	ds_read_b128 v[180:183], v158 offset:35840
	ds_read_b128 v[188:191], v158 offset:36864
	ds_read_b128 v[194:197], v158 offset:37888
	ds_read_b128 v[198:201], v158 offset:38912
	global_load_lds_dwordx4 v128, s[0:1]
	s_mov_b32 m0, s58
	ds_read_b128 v[202:205], v158 offset:39936
	global_load_lds_dwordx4 v132, s[0:1]
	s_waitcnt lgkmcnt(8)
	s_barrier
	s_waitcnt lgkmcnt(0)
	s_setprio 1
	v_mfma_f32_16x16x32_bf16 v[124:127], v[146:149], v[168:171], v[124:127]
	v_mfma_f32_16x16x32_bf16 v[120:123], v[160:163], v[168:171], v[120:123]
	v_mfma_f32_16x16x32_bf16 v[108:111], v[146:149], v[176:179], v[108:111]
	v_mfma_f32_16x16x32_bf16 v[104:107], v[160:163], v[176:179], v[104:107]
	v_mfma_f32_16x16x32_bf16 v[92:95], v[146:149], v[188:191], v[92:95]
	v_mfma_f32_16x16x32_bf16 v[88:91], v[160:163], v[188:191], v[88:91]
	v_mfma_f32_16x16x32_bf16 v[76:79], v[146:149], v[198:201], v[76:79]
	v_mfma_f32_16x16x32_bf16 v[72:75], v[160:163], v[198:201], v[72:75]
	v_mfma_f32_16x16x32_bf16 v[124:127], v[150:153], v[172:175], v[124:127]
	v_mfma_f32_16x16x32_bf16 v[120:123], v[164:167], v[172:175], v[120:123]
	v_mfma_f32_16x16x32_bf16 v[108:111], v[150:153], v[180:183], v[108:111]
	v_mfma_f32_16x16x32_bf16 v[104:107], v[164:167], v[180:183], v[104:107]
	v_mfma_f32_16x16x32_bf16 v[92:95], v[150:153], v[194:197], v[92:95]
	v_mfma_f32_16x16x32_bf16 v[88:91], v[164:167], v[194:197], v[88:91]
	v_mfma_f32_16x16x32_bf16 v[76:79], v[150:153], v[202:205], v[76:79]
	v_mfma_f32_16x16x32_bf16 v[72:75], v[164:167], v[202:205], v[72:75]
	s_setprio 0
	s_barrier
	s_add_i32 s5, 0, 0x1c000
	s_add_i32 s0, s4, s50
	v_add_u32_e32 v223, s5, v157
	s_add_i32 m0, s0, 0xffffff80
	ds_read_b128 v[206:209], v223
	ds_read_b128 v[210:213], v223 offset:1024
	ds_read_b128 v[214:217], v223 offset:2048
	global_load_lds_dwordx4 v130, s[44:45] offset:128
	s_add_i32 m0, s0, 0x1f80
	ds_read_b128 v[218:221], v223 offset:3072
	global_load_lds_dwordx4 v134, s[44:45] offset:128
	s_barrier
	s_waitcnt lgkmcnt(0)
	s_setprio 1
	v_mfma_f32_16x16x32_bf16 v[116:119], v[206:209], v[168:171], v[116:119]
	v_mfma_f32_16x16x32_bf16 v[112:115], v[214:217], v[168:171], v[112:115]
	v_mfma_f32_16x16x32_bf16 v[100:103], v[206:209], v[176:179], v[100:103]
	v_mfma_f32_16x16x32_bf16 v[96:99], v[214:217], v[176:179], v[96:99]
	v_mfma_f32_16x16x32_bf16 v[84:87], v[206:209], v[188:191], v[84:87]
	v_mfma_f32_16x16x32_bf16 v[80:83], v[214:217], v[188:191], v[80:83]
	v_mfma_f32_16x16x32_bf16 v[68:71], v[206:209], v[198:201], v[68:71]
	v_mfma_f32_16x16x32_bf16 v[64:67], v[214:217], v[198:201], v[64:67]
	v_mfma_f32_16x16x32_bf16 v[116:119], v[210:213], v[172:175], v[116:119]
	v_mfma_f32_16x16x32_bf16 v[112:115], v[218:221], v[172:175], v[112:115]
	v_mfma_f32_16x16x32_bf16 v[100:103], v[210:213], v[180:183], v[100:103]
	v_mfma_f32_16x16x32_bf16 v[96:99], v[218:221], v[180:183], v[96:99]
	v_mfma_f32_16x16x32_bf16 v[84:87], v[210:213], v[194:197], v[84:87]
	v_mfma_f32_16x16x32_bf16 v[80:83], v[218:221], v[194:197], v[80:83]
	v_mfma_f32_16x16x32_bf16 v[68:71], v[210:213], v[202:205], v[68:71]
	v_mfma_f32_16x16x32_bf16 v[64:67], v[218:221], v[202:205], v[64:67]
	s_setprio 0
	s_add_i32 m0, s62, 0xffffff80
	s_barrier
	ds_read_b128 v[168:171], v158 offset:49152
	ds_read_b128 v[172:175], v158 offset:50176
	ds_read_b128 v[176:179], v158 offset:51200
	ds_read_b128 v[180:183], v158 offset:52224
	ds_read_b128 v[188:191], v158 offset:53248
	ds_read_b128 v[194:197], v158 offset:54272
	ds_read_b128 v[198:201], v158 offset:55296
	global_load_lds_dwordx4 v128, s[46:47] offset:128
	s_add_i32 m0, s63, 0xffffff80
	ds_read_b128 v[202:205], v158 offset:56320
	global_load_lds_dwordx4 v132, s[46:47] offset:128
	s_barrier
; #define PG8_STAGE(bufoff, gbase, voff) do { _Pragma("unroll") for (int _i = 0; _i < 2; ++_i) \
;         __builtin_amdgcn_global_load_lds((const unsigned*)((const char*)(gbase) + (voff)[_i]), (LAS unsigned*)(lds + (bufoff) + ldsw + _i * 8192), 16, 0, 0); } while (0)
; #define PG8_LDA(dst, b, h) do { _Pragma("unroll") for (int m = 0; m < 4; ++m) _Pragma("unroll") for (int k = 0; k < 2; ++k) dst[m][k] = *(const LAS bf16x8*)(lds + PG8_SA(b, h) + aoff + m * 2048 + k * 1024); } while (0)
; #define PG8_LDB(dst, b, h) do { _Pragma("unroll") for (int n = 0; n < 2; ++n) _Pragma("unroll") for (int k = 0; k < 2; ++k) dst[n][k] = *(const LAS bf16x8*)(lds + PG8_SB(b, h) + boff + n * 2048 + k * 1024); } while (0)
; #define PG8_MMA(ai, bj, At, Bt) do { __builtin_amdgcn_s_setprio(1); _Pragma("unroll") for (int m = 0; m < 4; ++m) _Pragma("unroll") for (int n = 0; n < 2; ++n) _Pragma("unroll") for (int k = 0; k < 2; ++k) \
;         acc[ai][bj][m][n] = __builtin_amdgcn_mfma_f32_16x16x32_bf16(Bt[n][k], At[m][k], acc[ai][bj][m][n], 0, 0, 0); __builtin_amdgcn_s_setprio(0); } while (0)
; #define PG8_WAIT_V(n) asm volatile("s_waitcnt vmcnt(" #n ")" ::: "memory")
; #define PG8_WAIT_L(n) asm volatile("s_waitcnt lgkmcnt(" #n ")" ::: "memory")
; #define PG8_BAR __builtin_amdgcn_s_barrier()
; #define PG8_SCHED __builtin_amdgcn_sched_barrier(0)
; template <class Epi, class Sched>
; DI void gemm_phase(LAS unsigned char* lds, const Gemm g, const Sched& S, const Epi& E) {
;     ...
;             PG8_LDB(B0, 0, 0); PG8_SCHED; PG8_LDA(At, 0, 0); PG8_STAGE(PG8_SA(1, 1), a1 + hstep, voffA);
;             PG8_WAIT_L(8); PG8_BAR; PG8_WAIT_L(0); PG8_MMA(0, 0, At, B0); PG8_BAR; PG8_SCHED;
;             PG8_LDB(B1, 0, 1); PG8_STAGE(PG8_SB(0, 0), b2, voffB);
;     ...
;             PG8_BAR; PG8_WAIT_L(0); PG8_MMA(1, 0, At, B0); PG8_BAR; PG8_SCHED;
;             PG8_STAGE(PG8_SB(1, 1), b3 + hstep, voffB);
;             PG8_WAIT_V(6); PG8_BAR; PG8_MMA(1, 1, At, B1); PG8_BAR;
	s_waitcnt lgkmcnt(0)
	s_setprio 1
	v_mfma_f32_16x16x32_bf16 v[60:63], v[146:149], v[168:171], v[60:63]
	v_mfma_f32_16x16x32_bf16 v[56:59], v[160:163], v[168:171], v[56:59]
	v_mfma_f32_16x16x32_bf16 v[44:47], v[146:149], v[176:179], v[44:47]
	v_mfma_f32_16x16x32_bf16 v[40:43], v[160:163], v[176:179], v[40:43]
	v_mfma_f32_16x16x32_bf16 v[28:31], v[146:149], v[188:191], v[28:31]
	v_mfma_f32_16x16x32_bf16 v[24:27], v[160:163], v[188:191], v[24:27]
	v_mfma_f32_16x16x32_bf16 v[12:15], v[146:149], v[198:201], v[12:15]
	v_mfma_f32_16x16x32_bf16 v[8:11], v[160:163], v[198:201], v[8:11]
	v_mfma_f32_16x16x32_bf16 v[60:63], v[150:153], v[172:175], v[60:63]
	v_mfma_f32_16x16x32_bf16 v[56:59], v[164:167], v[172:175], v[56:59]
	v_mfma_f32_16x16x32_bf16 v[44:47], v[150:153], v[180:183], v[44:47]
	v_mfma_f32_16x16x32_bf16 v[40:43], v[164:167], v[180:183], v[40:43]
	v_mfma_f32_16x16x32_bf16 v[28:31], v[150:153], v[194:197], v[28:31]
	v_mfma_f32_16x16x32_bf16 v[24:27], v[164:167], v[194:197], v[24:27]
	v_mfma_f32_16x16x32_bf16 v[12:15], v[150:153], v[202:205], v[12:15]
	v_mfma_f32_16x16x32_bf16 v[8:11], v[164:167], v[202:205], v[8:11]
	s_setprio 0
	s_barrier
	s_add_i32 s4, s5, s50
	s_mov_b32 m0, s4
	s_add_u32 s0, s44, 0x20080
	s_addc_u32 s1, s45, 0
	global_load_lds_dwordx4 v130, s[0:1]
	v_lshl_add_u64 v[146:147], s[0:1], 0, v[134:135]
	s_add_i32 m0, s4, 0x2000
	s_nop 0
	global_load_lds_dwordx4 v134, s[0:1]
	s_waitcnt vmcnt(6)
	s_barrier
	s_setprio 1
	v_mfma_f32_16x16x32_bf16 v[52:55], v[206:209], v[168:171], v[52:55]
	v_mfma_f32_16x16x32_bf16 v[48:51], v[214:217], v[168:171], v[48:51]
	v_mfma_f32_16x16x32_bf16 v[36:39], v[206:209], v[176:179], v[36:39]
	v_mfma_f32_16x16x32_bf16 v[32:35], v[214:217], v[176:179], v[32:35]
	v_mfma_f32_16x16x32_bf16 v[20:23], v[206:209], v[188:191], v[20:23]
	v_mfma_f32_16x16x32_bf16 v[16:19], v[214:217], v[188:191], v[16:19]
	v_mfma_f32_16x16x32_bf16 v[4:7], v[206:209], v[198:201], v[4:7]
	v_mfma_f32_16x16x32_bf16 v[0:3], v[214:217], v[198:201], v[0:3]
	v_mfma_f32_16x16x32_bf16 v[52:55], v[210:213], v[172:175], v[52:55]
	v_mfma_f32_16x16x32_bf16 v[48:51], v[218:221], v[172:175], v[48:51]
	v_mfma_f32_16x16x32_bf16 v[36:39], v[210:213], v[180:183], v[36:39]
	v_mfma_f32_16x16x32_bf16 v[32:35], v[218:221], v[180:183], v[32:35]
	v_mfma_f32_16x16x32_bf16 v[20:23], v[210:213], v[194:197], v[20:23]
	v_mfma_f32_16x16x32_bf16 v[16:19], v[218:221], v[194:197], v[16:19]
	v_mfma_f32_16x16x32_bf16 v[4:7], v[210:213], v[202:205], v[4:7]
	v_mfma_f32_16x16x32_bf16 v[0:3], v[218:221], v[202:205], v[0:3]
	s_setprio 0
	s_add_i32 s79, s79, 2
	s_add_u32 s42, s42, 0x100
	s_addc_u32 s43, s43, 0
	s_add_u32 s35, s35, 0x100
	s_addc_u32 s41, s41, 0
	s_cmp_gt_u32 s79, 5
	s_barrier
	s_cbranch_scc0 .LBB0_984
	s_branch .Lpeel_done_984
.LBB0_984:
	ds_read_b128 v[146:149], v156
	ds_read_b128 v[150:153], v156 offset:1024
	ds_read_b128 v[160:163], v156 offset:2048
	ds_read_b128 v[164:167], v156 offset:3072
	s_add_u32 s0, s42, 0xfffe0080
	s_addc_u32 s1, s43, -1
	s_cmp_eq_u32 s79, 4
	s_cselect_b32 s47, s9, s1
	s_cselect_b32 s46, s31, s0
	s_cselect_b32 s45, s29, s41
	s_cselect_b32 s44, s34, s35
	s_add_i32 m0, s55, 0xc000
	ds_read_b128 v[168:171], v158
	ds_read_b128 v[172:175], v158 offset:1024
	ds_read_b128 v[176:179], v158 offset:2048
	ds_read_b128 v[180:183], v158 offset:3072
	ds_read_b128 v[188:191], v158 offset:4096
	ds_read_b128 v[194:197], v158 offset:5120
	ds_read_b128 v[198:201], v158 offset:6144
	global_load_lds_dwordx4 v138, s[42:43]
	s_add_i32 m0, s55, 0xe000
	ds_read_b128 v[202:205], v158 offset:7168
	global_load_lds_dwordx4 v140, s[42:43]
	s_waitcnt lgkmcnt(8)
	s_barrier
	s_waitcnt lgkmcnt(0)
	s_setprio 1
	v_mfma_f32_16x16x32_bf16 v[124:127], v[146:149], v[168:171], v[124:127]
	v_mfma_f32_16x16x32_bf16 v[120:123], v[160:163], v[168:171], v[120:123]
	v_mfma_f32_16x16x32_bf16 v[108:111], v[146:149], v[176:179], v[108:111]
	v_mfma_f32_16x16x32_bf16 v[104:107], v[160:163], v[176:179], v[104:107]
	v_mfma_f32_16x16x32_bf16 v[92:95], v[146:149], v[188:191], v[92:95]
	v_mfma_f32_16x16x32_bf16 v[88:91], v[160:163], v[188:191], v[88:91]
	v_mfma_f32_16x16x32_bf16 v[76:79], v[146:149], v[198:201], v[76:79]
	v_mfma_f32_16x16x32_bf16 v[72:75], v[160:163], v[198:201], v[72:75]
	v_mfma_f32_16x16x32_bf16 v[124:127], v[150:153], v[172:175], v[124:127]
	v_mfma_f32_16x16x32_bf16 v[120:123], v[164:167], v[172:175], v[120:123]
	v_mfma_f32_16x16x32_bf16 v[108:111], v[150:153], v[180:183], v[108:111]
	v_mfma_f32_16x16x32_bf16 v[104:107], v[164:167], v[180:183], v[104:107]
	v_mfma_f32_16x16x32_bf16 v[92:95], v[150:153], v[194:197], v[92:95]
	v_mfma_f32_16x16x32_bf16 v[88:91], v[164:167], v[194:197], v[88:91]
	v_mfma_f32_16x16x32_bf16 v[76:79], v[150:153], v[202:205], v[76:79]
	v_mfma_f32_16x16x32_bf16 v[72:75], v[164:167], v[202:205], v[72:75]
	s_setprio 0
	s_barrier
	s_add_i32 s0, s66, s50
	s_mov_b32 m0, s0
	ds_read_b128 v[206:209], v159
	ds_read_b128 v[210:213], v159 offset:1024
	ds_read_b128 v[214:217], v159 offset:2048
	global_load_lds_dwordx4 v130, s[44:45]
	s_add_i32 m0, s0, 0x2000
	ds_read_b128 v[218:221], v159 offset:3072
	global_load_lds_dwordx4 v134, s[44:45]
	s_barrier
; #define PG8_STAGE(bufoff, gbase, voff) do { _Pragma("unroll") for (int _i = 0; _i < 2; ++_i) \
;         __builtin_amdgcn_global_load_lds((const unsigned*)((const char*)(gbase) + (voff)[_i]), (LAS unsigned*)(lds + (bufoff) + ldsw + _i * 8192), 16, 0, 0); } while (0)
; #define PG8_LDA(dst, b, h) do { _Pragma("unroll") for (int m = 0; m < 4; ++m) _Pragma("unroll") for (int k = 0; k < 2; ++k) dst[m][k] = *(const LAS bf16x8*)(lds + PG8_SA(b, h) + aoff + m * 2048 + k * 1024); } while (0)
; #define PG8_LDB(dst, b, h) do { _Pragma("unroll") for (int n = 0; n < 2; ++n) _Pragma("unroll") for (int k = 0; k < 2; ++k) dst[n][k] = *(const LAS bf16x8*)(lds + PG8_SB(b, h) + boff + n * 2048 + k * 1024); } while (0)
; #define PG8_MMA(ai, bj, At, Bt) do { __builtin_amdgcn_s_setprio(1); _Pragma("unroll") for (int m = 0; m < 4; ++m) _Pragma("unroll") for (int n = 0; n < 2; ++n) _Pragma("unroll") for (int k = 0; k < 2; ++k) \
;         acc[ai][bj][m][n] = __builtin_amdgcn_mfma_f32_16x16x32_bf16(Bt[n][k], At[m][k], acc[ai][bj][m][n], 0, 0, 0); __builtin_amdgcn_s_setprio(0); } while (0)
; #define PG8_WAIT_V(n) asm volatile("s_waitcnt vmcnt(" #n ")" ::: "memory")
; #define PG8_WAIT_L(n) asm volatile("s_waitcnt lgkmcnt(" #n ")" ::: "memory")
; #define PG8_BAR __builtin_amdgcn_s_barrier()
; #define PG8_SCHED __builtin_amdgcn_sched_barrier(0)
; template <class Epi, class Sched>
; DI void gemm_phase(LAS unsigned char* lds, const Gemm g, const Sched& S, const Epi& E) {
;     ...
;             PG8_BAR; PG8_WAIT_L(0); PG8_MMA(0, 1, At, B1); PG8_BAR;
;             PG8_LDA(At, 0, 1); PG8_STAGE(PG8_SA(0, 0), a2, voffA);
;             PG8_BAR; PG8_WAIT_L(0); PG8_MMA(1, 0, At, B0); PG8_BAR; PG8_SCHED;
;             PG8_STAGE(PG8_SB(0, 1), b2 + hstep, voffB);
;             PG8_WAIT_V(6); PG8_BAR; PG8_MMA(1, 1, At, B1); PG8_BAR;
;             PG8_LDB(B0, 1, 0); PG8_SCHED; PG8_LDA(At, 1, 0); PG8_STAGE(PG8_SA(0, 1), a2 + hstep, voffA);
	s_waitcnt lgkmcnt(0)
	s_setprio 1
	v_mfma_f32_16x16x32_bf16 v[116:119], v[206:209], v[168:171], v[116:119]
	v_mfma_f32_16x16x32_bf16 v[112:115], v[214:217], v[168:171], v[112:115]
	v_mfma_f32_16x16x32_bf16 v[100:103], v[206:209], v[176:179], v[100:103]
	v_mfma_f32_16x16x32_bf16 v[96:99], v[214:217], v[176:179], v[96:99]
	v_mfma_f32_16x16x32_bf16 v[84:87], v[206:209], v[188:191], v[84:87]
	v_mfma_f32_16x16x32_bf16 v[80:83], v[214:217], v[188:191], v[80:83]
	v_mfma_f32_16x16x32_bf16 v[68:71], v[206:209], v[198:201], v[68:71]
	v_mfma_f32_16x16x32_bf16 v[64:67], v[214:217], v[198:201], v[64:67]
	v_mfma_f32_16x16x32_bf16 v[116:119], v[210:213], v[172:175], v[116:119]
	v_mfma_f32_16x16x32_bf16 v[112:115], v[218:221], v[172:175], v[112:115]
	v_mfma_f32_16x16x32_bf16 v[100:103], v[210:213], v[180:183], v[100:103]
	v_mfma_f32_16x16x32_bf16 v[96:99], v[218:221], v[180:183], v[96:99]
	v_mfma_f32_16x16x32_bf16 v[84:87], v[210:213], v[194:197], v[84:87]
	v_mfma_f32_16x16x32_bf16 v[80:83], v[218:221], v[194:197], v[80:83]
	v_mfma_f32_16x16x32_bf16 v[68:71], v[210:213], v[202:205], v[68:71]
	v_mfma_f32_16x16x32_bf16 v[64:67], v[218:221], v[202:205], v[64:67]
	s_setprio 0
	s_mov_b32 m0, s55
	s_barrier
	ds_read_b128 v[168:171], v158 offset:16384
	ds_read_b128 v[172:175], v158 offset:17408
	ds_read_b128 v[176:179], v158 offset:18432
	ds_read_b128 v[180:183], v158 offset:19456
	ds_read_b128 v[188:191], v158 offset:20480
	ds_read_b128 v[194:197], v158 offset:21504
	ds_read_b128 v[198:201], v158 offset:22528
	global_load_lds_dwordx4 v128, s[46:47]
	s_mov_b32 m0, s56
	ds_read_b128 v[202:205], v158 offset:23552
	global_load_lds_dwordx4 v132, s[46:47]
	s_barrier
	s_waitcnt lgkmcnt(0)
	s_setprio 1
	v_mfma_f32_16x16x32_bf16 v[60:63], v[146:149], v[168:171], v[60:63]
	v_mfma_f32_16x16x32_bf16 v[56:59], v[160:163], v[168:171], v[56:59]
	v_mfma_f32_16x16x32_bf16 v[44:47], v[146:149], v[176:179], v[44:47]
	v_mfma_f32_16x16x32_bf16 v[40:43], v[160:163], v[176:179], v[40:43]
	v_mfma_f32_16x16x32_bf16 v[28:31], v[146:149], v[188:191], v[28:31]
	v_mfma_f32_16x16x32_bf16 v[24:27], v[160:163], v[188:191], v[24:27]
	v_mfma_f32_16x16x32_bf16 v[12:15], v[146:149], v[198:201], v[12:15]
	v_mfma_f32_16x16x32_bf16 v[8:11], v[160:163], v[198:201], v[8:11]
	v_mfma_f32_16x16x32_bf16 v[60:63], v[150:153], v[172:175], v[60:63]
	v_mfma_f32_16x16x32_bf16 v[56:59], v[164:167], v[172:175], v[56:59]
	v_mfma_f32_16x16x32_bf16 v[44:47], v[150:153], v[180:183], v[44:47]
	v_mfma_f32_16x16x32_bf16 v[40:43], v[164:167], v[180:183], v[40:43]
	v_mfma_f32_16x16x32_bf16 v[28:31], v[150:153], v[194:197], v[28:31]
	v_mfma_f32_16x16x32_bf16 v[24:27], v[164:167], v[194:197], v[24:27]
	v_mfma_f32_16x16x32_bf16 v[12:15], v[150:153], v[202:205], v[12:15]
	v_mfma_f32_16x16x32_bf16 v[8:11], v[164:167], v[202:205], v[8:11]
	s_setprio 0
	s_barrier
	s_add_i32 s4, s67, s50
	s_mov_b32 m0, s4
	s_add_u32 s0, s44, 0x20000
	s_addc_u32 s1, s45, 0
	global_load_lds_dwordx4 v130, s[0:1]
	s_add_i32 m0, s4, 0x2000
	s_nop 0
	global_load_lds_dwordx4 v134, s[0:1]
	s_waitcnt vmcnt(6)
	s_barrier
	s_setprio 1
	v_mfma_f32_16x16x32_bf16 v[52:55], v[206:209], v[168:171], v[52:55]
	v_mfma_f32_16x16x32_bf16 v[48:51], v[214:217], v[168:171], v[48:51]
	v_mfma_f32_16x16x32_bf16 v[36:39], v[206:209], v[176:179], v[36:39]
	v_mfma_f32_16x16x32_bf16 v[32:35], v[214:217], v[176:179], v[32:35]
	v_mfma_f32_16x16x32_bf16 v[20:23], v[206:209], v[188:191], v[20:23]
	v_mfma_f32_16x16x32_bf16 v[16:19], v[214:217], v[188:191], v[16:19]
	v_mfma_f32_16x16x32_bf16 v[4:7], v[206:209], v[198:201], v[4:7]
	v_mfma_f32_16x16x32_bf16 v[0:3], v[214:217], v[198:201], v[0:3]
	v_mfma_f32_16x16x32_bf16 v[52:55], v[210:213], v[172:175], v[52:55]
	v_mfma_f32_16x16x32_bf16 v[48:51], v[218:221], v[172:175], v[48:51]
	v_mfma_f32_16x16x32_bf16 v[36:39], v[210:213], v[180:183], v[36:39]
	v_mfma_f32_16x16x32_bf16 v[32:35], v[218:221], v[180:183], v[32:35]
	v_mfma_f32_16x16x32_bf16 v[20:23], v[210:213], v[194:197], v[20:23]
	v_mfma_f32_16x16x32_bf16 v[16:19], v[218:221], v[194:197], v[16:19]
	v_mfma_f32_16x16x32_bf16 v[4:7], v[210:213], v[202:205], v[4:7]
	v_mfma_f32_16x16x32_bf16 v[0:3], v[218:221], v[202:205], v[0:3]
	s_setprio 0
	s_add_i32 s4, 0, 0x18000
	s_barrier
	ds_read_b128 v[146:149], v222
	ds_read_b128 v[150:153], v222 offset:1024
	ds_read_b128 v[160:163], v222 offset:2048
	ds_read_b128 v[164:167], v222 offset:3072
	s_add_u32 s0, s46, 0x20000
	s_addc_u32 s1, s47, 0
	s_mov_b32 m0, s57
	ds_read_b128 v[168:171], v158 offset:32768
	ds_read_b128 v[172:175], v158 offset:33792
	ds_read_b128 v[176:179], v158 offset:34816
	ds_read_b128 v[180:183], v158 offset:35840
	ds_read_b128 v[188:191], v158 offset:36864
	ds_read_b128 v[194:197], v158 offset:37888
	ds_read_b128 v[198:201], v158 offset:38912
	global_load_lds_dwordx4 v128, s[0:1]
	s_mov_b32 m0, s58
	ds_read_b128 v[202:205], v158 offset:39936
	global_load_lds_dwordx4 v132, s[0:1]
	s_waitcnt lgkmcnt(8)
	s_barrier
; #define PG8_STAGE(bufoff, gbase, voff) do { _Pragma("unroll") for (int _i = 0; _i < 2; ++_i) \
;         __builtin_amdgcn_global_load_lds((const unsigned*)((const char*)(gbase) + (voff)[_i]), (LAS unsigned*)(lds + (bufoff) + ldsw + _i * 8192), 16, 0, 0); } while (0)
; #define PG8_LDA(dst, b, h) do { _Pragma("unroll") for (int m = 0; m < 4; ++m) _Pragma("unroll") for (int k = 0; k < 2; ++k) dst[m][k] = *(const LAS bf16x8*)(lds + PG8_SA(b, h) + aoff + m * 2048 + k * 1024); } while (0)
; #define PG8_LDB(dst, b, h) do { _Pragma("unroll") for (int n = 0; n < 2; ++n) _Pragma("unroll") for (int k = 0; k < 2; ++k) dst[n][k] = *(const LAS bf16x8*)(lds + PG8_SB(b, h) + boff + n * 2048 + k * 1024); } while (0)
; #define PG8_MMA(ai, bj, At, Bt) do { __builtin_amdgcn_s_setprio(1); _Pragma("unroll") for (int m = 0; m < 4; ++m) _Pragma("unroll") for (int n = 0; n < 2; ++n) _Pragma("unroll") for (int k = 0; k < 2; ++k) \
;         acc[ai][bj][m][n] = __builtin_amdgcn_mfma_f32_16x16x32_bf16(Bt[n][k], At[m][k], acc[ai][bj][m][n], 0, 0, 0); __builtin_amdgcn_s_setprio(0); } while (0)
; #define PG8_WAIT_V(n) asm volatile("s_waitcnt vmcnt(" #n ")" ::: "memory")
; #define PG8_WAIT_L(n) asm volatile("s_waitcnt lgkmcnt(" #n ")" ::: "memory")
; #define PG8_BAR __builtin_amdgcn_s_barrier()
; #define PG8_SCHED __builtin_amdgcn_sched_barrier(0)
; template <class Epi, class Sched>
; DI void gemm_phase(LAS unsigned char* lds, const Gemm g, const Sched& S, const Epi& E) {
;     ...
;             PG8_WAIT_L(8); PG8_BAR; PG8_WAIT_L(0); PG8_MMA(0, 0, At, B0); PG8_BAR; PG8_SCHED;
;             PG8_LDB(B1, 1, 1); PG8_STAGE(PG8_SB(1, 0), b3, voffB);
;             PG8_BAR; PG8_WAIT_L(0); PG8_MMA(0, 1, At, B1); PG8_BAR;
;             PG8_LDA(At, 1, 1); PG8_STAGE(PG8_SA(1, 0), a3, voffA);
;             PG8_BAR; PG8_WAIT_L(0); PG8_MMA(1, 0, At, B0); PG8_BAR; PG8_SCHED;
;             PG8_STAGE(PG8_SB(1, 1), b3 + hstep, voffB);
;             PG8_WAIT_V(6); PG8_BAR; PG8_MMA(1, 1, At, B1); PG8_BAR;
	s_waitcnt lgkmcnt(0)
	s_setprio 1
	v_mfma_f32_16x16x32_bf16 v[124:127], v[146:149], v[168:171], v[124:127]
	v_mfma_f32_16x16x32_bf16 v[120:123], v[160:163], v[168:171], v[120:123]
	v_mfma_f32_16x16x32_bf16 v[108:111], v[146:149], v[176:179], v[108:111]
	v_mfma_f32_16x16x32_bf16 v[104:107], v[160:163], v[176:179], v[104:107]
	v_mfma_f32_16x16x32_bf16 v[92:95], v[146:149], v[188:191], v[92:95]
	v_mfma_f32_16x16x32_bf16 v[88:91], v[160:163], v[188:191], v[88:91]
	v_mfma_f32_16x16x32_bf16 v[76:79], v[146:149], v[198:201], v[76:79]
	v_mfma_f32_16x16x32_bf16 v[72:75], v[160:163], v[198:201], v[72:75]
	v_mfma_f32_16x16x32_bf16 v[124:127], v[150:153], v[172:175], v[124:127]
	v_mfma_f32_16x16x32_bf16 v[120:123], v[164:167], v[172:175], v[120:123]
	v_mfma_f32_16x16x32_bf16 v[108:111], v[150:153], v[180:183], v[108:111]
	v_mfma_f32_16x16x32_bf16 v[104:107], v[164:167], v[180:183], v[104:107]
	v_mfma_f32_16x16x32_bf16 v[92:95], v[150:153], v[194:197], v[92:95]
	v_mfma_f32_16x16x32_bf16 v[88:91], v[164:167], v[194:197], v[88:91]
	v_mfma_f32_16x16x32_bf16 v[76:79], v[150:153], v[202:205], v[76:79]
	v_mfma_f32_16x16x32_bf16 v[72:75], v[164:167], v[202:205], v[72:75]
	s_setprio 0
	s_barrier
	s_add_i32 s5, 0, 0x1c000
	s_add_i32 s0, s4, s50
	s_add_i32 m0, s0, 0xffffff80
	ds_read_b128 v[206:209], v223
	ds_read_b128 v[210:213], v223 offset:1024
	ds_read_b128 v[214:217], v223 offset:2048
	global_load_lds_dwordx4 v130, s[44:45] offset:128
	s_add_i32 m0, s0, 0x1f80
	ds_read_b128 v[218:221], v223 offset:3072
	global_load_lds_dwordx4 v134, s[44:45] offset:128
	s_barrier
	s_waitcnt lgkmcnt(0)
	s_setprio 1
	v_mfma_f32_16x16x32_bf16 v[116:119], v[206:209], v[168:171], v[116:119]
	v_mfma_f32_16x16x32_bf16 v[112:115], v[214:217], v[168:171], v[112:115]
	v_mfma_f32_16x16x32_bf16 v[100:103], v[206:209], v[176:179], v[100:103]
	v_mfma_f32_16x16x32_bf16 v[96:99], v[214:217], v[176:179], v[96:99]
	v_mfma_f32_16x16x32_bf16 v[84:87], v[206:209], v[188:191], v[84:87]
	v_mfma_f32_16x16x32_bf16 v[80:83], v[214:217], v[188:191], v[80:83]
	v_mfma_f32_16x16x32_bf16 v[68:71], v[206:209], v[198:201], v[68:71]
	v_mfma_f32_16x16x32_bf16 v[64:67], v[214:217], v[198:201], v[64:67]
	v_mfma_f32_16x16x32_bf16 v[116:119], v[210:213], v[172:175], v[116:119]
	v_mfma_f32_16x16x32_bf16 v[112:115], v[218:221], v[172:175], v[112:115]
	v_mfma_f32_16x16x32_bf16 v[100:103], v[210:213], v[180:183], v[100:103]
	v_mfma_f32_16x16x32_bf16 v[96:99], v[218:221], v[180:183], v[96:99]
	v_mfma_f32_16x16x32_bf16 v[84:87], v[210:213], v[194:197], v[84:87]
	v_mfma_f32_16x16x32_bf16 v[80:83], v[218:221], v[194:197], v[80:83]
	v_mfma_f32_16x16x32_bf16 v[68:71], v[210:213], v[202:205], v[68:71]
	v_mfma_f32_16x16x32_bf16 v[64:67], v[218:221], v[202:205], v[64:67]
	s_setprio 0
	s_add_i32 m0, s62, 0xffffff80
	s_barrier
	ds_read_b128 v[168:171], v158 offset:49152
	ds_read_b128 v[172:175], v158 offset:50176
	ds_read_b128 v[176:179], v158 offset:51200
	ds_read_b128 v[180:183], v158 offset:52224
	ds_read_b128 v[188:191], v158 offset:53248
	ds_read_b128 v[194:197], v158 offset:54272
	ds_read_b128 v[198:201], v158 offset:55296
	global_load_lds_dwordx4 v128, s[46:47] offset:128
	s_add_i32 m0, s63, 0xffffff80
	ds_read_b128 v[202:205], v158 offset:56320
	global_load_lds_dwordx4 v132, s[46:47] offset:128
	s_barrier
	s_waitcnt lgkmcnt(0)
	s_setprio 1
	v_mfma_f32_16x16x32_bf16 v[60:63], v[146:149], v[168:171], v[60:63]
	v_mfma_f32_16x16x32_bf16 v[56:59], v[160:163], v[168:171], v[56:59]
	v_mfma_f32_16x16x32_bf16 v[44:47], v[146:149], v[176:179], v[44:47]
	v_mfma_f32_16x16x32_bf16 v[40:43], v[160:163], v[176:179], v[40:43]
	v_mfma_f32_16x16x32_bf16 v[28:31], v[146:149], v[188:191], v[28:31]
	v_mfma_f32_16x16x32_bf16 v[24:27], v[160:163], v[188:191], v[24:27]
	v_mfma_f32_16x16x32_bf16 v[12:15], v[146:149], v[198:201], v[12:15]
	v_mfma_f32_16x16x32_bf16 v[8:11], v[160:163], v[198:201], v[8:11]
	v_mfma_f32_16x16x32_bf16 v[60:63], v[150:153], v[172:175], v[60:63]
	v_mfma_f32_16x16x32_bf16 v[56:59], v[164:167], v[172:175], v[56:59]
	v_mfma_f32_16x16x32_bf16 v[44:47], v[150:153], v[180:183], v[44:47]
	v_mfma_f32_16x16x32_bf16 v[40:43], v[164:167], v[180:183], v[40:43]
	v_mfma_f32_16x16x32_bf16 v[28:31], v[150:153], v[194:197], v[28:31]
	v_mfma_f32_16x16x32_bf16 v[24:27], v[164:167], v[194:197], v[24:27]
	v_mfma_f32_16x16x32_bf16 v[12:15], v[150:153], v[202:205], v[12:15]
	v_mfma_f32_16x16x32_bf16 v[8:11], v[164:167], v[202:205], v[8:11]
	s_setprio 0
	s_barrier
	s_add_i32 s4, s5, s50
	s_mov_b32 m0, s4
	s_add_u32 s0, s44, 0x20080
	s_addc_u32 s1, s45, 0
	global_load_lds_dwordx4 v130, s[0:1]
	v_lshl_add_u64 v[146:147], s[0:1], 0, v[134:135]
	s_add_i32 m0, s4, 0x2000
	s_nop 0
	global_load_lds_dwordx4 v134, s[0:1]
	s_waitcnt vmcnt(6)
	s_barrier
	s_setprio 1
	v_mfma_f32_16x16x32_bf16 v[52:55], v[206:209], v[168:171], v[52:55]
	v_mfma_f32_16x16x32_bf16 v[48:51], v[214:217], v[168:171], v[48:51]
	v_mfma_f32_16x16x32_bf16 v[36:39], v[206:209], v[176:179], v[36:39]
	v_mfma_f32_16x16x32_bf16 v[32:35], v[214:217], v[176:179], v[32:35]
	v_mfma_f32_16x16x32_bf16 v[20:23], v[206:209], v[188:191], v[20:23]
	v_mfma_f32_16x16x32_bf16 v[16:19], v[214:217], v[188:191], v[16:19]
	v_mfma_f32_16x16x32_bf16 v[4:7], v[206:209], v[198:201], v[4:7]
	v_mfma_f32_16x16x32_bf16 v[0:3], v[214:217], v[198:201], v[0:3]
	v_mfma_f32_16x16x32_bf16 v[52:55], v[210:213], v[172:175], v[52:55]
	v_mfma_f32_16x16x32_bf16 v[48:51], v[218:221], v[172:175], v[48:51]
	v_mfma_f32_16x16x32_bf16 v[36:39], v[210:213], v[180:183], v[36:39]
	v_mfma_f32_16x16x32_bf16 v[32:35], v[218:221], v[180:183], v[32:35]
	v_mfma_f32_16x16x32_bf16 v[20:23], v[210:213], v[194:197], v[20:23]
	v_mfma_f32_16x16x32_bf16 v[16:19], v[218:221], v[194:197], v[16:19]
	v_mfma_f32_16x16x32_bf16 v[4:7], v[210:213], v[202:205], v[4:7]
	v_mfma_f32_16x16x32_bf16 v[0:3], v[218:221], v[202:205], v[0:3]
	s_setprio 0
	s_add_i32 s79, s79, 2
	s_add_u32 s42, s42, 0x100
	s_addc_u32 s43, s43, 0
	s_add_u32 s35, s35, 0x100
	s_addc_u32 s41, s41, 0
	s_cmp_gt_u32 s79, 5
	s_barrier
	s_cbranch_scc0 .LBB0_984

; #define PG8_STAGE(bufoff, gbase, voff) do { _Pragma("unroll") for (int _i = 0; _i < 2; ++_i) \
;         __builtin_amdgcn_global_load_lds((const unsigned*)((const char*)(gbase) + (voff)[_i]), (LAS unsigned*)(lds + (bufoff) + ldsw + _i * 8192), 16, 0, 0); } while (0)
; #define PG8_LDA(dst, b, h) do { _Pragma("unroll") for (int m = 0; m < 4; ++m) _Pragma("unroll") for (int k = 0; k < 2; ++k) dst[m][k] = *(const LAS bf16x8*)(lds + PG8_SA(b, h) + aoff + m * 2048 + k * 1024); } while (0)
; #define PG8_LDB(dst, b, h) do { _Pragma("unroll") for (int n = 0; n < 2; ++n) _Pragma("unroll") for (int k = 0; k < 2; ++k) dst[n][k] = *(const LAS bf16x8*)(lds + PG8_SB(b, h) + boff + n * 2048 + k * 1024); } while (0)
; #define PG8_MMA(ai, bj, At, Bt) do { __builtin_amdgcn_s_setprio(1); _Pragma("unroll") for (int m = 0; m < 4; ++m) _Pragma("unroll") for (int n = 0; n < 2; ++n) _Pragma("unroll") for (int k = 0; k < 2; ++k) \
;         acc[ai][bj][m][n] = __builtin_amdgcn_mfma_f32_16x16x32_bf16(Bt[n][k], At[m][k], acc[ai][bj][m][n], 0, 0, 0); __builtin_amdgcn_s_setprio(0); } while (0)
; #define PG8_WAIT_V(n) asm volatile("s_waitcnt vmcnt(" #n ")" ::: "memory")
; #define PG8_WAIT_L(n) asm volatile("s_waitcnt lgkmcnt(" #n ")" ::: "memory")
; #define PG8_BAR __builtin_amdgcn_s_barrier()
; #define PG8_SCHED __builtin_amdgcn_sched_barrier(0)
; template <class Epi, class Sched>
; DI void gemm_phase(LAS unsigned char* lds, const Gemm g, const Sched& S, const Epi& E) {
;     ...
;             const char* a1 = cA + (size_t)(t + 1) * kstep;
;             const char* a2 = last ? nA : cA + (size_t)(t + 2) * kstep; const char* b2 = last ? nB : cB + (size_t)(t + 2) * kstep;
;             const char* a3 = a2 + kstep; const char* b3 = b2 + kstep;
;             PG8_LDB(B0, 0, 0); PG8_SCHED; PG8_LDA(At, 0, 0); PG8_STAGE(PG8_SA(1, 1), a1 + hstep, voffA);
;             PG8_WAIT_L(8); PG8_BAR; PG8_WAIT_L(0); PG8_MMA(0, 0, At, B0); PG8_BAR; PG8_SCHED;
;             PG8_LDB(B1, 0, 1); PG8_STAGE(PG8_SB(0, 0), b2, voffB);
;             PG8_BAR; PG8_WAIT_L(0); PG8_MMA(0, 1, At, B1); PG8_BAR;
;             PG8_LDA(At, 0, 1); PG8_STAGE(PG8_SA(0, 0), a2, voffA);
;             PG8_BAR; PG8_WAIT_L(0); PG8_MMA(1, 0, At, B0); PG8_BAR; PG8_SCHED;
;             PG8_STAGE(PG8_SB(0, 1), b2 + hstep, voffB);
;             PG8_WAIT_V(6); PG8_BAR; PG8_MMA(1, 1, At, B1); PG8_BAR;
.LBB0_1347:
	v_add_u32_e32 v1, s63, v202
	s_add_u32 s0, s40, s44
	ds_read_b128 v[132:135], v1
	ds_read_b128 v[136:139], v1 offset:1024
	ds_read_b128 v[140:143], v1 offset:2048
	ds_read_b128 v[144:147], v1 offset:3072
	s_addc_u32 s1, s41, s45
	s_add_u32 s0, s0, 0x100
	s_addc_u32 s1, s1, 0
	s_add_u32 s4, s79, s44
	s_addc_u32 s5, s80, s45
	s_cmpk_eq_i32 s44, 0xf00
	s_cselect_b32 s49, s70, s1
	s_cselect_b32 s48, s71, s0
	s_cselect_b32 s47, s37, s5
	s_cselect_b32 s46, s36, s4
	v_lshl_add_u64 v[2:3], v[188:189], 0, s[44:45]
	s_add_i32 m0, s53, 0xc000
	ds_read_b128 v[148:151], v203
	ds_read_b128 v[152:155], v203 offset:1024
	ds_read_b128 v[156:159], v203 offset:2048
	ds_read_b128 v[160:163], v203 offset:3072
	ds_read_b128 v[164:167], v203 offset:4096
	ds_read_b128 v[208:211], v203 offset:5120
	ds_read_b128 v[212:215], v203 offset:6144
	ds_read_b128 v[216:219], v203 offset:7168
	global_load_lds_dwordx4 v[2:3], off
	v_lshl_add_u64 v[2:3], v[190:191], 0, s[44:45]
	s_add_i32 m0, s53, 0xe000
	s_nop 0
	global_load_lds_dwordx4 v[2:3], off
	s_waitcnt lgkmcnt(8)
	s_barrier
	s_waitcnt lgkmcnt(0)
	s_setprio 1
	v_mfma_f32_16x16x32_bf16 v[128:131], v[132:135], v[148:151], v[128:131]
	v_mfma_f32_16x16x32_bf16 v[124:127], v[140:143], v[148:151], v[124:127]
	v_mfma_f32_16x16x32_bf16 v[112:115], v[132:135], v[156:159], v[112:115]
	v_mfma_f32_16x16x32_bf16 v[108:111], v[140:143], v[156:159], v[108:111]
	v_mfma_f32_16x16x32_bf16 v[96:99], v[132:135], v[164:167], v[96:99]
	v_mfma_f32_16x16x32_bf16 v[92:95], v[140:143], v[164:167], v[92:95]
	v_mfma_f32_16x16x32_bf16 v[80:83], v[132:135], v[212:215], v[80:83]
	v_mfma_f32_16x16x32_bf16 v[76:79], v[140:143], v[212:215], v[76:79]
	v_mfma_f32_16x16x32_bf16 v[128:131], v[136:139], v[152:155], v[128:131]
	v_mfma_f32_16x16x32_bf16 v[124:127], v[144:147], v[152:155], v[124:127]
	v_mfma_f32_16x16x32_bf16 v[112:115], v[136:139], v[160:163], v[112:115]
	v_mfma_f32_16x16x32_bf16 v[108:111], v[144:147], v[160:163], v[108:111]
	v_mfma_f32_16x16x32_bf16 v[96:99], v[136:139], v[208:211], v[96:99]
	v_mfma_f32_16x16x32_bf16 v[92:95], v[144:147], v[208:211], v[92:95]
	v_mfma_f32_16x16x32_bf16 v[80:83], v[136:139], v[216:219], v[80:83]
	v_mfma_f32_16x16x32_bf16 v[76:79], v[144:147], v[216:219], v[76:79]
	s_setprio 0
	s_barrier
	s_add_i32 s0, s63, s51
	v_add_u32_e32 v1, s64, v202
	s_mov_b32 m0, s0
	ds_read_b128 v[220:223], v1
	ds_read_b128 v[224:227], v1 offset:1024
	ds_read_b128 v[228:231], v1 offset:2048
	global_load_lds_dwordx4 v172, s[46:47]
	s_add_i32 m0, s0, 0x2000
	ds_read_b128 v[232:235], v1 offset:3072
	global_load_lds_dwordx4 v174, s[46:47]
	s_barrier
	s_waitcnt lgkmcnt(0)
	s_setprio 1
	v_mfma_f32_16x16x32_bf16 v[120:123], v[220:223], v[148:151], v[120:123]
	v_mfma_f32_16x16x32_bf16 v[116:119], v[228:231], v[148:151], v[116:119]
	v_mfma_f32_16x16x32_bf16 v[104:107], v[220:223], v[156:159], v[104:107]
	v_mfma_f32_16x16x32_bf16 v[100:103], v[228:231], v[156:159], v[100:103]
	v_mfma_f32_16x16x32_bf16 v[88:91], v[220:223], v[164:167], v[88:91]
	v_mfma_f32_16x16x32_bf16 v[84:87], v[228:231], v[164:167], v[84:87]
	v_mfma_f32_16x16x32_bf16 v[72:75], v[220:223], v[212:215], v[72:75]
	v_mfma_f32_16x16x32_bf16 v[68:71], v[228:231], v[212:215], v[68:71]
	v_mfma_f32_16x16x32_bf16 v[120:123], v[224:227], v[152:155], v[120:123]
	v_mfma_f32_16x16x32_bf16 v[116:119], v[232:235], v[152:155], v[116:119]
	v_mfma_f32_16x16x32_bf16 v[104:107], v[224:227], v[160:163], v[104:107]
	v_mfma_f32_16x16x32_bf16 v[100:103], v[232:235], v[160:163], v[100:103]
	v_mfma_f32_16x16x32_bf16 v[88:91], v[224:227], v[208:211], v[88:91]
	v_mfma_f32_16x16x32_bf16 v[84:87], v[232:235], v[208:211], v[84:87]
	v_mfma_f32_16x16x32_bf16 v[72:75], v[224:227], v[216:219], v[72:75]
	v_mfma_f32_16x16x32_bf16 v[68:71], v[232:235], v[216:219], v[68:71]
	s_setprio 0
	s_mov_b32 m0, s53
	s_barrier
	ds_read_b128 v[148:151], v203 offset:16384
	ds_read_b128 v[152:155], v203 offset:17408
	ds_read_b128 v[156:159], v203 offset:18432
	ds_read_b128 v[160:163], v203 offset:19456
	ds_read_b128 v[164:167], v203 offset:20480
	ds_read_b128 v[208:211], v203 offset:21504
	ds_read_b128 v[212:215], v203 offset:22528
	global_load_lds_dwordx4 v168, s[48:49]
	s_mov_b32 m0, s54
	ds_read_b128 v[216:219], v203 offset:23552
	global_load_lds_dwordx4 v170, s[48:49]
	s_barrier
	s_waitcnt lgkmcnt(0)
	s_setprio 1
	v_mfma_f32_16x16x32_bf16 v[64:67], v[132:135], v[148:151], v[64:67]
	v_mfma_f32_16x16x32_bf16 v[60:63], v[140:143], v[148:151], v[60:63]
	v_mfma_f32_16x16x32_bf16 v[48:51], v[132:135], v[156:159], v[48:51]
	v_mfma_f32_16x16x32_bf16 v[44:47], v[140:143], v[156:159], v[44:47]
	v_mfma_f32_16x16x32_bf16 v[32:35], v[132:135], v[164:167], v[32:35]
	v_mfma_f32_16x16x32_bf16 v[28:31], v[140:143], v[164:167], v[28:31]
	v_mfma_f32_16x16x32_bf16 v[16:19], v[132:135], v[212:215], v[16:19]
	v_mfma_f32_16x16x32_bf16 v[12:15], v[140:143], v[212:215], v[12:15]
	v_mfma_f32_16x16x32_bf16 v[64:67], v[136:139], v[152:155], v[64:67]
	v_mfma_f32_16x16x32_bf16 v[60:63], v[144:147], v[152:155], v[60:63]
	v_mfma_f32_16x16x32_bf16 v[48:51], v[136:139], v[160:163], v[48:51]
	v_mfma_f32_16x16x32_bf16 v[44:47], v[144:147], v[160:163], v[44:47]
	v_mfma_f32_16x16x32_bf16 v[32:35], v[136:139], v[208:211], v[32:35]
	v_mfma_f32_16x16x32_bf16 v[28:31], v[144:147], v[208:211], v[28:31]
	v_mfma_f32_16x16x32_bf16 v[16:19], v[136:139], v[216:219], v[16:19]
	v_mfma_f32_16x16x32_bf16 v[12:15], v[144:147], v[216:219], v[12:15]
	s_setprio 0
	s_barrier
	s_add_i32 s4, s64, s51
	s_mov_b32 m0, s4
	s_add_u32 s0, s46, 0x80000
	s_addc_u32 s1, s47, 0
	global_load_lds_dwordx4 v172, s[0:1]
	s_add_i32 m0, s4, 0x2000
	s_nop 0
	global_load_lds_dwordx4 v174, s[0:1]
	s_waitcnt vmcnt(6)
	s_barrier
; #define PG8_STAGE(bufoff, gbase, voff) do { _Pragma("unroll") for (int _i = 0; _i < 2; ++_i) \
;         __builtin_amdgcn_global_load_lds((const unsigned*)((const char*)(gbase) + (voff)[_i]), (LAS unsigned*)(lds + (bufoff) + ldsw + _i * 8192), 16, 0, 0); } while (0)
; #define PG8_LDA(dst, b, h) do { _Pragma("unroll") for (int m = 0; m < 4; ++m) _Pragma("unroll") for (int k = 0; k < 2; ++k) dst[m][k] = *(const LAS bf16x8*)(lds + PG8_SA(b, h) + aoff + m * 2048 + k * 1024); } while (0)
; #define PG8_LDB(dst, b, h) do { _Pragma("unroll") for (int n = 0; n < 2; ++n) _Pragma("unroll") for (int k = 0; k < 2; ++k) dst[n][k] = *(const LAS bf16x8*)(lds + PG8_SB(b, h) + boff + n * 2048 + k * 1024); } while (0)
; #define PG8_MMA(ai, bj, At, Bt) do { __builtin_amdgcn_s_setprio(1); _Pragma("unroll") for (int m = 0; m < 4; ++m) _Pragma("unroll") for (int n = 0; n < 2; ++n) _Pragma("unroll") for (int k = 0; k < 2; ++k) \
;         acc[ai][bj][m][n] = __builtin_amdgcn_mfma_f32_16x16x32_bf16(Bt[n][k], At[m][k], acc[ai][bj][m][n], 0, 0, 0); __builtin_amdgcn_s_setprio(0); } while (0)
; #define PG8_WAIT_V(n) asm volatile("s_waitcnt vmcnt(" #n ")" ::: "memory")
; #define PG8_WAIT_L(n) asm volatile("s_waitcnt lgkmcnt(" #n ")" ::: "memory")
; #define PG8_BAR __builtin_amdgcn_s_barrier()
; #define PG8_SCHED __builtin_amdgcn_sched_barrier(0)
; template <class Epi, class Sched>
; DI void gemm_phase(LAS unsigned char* lds, const Gemm g, const Sched& S, const Epi& E) {
;     ...
;             PG8_WAIT_V(6); PG8_BAR; PG8_MMA(1, 1, At, B1); PG8_BAR;
;             PG8_LDB(B0, 1, 0); PG8_SCHED; PG8_LDA(At, 1, 0); PG8_STAGE(PG8_SA(0, 1), a2 + hstep, voffA);
;             PG8_WAIT_L(8); PG8_BAR; PG8_WAIT_L(0); PG8_MMA(0, 0, At, B0); PG8_BAR; PG8_SCHED;
;             PG8_LDB(B1, 1, 1); PG8_STAGE(PG8_SB(1, 0), b3, voffB);
	s_setprio 1
	v_mfma_f32_16x16x32_bf16 v[56:59], v[220:223], v[148:151], v[56:59]
	v_mfma_f32_16x16x32_bf16 v[52:55], v[228:231], v[148:151], v[52:55]
	v_mfma_f32_16x16x32_bf16 v[40:43], v[220:223], v[156:159], v[40:43]
	v_mfma_f32_16x16x32_bf16 v[36:39], v[228:231], v[156:159], v[36:39]
	v_mfma_f32_16x16x32_bf16 v[24:27], v[220:223], v[164:167], v[24:27]
	v_mfma_f32_16x16x32_bf16 v[20:23], v[228:231], v[164:167], v[20:23]
	v_mfma_f32_16x16x32_bf16 v[8:11], v[220:223], v[212:215], v[8:11]
	v_mfma_f32_16x16x32_bf16 v[2:5], v[228:231], v[212:215], v[4:7]
	v_mfma_f32_16x16x32_bf16 v[56:59], v[224:227], v[152:155], v[56:59]
	v_mfma_f32_16x16x32_bf16 v[52:55], v[232:235], v[152:155], v[52:55]
	v_mfma_f32_16x16x32_bf16 v[40:43], v[224:227], v[160:163], v[40:43]
	v_mfma_f32_16x16x32_bf16 v[36:39], v[232:235], v[160:163], v[36:39]
	v_mfma_f32_16x16x32_bf16 v[24:27], v[224:227], v[208:211], v[24:27]
	v_mfma_f32_16x16x32_bf16 v[20:23], v[232:235], v[208:211], v[20:23]
	v_mfma_f32_16x16x32_bf16 v[8:11], v[224:227], v[216:219], v[8:11]
	v_mfma_f32_16x16x32_bf16 v[2:5], v[232:235], v[216:219], v[2:5]
	s_setprio 0
	s_add_i32 s4, 0, 0x18000
	v_add_u32_e32 v1, s4, v202
	s_barrier
	ds_read_b128 v[132:135], v1
	ds_read_b128 v[136:139], v1 offset:1024
	ds_read_b128 v[140:143], v1 offset:2048
	ds_read_b128 v[144:147], v1 offset:3072
	s_add_u32 s0, s48, 0x80000
	s_addc_u32 s1, s49, 0
	s_mov_b32 m0, s55
	ds_read_b128 v[148:151], v203 offset:32768
	ds_read_b128 v[152:155], v203 offset:33792
	ds_read_b128 v[156:159], v203 offset:34816
	ds_read_b128 v[160:163], v203 offset:35840
	ds_read_b128 v[164:167], v203 offset:36864
	ds_read_b128 v[208:211], v203 offset:37888
	ds_read_b128 v[212:215], v203 offset:38912
	global_load_lds_dwordx4 v168, s[0:1]
	s_mov_b32 m0, s56
	ds_read_b128 v[216:219], v203 offset:39936
	global_load_lds_dwordx4 v170, s[0:1]
	s_waitcnt lgkmcnt(8)
	s_barrier
	s_waitcnt lgkmcnt(0)
	s_setprio 1
	v_mfma_f32_16x16x32_bf16 v[128:131], v[132:135], v[148:151], v[128:131]
	v_mfma_f32_16x16x32_bf16 v[124:127], v[140:143], v[148:151], v[124:127]
	v_mfma_f32_16x16x32_bf16 v[112:115], v[132:135], v[156:159], v[112:115]
	v_mfma_f32_16x16x32_bf16 v[108:111], v[140:143], v[156:159], v[108:111]
	v_mfma_f32_16x16x32_bf16 v[96:99], v[132:135], v[164:167], v[96:99]
	v_mfma_f32_16x16x32_bf16 v[92:95], v[140:143], v[164:167], v[92:95]
	v_mfma_f32_16x16x32_bf16 v[80:83], v[132:135], v[212:215], v[80:83]
	v_mfma_f32_16x16x32_bf16 v[76:79], v[140:143], v[212:215], v[76:79]
	v_mfma_f32_16x16x32_bf16 v[128:131], v[136:139], v[152:155], v[128:131]
	v_mfma_f32_16x16x32_bf16 v[124:127], v[144:147], v[152:155], v[124:127]
	v_mfma_f32_16x16x32_bf16 v[112:115], v[136:139], v[160:163], v[112:115]
	v_mfma_f32_16x16x32_bf16 v[108:111], v[144:147], v[160:163], v[108:111]
	v_mfma_f32_16x16x32_bf16 v[96:99], v[136:139], v[208:211], v[96:99]
	v_mfma_f32_16x16x32_bf16 v[92:95], v[144:147], v[208:211], v[92:95]
	v_mfma_f32_16x16x32_bf16 v[80:83], v[136:139], v[216:219], v[80:83]
	v_mfma_f32_16x16x32_bf16 v[76:79], v[144:147], v[216:219], v[76:79]
	s_setprio 0
	s_barrier
	s_add_i32 s5, 0, 0x1c000
	s_add_i32 s0, s4, s51
	v_add_u32_e32 v1, s5, v202
	s_add_i32 m0, s0, 0xffffff80
	ds_read_b128 v[220:223], v1
	ds_read_b128 v[224:227], v1 offset:1024
	ds_read_b128 v[228:231], v1 offset:2048
	global_load_lds_dwordx4 v172, s[46:47] offset:128
	s_add_i32 m0, s0, 0x1f80
	ds_read_b128 v[232:235], v1 offset:3072
	global_load_lds_dwordx4 v174, s[46:47] offset:128
	s_barrier
; #define PG8_STAGE(bufoff, gbase, voff) do { _Pragma("unroll") for (int _i = 0; _i < 2; ++_i) \
;         __builtin_amdgcn_global_load_lds((const unsigned*)((const char*)(gbase) + (voff)[_i]), (LAS unsigned*)(lds + (bufoff) + ldsw + _i * 8192), 16, 0, 0); } while (0)
; #define PG8_LDA(dst, b, h) do { _Pragma("unroll") for (int m = 0; m < 4; ++m) _Pragma("unroll") for (int k = 0; k < 2; ++k) dst[m][k] = *(const LAS bf16x8*)(lds + PG8_SA(b, h) + aoff + m * 2048 + k * 1024); } while (0)
; #define PG8_MMA(ai, bj, At, Bt) do { __builtin_amdgcn_s_setprio(1); _Pragma("unroll") for (int m = 0; m < 4; ++m) _Pragma("unroll") for (int n = 0; n < 2; ++n) _Pragma("unroll") for (int k = 0; k < 2; ++k) \
;         acc[ai][bj][m][n] = __builtin_amdgcn_mfma_f32_16x16x32_bf16(Bt[n][k], At[m][k], acc[ai][bj][m][n], 0, 0, 0); __builtin_amdgcn_s_setprio(0); } while (0)
; #define PG8_WAIT_V(n) asm volatile("s_waitcnt vmcnt(" #n ")" ::: "memory")
; #define PG8_WAIT_L(n) asm volatile("s_waitcnt lgkmcnt(" #n ")" ::: "memory")
; #define PG8_BAR __builtin_amdgcn_s_barrier()
; #define PG8_SCHED __builtin_amdgcn_sched_barrier(0)
; template <class Epi, class Sched>
; DI void gemm_phase(LAS unsigned char* lds, const Gemm g, const Sched& S, const Epi& E) {
;     ...
;             PG8_BAR; PG8_WAIT_L(0); PG8_MMA(0, 1, At, B1); PG8_BAR;
;             PG8_LDA(At, 1, 1); PG8_STAGE(PG8_SA(1, 0), a3, voffA);
;             PG8_BAR; PG8_WAIT_L(0); PG8_MMA(1, 0, At, B0); PG8_BAR; PG8_SCHED;
;             PG8_STAGE(PG8_SB(1, 1), b3 + hstep, voffB);
;             PG8_WAIT_V(6); PG8_BAR; PG8_MMA(1, 1, At, B1); PG8_BAR;
	s_waitcnt lgkmcnt(0)
	s_setprio 1
	v_mfma_f32_16x16x32_bf16 v[120:123], v[220:223], v[148:151], v[120:123]
	v_mfma_f32_16x16x32_bf16 v[116:119], v[228:231], v[148:151], v[116:119]
	v_mfma_f32_16x16x32_bf16 v[104:107], v[220:223], v[156:159], v[104:107]
	v_mfma_f32_16x16x32_bf16 v[100:103], v[228:231], v[156:159], v[100:103]
	v_mfma_f32_16x16x32_bf16 v[88:91], v[220:223], v[164:167], v[88:91]
	v_mfma_f32_16x16x32_bf16 v[84:87], v[228:231], v[164:167], v[84:87]
	v_mfma_f32_16x16x32_bf16 v[72:75], v[220:223], v[212:215], v[72:75]
	v_mfma_f32_16x16x32_bf16 v[68:71], v[228:231], v[212:215], v[68:71]
	v_mfma_f32_16x16x32_bf16 v[120:123], v[224:227], v[152:155], v[120:123]
	v_mfma_f32_16x16x32_bf16 v[116:119], v[232:235], v[152:155], v[116:119]
	v_mfma_f32_16x16x32_bf16 v[104:107], v[224:227], v[160:163], v[104:107]
	v_mfma_f32_16x16x32_bf16 v[100:103], v[232:235], v[160:163], v[100:103]
	v_mfma_f32_16x16x32_bf16 v[88:91], v[224:227], v[208:211], v[88:91]
	v_mfma_f32_16x16x32_bf16 v[84:87], v[232:235], v[208:211], v[84:87]
	v_mfma_f32_16x16x32_bf16 v[72:75], v[224:227], v[216:219], v[72:75]
	v_mfma_f32_16x16x32_bf16 v[68:71], v[232:235], v[216:219], v[68:71]
	s_setprio 0
	s_add_i32 m0, s59, 0xffffff80
	s_barrier
	ds_read_b128 v[148:151], v203 offset:49152
	ds_read_b128 v[152:155], v203 offset:50176
	ds_read_b128 v[156:159], v203 offset:51200
	ds_read_b128 v[160:163], v203 offset:52224
	ds_read_b128 v[164:167], v203 offset:53248
	ds_read_b128 v[208:211], v203 offset:54272
	ds_read_b128 v[212:215], v203 offset:55296
	global_load_lds_dwordx4 v168, s[48:49] offset:128
	s_add_i32 m0, s60, 0xffffff80
	ds_read_b128 v[216:219], v203 offset:56320
	global_load_lds_dwordx4 v170, s[48:49] offset:128
	s_barrier
	s_waitcnt lgkmcnt(0)
	s_setprio 1
	v_mfma_f32_16x16x32_bf16 v[64:67], v[132:135], v[148:151], v[64:67]
	v_mfma_f32_16x16x32_bf16 v[60:63], v[140:143], v[148:151], v[60:63]
	v_mfma_f32_16x16x32_bf16 v[48:51], v[132:135], v[156:159], v[48:51]
	v_mfma_f32_16x16x32_bf16 v[44:47], v[140:143], v[156:159], v[44:47]
	v_mfma_f32_16x16x32_bf16 v[32:35], v[132:135], v[164:167], v[32:35]
	v_mfma_f32_16x16x32_bf16 v[28:31], v[140:143], v[164:167], v[28:31]
	v_mfma_f32_16x16x32_bf16 v[16:19], v[132:135], v[212:215], v[16:19]
	v_mfma_f32_16x16x32_bf16 v[12:15], v[140:143], v[212:215], v[12:15]
	v_mfma_f32_16x16x32_bf16 v[64:67], v[136:139], v[152:155], v[64:67]
	v_mfma_f32_16x16x32_bf16 v[60:63], v[144:147], v[152:155], v[60:63]
	v_mfma_f32_16x16x32_bf16 v[48:51], v[136:139], v[160:163], v[48:51]
	v_mfma_f32_16x16x32_bf16 v[44:47], v[144:147], v[160:163], v[44:47]
	v_mfma_f32_16x16x32_bf16 v[32:35], v[136:139], v[208:211], v[32:35]
	v_mfma_f32_16x16x32_bf16 v[28:31], v[144:147], v[208:211], v[28:31]
	v_mfma_f32_16x16x32_bf16 v[16:19], v[136:139], v[216:219], v[16:19]
	v_mfma_f32_16x16x32_bf16 v[12:15], v[144:147], v[216:219], v[12:15]
	s_setprio 0
	s_barrier
	s_add_i32 s4, s5, s51
	s_mov_b32 m0, s4
	s_add_u32 s0, s46, 0x80080
	s_addc_u32 s1, s47, 0
	global_load_lds_dwordx4 v172, s[0:1]
	s_add_i32 m0, s4, 0x2000
	s_nop 0
	global_load_lds_dwordx4 v174, s[0:1]
	s_waitcnt vmcnt(6)
	s_barrier
	s_setprio 1
	v_mfma_f32_16x16x32_bf16 v[56:59], v[220:223], v[148:151], v[56:59]
	v_mfma_f32_16x16x32_bf16 v[52:55], v[228:231], v[148:151], v[52:55]
	v_mfma_f32_16x16x32_bf16 v[40:43], v[220:223], v[156:159], v[40:43]
	v_mfma_f32_16x16x32_bf16 v[36:39], v[228:231], v[156:159], v[36:39]
	v_mfma_f32_16x16x32_bf16 v[24:27], v[220:223], v[164:167], v[24:27]
	v_mfma_f32_16x16x32_bf16 v[20:23], v[228:231], v[164:167], v[20:23]
	v_mfma_f32_16x16x32_bf16 v[6:9], v[220:223], v[212:215], v[8:11]
	v_mfma_f32_16x16x32_bf16 v[2:5], v[228:231], v[212:215], v[2:5]
	v_mfma_f32_16x16x32_bf16 v[56:59], v[224:227], v[152:155], v[56:59]
	v_mfma_f32_16x16x32_bf16 v[52:55], v[232:235], v[152:155], v[52:55]
	v_mfma_f32_16x16x32_bf16 v[40:43], v[224:227], v[160:163], v[40:43]
	v_mfma_f32_16x16x32_bf16 v[36:39], v[232:235], v[160:163], v[36:39]
	v_mfma_f32_16x16x32_bf16 v[24:27], v[224:227], v[208:211], v[24:27]
	v_mfma_f32_16x16x32_bf16 v[20:23], v[232:235], v[208:211], v[20:23]
	v_mfma_f32_16x16x32_bf16 v[8:11], v[224:227], v[216:219], v[6:9]
	v_mfma_f32_16x16x32_bf16 v[4:7], v[232:235], v[216:219], v[2:5]
	s_setprio 0
	s_add_i32 s81, s81, 2
	s_add_u32 s44, s44, 0x100
	s_addc_u32 s45, s45, 0
	s_cmp_gt_u32 s81, 29
	s_barrier
	s_cbranch_scc1 .LBB0_1351

;     DI size_t aoff(const Unit& u, size_t tstep) const { return (size_t)u.pm * tstep; }
;     DI size_t boff(const Unit& u, size_t tstep) const { return (size_t)u.pn * tstep; }
;     DI bool next(int i, Unit& u) const { const long L = (long)i * G + c; if (L >= np) return false; u.pm = pmv; u.pn = (int)(L % nN); u.ks = (int)(L / nN); return true; }
;     DI size_t aoff(const Unit& u, size_t) const { return (size_t)u.ks * kbytes; }
;     DI size_t boff(const Unit& u, size_t tstep) const { return (size_t)u.pn * tstep + (size_t)u.ks * kbytes; }
;     DI bool next(int i, Unit& u) const { Unit t; if (!S.next(i / 3, t)) return false; u.pm = t.pm; u.pn = t.pn; u.ks = i % 3; return true; }
;     DI size_t aoff(const Unit& u, size_t tstep) const { return (u.ks < 2 ? offU : offOA) + (size_t)u.pm * tstep; }
; #define PG8_LDA(dst, b, h) do { _Pragma("unroll") for (int m = 0; m < 4; ++m) _Pragma("unroll") for (int k = 0; k < 2; ++k) dst[m][k] = *(const LAS bf16x8*)(lds + PG8_SA(b, h) + aoff + m * 2048 + k * 1024); } while (0)
; template <class Epi, class Sched>
; DI void gemm_phase(LAS unsigned char* lds, const Gemm g, const Sched& S, const Epi& E) {
;     ...
;         const bool has_next = S.next(ui + 1, nxt);
;         const char* nA = has_next ? (const char*)g.A + S.aoff(nxt, tstep) : cA; const char* nB = has_next ? (const char*)g.Bt + S.boff(nxt, tstep) : cB;
;         for (int t = 0; t < nt; t += 2) {
;             if constexpr (Epi::HAS_MID) { if (t == E.mid_t(nt)) { int fr3 = fr, fq3 = fq; asm volatile("" : "+v"(fr3), "+v"(fq3)); E.mid(acc, cur, wr, wc, fr3, fq3); } }
;             const bool last = (t == nt - 2);
;             const char* a1 = cA + (size_t)(t + 1) * kstep;
;             const char* a2 = last ? nA : cA + (size_t)(t + 2) * kstep; const char* b2 = last ? nB : cB + (size_t)(t + 2) * kstep;
;             const char* a3 = a2 + kstep; const char* b3 = b2 + kstep;
;             PG8_LDB(B0, 0, 0); PG8_SCHED; PG8_LDA(At, 0, 0); PG8_STAGE(PG8_SA(1, 1), a1 + hstep, voffA);
;             PG8_WAIT_L(8); PG8_BAR; PG8_WAIT_L(0); PG8_MMA(0, 0, At, B0); PG8_BAR; PG8_SCHED;
;             PG8_LDB(B1, 0, 1); PG8_STAGE(PG8_SB(0, 0), b2, voffB);
;             PG8_BAR; PG8_WAIT_L(0); PG8_MMA(0, 1, At, B1); PG8_BAR;
;             PG8_LDA(At, 0, 1); PG8_STAGE(PG8_SA(0, 0), a2, voffA);
;             PG8_BAR; PG8_WAIT_L(0); PG8_MMA(1, 0, At, B0); PG8_BAR; PG8_SCHED;
.LBB0_1507:
	s_ashr_i32 s37, s36, 31
	s_lshl_b64 s[0:1], s[36:37], 20
	v_cmp_lt_i64_e32 vcc, s[38:39], v[140:141]
	s_add_u32 s38, s13, s0
	s_addc_u32 s39, s50, s1
	s_and_b64 s[0:1], vcc, exec
	s_cselect_b32 s34, s39, s45
	s_cselect_b32 s35, s38, s44
	s_ashr_i32 s31, s30, 31
	s_lshl_b64 s[0:1], s[30:31], 20
	s_add_u32 s40, s55, s0
	s_addc_u32 s41, s56, s1
	s_and_b64 s[0:1], vcc, exec
	s_cselect_b32 s31, s41, s47
	s_cselect_b32 s37, s40, s46
	s_add_u32 s44, s44, 0x80080
	s_addc_u32 s45, s45, 0
	s_add_u32 s43, s46, 0x100
	v_mov_b32_e32 v0, 0
	s_addc_u32 s68, s47, 0
	s_mov_b32 s69, -2
	s_waitcnt lgkmcnt(0)
	ds_read_b128 v[144:147], v150
	ds_read_b128 v[154:157], v150 offset:1024
	ds_read_b128 v[158:161], v150 offset:2048
	ds_read_b128 v[162:165], v150 offset:3072
	s_add_u32 s0, s44, 0xfff80080
	s_addc_u32 s1, s45, -1
	s_cmp_eq_u32 s69, 28
	s_cselect_b32 s49, s34, s1
	s_cselect_b32 s48, s35, s0
	s_cselect_b32 s47, s31, s68
	s_cselect_b32 s46, s37, s43
	s_add_i32 m0, s52, 0xc000
	ds_read_b128 v[166:169], v151
	ds_read_b128 v[170:173], v151 offset:1024
	ds_read_b128 v[174:177], v151 offset:2048
	ds_read_b128 v[178:181], v151 offset:3072
	ds_read_b128 v[188:191], v151 offset:4096
	ds_read_b128 v[206:209], v151 offset:5120
	ds_read_b128 v[210:213], v151 offset:6144
	global_load_lds_dwordx4 v136, s[44:45]
	s_add_i32 m0, s52, 0xe000
	ds_read_b128 v[214:217], v151 offset:7168
	global_load_lds_dwordx4 v138, s[44:45]
	s_waitcnt lgkmcnt(8)
	s_barrier
	s_waitcnt lgkmcnt(0)
	s_setprio 1
	v_mfma_f32_16x16x32_bf16 v[124:127], v[144:147], v[166:169], 0
	v_mfma_f32_16x16x32_bf16 v[120:123], v[158:161], v[166:169], 0
	v_mfma_f32_16x16x32_bf16 v[108:111], v[144:147], v[174:177], 0
	v_mfma_f32_16x16x32_bf16 v[104:107], v[158:161], v[174:177], 0
	v_mfma_f32_16x16x32_bf16 v[92:95], v[144:147], v[188:191], 0
	v_mfma_f32_16x16x32_bf16 v[88:91], v[158:161], v[188:191], 0
	v_mfma_f32_16x16x32_bf16 v[76:79], v[144:147], v[210:213], 0
	v_mfma_f32_16x16x32_bf16 v[72:75], v[158:161], v[210:213], 0
	v_mfma_f32_16x16x32_bf16 v[124:127], v[154:157], v[170:173], v[124:127]
	v_mfma_f32_16x16x32_bf16 v[120:123], v[162:165], v[170:173], v[120:123]
	v_mfma_f32_16x16x32_bf16 v[108:111], v[154:157], v[178:181], v[108:111]
	v_mfma_f32_16x16x32_bf16 v[104:107], v[162:165], v[178:181], v[104:107]
	v_mfma_f32_16x16x32_bf16 v[92:95], v[154:157], v[206:209], v[92:95]
	v_mfma_f32_16x16x32_bf16 v[88:91], v[162:165], v[206:209], v[88:91]
	v_mfma_f32_16x16x32_bf16 v[76:79], v[154:157], v[214:217], v[76:79]
	v_mfma_f32_16x16x32_bf16 v[72:75], v[162:165], v[214:217], v[72:75]
	s_setprio 0
	s_barrier
	s_add_i32 s0, s65, s51
	s_mov_b32 m0, s0
	ds_read_b128 v[218:221], v152
	ds_read_b128 v[222:225], v152 offset:1024
	ds_read_b128 v[226:229], v152 offset:2048
	global_load_lds_dwordx4 v132, s[46:47]
	s_add_i32 m0, s0, 0x2000
	ds_read_b128 v[230:233], v152 offset:3072
	global_load_lds_dwordx4 v134, s[46:47]
	s_barrier
	s_waitcnt lgkmcnt(0)
	s_setprio 1
	v_mfma_f32_16x16x32_bf16 v[116:119], v[218:221], v[166:169], 0
	v_mfma_f32_16x16x32_bf16 v[112:115], v[226:229], v[166:169], 0
	v_mfma_f32_16x16x32_bf16 v[100:103], v[218:221], v[174:177], 0
	v_mfma_f32_16x16x32_bf16 v[96:99], v[226:229], v[174:177], 0
	v_mfma_f32_16x16x32_bf16 v[84:87], v[218:221], v[188:191], 0
	v_mfma_f32_16x16x32_bf16 v[80:83], v[226:229], v[188:191], 0
	v_mfma_f32_16x16x32_bf16 v[68:71], v[218:221], v[210:213], 0
	v_mfma_f32_16x16x32_bf16 v[64:67], v[226:229], v[210:213], 0
	v_mfma_f32_16x16x32_bf16 v[116:119], v[222:225], v[170:173], v[116:119]
	v_mfma_f32_16x16x32_bf16 v[112:115], v[230:233], v[170:173], v[112:115]
	v_mfma_f32_16x16x32_bf16 v[100:103], v[222:225], v[178:181], v[100:103]
	v_mfma_f32_16x16x32_bf16 v[96:99], v[230:233], v[178:181], v[96:99]
	v_mfma_f32_16x16x32_bf16 v[84:87], v[222:225], v[206:209], v[84:87]
	v_mfma_f32_16x16x32_bf16 v[80:83], v[230:233], v[206:209], v[80:83]
	v_mfma_f32_16x16x32_bf16 v[68:71], v[222:225], v[214:217], v[68:71]
	v_mfma_f32_16x16x32_bf16 v[64:67], v[230:233], v[214:217], v[64:67]
	s_setprio 0
	s_mov_b32 m0, s52
	s_barrier
	ds_read_b128 v[166:169], v151 offset:16384
	ds_read_b128 v[170:173], v151 offset:17408
	ds_read_b128 v[174:177], v151 offset:18432
	ds_read_b128 v[178:181], v151 offset:19456
	ds_read_b128 v[188:191], v151 offset:20480
	ds_read_b128 v[206:209], v151 offset:21504
	ds_read_b128 v[210:213], v151 offset:22528
	global_load_lds_dwordx4 v128, s[48:49]
	s_mov_b32 m0, s53
	ds_read_b128 v[214:217], v151 offset:23552
	global_load_lds_dwordx4 v130, s[48:49]
	s_barrier
	s_waitcnt lgkmcnt(0)
	s_setprio 1
	v_mfma_f32_16x16x32_bf16 v[60:63], v[144:147], v[166:169], 0
	v_mfma_f32_16x16x32_bf16 v[56:59], v[158:161], v[166:169], 0
	v_mfma_f32_16x16x32_bf16 v[44:47], v[144:147], v[174:177], 0
	v_mfma_f32_16x16x32_bf16 v[40:43], v[158:161], v[174:177], 0
	v_mfma_f32_16x16x32_bf16 v[28:31], v[144:147], v[188:191], 0
	v_mfma_f32_16x16x32_bf16 v[24:27], v[158:161], v[188:191], 0
	v_mfma_f32_16x16x32_bf16 v[12:15], v[144:147], v[210:213], 0
	v_mfma_f32_16x16x32_bf16 v[8:11], v[158:161], v[210:213], 0
	v_mfma_f32_16x16x32_bf16 v[60:63], v[154:157], v[170:173], v[60:63]
	v_mfma_f32_16x16x32_bf16 v[56:59], v[162:165], v[170:173], v[56:59]
	v_mfma_f32_16x16x32_bf16 v[44:47], v[154:157], v[178:181], v[44:47]
	v_mfma_f32_16x16x32_bf16 v[40:43], v[162:165], v[178:181], v[40:43]
	v_mfma_f32_16x16x32_bf16 v[28:31], v[154:157], v[206:209], v[28:31]
	v_mfma_f32_16x16x32_bf16 v[24:27], v[162:165], v[206:209], v[24:27]
	v_mfma_f32_16x16x32_bf16 v[12:15], v[154:157], v[214:217], v[12:15]
	v_mfma_f32_16x16x32_bf16 v[8:11], v[162:165], v[214:217], v[8:11]
	s_setprio 0
	s_barrier
; #define PG8_STAGE(bufoff, gbase, voff) do { _Pragma("unroll") for (int _i = 0; _i < 2; ++_i) \
;         __builtin_amdgcn_global_load_lds((const unsigned*)((const char*)(gbase) + (voff)[_i]), (LAS unsigned*)(lds + (bufoff) + ldsw + _i * 8192), 16, 0, 0); } while (0)
; #define PG8_LDA(dst, b, h) do { _Pragma("unroll") for (int m = 0; m < 4; ++m) _Pragma("unroll") for (int k = 0; k < 2; ++k) dst[m][k] = *(const LAS bf16x8*)(lds + PG8_SA(b, h) + aoff + m * 2048 + k * 1024); } while (0)
; #define PG8_LDB(dst, b, h) do { _Pragma("unroll") for (int n = 0; n < 2; ++n) _Pragma("unroll") for (int k = 0; k < 2; ++k) dst[n][k] = *(const LAS bf16x8*)(lds + PG8_SB(b, h) + boff + n * 2048 + k * 1024); } while (0)
; #define PG8_MMA(ai, bj, At, Bt) do { __builtin_amdgcn_s_setprio(1); _Pragma("unroll") for (int m = 0; m < 4; ++m) _Pragma("unroll") for (int n = 0; n < 2; ++n) _Pragma("unroll") for (int k = 0; k < 2; ++k) \
;         acc[ai][bj][m][n] = __builtin_amdgcn_mfma_f32_16x16x32_bf16(Bt[n][k], At[m][k], acc[ai][bj][m][n], 0, 0, 0); __builtin_amdgcn_s_setprio(0); } while (0)
; #define PG8_WAIT_V(n) asm volatile("s_waitcnt vmcnt(" #n ")" ::: "memory")
; #define PG8_WAIT_L(n) asm volatile("s_waitcnt lgkmcnt(" #n ")" ::: "memory")
; #define PG8_BAR __builtin_amdgcn_s_barrier()
; #define PG8_SCHED __builtin_amdgcn_sched_barrier(0)
; template <class Epi, class Sched>
; DI void gemm_phase(LAS unsigned char* lds, const Gemm g, const Sched& S, const Epi& E) {
;     ...
;             PG8_STAGE(PG8_SB(0, 1), b2 + hstep, voffB);
;             PG8_WAIT_V(6); PG8_BAR; PG8_MMA(1, 1, At, B1); PG8_BAR;
;             PG8_LDB(B0, 1, 0); PG8_SCHED; PG8_LDA(At, 1, 0); PG8_STAGE(PG8_SA(0, 1), a2 + hstep, voffA);
;             PG8_WAIT_L(8); PG8_BAR; PG8_WAIT_L(0); PG8_MMA(0, 0, At, B0); PG8_BAR; PG8_SCHED;
;             PG8_LDB(B1, 1, 1); PG8_STAGE(PG8_SB(1, 0), b3, voffB);
;             PG8_BAR; PG8_WAIT_L(0); PG8_MMA(0, 1, At, B1); PG8_BAR;
;             PG8_LDA(At, 1, 1); PG8_STAGE(PG8_SA(1, 0), a3, voffA);
	s_add_i32 s4, s66, s51
	s_mov_b32 m0, s4
	s_add_u32 s0, s46, 0x80000
	s_addc_u32 s1, s47, 0
	global_load_lds_dwordx4 v132, s[0:1]
	s_add_i32 m0, s4, 0x2000
	s_nop 0
	global_load_lds_dwordx4 v134, s[0:1]
	s_waitcnt vmcnt(6)
	s_barrier
	s_setprio 1
	v_mfma_f32_16x16x32_bf16 v[52:55], v[218:221], v[166:169], 0
	v_mfma_f32_16x16x32_bf16 v[48:51], v[226:229], v[166:169], 0
	v_mfma_f32_16x16x32_bf16 v[36:39], v[218:221], v[174:177], 0
	v_mfma_f32_16x16x32_bf16 v[32:35], v[226:229], v[174:177], 0
	v_mfma_f32_16x16x32_bf16 v[20:23], v[218:221], v[188:191], 0
	v_mfma_f32_16x16x32_bf16 v[16:19], v[226:229], v[188:191], 0
	v_mfma_f32_16x16x32_bf16 v[4:7], v[218:221], v[210:213], 0
	v_mfma_f32_16x16x32_bf16 v[0:3], v[226:229], v[210:213], 0
	v_mfma_f32_16x16x32_bf16 v[52:55], v[222:225], v[170:173], v[52:55]
	v_mfma_f32_16x16x32_bf16 v[48:51], v[230:233], v[170:173], v[48:51]
	v_mfma_f32_16x16x32_bf16 v[36:39], v[222:225], v[178:181], v[36:39]
	v_mfma_f32_16x16x32_bf16 v[32:35], v[230:233], v[178:181], v[32:35]
	v_mfma_f32_16x16x32_bf16 v[20:23], v[222:225], v[206:209], v[20:23]
	v_mfma_f32_16x16x32_bf16 v[16:19], v[230:233], v[206:209], v[16:19]
	v_mfma_f32_16x16x32_bf16 v[4:7], v[222:225], v[214:217], v[4:7]
	v_mfma_f32_16x16x32_bf16 v[0:3], v[230:233], v[214:217], v[0:3]
	s_setprio 0
	s_add_i32 s4, 0, 0x18000
	v_add_u32_e32 v162, s4, v149
	s_barrier
	ds_read_b128 v[144:147], v162
	ds_read_b128 v[154:157], v162 offset:1024
	ds_read_b128 v[158:161], v162 offset:2048
	ds_read_b128 v[162:165], v162 offset:3072
	s_add_u32 s0, s48, 0x80000
	s_addc_u32 s1, s49, 0
	s_mov_b32 m0, s58
	ds_read_b128 v[166:169], v151 offset:32768
	ds_read_b128 v[170:173], v151 offset:33792
	ds_read_b128 v[174:177], v151 offset:34816
	ds_read_b128 v[178:181], v151 offset:35840
	ds_read_b128 v[188:191], v151 offset:36864
	ds_read_b128 v[206:209], v151 offset:37888
	ds_read_b128 v[210:213], v151 offset:38912
	global_load_lds_dwordx4 v128, s[0:1]
	s_mov_b32 m0, s59
	ds_read_b128 v[214:217], v151 offset:39936
	global_load_lds_dwordx4 v130, s[0:1]
	s_waitcnt lgkmcnt(8)
	s_barrier
	s_waitcnt lgkmcnt(0)
	s_setprio 1
	v_mfma_f32_16x16x32_bf16 v[124:127], v[144:147], v[166:169], v[124:127]
	v_mfma_f32_16x16x32_bf16 v[120:123], v[158:161], v[166:169], v[120:123]
	v_mfma_f32_16x16x32_bf16 v[108:111], v[144:147], v[174:177], v[108:111]
	v_mfma_f32_16x16x32_bf16 v[104:107], v[158:161], v[174:177], v[104:107]
	v_mfma_f32_16x16x32_bf16 v[92:95], v[144:147], v[188:191], v[92:95]
	v_mfma_f32_16x16x32_bf16 v[88:91], v[158:161], v[188:191], v[88:91]
	v_mfma_f32_16x16x32_bf16 v[76:79], v[144:147], v[210:213], v[76:79]
	v_mfma_f32_16x16x32_bf16 v[72:75], v[158:161], v[210:213], v[72:75]
	v_mfma_f32_16x16x32_bf16 v[124:127], v[154:157], v[170:173], v[124:127]
	v_mfma_f32_16x16x32_bf16 v[120:123], v[162:165], v[170:173], v[120:123]
	v_mfma_f32_16x16x32_bf16 v[108:111], v[154:157], v[178:181], v[108:111]
	v_mfma_f32_16x16x32_bf16 v[104:107], v[162:165], v[178:181], v[104:107]
	v_mfma_f32_16x16x32_bf16 v[92:95], v[154:157], v[206:209], v[92:95]
	v_mfma_f32_16x16x32_bf16 v[88:91], v[162:165], v[206:209], v[88:91]
	v_mfma_f32_16x16x32_bf16 v[76:79], v[154:157], v[214:217], v[76:79]
	v_mfma_f32_16x16x32_bf16 v[72:75], v[162:165], v[214:217], v[72:75]
	s_setprio 0
	s_barrier
	s_add_i32 s5, 0, 0x1c000
	s_add_i32 s0, s4, s51
	v_add_u32_e32 v201, s5, v149
	s_add_i32 m0, s0, 0xffffff80
	ds_read_b128 v[218:221], v201
	ds_read_b128 v[222:225], v201 offset:1024
	ds_read_b128 v[226:229], v201 offset:2048
	global_load_lds_dwordx4 v132, s[46:47] offset:128
	s_add_i32 m0, s0, 0x1f80
	ds_read_b128 v[230:233], v201 offset:3072
	global_load_lds_dwordx4 v134, s[46:47] offset:128
	s_barrier
	s_waitcnt lgkmcnt(0)
	s_setprio 1
	v_mfma_f32_16x16x32_bf16 v[116:119], v[218:221], v[166:169], v[116:119]
	v_mfma_f32_16x16x32_bf16 v[112:115], v[226:229], v[166:169], v[112:115]
	v_mfma_f32_16x16x32_bf16 v[100:103], v[218:221], v[174:177], v[100:103]
	v_mfma_f32_16x16x32_bf16 v[96:99], v[226:229], v[174:177], v[96:99]
	v_mfma_f32_16x16x32_bf16 v[84:87], v[218:221], v[188:191], v[84:87]
	v_mfma_f32_16x16x32_bf16 v[80:83], v[226:229], v[188:191], v[80:83]
	v_mfma_f32_16x16x32_bf16 v[68:71], v[218:221], v[210:213], v[68:71]
	v_mfma_f32_16x16x32_bf16 v[64:67], v[226:229], v[210:213], v[64:67]
	v_mfma_f32_16x16x32_bf16 v[116:119], v[222:225], v[170:173], v[116:119]
	v_mfma_f32_16x16x32_bf16 v[112:115], v[230:233], v[170:173], v[112:115]
	v_mfma_f32_16x16x32_bf16 v[100:103], v[222:225], v[178:181], v[100:103]
	v_mfma_f32_16x16x32_bf16 v[96:99], v[230:233], v[178:181], v[96:99]
	v_mfma_f32_16x16x32_bf16 v[84:87], v[222:225], v[206:209], v[84:87]
	v_mfma_f32_16x16x32_bf16 v[80:83], v[230:233], v[206:209], v[80:83]
	v_mfma_f32_16x16x32_bf16 v[68:71], v[222:225], v[214:217], v[68:71]
	v_mfma_f32_16x16x32_bf16 v[64:67], v[230:233], v[214:217], v[64:67]
	s_setprio 0
	s_add_i32 m0, s63, 0xffffff80
	s_barrier
	ds_read_b128 v[166:169], v151 offset:49152
	ds_read_b128 v[170:173], v151 offset:50176
	ds_read_b128 v[174:177], v151 offset:51200
	ds_read_b128 v[178:181], v151 offset:52224
	ds_read_b128 v[188:191], v151 offset:53248
	ds_read_b128 v[206:209], v151 offset:54272
	ds_read_b128 v[210:213], v151 offset:55296
	global_load_lds_dwordx4 v128, s[48:49] offset:128
	s_add_i32 m0, s64, 0xffffff80
	ds_read_b128 v[214:217], v151 offset:56320
	global_load_lds_dwordx4 v130, s[48:49] offset:128
	s_barrier
; #define PG8_STAGE(bufoff, gbase, voff) do { _Pragma("unroll") for (int _i = 0; _i < 2; ++_i) \
;         __builtin_amdgcn_global_load_lds((const unsigned*)((const char*)(gbase) + (voff)[_i]), (LAS unsigned*)(lds + (bufoff) + ldsw + _i * 8192), 16, 0, 0); } while (0)
; #define PG8_LDA(dst, b, h) do { _Pragma("unroll") for (int m = 0; m < 4; ++m) _Pragma("unroll") for (int k = 0; k < 2; ++k) dst[m][k] = *(const LAS bf16x8*)(lds + PG8_SA(b, h) + aoff + m * 2048 + k * 1024); } while (0)
; #define PG8_LDB(dst, b, h) do { _Pragma("unroll") for (int n = 0; n < 2; ++n) _Pragma("unroll") for (int k = 0; k < 2; ++k) dst[n][k] = *(const LAS bf16x8*)(lds + PG8_SB(b, h) + boff + n * 2048 + k * 1024); } while (0)
; #define PG8_MMA(ai, bj, At, Bt) do { __builtin_amdgcn_s_setprio(1); _Pragma("unroll") for (int m = 0; m < 4; ++m) _Pragma("unroll") for (int n = 0; n < 2; ++n) _Pragma("unroll") for (int k = 0; k < 2; ++k) \
;         acc[ai][bj][m][n] = __builtin_amdgcn_mfma_f32_16x16x32_bf16(Bt[n][k], At[m][k], acc[ai][bj][m][n], 0, 0, 0); __builtin_amdgcn_s_setprio(0); } while (0)
; #define PG8_WAIT_V(n) asm volatile("s_waitcnt vmcnt(" #n ")" ::: "memory")
; #define PG8_WAIT_L(n) asm volatile("s_waitcnt lgkmcnt(" #n ")" ::: "memory")
; #define PG8_BAR __builtin_amdgcn_s_barrier()
; #define PG8_SCHED __builtin_amdgcn_sched_barrier(0)
; template <class Epi, class Sched>
; DI void gemm_phase(LAS unsigned char* lds, const Gemm g, const Sched& S, const Epi& E) {
;     ...
;             PG8_LDB(B0, 0, 0); PG8_SCHED; PG8_LDA(At, 0, 0); PG8_STAGE(PG8_SA(1, 1), a1 + hstep, voffA);
;             PG8_WAIT_L(8); PG8_BAR; PG8_WAIT_L(0); PG8_MMA(0, 0, At, B0); PG8_BAR; PG8_SCHED;
;             PG8_LDB(B1, 0, 1); PG8_STAGE(PG8_SB(0, 0), b2, voffB);
;     ...
;             PG8_BAR; PG8_WAIT_L(0); PG8_MMA(1, 0, At, B0); PG8_BAR; PG8_SCHED;
;             PG8_STAGE(PG8_SB(1, 1), b3 + hstep, voffB);
;             PG8_WAIT_V(6); PG8_BAR; PG8_MMA(1, 1, At, B1); PG8_BAR;
	s_waitcnt lgkmcnt(0)
	s_setprio 1
	v_mfma_f32_16x16x32_bf16 v[60:63], v[144:147], v[166:169], v[60:63]
	v_mfma_f32_16x16x32_bf16 v[56:59], v[158:161], v[166:169], v[56:59]
	v_mfma_f32_16x16x32_bf16 v[44:47], v[144:147], v[174:177], v[44:47]
	v_mfma_f32_16x16x32_bf16 v[40:43], v[158:161], v[174:177], v[40:43]
	v_mfma_f32_16x16x32_bf16 v[28:31], v[144:147], v[188:191], v[28:31]
	v_mfma_f32_16x16x32_bf16 v[24:27], v[158:161], v[188:191], v[24:27]
	v_mfma_f32_16x16x32_bf16 v[12:15], v[144:147], v[210:213], v[12:15]
	v_mfma_f32_16x16x32_bf16 v[8:11], v[158:161], v[210:213], v[8:11]
	v_mfma_f32_16x16x32_bf16 v[60:63], v[154:157], v[170:173], v[60:63]
	v_mfma_f32_16x16x32_bf16 v[56:59], v[162:165], v[170:173], v[56:59]
	v_mfma_f32_16x16x32_bf16 v[44:47], v[154:157], v[178:181], v[44:47]
	v_mfma_f32_16x16x32_bf16 v[40:43], v[162:165], v[178:181], v[40:43]
	v_mfma_f32_16x16x32_bf16 v[28:31], v[154:157], v[206:209], v[28:31]
	v_mfma_f32_16x16x32_bf16 v[24:27], v[162:165], v[206:209], v[24:27]
	v_mfma_f32_16x16x32_bf16 v[12:15], v[154:157], v[214:217], v[12:15]
	v_mfma_f32_16x16x32_bf16 v[8:11], v[162:165], v[214:217], v[8:11]
	s_setprio 0
	s_barrier
	s_add_i32 s4, s5, s51
	s_mov_b32 m0, s4
	s_add_u32 s0, s46, 0x80080
	s_addc_u32 s1, s47, 0
	global_load_lds_dwordx4 v132, s[0:1]
	s_add_i32 m0, s4, 0x2000
	s_nop 0
	global_load_lds_dwordx4 v134, s[0:1]
	s_waitcnt vmcnt(6)
	s_barrier
	s_setprio 1
	v_mfma_f32_16x16x32_bf16 v[52:55], v[218:221], v[166:169], v[52:55]
	v_mfma_f32_16x16x32_bf16 v[48:51], v[226:229], v[166:169], v[48:51]
	v_mfma_f32_16x16x32_bf16 v[36:39], v[218:221], v[174:177], v[36:39]
	v_mfma_f32_16x16x32_bf16 v[32:35], v[226:229], v[174:177], v[32:35]
	v_mfma_f32_16x16x32_bf16 v[20:23], v[218:221], v[188:191], v[20:23]
	v_mfma_f32_16x16x32_bf16 v[16:19], v[226:229], v[188:191], v[16:19]
	v_mfma_f32_16x16x32_bf16 v[4:7], v[218:221], v[210:213], v[4:7]
	v_mfma_f32_16x16x32_bf16 v[0:3], v[226:229], v[210:213], v[0:3]
	v_mfma_f32_16x16x32_bf16 v[52:55], v[222:225], v[170:173], v[52:55]
	v_mfma_f32_16x16x32_bf16 v[48:51], v[230:233], v[170:173], v[48:51]
	v_mfma_f32_16x16x32_bf16 v[36:39], v[222:225], v[178:181], v[36:39]
	v_mfma_f32_16x16x32_bf16 v[32:35], v[230:233], v[178:181], v[32:35]
	v_mfma_f32_16x16x32_bf16 v[20:23], v[222:225], v[206:209], v[20:23]
	v_mfma_f32_16x16x32_bf16 v[16:19], v[230:233], v[206:209], v[16:19]
	v_mfma_f32_16x16x32_bf16 v[4:7], v[222:225], v[214:217], v[4:7]
	v_mfma_f32_16x16x32_bf16 v[0:3], v[230:233], v[214:217], v[0:3]
	s_setprio 0
	s_add_i32 s69, s69, 2
	s_add_u32 s44, s44, 0x100
	s_addc_u32 s45, s45, 0
	s_add_u32 s43, s43, 0x100
	s_addc_u32 s68, s68, 0
	s_cmp_gt_u32 s69, 29
	s_barrier
	s_cbranch_scc0 .LBB0_1508
	s_branch .Lpeel_done_1508
.LBB0_1508:
	ds_read_b128 v[144:147], v150
	ds_read_b128 v[154:157], v150 offset:1024
	ds_read_b128 v[158:161], v150 offset:2048
	ds_read_b128 v[162:165], v150 offset:3072
	s_add_u32 s0, s44, 0xfff80080
	s_addc_u32 s1, s45, -1
	s_cmp_eq_u32 s69, 28
	s_cselect_b32 s49, s34, s1
	s_cselect_b32 s48, s35, s0
	s_cselect_b32 s47, s31, s68
	s_cselect_b32 s46, s37, s43
	s_add_i32 m0, s52, 0xc000
	ds_read_b128 v[166:169], v151
	ds_read_b128 v[170:173], v151 offset:1024
	ds_read_b128 v[174:177], v151 offset:2048
	ds_read_b128 v[178:181], v151 offset:3072
	ds_read_b128 v[188:191], v151 offset:4096
	ds_read_b128 v[206:209], v151 offset:5120
	ds_read_b128 v[210:213], v151 offset:6144
	global_load_lds_dwordx4 v136, s[44:45]
	s_add_i32 m0, s52, 0xe000
	ds_read_b128 v[214:217], v151 offset:7168
	global_load_lds_dwordx4 v138, s[44:45]
	s_waitcnt lgkmcnt(8)
	s_barrier
	s_waitcnt lgkmcnt(0)
	s_setprio 1
	v_mfma_f32_16x16x32_bf16 v[124:127], v[144:147], v[166:169], v[124:127]
	v_mfma_f32_16x16x32_bf16 v[120:123], v[158:161], v[166:169], v[120:123]
	v_mfma_f32_16x16x32_bf16 v[108:111], v[144:147], v[174:177], v[108:111]
	v_mfma_f32_16x16x32_bf16 v[104:107], v[158:161], v[174:177], v[104:107]
	v_mfma_f32_16x16x32_bf16 v[92:95], v[144:147], v[188:191], v[92:95]
	v_mfma_f32_16x16x32_bf16 v[88:91], v[158:161], v[188:191], v[88:91]
	v_mfma_f32_16x16x32_bf16 v[76:79], v[144:147], v[210:213], v[76:79]
	v_mfma_f32_16x16x32_bf16 v[72:75], v[158:161], v[210:213], v[72:75]
	v_mfma_f32_16x16x32_bf16 v[124:127], v[154:157], v[170:173], v[124:127]
	v_mfma_f32_16x16x32_bf16 v[120:123], v[162:165], v[170:173], v[120:123]
	v_mfma_f32_16x16x32_bf16 v[108:111], v[154:157], v[178:181], v[108:111]
	v_mfma_f32_16x16x32_bf16 v[104:107], v[162:165], v[178:181], v[104:107]
	v_mfma_f32_16x16x32_bf16 v[92:95], v[154:157], v[206:209], v[92:95]
	v_mfma_f32_16x16x32_bf16 v[88:91], v[162:165], v[206:209], v[88:91]
	v_mfma_f32_16x16x32_bf16 v[76:79], v[154:157], v[214:217], v[76:79]
	v_mfma_f32_16x16x32_bf16 v[72:75], v[162:165], v[214:217], v[72:75]
	s_setprio 0
	s_barrier
	s_add_i32 s0, s65, s51
	s_mov_b32 m0, s0
	ds_read_b128 v[218:221], v152
	ds_read_b128 v[222:225], v152 offset:1024
	ds_read_b128 v[226:229], v152 offset:2048
	global_load_lds_dwordx4 v132, s[46:47]
	s_add_i32 m0, s0, 0x2000
	ds_read_b128 v[230:233], v152 offset:3072
	global_load_lds_dwordx4 v134, s[46:47]
	s_barrier
; #define PG8_STAGE(bufoff, gbase, voff) do { _Pragma("unroll") for (int _i = 0; _i < 2; ++_i) \
;         __builtin_amdgcn_global_load_lds((const unsigned*)((const char*)(gbase) + (voff)[_i]), (LAS unsigned*)(lds + (bufoff) + ldsw + _i * 8192), 16, 0, 0); } while (0)
; #define PG8_LDA(dst, b, h) do { _Pragma("unroll") for (int m = 0; m < 4; ++m) _Pragma("unroll") for (int k = 0; k < 2; ++k) dst[m][k] = *(const LAS bf16x8*)(lds + PG8_SA(b, h) + aoff + m * 2048 + k * 1024); } while (0)
; #define PG8_LDB(dst, b, h) do { _Pragma("unroll") for (int n = 0; n < 2; ++n) _Pragma("unroll") for (int k = 0; k < 2; ++k) dst[n][k] = *(const LAS bf16x8*)(lds + PG8_SB(b, h) + boff + n * 2048 + k * 1024); } while (0)
; #define PG8_MMA(ai, bj, At, Bt) do { __builtin_amdgcn_s_setprio(1); _Pragma("unroll") for (int m = 0; m < 4; ++m) _Pragma("unroll") for (int n = 0; n < 2; ++n) _Pragma("unroll") for (int k = 0; k < 2; ++k) \
;         acc[ai][bj][m][n] = __builtin_amdgcn_mfma_f32_16x16x32_bf16(Bt[n][k], At[m][k], acc[ai][bj][m][n], 0, 0, 0); __builtin_amdgcn_s_setprio(0); } while (0)
; #define PG8_WAIT_V(n) asm volatile("s_waitcnt vmcnt(" #n ")" ::: "memory")
; #define PG8_WAIT_L(n) asm volatile("s_waitcnt lgkmcnt(" #n ")" ::: "memory")
; #define PG8_BAR __builtin_amdgcn_s_barrier()
; #define PG8_SCHED __builtin_amdgcn_sched_barrier(0)
; template <class Epi, class Sched>
; DI void gemm_phase(LAS unsigned char* lds, const Gemm g, const Sched& S, const Epi& E) {
;     ...
;             PG8_BAR; PG8_WAIT_L(0); PG8_MMA(0, 1, At, B1); PG8_BAR;
;             PG8_LDA(At, 0, 1); PG8_STAGE(PG8_SA(0, 0), a2, voffA);
;             PG8_BAR; PG8_WAIT_L(0); PG8_MMA(1, 0, At, B0); PG8_BAR; PG8_SCHED;
;             PG8_STAGE(PG8_SB(0, 1), b2 + hstep, voffB);
;             PG8_WAIT_V(6); PG8_BAR; PG8_MMA(1, 1, At, B1); PG8_BAR;
;             PG8_LDB(B0, 1, 0); PG8_SCHED; PG8_LDA(At, 1, 0); PG8_STAGE(PG8_SA(0, 1), a2 + hstep, voffA);
	s_waitcnt lgkmcnt(0)
	s_setprio 1
	v_mfma_f32_16x16x32_bf16 v[116:119], v[218:221], v[166:169], v[116:119]
	v_mfma_f32_16x16x32_bf16 v[112:115], v[226:229], v[166:169], v[112:115]
	v_mfma_f32_16x16x32_bf16 v[100:103], v[218:221], v[174:177], v[100:103]
	v_mfma_f32_16x16x32_bf16 v[96:99], v[226:229], v[174:177], v[96:99]
	v_mfma_f32_16x16x32_bf16 v[84:87], v[218:221], v[188:191], v[84:87]
	v_mfma_f32_16x16x32_bf16 v[80:83], v[226:229], v[188:191], v[80:83]
	v_mfma_f32_16x16x32_bf16 v[68:71], v[218:221], v[210:213], v[68:71]
	v_mfma_f32_16x16x32_bf16 v[64:67], v[226:229], v[210:213], v[64:67]
	v_mfma_f32_16x16x32_bf16 v[116:119], v[222:225], v[170:173], v[116:119]
	v_mfma_f32_16x16x32_bf16 v[112:115], v[230:233], v[170:173], v[112:115]
	v_mfma_f32_16x16x32_bf16 v[100:103], v[222:225], v[178:181], v[100:103]
	v_mfma_f32_16x16x32_bf16 v[96:99], v[230:233], v[178:181], v[96:99]
	v_mfma_f32_16x16x32_bf16 v[84:87], v[222:225], v[206:209], v[84:87]
	v_mfma_f32_16x16x32_bf16 v[80:83], v[230:233], v[206:209], v[80:83]
	v_mfma_f32_16x16x32_bf16 v[68:71], v[222:225], v[214:217], v[68:71]
	v_mfma_f32_16x16x32_bf16 v[64:67], v[230:233], v[214:217], v[64:67]
	s_setprio 0
	s_mov_b32 m0, s52
	s_barrier
	ds_read_b128 v[166:169], v151 offset:16384
	ds_read_b128 v[170:173], v151 offset:17408
	ds_read_b128 v[174:177], v151 offset:18432
	ds_read_b128 v[178:181], v151 offset:19456
	ds_read_b128 v[188:191], v151 offset:20480
	ds_read_b128 v[206:209], v151 offset:21504
	ds_read_b128 v[210:213], v151 offset:22528
	global_load_lds_dwordx4 v128, s[48:49]
	s_mov_b32 m0, s53
	ds_read_b128 v[214:217], v151 offset:23552
	global_load_lds_dwordx4 v130, s[48:49]
	s_barrier
	s_waitcnt lgkmcnt(0)
	s_setprio 1
	v_mfma_f32_16x16x32_bf16 v[60:63], v[144:147], v[166:169], v[60:63]
	v_mfma_f32_16x16x32_bf16 v[56:59], v[158:161], v[166:169], v[56:59]
	v_mfma_f32_16x16x32_bf16 v[44:47], v[144:147], v[174:177], v[44:47]
	v_mfma_f32_16x16x32_bf16 v[40:43], v[158:161], v[174:177], v[40:43]
	v_mfma_f32_16x16x32_bf16 v[28:31], v[144:147], v[188:191], v[28:31]
	v_mfma_f32_16x16x32_bf16 v[24:27], v[158:161], v[188:191], v[24:27]
	v_mfma_f32_16x16x32_bf16 v[12:15], v[144:147], v[210:213], v[12:15]
	v_mfma_f32_16x16x32_bf16 v[8:11], v[158:161], v[210:213], v[8:11]
	v_mfma_f32_16x16x32_bf16 v[60:63], v[154:157], v[170:173], v[60:63]
	v_mfma_f32_16x16x32_bf16 v[56:59], v[162:165], v[170:173], v[56:59]
	v_mfma_f32_16x16x32_bf16 v[44:47], v[154:157], v[178:181], v[44:47]
	v_mfma_f32_16x16x32_bf16 v[40:43], v[162:165], v[178:181], v[40:43]
	v_mfma_f32_16x16x32_bf16 v[28:31], v[154:157], v[206:209], v[28:31]
	v_mfma_f32_16x16x32_bf16 v[24:27], v[162:165], v[206:209], v[24:27]
	v_mfma_f32_16x16x32_bf16 v[12:15], v[154:157], v[214:217], v[12:15]
	v_mfma_f32_16x16x32_bf16 v[8:11], v[162:165], v[214:217], v[8:11]
	s_setprio 0
	s_barrier
	s_add_i32 s4, s66, s51
	s_mov_b32 m0, s4
	s_add_u32 s0, s46, 0x80000
	s_addc_u32 s1, s47, 0
	global_load_lds_dwordx4 v132, s[0:1]
	s_add_i32 m0, s4, 0x2000
	s_nop 0
	global_load_lds_dwordx4 v134, s[0:1]
	s_waitcnt vmcnt(6)
	s_barrier
	s_setprio 1
	v_mfma_f32_16x16x32_bf16 v[52:55], v[218:221], v[166:169], v[52:55]
	v_mfma_f32_16x16x32_bf16 v[48:51], v[226:229], v[166:169], v[48:51]
	v_mfma_f32_16x16x32_bf16 v[36:39], v[218:221], v[174:177], v[36:39]
	v_mfma_f32_16x16x32_bf16 v[32:35], v[226:229], v[174:177], v[32:35]
	v_mfma_f32_16x16x32_bf16 v[20:23], v[218:221], v[188:191], v[20:23]
	v_mfma_f32_16x16x32_bf16 v[16:19], v[226:229], v[188:191], v[16:19]
	v_mfma_f32_16x16x32_bf16 v[4:7], v[218:221], v[210:213], v[4:7]
	v_mfma_f32_16x16x32_bf16 v[0:3], v[226:229], v[210:213], v[0:3]
	v_mfma_f32_16x16x32_bf16 v[52:55], v[222:225], v[170:173], v[52:55]
	v_mfma_f32_16x16x32_bf16 v[48:51], v[230:233], v[170:173], v[48:51]
	v_mfma_f32_16x16x32_bf16 v[36:39], v[222:225], v[178:181], v[36:39]
	v_mfma_f32_16x16x32_bf16 v[32:35], v[230:233], v[178:181], v[32:35]
	v_mfma_f32_16x16x32_bf16 v[20:23], v[222:225], v[206:209], v[20:23]
	v_mfma_f32_16x16x32_bf16 v[16:19], v[230:233], v[206:209], v[16:19]
	v_mfma_f32_16x16x32_bf16 v[4:7], v[222:225], v[214:217], v[4:7]
	v_mfma_f32_16x16x32_bf16 v[0:3], v[230:233], v[214:217], v[0:3]
	s_setprio 0
	s_add_i32 s4, 0, 0x18000
	v_add_u32_e32 v162, s4, v149
	s_barrier
	ds_read_b128 v[144:147], v162
	ds_read_b128 v[154:157], v162 offset:1024
	ds_read_b128 v[158:161], v162 offset:2048
	ds_read_b128 v[162:165], v162 offset:3072
	s_add_u32 s0, s48, 0x80000
	s_addc_u32 s1, s49, 0
	s_mov_b32 m0, s58
	ds_read_b128 v[166:169], v151 offset:32768
	ds_read_b128 v[170:173], v151 offset:33792
	ds_read_b128 v[174:177], v151 offset:34816
	ds_read_b128 v[178:181], v151 offset:35840
	ds_read_b128 v[188:191], v151 offset:36864
	ds_read_b128 v[206:209], v151 offset:37888
	ds_read_b128 v[210:213], v151 offset:38912
	global_load_lds_dwordx4 v128, s[0:1]
	s_mov_b32 m0, s59
	ds_read_b128 v[214:217], v151 offset:39936
	global_load_lds_dwordx4 v130, s[0:1]
	s_waitcnt lgkmcnt(8)
	s_barrier
; #define PG8_STAGE(bufoff, gbase, voff) do { _Pragma("unroll") for (int _i = 0; _i < 2; ++_i) \
;         __builtin_amdgcn_global_load_lds((const unsigned*)((const char*)(gbase) + (voff)[_i]), (LAS unsigned*)(lds + (bufoff) + ldsw + _i * 8192), 16, 0, 0); } while (0)
; #define PG8_LDA(dst, b, h) do { _Pragma("unroll") for (int m = 0; m < 4; ++m) _Pragma("unroll") for (int k = 0; k < 2; ++k) dst[m][k] = *(const LAS bf16x8*)(lds + PG8_SA(b, h) + aoff + m * 2048 + k * 1024); } while (0)
; #define PG8_LDB(dst, b, h) do { _Pragma("unroll") for (int n = 0; n < 2; ++n) _Pragma("unroll") for (int k = 0; k < 2; ++k) dst[n][k] = *(const LAS bf16x8*)(lds + PG8_SB(b, h) + boff + n * 2048 + k * 1024); } while (0)
; #define PG8_MMA(ai, bj, At, Bt) do { __builtin_amdgcn_s_setprio(1); _Pragma("unroll") for (int m = 0; m < 4; ++m) _Pragma("unroll") for (int n = 0; n < 2; ++n) _Pragma("unroll") for (int k = 0; k < 2; ++k) \
;         acc[ai][bj][m][n] = __builtin_amdgcn_mfma_f32_16x16x32_bf16(Bt[n][k], At[m][k], acc[ai][bj][m][n], 0, 0, 0); __builtin_amdgcn_s_setprio(0); } while (0)
; #define PG8_WAIT_V(n) asm volatile("s_waitcnt vmcnt(" #n ")" ::: "memory")
; #define PG8_WAIT_L(n) asm volatile("s_waitcnt lgkmcnt(" #n ")" ::: "memory")
; #define PG8_BAR __builtin_amdgcn_s_barrier()
; #define PG8_SCHED __builtin_amdgcn_sched_barrier(0)
; template <class Epi, class Sched>
; DI void gemm_phase(LAS unsigned char* lds, const Gemm g, const Sched& S, const Epi& E) {
;     ...
;             PG8_WAIT_L(8); PG8_BAR; PG8_WAIT_L(0); PG8_MMA(0, 0, At, B0); PG8_BAR; PG8_SCHED;
;             PG8_LDB(B1, 1, 1); PG8_STAGE(PG8_SB(1, 0), b3, voffB);
;             PG8_BAR; PG8_WAIT_L(0); PG8_MMA(0, 1, At, B1); PG8_BAR;
;             PG8_LDA(At, 1, 1); PG8_STAGE(PG8_SA(1, 0), a3, voffA);
;             PG8_BAR; PG8_WAIT_L(0); PG8_MMA(1, 0, At, B0); PG8_BAR; PG8_SCHED;
;             PG8_STAGE(PG8_SB(1, 1), b3 + hstep, voffB);
;             PG8_WAIT_V(6); PG8_BAR; PG8_MMA(1, 1, At, B1); PG8_BAR;
	s_waitcnt lgkmcnt(0)
	s_setprio 1
	v_mfma_f32_16x16x32_bf16 v[124:127], v[144:147], v[166:169], v[124:127]
	v_mfma_f32_16x16x32_bf16 v[120:123], v[158:161], v[166:169], v[120:123]
	v_mfma_f32_16x16x32_bf16 v[108:111], v[144:147], v[174:177], v[108:111]
	v_mfma_f32_16x16x32_bf16 v[104:107], v[158:161], v[174:177], v[104:107]
	v_mfma_f32_16x16x32_bf16 v[92:95], v[144:147], v[188:191], v[92:95]
	v_mfma_f32_16x16x32_bf16 v[88:91], v[158:161], v[188:191], v[88:91]
	v_mfma_f32_16x16x32_bf16 v[76:79], v[144:147], v[210:213], v[76:79]
	v_mfma_f32_16x16x32_bf16 v[72:75], v[158:161], v[210:213], v[72:75]
	v_mfma_f32_16x16x32_bf16 v[124:127], v[154:157], v[170:173], v[124:127]
	v_mfma_f32_16x16x32_bf16 v[120:123], v[162:165], v[170:173], v[120:123]
	v_mfma_f32_16x16x32_bf16 v[108:111], v[154:157], v[178:181], v[108:111]
	v_mfma_f32_16x16x32_bf16 v[104:107], v[162:165], v[178:181], v[104:107]
	v_mfma_f32_16x16x32_bf16 v[92:95], v[154:157], v[206:209], v[92:95]
	v_mfma_f32_16x16x32_bf16 v[88:91], v[162:165], v[206:209], v[88:91]
	v_mfma_f32_16x16x32_bf16 v[76:79], v[154:157], v[214:217], v[76:79]
	v_mfma_f32_16x16x32_bf16 v[72:75], v[162:165], v[214:217], v[72:75]
	s_setprio 0
	s_barrier
	s_add_i32 s5, 0, 0x1c000
	s_add_i32 s0, s4, s51
	v_add_u32_e32 v201, s5, v149
	s_add_i32 m0, s0, 0xffffff80
	ds_read_b128 v[218:221], v201
	ds_read_b128 v[222:225], v201 offset:1024
	ds_read_b128 v[226:229], v201 offset:2048
	global_load_lds_dwordx4 v132, s[46:47] offset:128
	s_add_i32 m0, s0, 0x1f80
	ds_read_b128 v[230:233], v201 offset:3072
	global_load_lds_dwordx4 v134, s[46:47] offset:128
	s_barrier
	s_waitcnt lgkmcnt(0)
	s_setprio 1
	v_mfma_f32_16x16x32_bf16 v[116:119], v[218:221], v[166:169], v[116:119]
	v_mfma_f32_16x16x32_bf16 v[112:115], v[226:229], v[166:169], v[112:115]
	v_mfma_f32_16x16x32_bf16 v[100:103], v[218:221], v[174:177], v[100:103]
	v_mfma_f32_16x16x32_bf16 v[96:99], v[226:229], v[174:177], v[96:99]
	v_mfma_f32_16x16x32_bf16 v[84:87], v[218:221], v[188:191], v[84:87]
	v_mfma_f32_16x16x32_bf16 v[80:83], v[226:229], v[188:191], v[80:83]
	v_mfma_f32_16x16x32_bf16 v[68:71], v[218:221], v[210:213], v[68:71]
	v_mfma_f32_16x16x32_bf16 v[64:67], v[226:229], v[210:213], v[64:67]
	v_mfma_f32_16x16x32_bf16 v[116:119], v[222:225], v[170:173], v[116:119]
	v_mfma_f32_16x16x32_bf16 v[112:115], v[230:233], v[170:173], v[112:115]
	v_mfma_f32_16x16x32_bf16 v[100:103], v[222:225], v[178:181], v[100:103]
	v_mfma_f32_16x16x32_bf16 v[96:99], v[230:233], v[178:181], v[96:99]
	v_mfma_f32_16x16x32_bf16 v[84:87], v[222:225], v[206:209], v[84:87]
	v_mfma_f32_16x16x32_bf16 v[80:83], v[230:233], v[206:209], v[80:83]
	v_mfma_f32_16x16x32_bf16 v[68:71], v[222:225], v[214:217], v[68:71]
	v_mfma_f32_16x16x32_bf16 v[64:67], v[230:233], v[214:217], v[64:67]
	s_setprio 0
	s_add_i32 m0, s63, 0xffffff80
	s_barrier
	ds_read_b128 v[166:169], v151 offset:49152
	ds_read_b128 v[170:173], v151 offset:50176
	ds_read_b128 v[174:177], v151 offset:51200
	ds_read_b128 v[178:181], v151 offset:52224
	ds_read_b128 v[188:191], v151 offset:53248
	ds_read_b128 v[206:209], v151 offset:54272
	ds_read_b128 v[210:213], v151 offset:55296
	global_load_lds_dwordx4 v128, s[48:49] offset:128
	s_add_i32 m0, s64, 0xffffff80
	ds_read_b128 v[214:217], v151 offset:56320
	global_load_lds_dwordx4 v130, s[48:49] offset:128
	s_barrier
	s_waitcnt lgkmcnt(0)
	s_setprio 1
	v_mfma_f32_16x16x32_bf16 v[60:63], v[144:147], v[166:169], v[60:63]
	v_mfma_f32_16x16x32_bf16 v[56:59], v[158:161], v[166:169], v[56:59]
	v_mfma_f32_16x16x32_bf16 v[44:47], v[144:147], v[174:177], v[44:47]
	v_mfma_f32_16x16x32_bf16 v[40:43], v[158:161], v[174:177], v[40:43]
	v_mfma_f32_16x16x32_bf16 v[28:31], v[144:147], v[188:191], v[28:31]
	v_mfma_f32_16x16x32_bf16 v[24:27], v[158:161], v[188:191], v[24:27]
	v_mfma_f32_16x16x32_bf16 v[12:15], v[144:147], v[210:213], v[12:15]
	v_mfma_f32_16x16x32_bf16 v[8:11], v[158:161], v[210:213], v[8:11]
	v_mfma_f32_16x16x32_bf16 v[60:63], v[154:157], v[170:173], v[60:63]
	v_mfma_f32_16x16x32_bf16 v[56:59], v[162:165], v[170:173], v[56:59]
	v_mfma_f32_16x16x32_bf16 v[44:47], v[154:157], v[178:181], v[44:47]
	v_mfma_f32_16x16x32_bf16 v[40:43], v[162:165], v[178:181], v[40:43]
	v_mfma_f32_16x16x32_bf16 v[28:31], v[154:157], v[206:209], v[28:31]
	v_mfma_f32_16x16x32_bf16 v[24:27], v[162:165], v[206:209], v[24:27]
	v_mfma_f32_16x16x32_bf16 v[12:15], v[154:157], v[214:217], v[12:15]
	v_mfma_f32_16x16x32_bf16 v[8:11], v[162:165], v[214:217], v[8:11]
	s_setprio 0
	s_barrier
	s_add_i32 s4, s5, s51
	s_mov_b32 m0, s4
	s_add_u32 s0, s46, 0x80080
	s_addc_u32 s1, s47, 0
	global_load_lds_dwordx4 v132, s[0:1]
	s_add_i32 m0, s4, 0x2000
	s_nop 0
	global_load_lds_dwordx4 v134, s[0:1]
	s_waitcnt vmcnt(6)
	s_barrier
	s_setprio 1
	v_mfma_f32_16x16x32_bf16 v[52:55], v[218:221], v[166:169], v[52:55]
	v_mfma_f32_16x16x32_bf16 v[48:51], v[226:229], v[166:169], v[48:51]
	v_mfma_f32_16x16x32_bf16 v[36:39], v[218:221], v[174:177], v[36:39]
	v_mfma_f32_16x16x32_bf16 v[32:35], v[226:229], v[174:177], v[32:35]
	v_mfma_f32_16x16x32_bf16 v[20:23], v[218:221], v[188:191], v[20:23]
	v_mfma_f32_16x16x32_bf16 v[16:19], v[226:229], v[188:191], v[16:19]
	v_mfma_f32_16x16x32_bf16 v[4:7], v[218:221], v[210:213], v[4:7]
	v_mfma_f32_16x16x32_bf16 v[0:3], v[226:229], v[210:213], v[0:3]
	v_mfma_f32_16x16x32_bf16 v[52:55], v[222:225], v[170:173], v[52:55]
	v_mfma_f32_16x16x32_bf16 v[48:51], v[230:233], v[170:173], v[48:51]
	v_mfma_f32_16x16x32_bf16 v[36:39], v[222:225], v[178:181], v[36:39]
	v_mfma_f32_16x16x32_bf16 v[32:35], v[230:233], v[178:181], v[32:35]
	v_mfma_f32_16x16x32_bf16 v[20:23], v[222:225], v[206:209], v[20:23]
	v_mfma_f32_16x16x32_bf16 v[16:19], v[230:233], v[206:209], v[16:19]
	v_mfma_f32_16x16x32_bf16 v[4:7], v[222:225], v[214:217], v[4:7]
	v_mfma_f32_16x16x32_bf16 v[0:3], v[230:233], v[214:217], v[0:3]
	s_setprio 0
	s_add_i32 s69, s69, 2
	s_add_u32 s44, s44, 0x100
	s_addc_u32 s45, s45, 0
	s_add_u32 s43, s43, 0x100
	s_addc_u32 s68, s68, 0
	s_cmp_gt_u32 s69, 29
	s_barrier
	s_cbranch_scc0 .LBB0_1508

;     DI size_t aoff(const Unit& u, size_t tstep) const { return (size_t)u.pm * tstep; }
;     DI size_t boff(const Unit& u, size_t tstep) const { return (size_t)u.pn * tstep; }
;     DI bool next(int i, Unit& u) const { const long L = (long)i * G + c; if (L >= np) return false; u.pm = pmv; u.pn = (int)(L % nN); u.ks = (int)(L / nN); return true; }
;     DI size_t aoff(const Unit& u, size_t) const { return (size_t)u.ks * kbytes; }
;     DI size_t boff(const Unit& u, size_t tstep) const { return (size_t)u.pn * tstep + (size_t)u.ks * kbytes; }
;     DI bool next(int i, Unit& u) const { Unit t; if (!S.next(i / 3, t)) return false; u.pm = t.pm; u.pn = t.pn; u.ks = i % 3; return true; }
;     DI size_t aoff(const Unit& u, size_t tstep) const { return (u.ks < 2 ? offU : offOA) + (size_t)u.pm * tstep; }
; #define PG8_LDA(dst, b, h) do { _Pragma("unroll") for (int m = 0; m < 4; ++m) _Pragma("unroll") for (int k = 0; k < 2; ++k) dst[m][k] = *(const LAS bf16x8*)(lds + PG8_SA(b, h) + aoff + m * 2048 + k * 1024); } while (0)
; template <class Epi, class Sched>
; DI void gemm_phase(LAS unsigned char* lds, const Gemm g, const Sched& S, const Epi& E) {
;     ...
;         const bool has_next = S.next(ui + 1, nxt);
;         const char* nA = has_next ? (const char*)g.A + S.aoff(nxt, tstep) : cA; const char* nB = has_next ? (const char*)g.Bt + S.boff(nxt, tstep) : cB;
;         for (int t = 0; t < nt; t += 2) {
;             if constexpr (Epi::HAS_MID) { if (t == E.mid_t(nt)) { int fr3 = fr, fq3 = fq; asm volatile("" : "+v"(fr3), "+v"(fq3)); E.mid(acc, cur, wr, wc, fr3, fq3); } }
;             const bool last = (t == nt - 2);
;             const char* a1 = cA + (size_t)(t + 1) * kstep;
;             const char* a2 = last ? nA : cA + (size_t)(t + 2) * kstep; const char* b2 = last ? nB : cB + (size_t)(t + 2) * kstep;
;             const char* a3 = a2 + kstep; const char* b3 = b2 + kstep;
;             PG8_LDB(B0, 0, 0); PG8_SCHED; PG8_LDA(At, 0, 0); PG8_STAGE(PG8_SA(1, 1), a1 + hstep, voffA);
;             PG8_WAIT_L(8); PG8_BAR; PG8_WAIT_L(0); PG8_MMA(0, 0, At, B0); PG8_BAR; PG8_SCHED;
;             PG8_LDB(B1, 0, 1); PG8_STAGE(PG8_SB(0, 0), b2, voffB);
;             PG8_BAR; PG8_WAIT_L(0); PG8_MMA(0, 1, At, B1); PG8_BAR;
;             PG8_LDA(At, 0, 1); PG8_STAGE(PG8_SA(0, 0), a2, voffA);
;             PG8_BAR; PG8_WAIT_L(0); PG8_MMA(1, 0, At, B0); PG8_BAR; PG8_SCHED;
.LBB0_1667:
	s_ashr_i32 s29, s28, 31
	s_lshl_b64 s[0:1], s[28:29], 20
	s_add_u32 s30, s45, s0
	v_cmp_lt_i64_e32 vcc, s[8:9], v[140:141]
	s_addc_u32 s31, s46, s1
	s_and_b64 s[0:1], vcc, exec
	s_cselect_b32 s29, s31, s43
	s_cselect_b32 s35, s30, s42
	s_ashr_i32 s19, s18, 31
	s_lshl_b64 s[0:1], s[18:19], 20
	s_add_u32 s36, s47, s0
	s_addc_u32 s37, s48, s1
	s_and_b64 s[0:1], vcc, exec
	s_cselect_b32 s19, s37, s41
	s_cselect_b32 s65, s36, s40
	s_add_u32 s8, s42, 0x80080
	s_addc_u32 s9, s43, 0
	s_add_u32 s66, s40, 0x100
	v_mov_b32_e32 v8, 0
	s_addc_u32 s67, s41, 0
	s_mov_b32 s68, -2
	ds_read_b128 v[144:147], v149
	ds_read_b128 v[156:159], v149 offset:1024
	ds_read_b128 v[160:163], v149 offset:2048
	ds_read_b128 v[164:167], v149 offset:3072
	s_add_u32 s0, s8, 0xfff80080
	s_addc_u32 s1, s9, -1
	s_cmp_eq_u32 s68, 28
	s_cselect_b32 s43, s29, s1
	s_cselect_b32 s42, s35, s0
	s_cselect_b32 s41, s19, s67
	s_cselect_b32 s40, s65, s66
	s_add_i32 m0, s39, 0xc000
	ds_read_b128 v[168:171], v150
	ds_read_b128 v[172:175], v150 offset:1024
	ds_read_b128 v[176:179], v150 offset:2048
	ds_read_b128 v[180:183], v150 offset:3072
	ds_read_b128 v[188:191], v150 offset:4096
	ds_read_b128 v[206:209], v150 offset:5120
	ds_read_b128 v[210:213], v150 offset:6144
	global_load_lds_dwordx4 v136, s[8:9]
	s_add_i32 m0, s39, 0xe000
	ds_read_b128 v[214:217], v150 offset:7168
	global_load_lds_dwordx4 v138, s[8:9]
	s_waitcnt lgkmcnt(8)
	s_barrier
	s_waitcnt lgkmcnt(0)
	s_setprio 1
	v_mfma_f32_16x16x32_bf16 v[116:119], v[144:147], v[168:171], 0
	v_mfma_f32_16x16x32_bf16 v[112:115], v[160:163], v[168:171], 0
	v_mfma_f32_16x16x32_bf16 v[100:103], v[144:147], v[176:179], 0
	v_mfma_f32_16x16x32_bf16 v[96:99], v[160:163], v[176:179], 0
	v_mfma_f32_16x16x32_bf16 v[84:87], v[144:147], v[188:191], 0
	v_mfma_f32_16x16x32_bf16 v[80:83], v[160:163], v[188:191], 0
	v_mfma_f32_16x16x32_bf16 v[68:71], v[144:147], v[210:213], 0
	v_mfma_f32_16x16x32_bf16 v[64:67], v[160:163], v[210:213], 0
	v_mfma_f32_16x16x32_bf16 v[116:119], v[156:159], v[172:175], v[116:119]
	v_mfma_f32_16x16x32_bf16 v[112:115], v[164:167], v[172:175], v[112:115]
	v_mfma_f32_16x16x32_bf16 v[100:103], v[156:159], v[180:183], v[100:103]
	v_mfma_f32_16x16x32_bf16 v[96:99], v[164:167], v[180:183], v[96:99]
	v_mfma_f32_16x16x32_bf16 v[84:87], v[156:159], v[206:209], v[84:87]
	v_mfma_f32_16x16x32_bf16 v[80:83], v[164:167], v[206:209], v[80:83]
	v_mfma_f32_16x16x32_bf16 v[68:71], v[156:159], v[214:217], v[68:71]
	v_mfma_f32_16x16x32_bf16 v[64:67], v[164:167], v[214:217], v[64:67]
	s_setprio 0
	s_barrier
	s_add_i32 s0, s61, s50
	s_mov_b32 m0, s0
	ds_read_b128 v[218:221], v151
	ds_read_b128 v[222:225], v151 offset:1024
	ds_read_b128 v[226:229], v151 offset:2048
	global_load_lds_dwordx4 v130, s[40:41]
	s_add_i32 m0, s0, 0x2000
	ds_read_b128 v[230:233], v151 offset:3072
	global_load_lds_dwordx4 v134, s[40:41]
	s_barrier
	s_waitcnt lgkmcnt(0)
	s_setprio 1
	v_mfma_f32_16x16x32_bf16 v[124:127], v[218:221], v[168:171], 0
	v_mfma_f32_16x16x32_bf16 v[120:123], v[226:229], v[168:171], 0
	v_mfma_f32_16x16x32_bf16 v[108:111], v[218:221], v[176:179], 0
	v_mfma_f32_16x16x32_bf16 v[104:107], v[226:229], v[176:179], 0
	v_mfma_f32_16x16x32_bf16 v[92:95], v[218:221], v[188:191], 0
	v_mfma_f32_16x16x32_bf16 v[88:91], v[226:229], v[188:191], 0
	v_mfma_f32_16x16x32_bf16 v[76:79], v[218:221], v[210:213], 0
	v_mfma_f32_16x16x32_bf16 v[72:75], v[226:229], v[210:213], 0
	v_mfma_f32_16x16x32_bf16 v[124:127], v[222:225], v[172:175], v[124:127]
	v_mfma_f32_16x16x32_bf16 v[120:123], v[230:233], v[172:175], v[120:123]
	v_mfma_f32_16x16x32_bf16 v[108:111], v[222:225], v[180:183], v[108:111]
	v_mfma_f32_16x16x32_bf16 v[104:107], v[230:233], v[180:183], v[104:107]
	v_mfma_f32_16x16x32_bf16 v[92:95], v[222:225], v[206:209], v[92:95]
	v_mfma_f32_16x16x32_bf16 v[88:91], v[230:233], v[206:209], v[88:91]
	v_mfma_f32_16x16x32_bf16 v[76:79], v[222:225], v[214:217], v[76:79]
	v_mfma_f32_16x16x32_bf16 v[72:75], v[230:233], v[214:217], v[72:75]
	s_setprio 0
	s_mov_b32 m0, s39
	s_barrier
	ds_read_b128 v[168:171], v150 offset:16384
	ds_read_b128 v[172:175], v150 offset:17408
	ds_read_b128 v[176:179], v150 offset:18432
	ds_read_b128 v[180:183], v150 offset:19456
	ds_read_b128 v[188:191], v150 offset:20480
	ds_read_b128 v[206:209], v150 offset:21504
	ds_read_b128 v[210:213], v150 offset:22528
	global_load_lds_dwordx4 v128, s[42:43]
	s_mov_b32 m0, s51
	ds_read_b128 v[214:217], v150 offset:23552
	global_load_lds_dwordx4 v132, s[42:43]
	s_barrier
	s_waitcnt lgkmcnt(0)
	s_setprio 1
	v_mfma_f32_16x16x32_bf16 v[52:55], v[144:147], v[168:171], 0
	v_mfma_f32_16x16x32_bf16 v[48:51], v[160:163], v[168:171], 0
	v_mfma_f32_16x16x32_bf16 v[36:39], v[144:147], v[176:179], 0
	v_mfma_f32_16x16x32_bf16 v[32:35], v[160:163], v[176:179], 0
	v_mfma_f32_16x16x32_bf16 v[20:23], v[144:147], v[188:191], 0
	v_mfma_f32_16x16x32_bf16 v[16:19], v[160:163], v[188:191], 0
	v_mfma_f32_16x16x32_bf16 v[4:7], v[144:147], v[210:213], 0
	v_mfma_f32_16x16x32_bf16 v[0:3], v[160:163], v[210:213], 0
	v_mfma_f32_16x16x32_bf16 v[52:55], v[156:159], v[172:175], v[52:55]
	v_mfma_f32_16x16x32_bf16 v[48:51], v[164:167], v[172:175], v[48:51]
	v_mfma_f32_16x16x32_bf16 v[36:39], v[156:159], v[180:183], v[36:39]
	v_mfma_f32_16x16x32_bf16 v[32:35], v[164:167], v[180:183], v[32:35]
	v_mfma_f32_16x16x32_bf16 v[20:23], v[156:159], v[206:209], v[20:23]
	v_mfma_f32_16x16x32_bf16 v[16:19], v[164:167], v[206:209], v[16:19]
	v_mfma_f32_16x16x32_bf16 v[4:7], v[156:159], v[214:217], v[4:7]
	v_mfma_f32_16x16x32_bf16 v[0:3], v[164:167], v[214:217], v[0:3]
	s_setprio 0
	s_barrier
; #define PG8_STAGE(bufoff, gbase, voff) do { _Pragma("unroll") for (int _i = 0; _i < 2; ++_i) \
;         __builtin_amdgcn_global_load_lds((const unsigned*)((const char*)(gbase) + (voff)[_i]), (LAS unsigned*)(lds + (bufoff) + ldsw + _i * 8192), 16, 0, 0); } while (0)
; #define PG8_LDA(dst, b, h) do { _Pragma("unroll") for (int m = 0; m < 4; ++m) _Pragma("unroll") for (int k = 0; k < 2; ++k) dst[m][k] = *(const LAS bf16x8*)(lds + PG8_SA(b, h) + aoff + m * 2048 + k * 1024); } while (0)
; #define PG8_LDB(dst, b, h) do { _Pragma("unroll") for (int n = 0; n < 2; ++n) _Pragma("unroll") for (int k = 0; k < 2; ++k) dst[n][k] = *(const LAS bf16x8*)(lds + PG8_SB(b, h) + boff + n * 2048 + k * 1024); } while (0)
; #define PG8_MMA(ai, bj, At, Bt) do { __builtin_amdgcn_s_setprio(1); _Pragma("unroll") for (int m = 0; m < 4; ++m) _Pragma("unroll") for (int n = 0; n < 2; ++n) _Pragma("unroll") for (int k = 0; k < 2; ++k) \
;         acc[ai][bj][m][n] = __builtin_amdgcn_mfma_f32_16x16x32_bf16(Bt[n][k], At[m][k], acc[ai][bj][m][n], 0, 0, 0); __builtin_amdgcn_s_setprio(0); } while (0)
; #define PG8_WAIT_V(n) asm volatile("s_waitcnt vmcnt(" #n ")" ::: "memory")
; #define PG8_WAIT_L(n) asm volatile("s_waitcnt lgkmcnt(" #n ")" ::: "memory")
; #define PG8_BAR __builtin_amdgcn_s_barrier()
; #define PG8_SCHED __builtin_amdgcn_sched_barrier(0)
; template <class Epi, class Sched>
; DI void gemm_phase(LAS unsigned char* lds, const Gemm g, const Sched& S, const Epi& E) {
;     ...
;             PG8_STAGE(PG8_SB(0, 1), b2 + hstep, voffB);
;             PG8_WAIT_V(6); PG8_BAR; PG8_MMA(1, 1, At, B1); PG8_BAR;
;             PG8_LDB(B0, 1, 0); PG8_SCHED; PG8_LDA(At, 1, 0); PG8_STAGE(PG8_SA(0, 1), a2 + hstep, voffA);
;             PG8_WAIT_L(8); PG8_BAR; PG8_WAIT_L(0); PG8_MMA(0, 0, At, B0); PG8_BAR; PG8_SCHED;
;             PG8_LDB(B1, 1, 1); PG8_STAGE(PG8_SB(1, 0), b3, voffB);
;             PG8_BAR; PG8_WAIT_L(0); PG8_MMA(0, 1, At, B1); PG8_BAR;
;             PG8_LDA(At, 1, 1); PG8_STAGE(PG8_SA(1, 0), a3, voffA);
	s_add_i32 s4, s62, s50
	s_mov_b32 m0, s4
	s_add_u32 s0, s40, 0x80000
	s_addc_u32 s1, s41, 0
	global_load_lds_dwordx4 v130, s[0:1]
	s_add_i32 m0, s4, 0x2000
	s_nop 0
	global_load_lds_dwordx4 v134, s[0:1]
	s_waitcnt vmcnt(6)
	s_barrier
	s_setprio 1
	v_mfma_f32_16x16x32_bf16 v[60:63], v[218:221], v[168:171], 0
	v_mfma_f32_16x16x32_bf16 v[56:59], v[226:229], v[168:171], 0
	v_mfma_f32_16x16x32_bf16 v[44:47], v[218:221], v[176:179], 0
	v_mfma_f32_16x16x32_bf16 v[40:43], v[226:229], v[176:179], 0
	v_mfma_f32_16x16x32_bf16 v[28:31], v[218:221], v[188:191], 0
	v_mfma_f32_16x16x32_bf16 v[24:27], v[226:229], v[188:191], 0
	v_mfma_f32_16x16x32_bf16 v[12:15], v[218:221], v[210:213], 0
	v_mfma_f32_16x16x32_bf16 v[8:11], v[226:229], v[210:213], 0
	v_mfma_f32_16x16x32_bf16 v[60:63], v[222:225], v[172:175], v[60:63]
	v_mfma_f32_16x16x32_bf16 v[56:59], v[230:233], v[172:175], v[56:59]
	v_mfma_f32_16x16x32_bf16 v[44:47], v[222:225], v[180:183], v[44:47]
	v_mfma_f32_16x16x32_bf16 v[40:43], v[230:233], v[180:183], v[40:43]
	v_mfma_f32_16x16x32_bf16 v[28:31], v[222:225], v[206:209], v[28:31]
	v_mfma_f32_16x16x32_bf16 v[24:27], v[230:233], v[206:209], v[24:27]
	v_mfma_f32_16x16x32_bf16 v[12:15], v[222:225], v[214:217], v[12:15]
	v_mfma_f32_16x16x32_bf16 v[8:11], v[230:233], v[214:217], v[8:11]
	s_setprio 0
	s_add_i32 s4, 0, 0x18000
	v_add_u32_e32 v202, s4, v148
	s_barrier
	ds_read_b128 v[144:147], v202
	ds_read_b128 v[156:159], v202 offset:1024
	ds_read_b128 v[160:163], v202 offset:2048
	ds_read_b128 v[164:167], v202 offset:3072
	s_add_u32 s0, s42, 0x80000
	s_addc_u32 s1, s43, 0
	s_mov_b32 m0, s52
	ds_read_b128 v[168:171], v150 offset:32768
	ds_read_b128 v[172:175], v150 offset:33792
	ds_read_b128 v[176:179], v150 offset:34816
	ds_read_b128 v[180:183], v150 offset:35840
	ds_read_b128 v[188:191], v150 offset:36864
	ds_read_b128 v[206:209], v150 offset:37888
	ds_read_b128 v[210:213], v150 offset:38912
	global_load_lds_dwordx4 v128, s[0:1]
	s_mov_b32 m0, s53
	ds_read_b128 v[214:217], v150 offset:39936
	global_load_lds_dwordx4 v132, s[0:1]
	s_waitcnt lgkmcnt(8)
	s_barrier
	s_waitcnt lgkmcnt(0)
	s_setprio 1
	v_mfma_f32_16x16x32_bf16 v[116:119], v[144:147], v[168:171], v[116:119]
	v_mfma_f32_16x16x32_bf16 v[112:115], v[160:163], v[168:171], v[112:115]
	v_mfma_f32_16x16x32_bf16 v[100:103], v[144:147], v[176:179], v[100:103]
	v_mfma_f32_16x16x32_bf16 v[96:99], v[160:163], v[176:179], v[96:99]
	v_mfma_f32_16x16x32_bf16 v[84:87], v[144:147], v[188:191], v[84:87]
	v_mfma_f32_16x16x32_bf16 v[80:83], v[160:163], v[188:191], v[80:83]
	v_mfma_f32_16x16x32_bf16 v[68:71], v[144:147], v[210:213], v[68:71]
	v_mfma_f32_16x16x32_bf16 v[64:67], v[160:163], v[210:213], v[64:67]
	v_mfma_f32_16x16x32_bf16 v[116:119], v[156:159], v[172:175], v[116:119]
	v_mfma_f32_16x16x32_bf16 v[112:115], v[164:167], v[172:175], v[112:115]
	v_mfma_f32_16x16x32_bf16 v[100:103], v[156:159], v[180:183], v[100:103]
	v_mfma_f32_16x16x32_bf16 v[96:99], v[164:167], v[180:183], v[96:99]
	v_mfma_f32_16x16x32_bf16 v[84:87], v[156:159], v[206:209], v[84:87]
	v_mfma_f32_16x16x32_bf16 v[80:83], v[164:167], v[206:209], v[80:83]
	v_mfma_f32_16x16x32_bf16 v[68:71], v[156:159], v[214:217], v[68:71]
	v_mfma_f32_16x16x32_bf16 v[64:67], v[164:167], v[214:217], v[64:67]
	s_setprio 0
	s_barrier
	s_add_i32 s5, 0, 0x1c000
	s_add_i32 s0, s4, s50
	v_add_u32_e32 v203, s5, v148
	s_add_i32 m0, s0, 0xffffff80
	ds_read_b128 v[218:221], v203
	ds_read_b128 v[222:225], v203 offset:1024
	ds_read_b128 v[226:229], v203 offset:2048
	global_load_lds_dwordx4 v130, s[40:41] offset:128
	s_add_i32 m0, s0, 0x1f80
	ds_read_b128 v[230:233], v203 offset:3072
	global_load_lds_dwordx4 v134, s[40:41] offset:128
	s_barrier
	s_waitcnt lgkmcnt(0)
	s_setprio 1
	v_mfma_f32_16x16x32_bf16 v[124:127], v[218:221], v[168:171], v[124:127]
	v_mfma_f32_16x16x32_bf16 v[120:123], v[226:229], v[168:171], v[120:123]
	v_mfma_f32_16x16x32_bf16 v[108:111], v[218:221], v[176:179], v[108:111]
	v_mfma_f32_16x16x32_bf16 v[104:107], v[226:229], v[176:179], v[104:107]
	v_mfma_f32_16x16x32_bf16 v[92:95], v[218:221], v[188:191], v[92:95]
	v_mfma_f32_16x16x32_bf16 v[88:91], v[226:229], v[188:191], v[88:91]
	v_mfma_f32_16x16x32_bf16 v[76:79], v[218:221], v[210:213], v[76:79]
	v_mfma_f32_16x16x32_bf16 v[72:75], v[226:229], v[210:213], v[72:75]
	v_mfma_f32_16x16x32_bf16 v[124:127], v[222:225], v[172:175], v[124:127]
	v_mfma_f32_16x16x32_bf16 v[120:123], v[230:233], v[172:175], v[120:123]
	v_mfma_f32_16x16x32_bf16 v[108:111], v[222:225], v[180:183], v[108:111]
	v_mfma_f32_16x16x32_bf16 v[104:107], v[230:233], v[180:183], v[104:107]
	v_mfma_f32_16x16x32_bf16 v[92:95], v[222:225], v[206:209], v[92:95]
	v_mfma_f32_16x16x32_bf16 v[88:91], v[230:233], v[206:209], v[88:91]
	v_mfma_f32_16x16x32_bf16 v[76:79], v[222:225], v[214:217], v[76:79]
	v_mfma_f32_16x16x32_bf16 v[72:75], v[230:233], v[214:217], v[72:75]
	s_setprio 0
	s_add_i32 m0, s57, 0xffffff80
	s_barrier
	ds_read_b128 v[168:171], v150 offset:49152
	ds_read_b128 v[172:175], v150 offset:50176
	ds_read_b128 v[176:179], v150 offset:51200
	ds_read_b128 v[180:183], v150 offset:52224
	ds_read_b128 v[188:191], v150 offset:53248
	ds_read_b128 v[206:209], v150 offset:54272
	ds_read_b128 v[210:213], v150 offset:55296
	global_load_lds_dwordx4 v128, s[42:43] offset:128
	s_add_i32 m0, s58, 0xffffff80
	ds_read_b128 v[214:217], v150 offset:56320
	global_load_lds_dwordx4 v132, s[42:43] offset:128
	s_barrier
; #define PG8_STAGE(bufoff, gbase, voff) do { _Pragma("unroll") for (int _i = 0; _i < 2; ++_i) \
;         __builtin_amdgcn_global_load_lds((const unsigned*)((const char*)(gbase) + (voff)[_i]), (LAS unsigned*)(lds + (bufoff) + ldsw + _i * 8192), 16, 0, 0); } while (0)
; #define PG8_LDA(dst, b, h) do { _Pragma("unroll") for (int m = 0; m < 4; ++m) _Pragma("unroll") for (int k = 0; k < 2; ++k) dst[m][k] = *(const LAS bf16x8*)(lds + PG8_SA(b, h) + aoff + m * 2048 + k * 1024); } while (0)
; #define PG8_LDB(dst, b, h) do { _Pragma("unroll") for (int n = 0; n < 2; ++n) _Pragma("unroll") for (int k = 0; k < 2; ++k) dst[n][k] = *(const LAS bf16x8*)(lds + PG8_SB(b, h) + boff + n * 2048 + k * 1024); } while (0)
; #define PG8_MMA(ai, bj, At, Bt) do { __builtin_amdgcn_s_setprio(1); _Pragma("unroll") for (int m = 0; m < 4; ++m) _Pragma("unroll") for (int n = 0; n < 2; ++n) _Pragma("unroll") for (int k = 0; k < 2; ++k) \
;         acc[ai][bj][m][n] = __builtin_amdgcn_mfma_f32_16x16x32_bf16(Bt[n][k], At[m][k], acc[ai][bj][m][n], 0, 0, 0); __builtin_amdgcn_s_setprio(0); } while (0)
; #define PG8_WAIT_V(n) asm volatile("s_waitcnt vmcnt(" #n ")" ::: "memory")
; #define PG8_WAIT_L(n) asm volatile("s_waitcnt lgkmcnt(" #n ")" ::: "memory")
; #define PG8_BAR __builtin_amdgcn_s_barrier()
; #define PG8_SCHED __builtin_amdgcn_sched_barrier(0)
; template <class Epi, class Sched>
; DI void gemm_phase(LAS unsigned char* lds, const Gemm g, const Sched& S, const Epi& E) {
;     ...
;             PG8_LDB(B0, 0, 0); PG8_SCHED; PG8_LDA(At, 0, 0); PG8_STAGE(PG8_SA(1, 1), a1 + hstep, voffA);
;             PG8_WAIT_L(8); PG8_BAR; PG8_WAIT_L(0); PG8_MMA(0, 0, At, B0); PG8_BAR; PG8_SCHED;
;             PG8_LDB(B1, 0, 1); PG8_STAGE(PG8_SB(0, 0), b2, voffB);
;     ...
;             PG8_BAR; PG8_WAIT_L(0); PG8_MMA(1, 0, At, B0); PG8_BAR; PG8_SCHED;
;             PG8_STAGE(PG8_SB(1, 1), b3 + hstep, voffB);
;             PG8_WAIT_V(6); PG8_BAR; PG8_MMA(1, 1, At, B1); PG8_BAR;
	s_waitcnt lgkmcnt(0)
	s_setprio 1
	v_mfma_f32_16x16x32_bf16 v[52:55], v[144:147], v[168:171], v[52:55]
	v_mfma_f32_16x16x32_bf16 v[48:51], v[160:163], v[168:171], v[48:51]
	v_mfma_f32_16x16x32_bf16 v[36:39], v[144:147], v[176:179], v[36:39]
	v_mfma_f32_16x16x32_bf16 v[32:35], v[160:163], v[176:179], v[32:35]
	v_mfma_f32_16x16x32_bf16 v[20:23], v[144:147], v[188:191], v[20:23]
	v_mfma_f32_16x16x32_bf16 v[16:19], v[160:163], v[188:191], v[16:19]
	v_mfma_f32_16x16x32_bf16 v[4:7], v[144:147], v[210:213], v[4:7]
	v_mfma_f32_16x16x32_bf16 v[0:3], v[160:163], v[210:213], v[0:3]
	v_mfma_f32_16x16x32_bf16 v[52:55], v[156:159], v[172:175], v[52:55]
	v_mfma_f32_16x16x32_bf16 v[48:51], v[164:167], v[172:175], v[48:51]
	v_mfma_f32_16x16x32_bf16 v[36:39], v[156:159], v[180:183], v[36:39]
	v_mfma_f32_16x16x32_bf16 v[32:35], v[164:167], v[180:183], v[32:35]
	v_mfma_f32_16x16x32_bf16 v[20:23], v[156:159], v[206:209], v[20:23]
	v_mfma_f32_16x16x32_bf16 v[16:19], v[164:167], v[206:209], v[16:19]
	v_mfma_f32_16x16x32_bf16 v[4:7], v[156:159], v[214:217], v[4:7]
	v_mfma_f32_16x16x32_bf16 v[0:3], v[164:167], v[214:217], v[0:3]
	s_setprio 0
	s_barrier
	s_add_i32 s4, s5, s50
	s_mov_b32 m0, s4
	s_add_u32 s0, s40, 0x80080
	s_addc_u32 s1, s41, 0
	global_load_lds_dwordx4 v130, s[0:1]
	s_add_i32 m0, s4, 0x2000
	s_nop 0
	global_load_lds_dwordx4 v134, s[0:1]
	s_waitcnt vmcnt(6)
	s_barrier
	s_setprio 1
	v_mfma_f32_16x16x32_bf16 v[60:63], v[218:221], v[168:171], v[60:63]
	v_mfma_f32_16x16x32_bf16 v[56:59], v[226:229], v[168:171], v[56:59]
	v_mfma_f32_16x16x32_bf16 v[44:47], v[218:221], v[176:179], v[44:47]
	v_mfma_f32_16x16x32_bf16 v[40:43], v[226:229], v[176:179], v[40:43]
	v_mfma_f32_16x16x32_bf16 v[28:31], v[218:221], v[188:191], v[28:31]
	v_mfma_f32_16x16x32_bf16 v[24:27], v[226:229], v[188:191], v[24:27]
	v_mfma_f32_16x16x32_bf16 v[12:15], v[218:221], v[210:213], v[12:15]
	v_mfma_f32_16x16x32_bf16 v[8:11], v[226:229], v[210:213], v[8:11]
	v_mfma_f32_16x16x32_bf16 v[60:63], v[222:225], v[172:175], v[60:63]
	v_mfma_f32_16x16x32_bf16 v[56:59], v[230:233], v[172:175], v[56:59]
	v_mfma_f32_16x16x32_bf16 v[44:47], v[222:225], v[180:183], v[44:47]
	v_mfma_f32_16x16x32_bf16 v[40:43], v[230:233], v[180:183], v[40:43]
	v_mfma_f32_16x16x32_bf16 v[28:31], v[222:225], v[206:209], v[28:31]
	v_mfma_f32_16x16x32_bf16 v[24:27], v[230:233], v[206:209], v[24:27]
	v_mfma_f32_16x16x32_bf16 v[12:15], v[222:225], v[214:217], v[12:15]
	v_mfma_f32_16x16x32_bf16 v[8:11], v[230:233], v[214:217], v[8:11]
	s_setprio 0
	s_add_i32 s68, s68, 2
	s_add_u32 s8, s8, 0x100
	s_addc_u32 s9, s9, 0
	s_add_u32 s66, s66, 0x100
	s_addc_u32 s67, s67, 0
	s_cmp_gt_u32 s68, 29
	s_barrier
	s_cbranch_scc0 .LBB0_1668
	s_branch .Lpeel_done_1668
.LBB0_1668:
	ds_read_b128 v[144:147], v149
	ds_read_b128 v[156:159], v149 offset:1024
	ds_read_b128 v[160:163], v149 offset:2048
	ds_read_b128 v[164:167], v149 offset:3072
	s_add_u32 s0, s8, 0xfff80080
	s_addc_u32 s1, s9, -1
	s_cmp_eq_u32 s68, 28
	s_cselect_b32 s43, s29, s1
	s_cselect_b32 s42, s35, s0
	s_cselect_b32 s41, s19, s67
	s_cselect_b32 s40, s65, s66
	s_add_i32 m0, s39, 0xc000
	ds_read_b128 v[168:171], v150
	ds_read_b128 v[172:175], v150 offset:1024
	ds_read_b128 v[176:179], v150 offset:2048
	ds_read_b128 v[180:183], v150 offset:3072
	ds_read_b128 v[188:191], v150 offset:4096
	ds_read_b128 v[206:209], v150 offset:5120
	ds_read_b128 v[210:213], v150 offset:6144
	global_load_lds_dwordx4 v136, s[8:9]
	s_add_i32 m0, s39, 0xe000
	ds_read_b128 v[214:217], v150 offset:7168
	global_load_lds_dwordx4 v138, s[8:9]
	s_waitcnt lgkmcnt(8)
	s_barrier
	s_waitcnt lgkmcnt(0)
	s_setprio 1
	v_mfma_f32_16x16x32_bf16 v[116:119], v[144:147], v[168:171], v[116:119]
	v_mfma_f32_16x16x32_bf16 v[112:115], v[160:163], v[168:171], v[112:115]
	v_mfma_f32_16x16x32_bf16 v[100:103], v[144:147], v[176:179], v[100:103]
	v_mfma_f32_16x16x32_bf16 v[96:99], v[160:163], v[176:179], v[96:99]
	v_mfma_f32_16x16x32_bf16 v[84:87], v[144:147], v[188:191], v[84:87]
	v_mfma_f32_16x16x32_bf16 v[80:83], v[160:163], v[188:191], v[80:83]
	v_mfma_f32_16x16x32_bf16 v[68:71], v[144:147], v[210:213], v[68:71]
	v_mfma_f32_16x16x32_bf16 v[64:67], v[160:163], v[210:213], v[64:67]
	v_mfma_f32_16x16x32_bf16 v[116:119], v[156:159], v[172:175], v[116:119]
	v_mfma_f32_16x16x32_bf16 v[112:115], v[164:167], v[172:175], v[112:115]
	v_mfma_f32_16x16x32_bf16 v[100:103], v[156:159], v[180:183], v[100:103]
	v_mfma_f32_16x16x32_bf16 v[96:99], v[164:167], v[180:183], v[96:99]
	v_mfma_f32_16x16x32_bf16 v[84:87], v[156:159], v[206:209], v[84:87]
	v_mfma_f32_16x16x32_bf16 v[80:83], v[164:167], v[206:209], v[80:83]
	v_mfma_f32_16x16x32_bf16 v[68:71], v[156:159], v[214:217], v[68:71]
	v_mfma_f32_16x16x32_bf16 v[64:67], v[164:167], v[214:217], v[64:67]
	s_setprio 0
	s_barrier
	s_add_i32 s0, s61, s50
	s_mov_b32 m0, s0
	ds_read_b128 v[218:221], v151
	ds_read_b128 v[222:225], v151 offset:1024
	ds_read_b128 v[226:229], v151 offset:2048
	global_load_lds_dwordx4 v130, s[40:41]
	s_add_i32 m0, s0, 0x2000
	ds_read_b128 v[230:233], v151 offset:3072
	global_load_lds_dwordx4 v134, s[40:41]
	s_barrier
; #define PG8_STAGE(bufoff, gbase, voff) do { _Pragma("unroll") for (int _i = 0; _i < 2; ++_i) \
;         __builtin_amdgcn_global_load_lds((const unsigned*)((const char*)(gbase) + (voff)[_i]), (LAS unsigned*)(lds + (bufoff) + ldsw + _i * 8192), 16, 0, 0); } while (0)
; #define PG8_LDA(dst, b, h) do { _Pragma("unroll") for (int m = 0; m < 4; ++m) _Pragma("unroll") for (int k = 0; k < 2; ++k) dst[m][k] = *(const LAS bf16x8*)(lds + PG8_SA(b, h) + aoff + m * 2048 + k * 1024); } while (0)
; #define PG8_LDB(dst, b, h) do { _Pragma("unroll") for (int n = 0; n < 2; ++n) _Pragma("unroll") for (int k = 0; k < 2; ++k) dst[n][k] = *(const LAS bf16x8*)(lds + PG8_SB(b, h) + boff + n * 2048 + k * 1024); } while (0)
; #define PG8_MMA(ai, bj, At, Bt) do { __builtin_amdgcn_s_setprio(1); _Pragma("unroll") for (int m = 0; m < 4; ++m) _Pragma("unroll") for (int n = 0; n < 2; ++n) _Pragma("unroll") for (int k = 0; k < 2; ++k) \
;         acc[ai][bj][m][n] = __builtin_amdgcn_mfma_f32_16x16x32_bf16(Bt[n][k], At[m][k], acc[ai][bj][m][n], 0, 0, 0); __builtin_amdgcn_s_setprio(0); } while (0)
; #define PG8_WAIT_V(n) asm volatile("s_waitcnt vmcnt(" #n ")" ::: "memory")
; #define PG8_WAIT_L(n) asm volatile("s_waitcnt lgkmcnt(" #n ")" ::: "memory")
; #define PG8_BAR __builtin_amdgcn_s_barrier()
; #define PG8_SCHED __builtin_amdgcn_sched_barrier(0)
; template <class Epi, class Sched>
; DI void gemm_phase(LAS unsigned char* lds, const Gemm g, const Sched& S, const Epi& E) {
;     ...
;             PG8_BAR; PG8_WAIT_L(0); PG8_MMA(0, 1, At, B1); PG8_BAR;
;             PG8_LDA(At, 0, 1); PG8_STAGE(PG8_SA(0, 0), a2, voffA);
;             PG8_BAR; PG8_WAIT_L(0); PG8_MMA(1, 0, At, B0); PG8_BAR; PG8_SCHED;
;             PG8_STAGE(PG8_SB(0, 1), b2 + hstep, voffB);
;             PG8_WAIT_V(6); PG8_BAR; PG8_MMA(1, 1, At, B1); PG8_BAR;
;             PG8_LDB(B0, 1, 0); PG8_SCHED; PG8_LDA(At, 1, 0); PG8_STAGE(PG8_SA(0, 1), a2 + hstep, voffA);
;             PG8_WAIT_L(8); PG8_BAR; PG8_WAIT_L(0); PG8_MMA(0, 0, At, B0); PG8_BAR; PG8_SCHED;
	s_waitcnt lgkmcnt(0)
	s_setprio 1
	v_mfma_f32_16x16x32_bf16 v[124:127], v[218:221], v[168:171], v[124:127]
	v_mfma_f32_16x16x32_bf16 v[120:123], v[226:229], v[168:171], v[120:123]
	v_mfma_f32_16x16x32_bf16 v[108:111], v[218:221], v[176:179], v[108:111]
	v_mfma_f32_16x16x32_bf16 v[104:107], v[226:229], v[176:179], v[104:107]
	v_mfma_f32_16x16x32_bf16 v[92:95], v[218:221], v[188:191], v[92:95]
	v_mfma_f32_16x16x32_bf16 v[88:91], v[226:229], v[188:191], v[88:91]
	v_mfma_f32_16x16x32_bf16 v[76:79], v[218:221], v[210:213], v[76:79]
	v_mfma_f32_16x16x32_bf16 v[72:75], v[226:229], v[210:213], v[72:75]
	v_mfma_f32_16x16x32_bf16 v[124:127], v[222:225], v[172:175], v[124:127]
	v_mfma_f32_16x16x32_bf16 v[120:123], v[230:233], v[172:175], v[120:123]
	v_mfma_f32_16x16x32_bf16 v[108:111], v[222:225], v[180:183], v[108:111]
	v_mfma_f32_16x16x32_bf16 v[104:107], v[230:233], v[180:183], v[104:107]
	v_mfma_f32_16x16x32_bf16 v[92:95], v[222:225], v[206:209], v[92:95]
	v_mfma_f32_16x16x32_bf16 v[88:91], v[230:233], v[206:209], v[88:91]
	v_mfma_f32_16x16x32_bf16 v[76:79], v[222:225], v[214:217], v[76:79]
	v_mfma_f32_16x16x32_bf16 v[72:75], v[230:233], v[214:217], v[72:75]
	s_setprio 0
	s_mov_b32 m0, s39
	s_barrier
	ds_read_b128 v[168:171], v150 offset:16384
	ds_read_b128 v[172:175], v150 offset:17408
	ds_read_b128 v[176:179], v150 offset:18432
	ds_read_b128 v[180:183], v150 offset:19456
	ds_read_b128 v[188:191], v150 offset:20480
	ds_read_b128 v[206:209], v150 offset:21504
	ds_read_b128 v[210:213], v150 offset:22528
	global_load_lds_dwordx4 v128, s[42:43]
	s_mov_b32 m0, s51
	ds_read_b128 v[214:217], v150 offset:23552
	global_load_lds_dwordx4 v132, s[42:43]
	s_barrier
	s_waitcnt lgkmcnt(0)
	s_setprio 1
	v_mfma_f32_16x16x32_bf16 v[52:55], v[144:147], v[168:171], v[52:55]
	v_mfma_f32_16x16x32_bf16 v[48:51], v[160:163], v[168:171], v[48:51]
	v_mfma_f32_16x16x32_bf16 v[36:39], v[144:147], v[176:179], v[36:39]
	v_mfma_f32_16x16x32_bf16 v[32:35], v[160:163], v[176:179], v[32:35]
	v_mfma_f32_16x16x32_bf16 v[20:23], v[144:147], v[188:191], v[20:23]
	v_mfma_f32_16x16x32_bf16 v[16:19], v[160:163], v[188:191], v[16:19]
	v_mfma_f32_16x16x32_bf16 v[4:7], v[144:147], v[210:213], v[4:7]
	v_mfma_f32_16x16x32_bf16 v[0:3], v[160:163], v[210:213], v[0:3]
	v_mfma_f32_16x16x32_bf16 v[52:55], v[156:159], v[172:175], v[52:55]
	v_mfma_f32_16x16x32_bf16 v[48:51], v[164:167], v[172:175], v[48:51]
	v_mfma_f32_16x16x32_bf16 v[36:39], v[156:159], v[180:183], v[36:39]
	v_mfma_f32_16x16x32_bf16 v[32:35], v[164:167], v[180:183], v[32:35]
	v_mfma_f32_16x16x32_bf16 v[20:23], v[156:159], v[206:209], v[20:23]
	v_mfma_f32_16x16x32_bf16 v[16:19], v[164:167], v[206:209], v[16:19]
	v_mfma_f32_16x16x32_bf16 v[4:7], v[156:159], v[214:217], v[4:7]
	v_mfma_f32_16x16x32_bf16 v[0:3], v[164:167], v[214:217], v[0:3]
	s_setprio 0
	s_barrier
	s_add_i32 s4, s62, s50
	s_mov_b32 m0, s4
	s_add_u32 s0, s40, 0x80000
	s_addc_u32 s1, s41, 0
	global_load_lds_dwordx4 v130, s[0:1]
	s_add_i32 m0, s4, 0x2000
	s_nop 0
	global_load_lds_dwordx4 v134, s[0:1]
	s_waitcnt vmcnt(6)
	s_barrier
	s_setprio 1
	v_mfma_f32_16x16x32_bf16 v[60:63], v[218:221], v[168:171], v[60:63]
	v_mfma_f32_16x16x32_bf16 v[56:59], v[226:229], v[168:171], v[56:59]
	v_mfma_f32_16x16x32_bf16 v[44:47], v[218:221], v[176:179], v[44:47]
	v_mfma_f32_16x16x32_bf16 v[40:43], v[226:229], v[176:179], v[40:43]
	v_mfma_f32_16x16x32_bf16 v[28:31], v[218:221], v[188:191], v[28:31]
	v_mfma_f32_16x16x32_bf16 v[24:27], v[226:229], v[188:191], v[24:27]
	v_mfma_f32_16x16x32_bf16 v[12:15], v[218:221], v[210:213], v[12:15]
	v_mfma_f32_16x16x32_bf16 v[8:11], v[226:229], v[210:213], v[8:11]
	v_mfma_f32_16x16x32_bf16 v[60:63], v[222:225], v[172:175], v[60:63]
	v_mfma_f32_16x16x32_bf16 v[56:59], v[230:233], v[172:175], v[56:59]
	v_mfma_f32_16x16x32_bf16 v[44:47], v[222:225], v[180:183], v[44:47]
	v_mfma_f32_16x16x32_bf16 v[40:43], v[230:233], v[180:183], v[40:43]
	v_mfma_f32_16x16x32_bf16 v[28:31], v[222:225], v[206:209], v[28:31]
	v_mfma_f32_16x16x32_bf16 v[24:27], v[230:233], v[206:209], v[24:27]
	v_mfma_f32_16x16x32_bf16 v[12:15], v[222:225], v[214:217], v[12:15]
	v_mfma_f32_16x16x32_bf16 v[8:11], v[230:233], v[214:217], v[8:11]
	s_setprio 0
	s_add_i32 s4, 0, 0x18000
	s_barrier
	ds_read_b128 v[144:147], v202
	ds_read_b128 v[156:159], v202 offset:1024
	ds_read_b128 v[160:163], v202 offset:2048
	ds_read_b128 v[164:167], v202 offset:3072
	s_add_u32 s0, s42, 0x80000
	s_addc_u32 s1, s43, 0
	s_mov_b32 m0, s52
	ds_read_b128 v[168:171], v150 offset:32768
	ds_read_b128 v[172:175], v150 offset:33792
	ds_read_b128 v[176:179], v150 offset:34816
	ds_read_b128 v[180:183], v150 offset:35840
	ds_read_b128 v[188:191], v150 offset:36864
	ds_read_b128 v[206:209], v150 offset:37888
	ds_read_b128 v[210:213], v150 offset:38912
	global_load_lds_dwordx4 v128, s[0:1]
	s_mov_b32 m0, s53
	ds_read_b128 v[214:217], v150 offset:39936
	global_load_lds_dwordx4 v132, s[0:1]
	s_waitcnt lgkmcnt(8)
	s_barrier
; #define PG8_STAGE(bufoff, gbase, voff) do { _Pragma("unroll") for (int _i = 0; _i < 2; ++_i) \
;         __builtin_amdgcn_global_load_lds((const unsigned*)((const char*)(gbase) + (voff)[_i]), (LAS unsigned*)(lds + (bufoff) + ldsw + _i * 8192), 16, 0, 0); } while (0)
; #define PG8_LDA(dst, b, h) do { _Pragma("unroll") for (int m = 0; m < 4; ++m) _Pragma("unroll") for (int k = 0; k < 2; ++k) dst[m][k] = *(const LAS bf16x8*)(lds + PG8_SA(b, h) + aoff + m * 2048 + k * 1024); } while (0)
; #define PG8_LDB(dst, b, h) do { _Pragma("unroll") for (int n = 0; n < 2; ++n) _Pragma("unroll") for (int k = 0; k < 2; ++k) dst[n][k] = *(const LAS bf16x8*)(lds + PG8_SB(b, h) + boff + n * 2048 + k * 1024); } while (0)
; #define PG8_MMA(ai, bj, At, Bt) do { __builtin_amdgcn_s_setprio(1); _Pragma("unroll") for (int m = 0; m < 4; ++m) _Pragma("unroll") for (int n = 0; n < 2; ++n) _Pragma("unroll") for (int k = 0; k < 2; ++k) \
;         acc[ai][bj][m][n] = __builtin_amdgcn_mfma_f32_16x16x32_bf16(Bt[n][k], At[m][k], acc[ai][bj][m][n], 0, 0, 0); __builtin_amdgcn_s_setprio(0); } while (0)
; #define PG8_WAIT_V(n) asm volatile("s_waitcnt vmcnt(" #n ")" ::: "memory")
; #define PG8_WAIT_L(n) asm volatile("s_waitcnt lgkmcnt(" #n ")" ::: "memory")
; #define PG8_BAR __builtin_amdgcn_s_barrier()
; #define PG8_SCHED __builtin_amdgcn_sched_barrier(0)
; template <class Epi, class Sched>
; DI void gemm_phase(LAS unsigned char* lds, const Gemm g, const Sched& S, const Epi& E) {
;     ...
;             PG8_WAIT_L(8); PG8_BAR; PG8_WAIT_L(0); PG8_MMA(0, 0, At, B0); PG8_BAR; PG8_SCHED;
;             PG8_LDB(B1, 1, 1); PG8_STAGE(PG8_SB(1, 0), b3, voffB);
;             PG8_BAR; PG8_WAIT_L(0); PG8_MMA(0, 1, At, B1); PG8_BAR;
;             PG8_LDA(At, 1, 1); PG8_STAGE(PG8_SA(1, 0), a3, voffA);
;             PG8_BAR; PG8_WAIT_L(0); PG8_MMA(1, 0, At, B0); PG8_BAR; PG8_SCHED;
;             PG8_STAGE(PG8_SB(1, 1), b3 + hstep, voffB);
;             PG8_WAIT_V(6); PG8_BAR; PG8_MMA(1, 1, At, B1); PG8_BAR;
	s_waitcnt lgkmcnt(0)
	s_setprio 1
	v_mfma_f32_16x16x32_bf16 v[116:119], v[144:147], v[168:171], v[116:119]
	v_mfma_f32_16x16x32_bf16 v[112:115], v[160:163], v[168:171], v[112:115]
	v_mfma_f32_16x16x32_bf16 v[100:103], v[144:147], v[176:179], v[100:103]
	v_mfma_f32_16x16x32_bf16 v[96:99], v[160:163], v[176:179], v[96:99]
	v_mfma_f32_16x16x32_bf16 v[84:87], v[144:147], v[188:191], v[84:87]
	v_mfma_f32_16x16x32_bf16 v[80:83], v[160:163], v[188:191], v[80:83]
	v_mfma_f32_16x16x32_bf16 v[68:71], v[144:147], v[210:213], v[68:71]
	v_mfma_f32_16x16x32_bf16 v[64:67], v[160:163], v[210:213], v[64:67]
	v_mfma_f32_16x16x32_bf16 v[116:119], v[156:159], v[172:175], v[116:119]
	v_mfma_f32_16x16x32_bf16 v[112:115], v[164:167], v[172:175], v[112:115]
	v_mfma_f32_16x16x32_bf16 v[100:103], v[156:159], v[180:183], v[100:103]
	v_mfma_f32_16x16x32_bf16 v[96:99], v[164:167], v[180:183], v[96:99]
	v_mfma_f32_16x16x32_bf16 v[84:87], v[156:159], v[206:209], v[84:87]
	v_mfma_f32_16x16x32_bf16 v[80:83], v[164:167], v[206:209], v[80:83]
	v_mfma_f32_16x16x32_bf16 v[68:71], v[156:159], v[214:217], v[68:71]
	v_mfma_f32_16x16x32_bf16 v[64:67], v[164:167], v[214:217], v[64:67]
	s_setprio 0
	s_barrier
	s_add_i32 s5, 0, 0x1c000
	s_add_i32 s0, s4, s50
	s_add_i32 m0, s0, 0xffffff80
	ds_read_b128 v[218:221], v203
	ds_read_b128 v[222:225], v203 offset:1024
	ds_read_b128 v[226:229], v203 offset:2048
	global_load_lds_dwordx4 v130, s[40:41] offset:128
	s_add_i32 m0, s0, 0x1f80
	ds_read_b128 v[230:233], v203 offset:3072
	global_load_lds_dwordx4 v134, s[40:41] offset:128
	s_barrier
	s_waitcnt lgkmcnt(0)
	s_setprio 1
	v_mfma_f32_16x16x32_bf16 v[124:127], v[218:221], v[168:171], v[124:127]
	v_mfma_f32_16x16x32_bf16 v[120:123], v[226:229], v[168:171], v[120:123]
	v_mfma_f32_16x16x32_bf16 v[108:111], v[218:221], v[176:179], v[108:111]
	v_mfma_f32_16x16x32_bf16 v[104:107], v[226:229], v[176:179], v[104:107]
	v_mfma_f32_16x16x32_bf16 v[92:95], v[218:221], v[188:191], v[92:95]
	v_mfma_f32_16x16x32_bf16 v[88:91], v[226:229], v[188:191], v[88:91]
	v_mfma_f32_16x16x32_bf16 v[76:79], v[218:221], v[210:213], v[76:79]
	v_mfma_f32_16x16x32_bf16 v[72:75], v[226:229], v[210:213], v[72:75]
	v_mfma_f32_16x16x32_bf16 v[124:127], v[222:225], v[172:175], v[124:127]
	v_mfma_f32_16x16x32_bf16 v[120:123], v[230:233], v[172:175], v[120:123]
	v_mfma_f32_16x16x32_bf16 v[108:111], v[222:225], v[180:183], v[108:111]
	v_mfma_f32_16x16x32_bf16 v[104:107], v[230:233], v[180:183], v[104:107]
	v_mfma_f32_16x16x32_bf16 v[92:95], v[222:225], v[206:209], v[92:95]
	v_mfma_f32_16x16x32_bf16 v[88:91], v[230:233], v[206:209], v[88:91]
	v_mfma_f32_16x16x32_bf16 v[76:79], v[222:225], v[214:217], v[76:79]
	v_mfma_f32_16x16x32_bf16 v[72:75], v[230:233], v[214:217], v[72:75]
	s_setprio 0
	s_add_i32 m0, s57, 0xffffff80
	s_barrier
	ds_read_b128 v[168:171], v150 offset:49152
	ds_read_b128 v[172:175], v150 offset:50176
	ds_read_b128 v[176:179], v150 offset:51200
	ds_read_b128 v[180:183], v150 offset:52224
	ds_read_b128 v[188:191], v150 offset:53248
	ds_read_b128 v[206:209], v150 offset:54272
	ds_read_b128 v[210:213], v150 offset:55296
	global_load_lds_dwordx4 v128, s[42:43] offset:128
	s_add_i32 m0, s58, 0xffffff80
	ds_read_b128 v[214:217], v150 offset:56320
	global_load_lds_dwordx4 v132, s[42:43] offset:128
	s_barrier
	s_waitcnt lgkmcnt(0)
	s_setprio 1
	v_mfma_f32_16x16x32_bf16 v[52:55], v[144:147], v[168:171], v[52:55]
	v_mfma_f32_16x16x32_bf16 v[48:51], v[160:163], v[168:171], v[48:51]
	v_mfma_f32_16x16x32_bf16 v[36:39], v[144:147], v[176:179], v[36:39]
	v_mfma_f32_16x16x32_bf16 v[32:35], v[160:163], v[176:179], v[32:35]
	v_mfma_f32_16x16x32_bf16 v[20:23], v[144:147], v[188:191], v[20:23]
	v_mfma_f32_16x16x32_bf16 v[16:19], v[160:163], v[188:191], v[16:19]
	v_mfma_f32_16x16x32_bf16 v[4:7], v[144:147], v[210:213], v[4:7]
	v_mfma_f32_16x16x32_bf16 v[0:3], v[160:163], v[210:213], v[0:3]
	v_mfma_f32_16x16x32_bf16 v[52:55], v[156:159], v[172:175], v[52:55]
	v_mfma_f32_16x16x32_bf16 v[48:51], v[164:167], v[172:175], v[48:51]
	v_mfma_f32_16x16x32_bf16 v[36:39], v[156:159], v[180:183], v[36:39]
	v_mfma_f32_16x16x32_bf16 v[32:35], v[164:167], v[180:183], v[32:35]
	v_mfma_f32_16x16x32_bf16 v[20:23], v[156:159], v[206:209], v[20:23]
	v_mfma_f32_16x16x32_bf16 v[16:19], v[164:167], v[206:209], v[16:19]
	v_mfma_f32_16x16x32_bf16 v[4:7], v[156:159], v[214:217], v[4:7]
	v_mfma_f32_16x16x32_bf16 v[0:3], v[164:167], v[214:217], v[0:3]
	s_setprio 0
	s_barrier
	s_add_i32 s4, s5, s50
	s_mov_b32 m0, s4
	s_add_u32 s0, s40, 0x80080
	s_addc_u32 s1, s41, 0
	global_load_lds_dwordx4 v130, s[0:1]
	s_add_i32 m0, s4, 0x2000
	s_nop 0
	global_load_lds_dwordx4 v134, s[0:1]
	s_waitcnt vmcnt(6)
	s_barrier
	s_setprio 1
	v_mfma_f32_16x16x32_bf16 v[60:63], v[218:221], v[168:171], v[60:63]
	v_mfma_f32_16x16x32_bf16 v[56:59], v[226:229], v[168:171], v[56:59]
	v_mfma_f32_16x16x32_bf16 v[44:47], v[218:221], v[176:179], v[44:47]
	v_mfma_f32_16x16x32_bf16 v[40:43], v[226:229], v[176:179], v[40:43]
	v_mfma_f32_16x16x32_bf16 v[28:31], v[218:221], v[188:191], v[28:31]
	v_mfma_f32_16x16x32_bf16 v[24:27], v[226:229], v[188:191], v[24:27]
	v_mfma_f32_16x16x32_bf16 v[12:15], v[218:221], v[210:213], v[12:15]
	v_mfma_f32_16x16x32_bf16 v[8:11], v[226:229], v[210:213], v[8:11]
	v_mfma_f32_16x16x32_bf16 v[60:63], v[222:225], v[172:175], v[60:63]
	v_mfma_f32_16x16x32_bf16 v[56:59], v[230:233], v[172:175], v[56:59]
	v_mfma_f32_16x16x32_bf16 v[44:47], v[222:225], v[180:183], v[44:47]
	v_mfma_f32_16x16x32_bf16 v[40:43], v[230:233], v[180:183], v[40:43]
	v_mfma_f32_16x16x32_bf16 v[28:31], v[222:225], v[206:209], v[28:31]
	v_mfma_f32_16x16x32_bf16 v[24:27], v[230:233], v[206:209], v[24:27]
	v_mfma_f32_16x16x32_bf16 v[12:15], v[222:225], v[214:217], v[12:15]
	v_mfma_f32_16x16x32_bf16 v[8:11], v[230:233], v[214:217], v[8:11]
	s_setprio 0
	s_add_i32 s68, s68, 2
	s_add_u32 s8, s8, 0x100
	s_addc_u32 s9, s9, 0
	s_add_u32 s66, s66, 0x100
	s_addc_u32 s67, s67, 0
	s_cmp_gt_u32 s68, 29
	s_barrier
	s_cbranch_scc0 .LBB0_1668

;     DI size_t aoff(const Unit& u, size_t tstep) const { return (size_t)u.pm * tstep; }
;     DI size_t boff(const Unit& u, size_t tstep) const { return (size_t)u.pn * tstep; }
;     DI bool next(int i, Unit& u) const { const long L = (long)i * G + c; if (L >= np) return false; u.pm = pmv; u.pn = (int)(L % nN); u.ks = (int)(L / nN); return true; }
;     DI size_t aoff(const Unit& u, size_t) const { return (size_t)u.ks * kbytes; }
;     DI size_t boff(const Unit& u, size_t tstep) const { return (size_t)u.pn * tstep + (size_t)u.ks * kbytes; }
;     DI bool next(int i, Unit& u) const { Unit t; if (!S.next(i / 3, t)) return false; u.pm = t.pm; u.pn = t.pn; u.ks = i % 3; return true; }
;     DI size_t aoff(const Unit& u, size_t tstep) const { return (u.ks < 2 ? offU : offOA) + (size_t)u.pm * tstep; }
; #define PG8_WAIT_V(n) asm volatile("s_waitcnt vmcnt(" #n ")" ::: "memory")
; template <class Epi, class Sched>
; DI void gemm_phase(LAS unsigned char* lds, const Gemm g, const Sched& S, const Epi& E) {
;     ...
;         const bool has_next = S.next(ui + 1, nxt);
;         const char* nA = has_next ? (const char*)g.A + S.aoff(nxt, tstep) : cA; const char* nB = has_next ? (const char*)g.Bt + S.boff(nxt, tstep) : cB;
;         for (int t = 0; t < nt; t += 2) {
;             if constexpr (Epi::HAS_MID) { if (t == E.mid_t(nt)) { int fr3 = fr, fq3 = fq; asm volatile("" : "+v"(fr3), "+v"(fq3)); E.mid(acc, cur, wr, wc, fr3, fq3); } }
;             const bool last = (t == nt - 2);
;             const char* a1 = cA + (size_t)(t + 1) * kstep;
;             const char* a2 = last ? nA : cA + (size_t)(t + 2) * kstep; const char* b2 = last ? nB : cB + (size_t)(t + 2) * kstep;
;             const char* a3 = a2 + kstep; const char* b3 = b2 + kstep;
;             PG8_LDB(B0, 0, 0); PG8_SCHED; PG8_LDA(At, 0, 0); PG8_STAGE(PG8_SA(1, 1), a1 + hstep, voffA);
;             PG8_WAIT_L(8); PG8_BAR; PG8_WAIT_L(0); PG8_MMA(0, 0, At, B0); PG8_BAR; PG8_SCHED;
;             PG8_LDB(B1, 0, 1); PG8_STAGE(PG8_SB(0, 0), b2, voffB);
;             PG8_BAR; PG8_WAIT_L(0); PG8_MMA(0, 1, At, B1); PG8_BAR;
;             PG8_LDA(At, 0, 1); PG8_STAGE(PG8_SA(0, 0), a2, voffA);
;             PG8_BAR; PG8_WAIT_L(0); PG8_MMA(1, 0, At, B0); PG8_BAR; PG8_SCHED;
;             PG8_STAGE(PG8_SB(0, 1), b2 + hstep, voffB);
;             PG8_WAIT_V(6); PG8_BAR; PG8_MMA(1, 1, At, B1); PG8_BAR;
.LBB0_1745:
	s_add_u32 s38, s38, 0x160080
	s_addc_u32 s39, s39, 0
	s_add_u32 s35, s40, 0x100
	v_mov_b32_e32 v0, 0
	s_addc_u32 s67, s41, 0
	s_mov_b32 s68, -2
	s_waitcnt lgkmcnt(0)
	ds_read_b128 v[144:147], v155
	ds_read_b128 v[160:163], v155 offset:1024
	ds_read_b128 v[164:167], v155 offset:2048
	ds_read_b128 v[168:171], v155 offset:3072
	s_add_u32 s0, s38, 0xffea0080
	s_addc_u32 s1, s39, -1
	s_cmpk_eq_i32 s68, 0x54
	s_cselect_b32 s43, s9, s1
	s_cselect_b32 s42, s8, s0
	s_cselect_b32 s41, s11, s67
	s_cselect_b32 s40, s10, s35
	s_add_i32 m0, s52, 0xc000
	ds_read_b128 v[172:175], v156
	ds_read_b128 v[176:179], v156 offset:1024
	ds_read_b128 v[180:183], v156 offset:2048
	ds_read_b128 v[188:191], v156 offset:3072
	ds_read_b128 v[206:209], v156 offset:4096
	ds_read_b128 v[210:213], v156 offset:5120
	ds_read_b128 v[214:217], v156 offset:6144
	global_load_lds_dwordx4 v136, s[38:39]
	s_add_i32 m0, s52, 0xe000
	ds_read_b128 v[218:221], v156 offset:7168
	global_load_lds_dwordx4 v138, s[38:39]
	s_waitcnt lgkmcnt(8)
	s_barrier
	s_waitcnt lgkmcnt(0)
	s_setprio 1
	v_mfma_f32_16x16x32_bf16 v[124:127], v[144:147], v[172:175], 0
	v_mfma_f32_16x16x32_bf16 v[120:123], v[164:167], v[172:175], 0
	v_mfma_f32_16x16x32_bf16 v[108:111], v[144:147], v[180:183], 0
	v_mfma_f32_16x16x32_bf16 v[104:107], v[164:167], v[180:183], 0
	v_mfma_f32_16x16x32_bf16 v[92:95], v[144:147], v[206:209], 0
	v_mfma_f32_16x16x32_bf16 v[88:91], v[164:167], v[206:209], 0
	v_mfma_f32_16x16x32_bf16 v[76:79], v[144:147], v[214:217], 0
	v_mfma_f32_16x16x32_bf16 v[72:75], v[164:167], v[214:217], 0
	v_mfma_f32_16x16x32_bf16 v[124:127], v[160:163], v[176:179], v[124:127]
	v_mfma_f32_16x16x32_bf16 v[120:123], v[168:171], v[176:179], v[120:123]
	v_mfma_f32_16x16x32_bf16 v[108:111], v[160:163], v[188:191], v[108:111]
	v_mfma_f32_16x16x32_bf16 v[104:107], v[168:171], v[188:191], v[104:107]
	v_mfma_f32_16x16x32_bf16 v[92:95], v[160:163], v[210:213], v[92:95]
	v_mfma_f32_16x16x32_bf16 v[88:91], v[168:171], v[210:213], v[88:91]
	v_mfma_f32_16x16x32_bf16 v[76:79], v[160:163], v[218:221], v[76:79]
	v_mfma_f32_16x16x32_bf16 v[72:75], v[168:171], v[218:221], v[72:75]
	s_setprio 0
	s_barrier
	s_add_i32 s0, s61, s51
	s_mov_b32 m0, s0
	ds_read_b128 v[222:225], v157
	ds_read_b128 v[226:229], v157 offset:1024
	ds_read_b128 v[230:233], v157 offset:2048
	global_load_lds_dwordx4 v130, s[40:41]
	s_add_i32 m0, s0, 0x2000
	ds_read_b128 v[234:237], v157 offset:3072
	global_load_lds_dwordx4 v134, s[40:41]
	s_barrier
	s_waitcnt lgkmcnt(0)
	s_setprio 1
	v_mfma_f32_16x16x32_bf16 v[116:119], v[222:225], v[172:175], 0
	v_mfma_f32_16x16x32_bf16 v[112:115], v[230:233], v[172:175], 0
	v_mfma_f32_16x16x32_bf16 v[100:103], v[222:225], v[180:183], 0
	v_mfma_f32_16x16x32_bf16 v[96:99], v[230:233], v[180:183], 0
	v_mfma_f32_16x16x32_bf16 v[84:87], v[222:225], v[206:209], 0
	v_mfma_f32_16x16x32_bf16 v[80:83], v[230:233], v[206:209], 0
	v_mfma_f32_16x16x32_bf16 v[68:71], v[222:225], v[214:217], 0
	v_mfma_f32_16x16x32_bf16 v[64:67], v[230:233], v[214:217], 0
	v_mfma_f32_16x16x32_bf16 v[116:119], v[226:229], v[176:179], v[116:119]
	v_mfma_f32_16x16x32_bf16 v[112:115], v[234:237], v[176:179], v[112:115]
	v_mfma_f32_16x16x32_bf16 v[100:103], v[226:229], v[188:191], v[100:103]
	v_mfma_f32_16x16x32_bf16 v[96:99], v[234:237], v[188:191], v[96:99]
	v_mfma_f32_16x16x32_bf16 v[84:87], v[226:229], v[210:213], v[84:87]
	v_mfma_f32_16x16x32_bf16 v[80:83], v[234:237], v[210:213], v[80:83]
	v_mfma_f32_16x16x32_bf16 v[68:71], v[226:229], v[218:221], v[68:71]
	v_mfma_f32_16x16x32_bf16 v[64:67], v[234:237], v[218:221], v[64:67]
	s_setprio 0
	s_mov_b32 m0, s52
	s_barrier
	ds_read_b128 v[172:175], v156 offset:16384
	ds_read_b128 v[176:179], v156 offset:17408
	ds_read_b128 v[180:183], v156 offset:18432
	ds_read_b128 v[188:191], v156 offset:19456
	ds_read_b128 v[206:209], v156 offset:20480
	ds_read_b128 v[210:213], v156 offset:21504
	ds_read_b128 v[214:217], v156 offset:22528
	global_load_lds_dwordx4 v128, s[42:43]
	s_mov_b32 m0, s53
	ds_read_b128 v[218:221], v156 offset:23552
	global_load_lds_dwordx4 v132, s[42:43]
	s_barrier
	s_waitcnt lgkmcnt(0)
	s_setprio 1
	v_mfma_f32_16x16x32_bf16 v[60:63], v[144:147], v[172:175], 0
	v_mfma_f32_16x16x32_bf16 v[56:59], v[164:167], v[172:175], 0
	v_mfma_f32_16x16x32_bf16 v[44:47], v[144:147], v[180:183], 0
	v_mfma_f32_16x16x32_bf16 v[40:43], v[164:167], v[180:183], 0
	v_mfma_f32_16x16x32_bf16 v[28:31], v[144:147], v[206:209], 0
	v_mfma_f32_16x16x32_bf16 v[24:27], v[164:167], v[206:209], 0
	v_mfma_f32_16x16x32_bf16 v[12:15], v[144:147], v[214:217], 0
	v_mfma_f32_16x16x32_bf16 v[8:11], v[164:167], v[214:217], 0
	v_mfma_f32_16x16x32_bf16 v[60:63], v[160:163], v[176:179], v[60:63]
	v_mfma_f32_16x16x32_bf16 v[56:59], v[168:171], v[176:179], v[56:59]
	v_mfma_f32_16x16x32_bf16 v[44:47], v[160:163], v[188:191], v[44:47]
	v_mfma_f32_16x16x32_bf16 v[40:43], v[168:171], v[188:191], v[40:43]
	v_mfma_f32_16x16x32_bf16 v[28:31], v[160:163], v[210:213], v[28:31]
	v_mfma_f32_16x16x32_bf16 v[24:27], v[168:171], v[210:213], v[24:27]
	v_mfma_f32_16x16x32_bf16 v[12:15], v[160:163], v[218:221], v[12:15]
	v_mfma_f32_16x16x32_bf16 v[8:11], v[168:171], v[218:221], v[8:11]
	s_setprio 0
	s_barrier
	s_add_i32 s4, s62, s51
	s_mov_b32 m0, s4
	s_add_u32 s0, s40, 0x160000
	s_addc_u32 s1, s41, 0
	global_load_lds_dwordx4 v130, s[0:1]
	s_add_i32 m0, s4, 0x2000
	s_nop 0
	global_load_lds_dwordx4 v134, s[0:1]
	s_waitcnt vmcnt(6)
	s_barrier
; #define PG8_STAGE(bufoff, gbase, voff) do { _Pragma("unroll") for (int _i = 0; _i < 2; ++_i) \
;         __builtin_amdgcn_global_load_lds((const unsigned*)((const char*)(gbase) + (voff)[_i]), (LAS unsigned*)(lds + (bufoff) + ldsw + _i * 8192), 16, 0, 0); } while (0)
; #define PG8_LDA(dst, b, h) do { _Pragma("unroll") for (int m = 0; m < 4; ++m) _Pragma("unroll") for (int k = 0; k < 2; ++k) dst[m][k] = *(const LAS bf16x8*)(lds + PG8_SA(b, h) + aoff + m * 2048 + k * 1024); } while (0)
; #define PG8_LDB(dst, b, h) do { _Pragma("unroll") for (int n = 0; n < 2; ++n) _Pragma("unroll") for (int k = 0; k < 2; ++k) dst[n][k] = *(const LAS bf16x8*)(lds + PG8_SB(b, h) + boff + n * 2048 + k * 1024); } while (0)
; #define PG8_MMA(ai, bj, At, Bt) do { __builtin_amdgcn_s_setprio(1); _Pragma("unroll") for (int m = 0; m < 4; ++m) _Pragma("unroll") for (int n = 0; n < 2; ++n) _Pragma("unroll") for (int k = 0; k < 2; ++k) \
;         acc[ai][bj][m][n] = __builtin_amdgcn_mfma_f32_16x16x32_bf16(Bt[n][k], At[m][k], acc[ai][bj][m][n], 0, 0, 0); __builtin_amdgcn_s_setprio(0); } while (0)
; #define PG8_WAIT_V(n) asm volatile("s_waitcnt vmcnt(" #n ")" ::: "memory")
; #define PG8_WAIT_L(n) asm volatile("s_waitcnt lgkmcnt(" #n ")" ::: "memory")
; #define PG8_BAR __builtin_amdgcn_s_barrier()
; #define PG8_SCHED __builtin_amdgcn_sched_barrier(0)
; template <class Epi, class Sched>
; DI void gemm_phase(LAS unsigned char* lds, const Gemm g, const Sched& S, const Epi& E) {
;     ...
;             PG8_WAIT_V(6); PG8_BAR; PG8_MMA(1, 1, At, B1); PG8_BAR;
;             PG8_LDB(B0, 1, 0); PG8_SCHED; PG8_LDA(At, 1, 0); PG8_STAGE(PG8_SA(0, 1), a2 + hstep, voffA);
;             PG8_WAIT_L(8); PG8_BAR; PG8_WAIT_L(0); PG8_MMA(0, 0, At, B0); PG8_BAR; PG8_SCHED;
;             PG8_LDB(B1, 1, 1); PG8_STAGE(PG8_SB(1, 0), b3, voffB);
;             PG8_BAR; PG8_WAIT_L(0); PG8_MMA(0, 1, At, B1); PG8_BAR;
;             PG8_LDA(At, 1, 1); PG8_STAGE(PG8_SA(1, 0), a3, voffA);
;             PG8_BAR; PG8_WAIT_L(0); PG8_MMA(1, 0, At, B0); PG8_BAR; PG8_SCHED;
	s_setprio 1
	v_mfma_f32_16x16x32_bf16 v[52:55], v[222:225], v[172:175], 0
	v_mfma_f32_16x16x32_bf16 v[48:51], v[230:233], v[172:175], 0
	v_mfma_f32_16x16x32_bf16 v[36:39], v[222:225], v[180:183], 0
	v_mfma_f32_16x16x32_bf16 v[32:35], v[230:233], v[180:183], 0
	v_mfma_f32_16x16x32_bf16 v[20:23], v[222:225], v[206:209], 0
	v_mfma_f32_16x16x32_bf16 v[16:19], v[230:233], v[206:209], 0
	v_mfma_f32_16x16x32_bf16 v[4:7], v[222:225], v[214:217], 0
	v_mfma_f32_16x16x32_bf16 v[0:3], v[230:233], v[214:217], 0
	v_mfma_f32_16x16x32_bf16 v[52:55], v[226:229], v[176:179], v[52:55]
	v_mfma_f32_16x16x32_bf16 v[48:51], v[234:237], v[176:179], v[48:51]
	v_mfma_f32_16x16x32_bf16 v[36:39], v[226:229], v[188:191], v[36:39]
	v_mfma_f32_16x16x32_bf16 v[32:35], v[234:237], v[188:191], v[32:35]
	v_mfma_f32_16x16x32_bf16 v[20:23], v[226:229], v[210:213], v[20:23]
	v_mfma_f32_16x16x32_bf16 v[16:19], v[234:237], v[210:213], v[16:19]
	v_mfma_f32_16x16x32_bf16 v[4:7], v[226:229], v[218:221], v[4:7]
	v_mfma_f32_16x16x32_bf16 v[0:3], v[234:237], v[218:221], v[0:3]
	s_setprio 0
	s_add_i32 s4, 0, 0x18000
	v_add_u32_e32 v202, s4, v154
	s_barrier
	ds_read_b128 v[144:147], v202
	ds_read_b128 v[160:163], v202 offset:1024
	ds_read_b128 v[164:167], v202 offset:2048
	ds_read_b128 v[168:171], v202 offset:3072
	s_add_u32 s0, s42, 0x160000
	s_addc_u32 s1, s43, 0
	s_mov_b32 m0, s54
	ds_read_b128 v[172:175], v156 offset:32768
	ds_read_b128 v[176:179], v156 offset:33792
	ds_read_b128 v[180:183], v156 offset:34816
	ds_read_b128 v[188:191], v156 offset:35840
	ds_read_b128 v[206:209], v156 offset:36864
	ds_read_b128 v[210:213], v156 offset:37888
	ds_read_b128 v[214:217], v156 offset:38912
	global_load_lds_dwordx4 v128, s[0:1]
	s_mov_b32 m0, s55
	ds_read_b128 v[218:221], v156 offset:39936
	global_load_lds_dwordx4 v132, s[0:1]
	s_waitcnt lgkmcnt(8)
	s_barrier
	s_waitcnt lgkmcnt(0)
	s_setprio 1
	v_mfma_f32_16x16x32_bf16 v[124:127], v[144:147], v[172:175], v[124:127]
	v_mfma_f32_16x16x32_bf16 v[120:123], v[164:167], v[172:175], v[120:123]
	v_mfma_f32_16x16x32_bf16 v[108:111], v[144:147], v[180:183], v[108:111]
	v_mfma_f32_16x16x32_bf16 v[104:107], v[164:167], v[180:183], v[104:107]
	v_mfma_f32_16x16x32_bf16 v[92:95], v[144:147], v[206:209], v[92:95]
	v_mfma_f32_16x16x32_bf16 v[88:91], v[164:167], v[206:209], v[88:91]
	v_mfma_f32_16x16x32_bf16 v[76:79], v[144:147], v[214:217], v[76:79]
	v_mfma_f32_16x16x32_bf16 v[72:75], v[164:167], v[214:217], v[72:75]
	v_mfma_f32_16x16x32_bf16 v[124:127], v[160:163], v[176:179], v[124:127]
	v_mfma_f32_16x16x32_bf16 v[120:123], v[168:171], v[176:179], v[120:123]
	v_mfma_f32_16x16x32_bf16 v[108:111], v[160:163], v[188:191], v[108:111]
	v_mfma_f32_16x16x32_bf16 v[104:107], v[168:171], v[188:191], v[104:107]
	v_mfma_f32_16x16x32_bf16 v[92:95], v[160:163], v[210:213], v[92:95]
	v_mfma_f32_16x16x32_bf16 v[88:91], v[168:171], v[210:213], v[88:91]
	v_mfma_f32_16x16x32_bf16 v[76:79], v[160:163], v[218:221], v[76:79]
	v_mfma_f32_16x16x32_bf16 v[72:75], v[168:171], v[218:221], v[72:75]
	s_setprio 0
	s_barrier
	s_add_i32 s5, 0, 0x1c000
	s_add_i32 s0, s4, s51
	v_add_u32_e32 v203, s5, v154
	s_add_i32 m0, s0, 0xffffff80
	ds_read_b128 v[222:225], v203
	ds_read_b128 v[226:229], v203 offset:1024
	ds_read_b128 v[230:233], v203 offset:2048
	global_load_lds_dwordx4 v130, s[40:41] offset:128
	s_add_i32 m0, s0, 0x1f80
	ds_read_b128 v[234:237], v203 offset:3072
	global_load_lds_dwordx4 v134, s[40:41] offset:128
	s_barrier
	s_waitcnt lgkmcnt(0)
	s_setprio 1
	v_mfma_f32_16x16x32_bf16 v[116:119], v[222:225], v[172:175], v[116:119]
	v_mfma_f32_16x16x32_bf16 v[112:115], v[230:233], v[172:175], v[112:115]
	v_mfma_f32_16x16x32_bf16 v[100:103], v[222:225], v[180:183], v[100:103]
	v_mfma_f32_16x16x32_bf16 v[96:99], v[230:233], v[180:183], v[96:99]
	v_mfma_f32_16x16x32_bf16 v[84:87], v[222:225], v[206:209], v[84:87]
	v_mfma_f32_16x16x32_bf16 v[80:83], v[230:233], v[206:209], v[80:83]
	v_mfma_f32_16x16x32_bf16 v[68:71], v[222:225], v[214:217], v[68:71]
	v_mfma_f32_16x16x32_bf16 v[64:67], v[230:233], v[214:217], v[64:67]
	v_mfma_f32_16x16x32_bf16 v[116:119], v[226:229], v[176:179], v[116:119]
	v_mfma_f32_16x16x32_bf16 v[112:115], v[234:237], v[176:179], v[112:115]
	v_mfma_f32_16x16x32_bf16 v[100:103], v[226:229], v[188:191], v[100:103]
	v_mfma_f32_16x16x32_bf16 v[96:99], v[234:237], v[188:191], v[96:99]
	v_mfma_f32_16x16x32_bf16 v[84:87], v[226:229], v[210:213], v[84:87]
	v_mfma_f32_16x16x32_bf16 v[80:83], v[234:237], v[210:213], v[80:83]
	v_mfma_f32_16x16x32_bf16 v[68:71], v[226:229], v[218:221], v[68:71]
	v_mfma_f32_16x16x32_bf16 v[64:67], v[234:237], v[218:221], v[64:67]
	s_setprio 0
	s_add_i32 m0, s59, 0xffffff80
	s_barrier
	ds_read_b128 v[172:175], v156 offset:49152
	ds_read_b128 v[176:179], v156 offset:50176
	ds_read_b128 v[180:183], v156 offset:51200
	ds_read_b128 v[188:191], v156 offset:52224
	ds_read_b128 v[206:209], v156 offset:53248
	ds_read_b128 v[210:213], v156 offset:54272
	ds_read_b128 v[214:217], v156 offset:55296
	global_load_lds_dwordx4 v128, s[42:43] offset:128
	s_add_i32 m0, s60, 0xffffff80
	ds_read_b128 v[218:221], v156 offset:56320
	global_load_lds_dwordx4 v132, s[42:43] offset:128
	s_barrier
; #define PG8_STAGE(bufoff, gbase, voff) do { _Pragma("unroll") for (int _i = 0; _i < 2; ++_i) \
;         __builtin_amdgcn_global_load_lds((const unsigned*)((const char*)(gbase) + (voff)[_i]), (LAS unsigned*)(lds + (bufoff) + ldsw + _i * 8192), 16, 0, 0); } while (0)
; #define PG8_LDA(dst, b, h) do { _Pragma("unroll") for (int m = 0; m < 4; ++m) _Pragma("unroll") for (int k = 0; k < 2; ++k) dst[m][k] = *(const LAS bf16x8*)(lds + PG8_SA(b, h) + aoff + m * 2048 + k * 1024); } while (0)
; #define PG8_LDB(dst, b, h) do { _Pragma("unroll") for (int n = 0; n < 2; ++n) _Pragma("unroll") for (int k = 0; k < 2; ++k) dst[n][k] = *(const LAS bf16x8*)(lds + PG8_SB(b, h) + boff + n * 2048 + k * 1024); } while (0)
; #define PG8_WAIT_V(n) asm volatile("s_waitcnt vmcnt(" #n ")" ::: "memory")
; #define PG8_WAIT_L(n) asm volatile("s_waitcnt lgkmcnt(" #n ")" ::: "memory")
; #define PG8_BAR __builtin_amdgcn_s_barrier()
; #define PG8_SCHED __builtin_amdgcn_sched_barrier(0)
; template <class Epi, class Sched>
; DI void gemm_phase(LAS unsigned char* lds, const Gemm g, const Sched& S, const Epi& E) {
;     ...
;             PG8_LDB(B0, 0, 0); PG8_SCHED; PG8_LDA(At, 0, 0); PG8_STAGE(PG8_SA(1, 1), a1 + hstep, voffA);
;             PG8_WAIT_L(8); PG8_BAR; PG8_WAIT_L(0); PG8_MMA(0, 0, At, B0); PG8_BAR; PG8_SCHED;
;             PG8_LDB(B1, 0, 1); PG8_STAGE(PG8_SB(0, 0), b2, voffB);
;             PG8_BAR; PG8_WAIT_L(0); PG8_MMA(0, 1, At, B1); PG8_BAR;
;             PG8_LDA(At, 0, 1); PG8_STAGE(PG8_SA(0, 0), a2, voffA);
;             PG8_BAR; PG8_WAIT_L(0); PG8_MMA(1, 0, At, B0); PG8_BAR; PG8_SCHED;
;             PG8_STAGE(PG8_SB(0, 1), b2 + hstep, voffB);
;             PG8_WAIT_V(6); PG8_BAR; PG8_MMA(1, 1, At, B1); PG8_BAR;
;             PG8_LDB(B0, 1, 0); PG8_SCHED; PG8_LDA(At, 1, 0); PG8_STAGE(PG8_SA(0, 1), a2 + hstep, voffA);
;             PG8_WAIT_L(8); PG8_BAR; PG8_WAIT_L(0); PG8_MMA(0, 0, At, B0); PG8_BAR; PG8_SCHED;
;             PG8_LDB(B1, 1, 1); PG8_STAGE(PG8_SB(1, 0), b3, voffB);
;             PG8_BAR; PG8_WAIT_L(0); PG8_MMA(0, 1, At, B1); PG8_BAR;
;             PG8_LDA(At, 1, 1); PG8_STAGE(PG8_SA(1, 0), a3, voffA);
;             PG8_BAR; PG8_WAIT_L(0); PG8_MMA(1, 0, At, B0); PG8_BAR; PG8_SCHED;
;             PG8_STAGE(PG8_SB(1, 1), b3 + hstep, voffB);
;             PG8_WAIT_V(6); PG8_BAR; PG8_MMA(1, 1, At, B1); PG8_BAR;
	s_waitcnt lgkmcnt(0)
	s_setprio 1
	v_mfma_f32_16x16x32_bf16 v[60:63], v[144:147], v[172:175], v[60:63]
	v_mfma_f32_16x16x32_bf16 v[56:59], v[164:167], v[172:175], v[56:59]
	v_mfma_f32_16x16x32_bf16 v[44:47], v[144:147], v[180:183], v[44:47]
	v_mfma_f32_16x16x32_bf16 v[40:43], v[164:167], v[180:183], v[40:43]
	v_mfma_f32_16x16x32_bf16 v[28:31], v[144:147], v[206:209], v[28:31]
	v_mfma_f32_16x16x32_bf16 v[24:27], v[164:167], v[206:209], v[24:27]
	v_mfma_f32_16x16x32_bf16 v[12:15], v[144:147], v[214:217], v[12:15]
	v_mfma_f32_16x16x32_bf16 v[8:11], v[164:167], v[214:217], v[8:11]
	v_mfma_f32_16x16x32_bf16 v[60:63], v[160:163], v[176:179], v[60:63]
	v_mfma_f32_16x16x32_bf16 v[56:59], v[168:171], v[176:179], v[56:59]
	v_mfma_f32_16x16x32_bf16 v[44:47], v[160:163], v[188:191], v[44:47]
	v_mfma_f32_16x16x32_bf16 v[40:43], v[168:171], v[188:191], v[40:43]
	v_mfma_f32_16x16x32_bf16 v[28:31], v[160:163], v[210:213], v[28:31]
	v_mfma_f32_16x16x32_bf16 v[24:27], v[168:171], v[210:213], v[24:27]
	v_mfma_f32_16x16x32_bf16 v[12:15], v[160:163], v[218:221], v[12:15]
	v_mfma_f32_16x16x32_bf16 v[8:11], v[168:171], v[218:221], v[8:11]
	s_setprio 0
	s_barrier
	s_add_i32 s4, s5, s51
	s_mov_b32 m0, s4
	s_add_u32 s0, s40, 0x160080
	s_addc_u32 s1, s41, 0
	global_load_lds_dwordx4 v130, s[0:1]
	s_add_i32 m0, s4, 0x2000
	s_nop 0
	global_load_lds_dwordx4 v134, s[0:1]
	s_waitcnt vmcnt(6)
	s_barrier
	s_setprio 1
	v_mfma_f32_16x16x32_bf16 v[52:55], v[222:225], v[172:175], v[52:55]
	v_mfma_f32_16x16x32_bf16 v[48:51], v[230:233], v[172:175], v[48:51]
	v_mfma_f32_16x16x32_bf16 v[36:39], v[222:225], v[180:183], v[36:39]
	v_mfma_f32_16x16x32_bf16 v[32:35], v[230:233], v[180:183], v[32:35]
	v_mfma_f32_16x16x32_bf16 v[20:23], v[222:225], v[206:209], v[20:23]
	v_mfma_f32_16x16x32_bf16 v[16:19], v[230:233], v[206:209], v[16:19]
	v_mfma_f32_16x16x32_bf16 v[4:7], v[222:225], v[214:217], v[4:7]
	v_mfma_f32_16x16x32_bf16 v[0:3], v[230:233], v[214:217], v[0:3]
	v_mfma_f32_16x16x32_bf16 v[52:55], v[226:229], v[176:179], v[52:55]
	v_mfma_f32_16x16x32_bf16 v[48:51], v[234:237], v[176:179], v[48:51]
	v_mfma_f32_16x16x32_bf16 v[36:39], v[226:229], v[188:191], v[36:39]
	v_mfma_f32_16x16x32_bf16 v[32:35], v[234:237], v[188:191], v[32:35]
	v_mfma_f32_16x16x32_bf16 v[20:23], v[226:229], v[210:213], v[20:23]
	v_mfma_f32_16x16x32_bf16 v[16:19], v[234:237], v[210:213], v[16:19]
	v_mfma_f32_16x16x32_bf16 v[4:7], v[226:229], v[218:221], v[4:7]
	v_mfma_f32_16x16x32_bf16 v[0:3], v[234:237], v[218:221], v[0:3]
	s_setprio 0
	s_add_i32 s68, s68, 2
	s_add_u32 s38, s38, 0x100
	s_addc_u32 s39, s39, 0
	s_add_u32 s35, s35, 0x100
	s_addc_u32 s67, s67, 0
	s_cmpk_gt_u32 s68, 0x55
	s_barrier
	s_cbranch_scc0 .LBB0_1746
	s_branch .Lpeel_done_1746
.LBB0_1746:
	ds_read_b128 v[144:147], v155
	ds_read_b128 v[160:163], v155 offset:1024
	ds_read_b128 v[164:167], v155 offset:2048
	ds_read_b128 v[168:171], v155 offset:3072
	s_add_u32 s0, s38, 0xffea0080
	s_addc_u32 s1, s39, -1
	s_cmpk_eq_i32 s68, 0x54
	s_cselect_b32 s43, s9, s1
	s_cselect_b32 s42, s8, s0
	s_cselect_b32 s41, s11, s67
	s_cselect_b32 s40, s10, s35
	s_add_i32 m0, s52, 0xc000
	ds_read_b128 v[172:175], v156
	ds_read_b128 v[176:179], v156 offset:1024
	ds_read_b128 v[180:183], v156 offset:2048
	ds_read_b128 v[188:191], v156 offset:3072
	ds_read_b128 v[206:209], v156 offset:4096
	ds_read_b128 v[210:213], v156 offset:5120
	ds_read_b128 v[214:217], v156 offset:6144
	global_load_lds_dwordx4 v136, s[38:39]
	s_add_i32 m0, s52, 0xe000
	ds_read_b128 v[218:221], v156 offset:7168
	global_load_lds_dwordx4 v138, s[38:39]
	s_waitcnt lgkmcnt(8)
	s_barrier
	s_waitcnt lgkmcnt(0)
	s_setprio 1
	v_mfma_f32_16x16x32_bf16 v[124:127], v[144:147], v[172:175], v[124:127]
	v_mfma_f32_16x16x32_bf16 v[120:123], v[164:167], v[172:175], v[120:123]
	v_mfma_f32_16x16x32_bf16 v[108:111], v[144:147], v[180:183], v[108:111]
	v_mfma_f32_16x16x32_bf16 v[104:107], v[164:167], v[180:183], v[104:107]
	v_mfma_f32_16x16x32_bf16 v[92:95], v[144:147], v[206:209], v[92:95]
	v_mfma_f32_16x16x32_bf16 v[88:91], v[164:167], v[206:209], v[88:91]
	v_mfma_f32_16x16x32_bf16 v[76:79], v[144:147], v[214:217], v[76:79]
	v_mfma_f32_16x16x32_bf16 v[72:75], v[164:167], v[214:217], v[72:75]
	v_mfma_f32_16x16x32_bf16 v[124:127], v[160:163], v[176:179], v[124:127]
	v_mfma_f32_16x16x32_bf16 v[120:123], v[168:171], v[176:179], v[120:123]
	v_mfma_f32_16x16x32_bf16 v[108:111], v[160:163], v[188:191], v[108:111]
	v_mfma_f32_16x16x32_bf16 v[104:107], v[168:171], v[188:191], v[104:107]
	v_mfma_f32_16x16x32_bf16 v[92:95], v[160:163], v[210:213], v[92:95]
	v_mfma_f32_16x16x32_bf16 v[88:91], v[168:171], v[210:213], v[88:91]
	v_mfma_f32_16x16x32_bf16 v[76:79], v[160:163], v[218:221], v[76:79]
	v_mfma_f32_16x16x32_bf16 v[72:75], v[168:171], v[218:221], v[72:75]
	s_setprio 0
	s_barrier
	s_add_i32 s0, s61, s51
	s_mov_b32 m0, s0
	ds_read_b128 v[222:225], v157
	ds_read_b128 v[226:229], v157 offset:1024
	ds_read_b128 v[230:233], v157 offset:2048
	global_load_lds_dwordx4 v130, s[40:41]
	s_add_i32 m0, s0, 0x2000
	ds_read_b128 v[234:237], v157 offset:3072
	global_load_lds_dwordx4 v134, s[40:41]
	s_barrier
; #define PG8_STAGE(bufoff, gbase, voff) do { _Pragma("unroll") for (int _i = 0; _i < 2; ++_i) \
;         __builtin_amdgcn_global_load_lds((const unsigned*)((const char*)(gbase) + (voff)[_i]), (LAS unsigned*)(lds + (bufoff) + ldsw + _i * 8192), 16, 0, 0); } while (0)
; #define PG8_LDA(dst, b, h) do { _Pragma("unroll") for (int m = 0; m < 4; ++m) _Pragma("unroll") for (int k = 0; k < 2; ++k) dst[m][k] = *(const LAS bf16x8*)(lds + PG8_SA(b, h) + aoff + m * 2048 + k * 1024); } while (0)
; #define PG8_LDB(dst, b, h) do { _Pragma("unroll") for (int n = 0; n < 2; ++n) _Pragma("unroll") for (int k = 0; k < 2; ++k) dst[n][k] = *(const LAS bf16x8*)(lds + PG8_SB(b, h) + boff + n * 2048 + k * 1024); } while (0)
; #define PG8_MMA(ai, bj, At, Bt) do { __builtin_amdgcn_s_setprio(1); _Pragma("unroll") for (int m = 0; m < 4; ++m) _Pragma("unroll") for (int n = 0; n < 2; ++n) _Pragma("unroll") for (int k = 0; k < 2; ++k) \
;         acc[ai][bj][m][n] = __builtin_amdgcn_mfma_f32_16x16x32_bf16(Bt[n][k], At[m][k], acc[ai][bj][m][n], 0, 0, 0); __builtin_amdgcn_s_setprio(0); } while (0)
; #define PG8_WAIT_V(n) asm volatile("s_waitcnt vmcnt(" #n ")" ::: "memory")
; #define PG8_WAIT_L(n) asm volatile("s_waitcnt lgkmcnt(" #n ")" ::: "memory")
; #define PG8_BAR __builtin_amdgcn_s_barrier()
; #define PG8_SCHED __builtin_amdgcn_sched_barrier(0)
; template <class Epi, class Sched>
; DI void gemm_phase(LAS unsigned char* lds, const Gemm g, const Sched& S, const Epi& E) {
;     ...
;             PG8_BAR; PG8_WAIT_L(0); PG8_MMA(0, 1, At, B1); PG8_BAR;
;             PG8_LDA(At, 0, 1); PG8_STAGE(PG8_SA(0, 0), a2, voffA);
;             PG8_BAR; PG8_WAIT_L(0); PG8_MMA(1, 0, At, B0); PG8_BAR; PG8_SCHED;
;             PG8_STAGE(PG8_SB(0, 1), b2 + hstep, voffB);
;             PG8_WAIT_V(6); PG8_BAR; PG8_MMA(1, 1, At, B1); PG8_BAR;
;             PG8_LDB(B0, 1, 0); PG8_SCHED; PG8_LDA(At, 1, 0); PG8_STAGE(PG8_SA(0, 1), a2 + hstep, voffA);
;             PG8_WAIT_L(8); PG8_BAR; PG8_WAIT_L(0); PG8_MMA(0, 0, At, B0); PG8_BAR; PG8_SCHED;
	s_waitcnt lgkmcnt(0)
	s_setprio 1
	v_mfma_f32_16x16x32_bf16 v[116:119], v[222:225], v[172:175], v[116:119]
	v_mfma_f32_16x16x32_bf16 v[112:115], v[230:233], v[172:175], v[112:115]
	v_mfma_f32_16x16x32_bf16 v[100:103], v[222:225], v[180:183], v[100:103]
	v_mfma_f32_16x16x32_bf16 v[96:99], v[230:233], v[180:183], v[96:99]
	v_mfma_f32_16x16x32_bf16 v[84:87], v[222:225], v[206:209], v[84:87]
	v_mfma_f32_16x16x32_bf16 v[80:83], v[230:233], v[206:209], v[80:83]
	v_mfma_f32_16x16x32_bf16 v[68:71], v[222:225], v[214:217], v[68:71]
	v_mfma_f32_16x16x32_bf16 v[64:67], v[230:233], v[214:217], v[64:67]
	v_mfma_f32_16x16x32_bf16 v[116:119], v[226:229], v[176:179], v[116:119]
	v_mfma_f32_16x16x32_bf16 v[112:115], v[234:237], v[176:179], v[112:115]
	v_mfma_f32_16x16x32_bf16 v[100:103], v[226:229], v[188:191], v[100:103]
	v_mfma_f32_16x16x32_bf16 v[96:99], v[234:237], v[188:191], v[96:99]
	v_mfma_f32_16x16x32_bf16 v[84:87], v[226:229], v[210:213], v[84:87]
	v_mfma_f32_16x16x32_bf16 v[80:83], v[234:237], v[210:213], v[80:83]
	v_mfma_f32_16x16x32_bf16 v[68:71], v[226:229], v[218:221], v[68:71]
	v_mfma_f32_16x16x32_bf16 v[64:67], v[234:237], v[218:221], v[64:67]
	s_setprio 0
	s_mov_b32 m0, s52
	s_barrier
	ds_read_b128 v[172:175], v156 offset:16384
	ds_read_b128 v[176:179], v156 offset:17408
	ds_read_b128 v[180:183], v156 offset:18432
	ds_read_b128 v[188:191], v156 offset:19456
	ds_read_b128 v[206:209], v156 offset:20480
	ds_read_b128 v[210:213], v156 offset:21504
	ds_read_b128 v[214:217], v156 offset:22528
	global_load_lds_dwordx4 v128, s[42:43]
	s_mov_b32 m0, s53
	ds_read_b128 v[218:221], v156 offset:23552
	global_load_lds_dwordx4 v132, s[42:43]
	s_barrier
	s_waitcnt lgkmcnt(0)
	s_setprio 1
	v_mfma_f32_16x16x32_bf16 v[60:63], v[144:147], v[172:175], v[60:63]
	v_mfma_f32_16x16x32_bf16 v[56:59], v[164:167], v[172:175], v[56:59]
	v_mfma_f32_16x16x32_bf16 v[44:47], v[144:147], v[180:183], v[44:47]
	v_mfma_f32_16x16x32_bf16 v[40:43], v[164:167], v[180:183], v[40:43]
	v_mfma_f32_16x16x32_bf16 v[28:31], v[144:147], v[206:209], v[28:31]
	v_mfma_f32_16x16x32_bf16 v[24:27], v[164:167], v[206:209], v[24:27]
	v_mfma_f32_16x16x32_bf16 v[12:15], v[144:147], v[214:217], v[12:15]
	v_mfma_f32_16x16x32_bf16 v[8:11], v[164:167], v[214:217], v[8:11]
	v_mfma_f32_16x16x32_bf16 v[60:63], v[160:163], v[176:179], v[60:63]
	v_mfma_f32_16x16x32_bf16 v[56:59], v[168:171], v[176:179], v[56:59]
	v_mfma_f32_16x16x32_bf16 v[44:47], v[160:163], v[188:191], v[44:47]
	v_mfma_f32_16x16x32_bf16 v[40:43], v[168:171], v[188:191], v[40:43]
	v_mfma_f32_16x16x32_bf16 v[28:31], v[160:163], v[210:213], v[28:31]
	v_mfma_f32_16x16x32_bf16 v[24:27], v[168:171], v[210:213], v[24:27]
	v_mfma_f32_16x16x32_bf16 v[12:15], v[160:163], v[218:221], v[12:15]
	v_mfma_f32_16x16x32_bf16 v[8:11], v[168:171], v[218:221], v[8:11]
	s_setprio 0
	s_barrier
	s_add_i32 s4, s62, s51
	s_mov_b32 m0, s4
	s_add_u32 s0, s40, 0x160000
	s_addc_u32 s1, s41, 0
	global_load_lds_dwordx4 v130, s[0:1]
	s_add_i32 m0, s4, 0x2000
	s_nop 0
	global_load_lds_dwordx4 v134, s[0:1]
	s_waitcnt vmcnt(6)
	s_barrier
	s_setprio 1
	v_mfma_f32_16x16x32_bf16 v[52:55], v[222:225], v[172:175], v[52:55]
	v_mfma_f32_16x16x32_bf16 v[48:51], v[230:233], v[172:175], v[48:51]
	v_mfma_f32_16x16x32_bf16 v[36:39], v[222:225], v[180:183], v[36:39]
	v_mfma_f32_16x16x32_bf16 v[32:35], v[230:233], v[180:183], v[32:35]
	v_mfma_f32_16x16x32_bf16 v[20:23], v[222:225], v[206:209], v[20:23]
	v_mfma_f32_16x16x32_bf16 v[16:19], v[230:233], v[206:209], v[16:19]
	v_mfma_f32_16x16x32_bf16 v[4:7], v[222:225], v[214:217], v[4:7]
	v_mfma_f32_16x16x32_bf16 v[0:3], v[230:233], v[214:217], v[0:3]
	v_mfma_f32_16x16x32_bf16 v[52:55], v[226:229], v[176:179], v[52:55]
	v_mfma_f32_16x16x32_bf16 v[48:51], v[234:237], v[176:179], v[48:51]
	v_mfma_f32_16x16x32_bf16 v[36:39], v[226:229], v[188:191], v[36:39]
	v_mfma_f32_16x16x32_bf16 v[32:35], v[234:237], v[188:191], v[32:35]
	v_mfma_f32_16x16x32_bf16 v[20:23], v[226:229], v[210:213], v[20:23]
	v_mfma_f32_16x16x32_bf16 v[16:19], v[234:237], v[210:213], v[16:19]
	v_mfma_f32_16x16x32_bf16 v[4:7], v[226:229], v[218:221], v[4:7]
	v_mfma_f32_16x16x32_bf16 v[0:3], v[234:237], v[218:221], v[0:3]
	s_setprio 0
	s_add_i32 s4, 0, 0x18000
	s_barrier
	ds_read_b128 v[144:147], v202
	ds_read_b128 v[160:163], v202 offset:1024
	ds_read_b128 v[164:167], v202 offset:2048
	ds_read_b128 v[168:171], v202 offset:3072
	s_add_u32 s0, s42, 0x160000
	s_addc_u32 s1, s43, 0
	s_mov_b32 m0, s54
	ds_read_b128 v[172:175], v156 offset:32768
	ds_read_b128 v[176:179], v156 offset:33792
	ds_read_b128 v[180:183], v156 offset:34816
	ds_read_b128 v[188:191], v156 offset:35840
	ds_read_b128 v[206:209], v156 offset:36864
	ds_read_b128 v[210:213], v156 offset:37888
	ds_read_b128 v[214:217], v156 offset:38912
	global_load_lds_dwordx4 v128, s[0:1]
	s_mov_b32 m0, s55
	ds_read_b128 v[218:221], v156 offset:39936
	global_load_lds_dwordx4 v132, s[0:1]
	s_waitcnt lgkmcnt(8)
	s_barrier
; #define PG8_STAGE(bufoff, gbase, voff) do { _Pragma("unroll") for (int _i = 0; _i < 2; ++_i) \
;         __builtin_amdgcn_global_load_lds((const unsigned*)((const char*)(gbase) + (voff)[_i]), (LAS unsigned*)(lds + (bufoff) + ldsw + _i * 8192), 16, 0, 0); } while (0)
; #define PG8_LDA(dst, b, h) do { _Pragma("unroll") for (int m = 0; m < 4; ++m) _Pragma("unroll") for (int k = 0; k < 2; ++k) dst[m][k] = *(const LAS bf16x8*)(lds + PG8_SA(b, h) + aoff + m * 2048 + k * 1024); } while (0)
; #define PG8_LDB(dst, b, h) do { _Pragma("unroll") for (int n = 0; n < 2; ++n) _Pragma("unroll") for (int k = 0; k < 2; ++k) dst[n][k] = *(const LAS bf16x8*)(lds + PG8_SB(b, h) + boff + n * 2048 + k * 1024); } while (0)
; #define PG8_MMA(ai, bj, At, Bt) do { __builtin_amdgcn_s_setprio(1); _Pragma("unroll") for (int m = 0; m < 4; ++m) _Pragma("unroll") for (int n = 0; n < 2; ++n) _Pragma("unroll") for (int k = 0; k < 2; ++k) \
;         acc[ai][bj][m][n] = __builtin_amdgcn_mfma_f32_16x16x32_bf16(Bt[n][k], At[m][k], acc[ai][bj][m][n], 0, 0, 0); __builtin_amdgcn_s_setprio(0); } while (0)
; #define PG8_WAIT_V(n) asm volatile("s_waitcnt vmcnt(" #n ")" ::: "memory")
; #define PG8_WAIT_L(n) asm volatile("s_waitcnt lgkmcnt(" #n ")" ::: "memory")
; #define PG8_BAR __builtin_amdgcn_s_barrier()
; #define PG8_SCHED __builtin_amdgcn_sched_barrier(0)
; template <class Epi, class Sched>
; DI void gemm_phase(LAS unsigned char* lds, const Gemm g, const Sched& S, const Epi& E) {
;     ...
;             PG8_WAIT_L(8); PG8_BAR; PG8_WAIT_L(0); PG8_MMA(0, 0, At, B0); PG8_BAR; PG8_SCHED;
;             PG8_LDB(B1, 1, 1); PG8_STAGE(PG8_SB(1, 0), b3, voffB);
;             PG8_BAR; PG8_WAIT_L(0); PG8_MMA(0, 1, At, B1); PG8_BAR;
;             PG8_LDA(At, 1, 1); PG8_STAGE(PG8_SA(1, 0), a3, voffA);
;             PG8_BAR; PG8_WAIT_L(0); PG8_MMA(1, 0, At, B0); PG8_BAR; PG8_SCHED;
;             PG8_STAGE(PG8_SB(1, 1), b3 + hstep, voffB);
;             PG8_WAIT_V(6); PG8_BAR; PG8_MMA(1, 1, At, B1); PG8_BAR;
	s_waitcnt lgkmcnt(0)
	s_setprio 1
	v_mfma_f32_16x16x32_bf16 v[124:127], v[144:147], v[172:175], v[124:127]
	v_mfma_f32_16x16x32_bf16 v[120:123], v[164:167], v[172:175], v[120:123]
	v_mfma_f32_16x16x32_bf16 v[108:111], v[144:147], v[180:183], v[108:111]
	v_mfma_f32_16x16x32_bf16 v[104:107], v[164:167], v[180:183], v[104:107]
	v_mfma_f32_16x16x32_bf16 v[92:95], v[144:147], v[206:209], v[92:95]
	v_mfma_f32_16x16x32_bf16 v[88:91], v[164:167], v[206:209], v[88:91]
	v_mfma_f32_16x16x32_bf16 v[76:79], v[144:147], v[214:217], v[76:79]
	v_mfma_f32_16x16x32_bf16 v[72:75], v[164:167], v[214:217], v[72:75]
	v_mfma_f32_16x16x32_bf16 v[124:127], v[160:163], v[176:179], v[124:127]
	v_mfma_f32_16x16x32_bf16 v[120:123], v[168:171], v[176:179], v[120:123]
	v_mfma_f32_16x16x32_bf16 v[108:111], v[160:163], v[188:191], v[108:111]
	v_mfma_f32_16x16x32_bf16 v[104:107], v[168:171], v[188:191], v[104:107]
	v_mfma_f32_16x16x32_bf16 v[92:95], v[160:163], v[210:213], v[92:95]
	v_mfma_f32_16x16x32_bf16 v[88:91], v[168:171], v[210:213], v[88:91]
	v_mfma_f32_16x16x32_bf16 v[76:79], v[160:163], v[218:221], v[76:79]
	v_mfma_f32_16x16x32_bf16 v[72:75], v[168:171], v[218:221], v[72:75]
	s_setprio 0
	s_barrier
	s_add_i32 s5, 0, 0x1c000
	s_add_i32 s0, s4, s51
	s_add_i32 m0, s0, 0xffffff80
	ds_read_b128 v[222:225], v203
	ds_read_b128 v[226:229], v203 offset:1024
	ds_read_b128 v[230:233], v203 offset:2048
	global_load_lds_dwordx4 v130, s[40:41] offset:128
	s_add_i32 m0, s0, 0x1f80
	ds_read_b128 v[234:237], v203 offset:3072
	global_load_lds_dwordx4 v134, s[40:41] offset:128
	s_barrier
	s_waitcnt lgkmcnt(0)
	s_setprio 1
	v_mfma_f32_16x16x32_bf16 v[116:119], v[222:225], v[172:175], v[116:119]
	v_mfma_f32_16x16x32_bf16 v[112:115], v[230:233], v[172:175], v[112:115]
	v_mfma_f32_16x16x32_bf16 v[100:103], v[222:225], v[180:183], v[100:103]
	v_mfma_f32_16x16x32_bf16 v[96:99], v[230:233], v[180:183], v[96:99]
	v_mfma_f32_16x16x32_bf16 v[84:87], v[222:225], v[206:209], v[84:87]
	v_mfma_f32_16x16x32_bf16 v[80:83], v[230:233], v[206:209], v[80:83]
	v_mfma_f32_16x16x32_bf16 v[68:71], v[222:225], v[214:217], v[68:71]
	v_mfma_f32_16x16x32_bf16 v[64:67], v[230:233], v[214:217], v[64:67]
	v_mfma_f32_16x16x32_bf16 v[116:119], v[226:229], v[176:179], v[116:119]
	v_mfma_f32_16x16x32_bf16 v[112:115], v[234:237], v[176:179], v[112:115]
	v_mfma_f32_16x16x32_bf16 v[100:103], v[226:229], v[188:191], v[100:103]
	v_mfma_f32_16x16x32_bf16 v[96:99], v[234:237], v[188:191], v[96:99]
	v_mfma_f32_16x16x32_bf16 v[84:87], v[226:229], v[210:213], v[84:87]
	v_mfma_f32_16x16x32_bf16 v[80:83], v[234:237], v[210:213], v[80:83]
	v_mfma_f32_16x16x32_bf16 v[68:71], v[226:229], v[218:221], v[68:71]
	v_mfma_f32_16x16x32_bf16 v[64:67], v[234:237], v[218:221], v[64:67]
	s_setprio 0
	s_add_i32 m0, s59, 0xffffff80
	s_barrier
	ds_read_b128 v[172:175], v156 offset:49152
	ds_read_b128 v[176:179], v156 offset:50176
	ds_read_b128 v[180:183], v156 offset:51200
	ds_read_b128 v[188:191], v156 offset:52224
	ds_read_b128 v[206:209], v156 offset:53248
	ds_read_b128 v[210:213], v156 offset:54272
	ds_read_b128 v[214:217], v156 offset:55296
	global_load_lds_dwordx4 v128, s[42:43] offset:128
	s_add_i32 m0, s60, 0xffffff80
	ds_read_b128 v[218:221], v156 offset:56320
	global_load_lds_dwordx4 v132, s[42:43] offset:128
	s_barrier
	s_waitcnt lgkmcnt(0)
	s_setprio 1
	v_mfma_f32_16x16x32_bf16 v[60:63], v[144:147], v[172:175], v[60:63]
	v_mfma_f32_16x16x32_bf16 v[56:59], v[164:167], v[172:175], v[56:59]
	v_mfma_f32_16x16x32_bf16 v[44:47], v[144:147], v[180:183], v[44:47]
	v_mfma_f32_16x16x32_bf16 v[40:43], v[164:167], v[180:183], v[40:43]
	v_mfma_f32_16x16x32_bf16 v[28:31], v[144:147], v[206:209], v[28:31]
	v_mfma_f32_16x16x32_bf16 v[24:27], v[164:167], v[206:209], v[24:27]
	v_mfma_f32_16x16x32_bf16 v[12:15], v[144:147], v[214:217], v[12:15]
	v_mfma_f32_16x16x32_bf16 v[8:11], v[164:167], v[214:217], v[8:11]
	v_mfma_f32_16x16x32_bf16 v[60:63], v[160:163], v[176:179], v[60:63]
	v_mfma_f32_16x16x32_bf16 v[56:59], v[168:171], v[176:179], v[56:59]
	v_mfma_f32_16x16x32_bf16 v[44:47], v[160:163], v[188:191], v[44:47]
	v_mfma_f32_16x16x32_bf16 v[40:43], v[168:171], v[188:191], v[40:43]
	v_mfma_f32_16x16x32_bf16 v[28:31], v[160:163], v[210:213], v[28:31]
	v_mfma_f32_16x16x32_bf16 v[24:27], v[168:171], v[210:213], v[24:27]
	v_mfma_f32_16x16x32_bf16 v[12:15], v[160:163], v[218:221], v[12:15]
	v_mfma_f32_16x16x32_bf16 v[8:11], v[168:171], v[218:221], v[8:11]
	s_setprio 0
	s_barrier
	s_add_i32 s4, s5, s51
	s_mov_b32 m0, s4
	s_add_u32 s0, s40, 0x160080
	s_addc_u32 s1, s41, 0
	global_load_lds_dwordx4 v130, s[0:1]
	s_add_i32 m0, s4, 0x2000
	s_nop 0
	global_load_lds_dwordx4 v134, s[0:1]
	s_waitcnt vmcnt(6)
	s_barrier
	s_setprio 1
	v_mfma_f32_16x16x32_bf16 v[52:55], v[222:225], v[172:175], v[52:55]
	v_mfma_f32_16x16x32_bf16 v[48:51], v[230:233], v[172:175], v[48:51]
	v_mfma_f32_16x16x32_bf16 v[36:39], v[222:225], v[180:183], v[36:39]
	v_mfma_f32_16x16x32_bf16 v[32:35], v[230:233], v[180:183], v[32:35]
	v_mfma_f32_16x16x32_bf16 v[20:23], v[222:225], v[206:209], v[20:23]
	v_mfma_f32_16x16x32_bf16 v[16:19], v[230:233], v[206:209], v[16:19]
	v_mfma_f32_16x16x32_bf16 v[4:7], v[222:225], v[214:217], v[4:7]
	v_mfma_f32_16x16x32_bf16 v[0:3], v[230:233], v[214:217], v[0:3]
	v_mfma_f32_16x16x32_bf16 v[52:55], v[226:229], v[176:179], v[52:55]
	v_mfma_f32_16x16x32_bf16 v[48:51], v[234:237], v[176:179], v[48:51]
	v_mfma_f32_16x16x32_bf16 v[36:39], v[226:229], v[188:191], v[36:39]
	v_mfma_f32_16x16x32_bf16 v[32:35], v[234:237], v[188:191], v[32:35]
	v_mfma_f32_16x16x32_bf16 v[20:23], v[226:229], v[210:213], v[20:23]
	v_mfma_f32_16x16x32_bf16 v[16:19], v[234:237], v[210:213], v[16:19]
	v_mfma_f32_16x16x32_bf16 v[4:7], v[226:229], v[218:221], v[4:7]
	v_mfma_f32_16x16x32_bf16 v[0:3], v[234:237], v[218:221], v[0:3]
	s_setprio 0
	s_add_i32 s68, s68, 2
	s_add_u32 s38, s38, 0x100
	s_addc_u32 s39, s39, 0
	s_add_u32 s35, s35, 0x100
	s_addc_u32 s67, s67, 0
	s_cmpk_gt_u32 s68, 0x55
	s_barrier
	s_cbranch_scc0 .LBB0_1746

;     DI size_t aoff(const Unit& u, size_t tstep) const { return (size_t)u.pm * tstep; }
;     DI size_t boff(const Unit& u, size_t tstep) const { return (size_t)u.pn * tstep; }
;     DI bool next(int i, Unit& u) const { const long L = (long)i * G + c; if (L >= np) return false; u.pm = pmv; u.pn = (int)(L % nN); u.ks = (int)(L / nN); return true; }
;     DI size_t aoff(const Unit& u, size_t) const { return (size_t)u.ks * kbytes; }
;     DI size_t boff(const Unit& u, size_t tstep) const { return (size_t)u.pn * tstep + (size_t)u.ks * kbytes; }
;     DI bool next(int i, Unit& u) const { Unit t; if (!S.next(i / 3, t)) return false; u.pm = t.pm; u.pn = t.pn; u.ks = i % 3; return true; }
;     DI size_t aoff(const Unit& u, size_t tstep) const { return (u.ks < 2 ? offU : offOA) + (size_t)u.pm * tstep; }
; #define PG8_WAIT_V(n) asm volatile("s_waitcnt vmcnt(" #n ")" ::: "memory")
; template <class Epi, class Sched>
; DI void gemm_phase(LAS unsigned char* lds, const Gemm g, const Sched& S, const Epi& E) {
;     ...
;         const bool has_next = S.next(ui + 1, nxt);
;         const char* nA = has_next ? (const char*)g.A + S.aoff(nxt, tstep) : cA; const char* nB = has_next ? (const char*)g.Bt + S.boff(nxt, tstep) : cB;
;         for (int t = 0; t < nt; t += 2) {
;             if constexpr (Epi::HAS_MID) { if (t == E.mid_t(nt)) { int fr3 = fr, fq3 = fq; asm volatile("" : "+v"(fr3), "+v"(fq3)); E.mid(acc, cur, wr, wc, fr3, fq3); } }
;             const bool last = (t == nt - 2);
;             const char* a1 = cA + (size_t)(t + 1) * kstep;
;             const char* a2 = last ? nA : cA + (size_t)(t + 2) * kstep; const char* b2 = last ? nB : cB + (size_t)(t + 2) * kstep;
;             const char* a3 = a2 + kstep; const char* b3 = b2 + kstep;
;             PG8_LDB(B0, 0, 0); PG8_SCHED; PG8_LDA(At, 0, 0); PG8_STAGE(PG8_SA(1, 1), a1 + hstep, voffA);
;             PG8_WAIT_L(8); PG8_BAR; PG8_WAIT_L(0); PG8_MMA(0, 0, At, B0); PG8_BAR; PG8_SCHED;
;             PG8_LDB(B1, 0, 1); PG8_STAGE(PG8_SB(0, 0), b2, voffB);
;             PG8_BAR; PG8_WAIT_L(0); PG8_MMA(0, 1, At, B1); PG8_BAR;
;             PG8_LDA(At, 0, 1); PG8_STAGE(PG8_SA(0, 0), a2, voffA);
;             PG8_BAR; PG8_WAIT_L(0); PG8_MMA(1, 0, At, B0); PG8_BAR; PG8_SCHED;
;             PG8_STAGE(PG8_SB(0, 1), b2 + hstep, voffB);
;             PG8_WAIT_V(6); PG8_BAR; PG8_MMA(1, 1, At, B1); PG8_BAR;
.LBB0_1774:
	s_add_u32 s28, s38, s28
	s_addc_u32 s29, s39, s29
	s_and_b64 s[0:1], s[8:9], exec
	s_cselect_b32 s15, s29, s37
	s_cselect_b32 s17, s28, s36
	s_add_u32 s8, s36, 0x160080
	s_addc_u32 s9, s37, 0
	s_add_u32 s64, s30, 0x100
	v_mov_b32_e32 v0, 0
	s_addc_u32 s65, s31, 0
	s_mov_b32 s66, -2
	ds_read_b128 v[146:149], v141
	ds_read_b128 v[154:157], v141 offset:1024
	ds_read_b128 v[158:161], v141 offset:2048
	ds_read_b128 v[162:165], v141 offset:3072
	s_add_u32 s0, s8, 0xffea0080
	s_addc_u32 s1, s9, -1
	s_cmp_eq_u32 s66, 4
	s_cselect_b32 s37, s15, s1
	s_cselect_b32 s36, s17, s0
	s_cselect_b32 s31, s19, s65
	s_cselect_b32 s30, s18, s64
	s_mov_b32 m0, s56
	ds_read_b128 v[166:169], v142
	ds_read_b128 v[170:173], v142 offset:1024
	ds_read_b128 v[174:177], v142 offset:2048
	ds_read_b128 v[178:181], v142 offset:3072
	ds_read_b128 v[188:191], v142 offset:4096
	ds_read_b128 v[206:209], v142 offset:5120
	ds_read_b128 v[210:213], v142 offset:6144
	global_load_lds_dwordx4 v132, s[8:9]
	s_mov_b32 m0, s57
	ds_read_b128 v[214:217], v142 offset:7168
	global_load_lds_dwordx4 v134, s[8:9]
	s_waitcnt lgkmcnt(8)
	s_barrier
	s_waitcnt lgkmcnt(0)
	s_setprio 1
	v_mfma_f32_16x16x32_bf16 v[124:127], v[146:149], v[166:169], 0
	v_mfma_f32_16x16x32_bf16 v[120:123], v[158:161], v[166:169], 0
	v_mfma_f32_16x16x32_bf16 v[116:119], v[146:149], v[174:177], 0
	v_mfma_f32_16x16x32_bf16 v[112:115], v[158:161], v[174:177], 0
	v_mfma_f32_16x16x32_bf16 v[104:107], v[146:149], v[188:191], 0
	v_mfma_f32_16x16x32_bf16 v[96:99], v[158:161], v[188:191], 0
	v_mfma_f32_16x16x32_bf16 v[88:91], v[146:149], v[210:213], 0
	v_mfma_f32_16x16x32_bf16 v[80:83], v[158:161], v[210:213], 0
	v_mfma_f32_16x16x32_bf16 v[124:127], v[154:157], v[170:173], v[124:127]
	v_mfma_f32_16x16x32_bf16 v[120:123], v[162:165], v[170:173], v[120:123]
	v_mfma_f32_16x16x32_bf16 v[116:119], v[154:157], v[178:181], v[116:119]
	v_mfma_f32_16x16x32_bf16 v[112:115], v[162:165], v[178:181], v[112:115]
	v_mfma_f32_16x16x32_bf16 v[104:107], v[154:157], v[206:209], v[104:107]
	v_mfma_f32_16x16x32_bf16 v[96:99], v[162:165], v[206:209], v[96:99]
	v_mfma_f32_16x16x32_bf16 v[88:91], v[154:157], v[214:217], v[88:91]
	v_mfma_f32_16x16x32_bf16 v[80:83], v[162:165], v[214:217], v[80:83]
	s_setprio 0
	s_barrier
	s_mov_b32 m0, s58
	ds_read_b128 v[218:221], v143
	ds_read_b128 v[222:225], v143 offset:1024
	ds_read_b128 v[226:229], v143 offset:2048
	global_load_lds_dwordx4 v130, s[30:31]
	s_mov_b32 m0, s59
	ds_read_b128 v[230:233], v143 offset:3072
	global_load_lds_dwordx4 v128, s[30:31]
	s_barrier
	s_waitcnt lgkmcnt(0)
	s_setprio 1
	v_mfma_f32_16x16x32_bf16 v[108:111], v[218:221], v[166:169], 0
	v_mfma_f32_16x16x32_bf16 v[100:103], v[226:229], v[166:169], 0
	v_mfma_f32_16x16x32_bf16 v[92:95], v[218:221], v[174:177], 0
	v_mfma_f32_16x16x32_bf16 v[84:87], v[226:229], v[174:177], 0
	v_mfma_f32_16x16x32_bf16 v[76:79], v[218:221], v[188:191], 0
	v_mfma_f32_16x16x32_bf16 v[72:75], v[226:229], v[188:191], 0
	v_mfma_f32_16x16x32_bf16 v[68:71], v[218:221], v[210:213], 0
	v_mfma_f32_16x16x32_bf16 v[64:67], v[226:229], v[210:213], 0
	v_mfma_f32_16x16x32_bf16 v[108:111], v[222:225], v[170:173], v[108:111]
	v_mfma_f32_16x16x32_bf16 v[100:103], v[230:233], v[170:173], v[100:103]
	v_mfma_f32_16x16x32_bf16 v[92:95], v[222:225], v[178:181], v[92:95]
	v_mfma_f32_16x16x32_bf16 v[84:87], v[230:233], v[178:181], v[84:87]
	v_mfma_f32_16x16x32_bf16 v[76:79], v[222:225], v[206:209], v[76:79]
	v_mfma_f32_16x16x32_bf16 v[72:75], v[230:233], v[206:209], v[72:75]
	v_mfma_f32_16x16x32_bf16 v[68:71], v[222:225], v[214:217], v[68:71]
	v_mfma_f32_16x16x32_bf16 v[64:67], v[230:233], v[214:217], v[64:67]
	s_setprio 0
	s_mov_b32 m0, s40
	s_barrier
	ds_read_b128 v[166:169], v142 offset:16384
	ds_read_b128 v[170:173], v142 offset:17408
	ds_read_b128 v[174:177], v142 offset:18432
	ds_read_b128 v[178:181], v142 offset:19456
	ds_read_b128 v[188:191], v142 offset:20480
	ds_read_b128 v[206:209], v142 offset:21504
	ds_read_b128 v[210:213], v142 offset:22528
	global_load_lds_dwordx4 v130, s[36:37]
	s_mov_b32 m0, s41
	ds_read_b128 v[214:217], v142 offset:23552
	global_load_lds_dwordx4 v128, s[36:37]
	s_barrier
	s_waitcnt lgkmcnt(0)
	s_setprio 1
	v_mfma_f32_16x16x32_bf16 v[60:63], v[146:149], v[166:169], 0
	v_mfma_f32_16x16x32_bf16 v[56:59], v[158:161], v[166:169], 0
	v_mfma_f32_16x16x32_bf16 v[52:55], v[146:149], v[174:177], 0
	v_mfma_f32_16x16x32_bf16 v[48:51], v[158:161], v[174:177], 0
	v_mfma_f32_16x16x32_bf16 v[40:43], v[146:149], v[188:191], 0
	v_mfma_f32_16x16x32_bf16 v[32:35], v[158:161], v[188:191], 0
	v_mfma_f32_16x16x32_bf16 v[24:27], v[146:149], v[210:213], 0
	v_mfma_f32_16x16x32_bf16 v[16:19], v[158:161], v[210:213], 0
	v_mfma_f32_16x16x32_bf16 v[60:63], v[154:157], v[170:173], v[60:63]
	v_mfma_f32_16x16x32_bf16 v[56:59], v[162:165], v[170:173], v[56:59]
	v_mfma_f32_16x16x32_bf16 v[52:55], v[154:157], v[178:181], v[52:55]
	v_mfma_f32_16x16x32_bf16 v[48:51], v[162:165], v[178:181], v[48:51]
	v_mfma_f32_16x16x32_bf16 v[40:43], v[154:157], v[206:209], v[40:43]
	v_mfma_f32_16x16x32_bf16 v[32:35], v[162:165], v[206:209], v[32:35]
	v_mfma_f32_16x16x32_bf16 v[24:27], v[154:157], v[214:217], v[24:27]
	v_mfma_f32_16x16x32_bf16 v[16:19], v[162:165], v[214:217], v[16:19]
	s_setprio 0
	s_barrier
	s_add_u32 s0, s30, 0x160000
	s_addc_u32 s1, s31, 0
	s_mov_b32 m0, s60
	s_nop 0
	global_load_lds_dwordx4 v130, s[0:1]
	s_mov_b32 m0, s61
	s_nop 0
	global_load_lds_dwordx4 v128, s[0:1]
	s_waitcnt vmcnt(6)
	s_barrier
; #define PG8_STAGE(bufoff, gbase, voff) do { _Pragma("unroll") for (int _i = 0; _i < 2; ++_i) \
;         __builtin_amdgcn_global_load_lds((const unsigned*)((const char*)(gbase) + (voff)[_i]), (LAS unsigned*)(lds + (bufoff) + ldsw + _i * 8192), 16, 0, 0); } while (0)
; #define PG8_LDA(dst, b, h) do { _Pragma("unroll") for (int m = 0; m < 4; ++m) _Pragma("unroll") for (int k = 0; k < 2; ++k) dst[m][k] = *(const LAS bf16x8*)(lds + PG8_SA(b, h) + aoff + m * 2048 + k * 1024); } while (0)
; #define PG8_LDB(dst, b, h) do { _Pragma("unroll") for (int n = 0; n < 2; ++n) _Pragma("unroll") for (int k = 0; k < 2; ++k) dst[n][k] = *(const LAS bf16x8*)(lds + PG8_SB(b, h) + boff + n * 2048 + k * 1024); } while (0)
; #define PG8_MMA(ai, bj, At, Bt) do { __builtin_amdgcn_s_setprio(1); _Pragma("unroll") for (int m = 0; m < 4; ++m) _Pragma("unroll") for (int n = 0; n < 2; ++n) _Pragma("unroll") for (int k = 0; k < 2; ++k) \
;         acc[ai][bj][m][n] = __builtin_amdgcn_mfma_f32_16x16x32_bf16(Bt[n][k], At[m][k], acc[ai][bj][m][n], 0, 0, 0); __builtin_amdgcn_s_setprio(0); } while (0)
; #define PG8_WAIT_V(n) asm volatile("s_waitcnt vmcnt(" #n ")" ::: "memory")
; #define PG8_WAIT_L(n) asm volatile("s_waitcnt lgkmcnt(" #n ")" ::: "memory")
; #define PG8_BAR __builtin_amdgcn_s_barrier()
; #define PG8_SCHED __builtin_amdgcn_sched_barrier(0)
; template <class Epi, class Sched>
; DI void gemm_phase(LAS unsigned char* lds, const Gemm g, const Sched& S, const Epi& E) {
;     ...
;             PG8_WAIT_V(6); PG8_BAR; PG8_MMA(1, 1, At, B1); PG8_BAR;
;             PG8_LDB(B0, 1, 0); PG8_SCHED; PG8_LDA(At, 1, 0); PG8_STAGE(PG8_SA(0, 1), a2 + hstep, voffA);
;             PG8_WAIT_L(8); PG8_BAR; PG8_WAIT_L(0); PG8_MMA(0, 0, At, B0); PG8_BAR; PG8_SCHED;
;             PG8_LDB(B1, 1, 1); PG8_STAGE(PG8_SB(1, 0), b3, voffB);
;             PG8_BAR; PG8_WAIT_L(0); PG8_MMA(0, 1, At, B1); PG8_BAR;
;             PG8_LDA(At, 1, 1); PG8_STAGE(PG8_SA(1, 0), a3, voffA);
;             PG8_BAR; PG8_WAIT_L(0); PG8_MMA(1, 0, At, B0); PG8_BAR; PG8_SCHED;
	s_setprio 1
	v_mfma_f32_16x16x32_bf16 v[44:47], v[218:221], v[166:169], 0
	v_mfma_f32_16x16x32_bf16 v[36:39], v[226:229], v[166:169], 0
	v_mfma_f32_16x16x32_bf16 v[28:31], v[218:221], v[174:177], 0
	v_mfma_f32_16x16x32_bf16 v[20:23], v[226:229], v[174:177], 0
	v_mfma_f32_16x16x32_bf16 v[12:15], v[218:221], v[188:191], 0
	v_mfma_f32_16x16x32_bf16 v[8:11], v[226:229], v[188:191], 0
	v_mfma_f32_16x16x32_bf16 v[4:7], v[218:221], v[210:213], 0
	v_mfma_f32_16x16x32_bf16 v[0:3], v[226:229], v[210:213], 0
	v_mfma_f32_16x16x32_bf16 v[44:47], v[222:225], v[170:173], v[44:47]
	v_mfma_f32_16x16x32_bf16 v[36:39], v[230:233], v[170:173], v[36:39]
	v_mfma_f32_16x16x32_bf16 v[28:31], v[222:225], v[178:181], v[28:31]
	v_mfma_f32_16x16x32_bf16 v[20:23], v[230:233], v[178:181], v[20:23]
	v_mfma_f32_16x16x32_bf16 v[12:15], v[222:225], v[206:209], v[12:15]
	v_mfma_f32_16x16x32_bf16 v[8:11], v[230:233], v[206:209], v[8:11]
	v_mfma_f32_16x16x32_bf16 v[4:7], v[222:225], v[214:217], v[4:7]
	v_mfma_f32_16x16x32_bf16 v[0:3], v[230:233], v[214:217], v[0:3]
	s_setprio 0
	s_barrier
	ds_read_b128 v[146:149], v144
	ds_read_b128 v[154:157], v144 offset:1024
	ds_read_b128 v[158:161], v144 offset:2048
	ds_read_b128 v[162:165], v144 offset:3072
	s_add_u32 s0, s36, 0x160000
	s_addc_u32 s1, s37, 0
	s_mov_b32 m0, s42
	ds_read_b128 v[166:169], v142 offset:32768
	ds_read_b128 v[170:173], v142 offset:33792
	ds_read_b128 v[174:177], v142 offset:34816
	ds_read_b128 v[178:181], v142 offset:35840
	ds_read_b128 v[188:191], v142 offset:36864
	ds_read_b128 v[206:209], v142 offset:37888
	ds_read_b128 v[210:213], v142 offset:38912
	global_load_lds_dwordx4 v130, s[0:1]
	s_mov_b32 m0, s43
	ds_read_b128 v[214:217], v142 offset:39936
	global_load_lds_dwordx4 v128, s[0:1]
	s_waitcnt lgkmcnt(8)
	s_barrier
	s_waitcnt lgkmcnt(0)
	s_setprio 1
	v_mfma_f32_16x16x32_bf16 v[124:127], v[146:149], v[166:169], v[124:127]
	v_mfma_f32_16x16x32_bf16 v[120:123], v[158:161], v[166:169], v[120:123]
	v_mfma_f32_16x16x32_bf16 v[116:119], v[146:149], v[174:177], v[116:119]
	v_mfma_f32_16x16x32_bf16 v[112:115], v[158:161], v[174:177], v[112:115]
	v_mfma_f32_16x16x32_bf16 v[104:107], v[146:149], v[188:191], v[104:107]
	v_mfma_f32_16x16x32_bf16 v[96:99], v[158:161], v[188:191], v[96:99]
	v_mfma_f32_16x16x32_bf16 v[88:91], v[146:149], v[210:213], v[88:91]
	v_mfma_f32_16x16x32_bf16 v[80:83], v[158:161], v[210:213], v[80:83]
	v_mfma_f32_16x16x32_bf16 v[124:127], v[154:157], v[170:173], v[124:127]
	v_mfma_f32_16x16x32_bf16 v[120:123], v[162:165], v[170:173], v[120:123]
	v_mfma_f32_16x16x32_bf16 v[116:119], v[154:157], v[178:181], v[116:119]
	v_mfma_f32_16x16x32_bf16 v[112:115], v[162:165], v[178:181], v[112:115]
	v_mfma_f32_16x16x32_bf16 v[104:107], v[154:157], v[206:209], v[104:107]
	v_mfma_f32_16x16x32_bf16 v[96:99], v[162:165], v[206:209], v[96:99]
	v_mfma_f32_16x16x32_bf16 v[88:91], v[154:157], v[214:217], v[88:91]
	v_mfma_f32_16x16x32_bf16 v[80:83], v[162:165], v[214:217], v[80:83]
	s_setprio 0
	s_barrier
	s_add_i32 s4, 0, 0x1c000
	s_add_i32 s0, s62, s35
	v_add_u32_e32 v145, s4, v140
	s_add_i32 m0, s0, 0xffffff80
	ds_read_b128 v[218:221], v145
	ds_read_b128 v[222:225], v145 offset:1024
	ds_read_b128 v[226:229], v145 offset:2048
	global_load_lds_dwordx4 v130, s[30:31] offset:128
	s_add_i32 m0, s0, 0x1f80
	ds_read_b128 v[230:233], v145 offset:3072
	global_load_lds_dwordx4 v128, s[30:31] offset:128
	s_barrier
	s_waitcnt lgkmcnt(0)
	s_setprio 1
	v_mfma_f32_16x16x32_bf16 v[108:111], v[218:221], v[166:169], v[108:111]
	v_mfma_f32_16x16x32_bf16 v[100:103], v[226:229], v[166:169], v[100:103]
	v_mfma_f32_16x16x32_bf16 v[92:95], v[218:221], v[174:177], v[92:95]
	v_mfma_f32_16x16x32_bf16 v[84:87], v[226:229], v[174:177], v[84:87]
	v_mfma_f32_16x16x32_bf16 v[76:79], v[218:221], v[188:191], v[76:79]
	v_mfma_f32_16x16x32_bf16 v[72:75], v[226:229], v[188:191], v[72:75]
	v_mfma_f32_16x16x32_bf16 v[68:71], v[218:221], v[210:213], v[68:71]
	v_mfma_f32_16x16x32_bf16 v[64:67], v[226:229], v[210:213], v[64:67]
	v_mfma_f32_16x16x32_bf16 v[108:111], v[222:225], v[170:173], v[108:111]
	v_mfma_f32_16x16x32_bf16 v[100:103], v[230:233], v[170:173], v[100:103]
	v_mfma_f32_16x16x32_bf16 v[92:95], v[222:225], v[178:181], v[92:95]
	v_mfma_f32_16x16x32_bf16 v[84:87], v[230:233], v[178:181], v[84:87]
	v_mfma_f32_16x16x32_bf16 v[76:79], v[222:225], v[206:209], v[76:79]
	v_mfma_f32_16x16x32_bf16 v[72:75], v[230:233], v[206:209], v[72:75]
	v_mfma_f32_16x16x32_bf16 v[68:71], v[222:225], v[214:217], v[68:71]
	v_mfma_f32_16x16x32_bf16 v[64:67], v[230:233], v[214:217], v[64:67]
	s_setprio 0
	s_add_i32 m0, s54, 0xffffff80
	s_barrier
	ds_read_b128 v[166:169], v142 offset:49152
	ds_read_b128 v[170:173], v142 offset:50176
	ds_read_b128 v[174:177], v142 offset:51200
	ds_read_b128 v[178:181], v142 offset:52224
	ds_read_b128 v[188:191], v142 offset:53248
	ds_read_b128 v[206:209], v142 offset:54272
	ds_read_b128 v[210:213], v142 offset:55296
	global_load_lds_dwordx4 v130, s[36:37] offset:128
	s_add_i32 m0, s55, 0xffffff80
	ds_read_b128 v[214:217], v142 offset:56320
	global_load_lds_dwordx4 v128, s[36:37] offset:128
	s_barrier
; #define PG8_STAGE(bufoff, gbase, voff) do { _Pragma("unroll") for (int _i = 0; _i < 2; ++_i) \
;         __builtin_amdgcn_global_load_lds((const unsigned*)((const char*)(gbase) + (voff)[_i]), (LAS unsigned*)(lds + (bufoff) + ldsw + _i * 8192), 16, 0, 0); } while (0)
; #define PG8_LDA(dst, b, h) do { _Pragma("unroll") for (int m = 0; m < 4; ++m) _Pragma("unroll") for (int k = 0; k < 2; ++k) dst[m][k] = *(const LAS bf16x8*)(lds + PG8_SA(b, h) + aoff + m * 2048 + k * 1024); } while (0)
; #define PG8_LDB(dst, b, h) do { _Pragma("unroll") for (int n = 0; n < 2; ++n) _Pragma("unroll") for (int k = 0; k < 2; ++k) dst[n][k] = *(const LAS bf16x8*)(lds + PG8_SB(b, h) + boff + n * 2048 + k * 1024); } while (0)
; #define PG8_MMA(ai, bj, At, Bt) do { __builtin_amdgcn_s_setprio(1); _Pragma("unroll") for (int m = 0; m < 4; ++m) _Pragma("unroll") for (int n = 0; n < 2; ++n) _Pragma("unroll") for (int k = 0; k < 2; ++k) \
;         acc[ai][bj][m][n] = __builtin_amdgcn_mfma_f32_16x16x32_bf16(Bt[n][k], At[m][k], acc[ai][bj][m][n], 0, 0, 0); __builtin_amdgcn_s_setprio(0); } while (0)
; #define PG8_WAIT_V(n) asm volatile("s_waitcnt vmcnt(" #n ")" ::: "memory")
; #define PG8_WAIT_L(n) asm volatile("s_waitcnt lgkmcnt(" #n ")" ::: "memory")
; #define PG8_BAR __builtin_amdgcn_s_barrier()
; #define PG8_SCHED __builtin_amdgcn_sched_barrier(0)
; template <class Epi, class Sched>
; DI void gemm_phase(LAS unsigned char* lds, const Gemm g, const Sched& S, const Epi& E) {
;     ...
;             PG8_LDB(B0, 0, 0); PG8_SCHED; PG8_LDA(At, 0, 0); PG8_STAGE(PG8_SA(1, 1), a1 + hstep, voffA);
;             PG8_WAIT_L(8); PG8_BAR; PG8_WAIT_L(0); PG8_MMA(0, 0, At, B0); PG8_BAR; PG8_SCHED;
;             PG8_LDB(B1, 0, 1); PG8_STAGE(PG8_SB(0, 0), b2, voffB);
;     ...
;             PG8_BAR; PG8_WAIT_L(0); PG8_MMA(1, 0, At, B0); PG8_BAR; PG8_SCHED;
;             PG8_STAGE(PG8_SB(1, 1), b3 + hstep, voffB);
;             PG8_WAIT_V(6); PG8_BAR; PG8_MMA(1, 1, At, B1); PG8_BAR;
	s_waitcnt lgkmcnt(0)
	s_setprio 1
	v_mfma_f32_16x16x32_bf16 v[60:63], v[146:149], v[166:169], v[60:63]
	v_mfma_f32_16x16x32_bf16 v[56:59], v[158:161], v[166:169], v[56:59]
	v_mfma_f32_16x16x32_bf16 v[52:55], v[146:149], v[174:177], v[52:55]
	v_mfma_f32_16x16x32_bf16 v[48:51], v[158:161], v[174:177], v[48:51]
	v_mfma_f32_16x16x32_bf16 v[40:43], v[146:149], v[188:191], v[40:43]
	v_mfma_f32_16x16x32_bf16 v[32:35], v[158:161], v[188:191], v[32:35]
	v_mfma_f32_16x16x32_bf16 v[24:27], v[146:149], v[210:213], v[24:27]
	v_mfma_f32_16x16x32_bf16 v[16:19], v[158:161], v[210:213], v[16:19]
	v_mfma_f32_16x16x32_bf16 v[60:63], v[154:157], v[170:173], v[60:63]
	v_mfma_f32_16x16x32_bf16 v[56:59], v[162:165], v[170:173], v[56:59]
	v_mfma_f32_16x16x32_bf16 v[52:55], v[154:157], v[178:181], v[52:55]
	v_mfma_f32_16x16x32_bf16 v[48:51], v[162:165], v[178:181], v[48:51]
	v_mfma_f32_16x16x32_bf16 v[40:43], v[154:157], v[206:209], v[40:43]
	v_mfma_f32_16x16x32_bf16 v[32:35], v[162:165], v[206:209], v[32:35]
	v_mfma_f32_16x16x32_bf16 v[24:27], v[154:157], v[214:217], v[24:27]
	v_mfma_f32_16x16x32_bf16 v[16:19], v[162:165], v[214:217], v[16:19]
	s_setprio 0
	s_barrier
	s_add_i32 s4, s4, s35
	s_mov_b32 m0, s4
	s_add_u32 s0, s30, 0x160080
	s_addc_u32 s1, s31, 0
	global_load_lds_dwordx4 v130, s[0:1]
	s_add_i32 m0, s4, 0x2000
	s_nop 0
	global_load_lds_dwordx4 v128, s[0:1]
	s_waitcnt vmcnt(6)
	s_barrier
	s_setprio 1
	v_mfma_f32_16x16x32_bf16 v[44:47], v[218:221], v[166:169], v[44:47]
	v_mfma_f32_16x16x32_bf16 v[36:39], v[226:229], v[166:169], v[36:39]
	v_mfma_f32_16x16x32_bf16 v[28:31], v[218:221], v[174:177], v[28:31]
	v_mfma_f32_16x16x32_bf16 v[20:23], v[226:229], v[174:177], v[20:23]
	v_mfma_f32_16x16x32_bf16 v[12:15], v[218:221], v[188:191], v[12:15]
	v_mfma_f32_16x16x32_bf16 v[8:11], v[226:229], v[188:191], v[8:11]
	v_mfma_f32_16x16x32_bf16 v[4:7], v[218:221], v[210:213], v[4:7]
	v_mfma_f32_16x16x32_bf16 v[0:3], v[226:229], v[210:213], v[0:3]
	v_mfma_f32_16x16x32_bf16 v[44:47], v[222:225], v[170:173], v[44:47]
	v_mfma_f32_16x16x32_bf16 v[36:39], v[230:233], v[170:173], v[36:39]
	v_mfma_f32_16x16x32_bf16 v[28:31], v[222:225], v[178:181], v[28:31]
	v_mfma_f32_16x16x32_bf16 v[20:23], v[230:233], v[178:181], v[20:23]
	v_mfma_f32_16x16x32_bf16 v[12:15], v[222:225], v[206:209], v[12:15]
	v_mfma_f32_16x16x32_bf16 v[8:11], v[230:233], v[206:209], v[8:11]
	v_mfma_f32_16x16x32_bf16 v[4:7], v[222:225], v[214:217], v[4:7]
	v_mfma_f32_16x16x32_bf16 v[0:3], v[230:233], v[214:217], v[0:3]
	s_setprio 0
	s_add_i32 s66, s66, 2
	s_add_u32 s8, s8, 0x100
	s_addc_u32 s9, s9, 0
	s_add_u32 s64, s64, 0x100
	s_addc_u32 s65, s65, 0
	s_cmp_gt_u32 s66, 5
	s_barrier
	s_cbranch_scc0 .LBB0_1775
	s_branch .Lpeel_done_1775
.LBB0_1775:
	ds_read_b128 v[146:149], v141
	ds_read_b128 v[154:157], v141 offset:1024
	ds_read_b128 v[158:161], v141 offset:2048
	ds_read_b128 v[162:165], v141 offset:3072
	s_add_u32 s0, s8, 0xffea0080
	s_addc_u32 s1, s9, -1
	s_cmp_eq_u32 s66, 4
	s_cselect_b32 s37, s15, s1
	s_cselect_b32 s36, s17, s0
	s_cselect_b32 s31, s19, s65
	s_cselect_b32 s30, s18, s64
	s_mov_b32 m0, s56
	ds_read_b128 v[166:169], v142
	ds_read_b128 v[170:173], v142 offset:1024
	ds_read_b128 v[174:177], v142 offset:2048
	ds_read_b128 v[178:181], v142 offset:3072
	ds_read_b128 v[188:191], v142 offset:4096
	ds_read_b128 v[206:209], v142 offset:5120
	ds_read_b128 v[210:213], v142 offset:6144
	global_load_lds_dwordx4 v132, s[8:9]
	s_mov_b32 m0, s57
	ds_read_b128 v[214:217], v142 offset:7168
	global_load_lds_dwordx4 v134, s[8:9]
	s_waitcnt lgkmcnt(8)
	s_barrier
	s_waitcnt lgkmcnt(0)
	s_setprio 1
	v_mfma_f32_16x16x32_bf16 v[124:127], v[146:149], v[166:169], v[124:127]
	v_mfma_f32_16x16x32_bf16 v[120:123], v[158:161], v[166:169], v[120:123]
	v_mfma_f32_16x16x32_bf16 v[116:119], v[146:149], v[174:177], v[116:119]
	v_mfma_f32_16x16x32_bf16 v[112:115], v[158:161], v[174:177], v[112:115]
	v_mfma_f32_16x16x32_bf16 v[104:107], v[146:149], v[188:191], v[104:107]
	v_mfma_f32_16x16x32_bf16 v[96:99], v[158:161], v[188:191], v[96:99]
	v_mfma_f32_16x16x32_bf16 v[88:91], v[146:149], v[210:213], v[88:91]
	v_mfma_f32_16x16x32_bf16 v[80:83], v[158:161], v[210:213], v[80:83]
	v_mfma_f32_16x16x32_bf16 v[124:127], v[154:157], v[170:173], v[124:127]
	v_mfma_f32_16x16x32_bf16 v[120:123], v[162:165], v[170:173], v[120:123]
	v_mfma_f32_16x16x32_bf16 v[116:119], v[154:157], v[178:181], v[116:119]
	v_mfma_f32_16x16x32_bf16 v[112:115], v[162:165], v[178:181], v[112:115]
	v_mfma_f32_16x16x32_bf16 v[104:107], v[154:157], v[206:209], v[104:107]
	v_mfma_f32_16x16x32_bf16 v[96:99], v[162:165], v[206:209], v[96:99]
	v_mfma_f32_16x16x32_bf16 v[88:91], v[154:157], v[214:217], v[88:91]
	v_mfma_f32_16x16x32_bf16 v[80:83], v[162:165], v[214:217], v[80:83]
	s_setprio 0
	s_barrier
	s_mov_b32 m0, s58
	ds_read_b128 v[218:221], v143
	ds_read_b128 v[222:225], v143 offset:1024
	ds_read_b128 v[226:229], v143 offset:2048
	global_load_lds_dwordx4 v130, s[30:31]
	s_mov_b32 m0, s59
	ds_read_b128 v[230:233], v143 offset:3072
	global_load_lds_dwordx4 v128, s[30:31]
	s_barrier
; #define PG8_STAGE(bufoff, gbase, voff) do { _Pragma("unroll") for (int _i = 0; _i < 2; ++_i) \
;         __builtin_amdgcn_global_load_lds((const unsigned*)((const char*)(gbase) + (voff)[_i]), (LAS unsigned*)(lds + (bufoff) + ldsw + _i * 8192), 16, 0, 0); } while (0)
; #define PG8_LDA(dst, b, h) do { _Pragma("unroll") for (int m = 0; m < 4; ++m) _Pragma("unroll") for (int k = 0; k < 2; ++k) dst[m][k] = *(const LAS bf16x8*)(lds + PG8_SA(b, h) + aoff + m * 2048 + k * 1024); } while (0)
; #define PG8_LDB(dst, b, h) do { _Pragma("unroll") for (int n = 0; n < 2; ++n) _Pragma("unroll") for (int k = 0; k < 2; ++k) dst[n][k] = *(const LAS bf16x8*)(lds + PG8_SB(b, h) + boff + n * 2048 + k * 1024); } while (0)
; #define PG8_MMA(ai, bj, At, Bt) do { __builtin_amdgcn_s_setprio(1); _Pragma("unroll") for (int m = 0; m < 4; ++m) _Pragma("unroll") for (int n = 0; n < 2; ++n) _Pragma("unroll") for (int k = 0; k < 2; ++k) \
;         acc[ai][bj][m][n] = __builtin_amdgcn_mfma_f32_16x16x32_bf16(Bt[n][k], At[m][k], acc[ai][bj][m][n], 0, 0, 0); __builtin_amdgcn_s_setprio(0); } while (0)
; #define PG8_WAIT_V(n) asm volatile("s_waitcnt vmcnt(" #n ")" ::: "memory")
; #define PG8_WAIT_L(n) asm volatile("s_waitcnt lgkmcnt(" #n ")" ::: "memory")
; #define PG8_BAR __builtin_amdgcn_s_barrier()
; #define PG8_SCHED __builtin_amdgcn_sched_barrier(0)
; template <class Epi, class Sched>
; DI void gemm_phase(LAS unsigned char* lds, const Gemm g, const Sched& S, const Epi& E) {
;     ...
;             PG8_BAR; PG8_WAIT_L(0); PG8_MMA(0, 1, At, B1); PG8_BAR;
;             PG8_LDA(At, 0, 1); PG8_STAGE(PG8_SA(0, 0), a2, voffA);
;             PG8_BAR; PG8_WAIT_L(0); PG8_MMA(1, 0, At, B0); PG8_BAR; PG8_SCHED;
;             PG8_STAGE(PG8_SB(0, 1), b2 + hstep, voffB);
;             PG8_WAIT_V(6); PG8_BAR; PG8_MMA(1, 1, At, B1); PG8_BAR;
;             PG8_LDB(B0, 1, 0); PG8_SCHED; PG8_LDA(At, 1, 0); PG8_STAGE(PG8_SA(0, 1), a2 + hstep, voffA);
;             PG8_WAIT_L(8); PG8_BAR; PG8_WAIT_L(0); PG8_MMA(0, 0, At, B0); PG8_BAR; PG8_SCHED;
	s_waitcnt lgkmcnt(0)
	s_setprio 1
	v_mfma_f32_16x16x32_bf16 v[108:111], v[218:221], v[166:169], v[108:111]
	v_mfma_f32_16x16x32_bf16 v[100:103], v[226:229], v[166:169], v[100:103]
	v_mfma_f32_16x16x32_bf16 v[92:95], v[218:221], v[174:177], v[92:95]
	v_mfma_f32_16x16x32_bf16 v[84:87], v[226:229], v[174:177], v[84:87]
	v_mfma_f32_16x16x32_bf16 v[76:79], v[218:221], v[188:191], v[76:79]
	v_mfma_f32_16x16x32_bf16 v[72:75], v[226:229], v[188:191], v[72:75]
	v_mfma_f32_16x16x32_bf16 v[68:71], v[218:221], v[210:213], v[68:71]
	v_mfma_f32_16x16x32_bf16 v[64:67], v[226:229], v[210:213], v[64:67]
	v_mfma_f32_16x16x32_bf16 v[108:111], v[222:225], v[170:173], v[108:111]
	v_mfma_f32_16x16x32_bf16 v[100:103], v[230:233], v[170:173], v[100:103]
	v_mfma_f32_16x16x32_bf16 v[92:95], v[222:225], v[178:181], v[92:95]
	v_mfma_f32_16x16x32_bf16 v[84:87], v[230:233], v[178:181], v[84:87]
	v_mfma_f32_16x16x32_bf16 v[76:79], v[222:225], v[206:209], v[76:79]
	v_mfma_f32_16x16x32_bf16 v[72:75], v[230:233], v[206:209], v[72:75]
	v_mfma_f32_16x16x32_bf16 v[68:71], v[222:225], v[214:217], v[68:71]
	v_mfma_f32_16x16x32_bf16 v[64:67], v[230:233], v[214:217], v[64:67]
	s_setprio 0
	s_mov_b32 m0, s40
	s_barrier
	ds_read_b128 v[166:169], v142 offset:16384
	ds_read_b128 v[170:173], v142 offset:17408
	ds_read_b128 v[174:177], v142 offset:18432
	ds_read_b128 v[178:181], v142 offset:19456
	ds_read_b128 v[188:191], v142 offset:20480
	ds_read_b128 v[206:209], v142 offset:21504
	ds_read_b128 v[210:213], v142 offset:22528
	global_load_lds_dwordx4 v130, s[36:37]
	s_mov_b32 m0, s41
	ds_read_b128 v[214:217], v142 offset:23552
	global_load_lds_dwordx4 v128, s[36:37]
	s_barrier
	s_waitcnt lgkmcnt(0)
	s_setprio 1
	v_mfma_f32_16x16x32_bf16 v[60:63], v[146:149], v[166:169], v[60:63]
	v_mfma_f32_16x16x32_bf16 v[56:59], v[158:161], v[166:169], v[56:59]
	v_mfma_f32_16x16x32_bf16 v[52:55], v[146:149], v[174:177], v[52:55]
	v_mfma_f32_16x16x32_bf16 v[48:51], v[158:161], v[174:177], v[48:51]
	v_mfma_f32_16x16x32_bf16 v[40:43], v[146:149], v[188:191], v[40:43]
	v_mfma_f32_16x16x32_bf16 v[32:35], v[158:161], v[188:191], v[32:35]
	v_mfma_f32_16x16x32_bf16 v[24:27], v[146:149], v[210:213], v[24:27]
	v_mfma_f32_16x16x32_bf16 v[16:19], v[158:161], v[210:213], v[16:19]
	v_mfma_f32_16x16x32_bf16 v[60:63], v[154:157], v[170:173], v[60:63]
	v_mfma_f32_16x16x32_bf16 v[56:59], v[162:165], v[170:173], v[56:59]
	v_mfma_f32_16x16x32_bf16 v[52:55], v[154:157], v[178:181], v[52:55]
	v_mfma_f32_16x16x32_bf16 v[48:51], v[162:165], v[178:181], v[48:51]
	v_mfma_f32_16x16x32_bf16 v[40:43], v[154:157], v[206:209], v[40:43]
	v_mfma_f32_16x16x32_bf16 v[32:35], v[162:165], v[206:209], v[32:35]
	v_mfma_f32_16x16x32_bf16 v[24:27], v[154:157], v[214:217], v[24:27]
	v_mfma_f32_16x16x32_bf16 v[16:19], v[162:165], v[214:217], v[16:19]
	s_setprio 0
	s_barrier
	s_add_u32 s0, s30, 0x160000
	s_addc_u32 s1, s31, 0
	s_mov_b32 m0, s60
	s_nop 0
	global_load_lds_dwordx4 v130, s[0:1]
	s_mov_b32 m0, s61
	s_nop 0
	global_load_lds_dwordx4 v128, s[0:1]
	s_waitcnt vmcnt(6)
	s_barrier
	s_setprio 1
	v_mfma_f32_16x16x32_bf16 v[44:47], v[218:221], v[166:169], v[44:47]
	v_mfma_f32_16x16x32_bf16 v[36:39], v[226:229], v[166:169], v[36:39]
	v_mfma_f32_16x16x32_bf16 v[28:31], v[218:221], v[174:177], v[28:31]
	v_mfma_f32_16x16x32_bf16 v[20:23], v[226:229], v[174:177], v[20:23]
	v_mfma_f32_16x16x32_bf16 v[12:15], v[218:221], v[188:191], v[12:15]
	v_mfma_f32_16x16x32_bf16 v[8:11], v[226:229], v[188:191], v[8:11]
	v_mfma_f32_16x16x32_bf16 v[4:7], v[218:221], v[210:213], v[4:7]
	v_mfma_f32_16x16x32_bf16 v[0:3], v[226:229], v[210:213], v[0:3]
	v_mfma_f32_16x16x32_bf16 v[44:47], v[222:225], v[170:173], v[44:47]
	v_mfma_f32_16x16x32_bf16 v[36:39], v[230:233], v[170:173], v[36:39]
	v_mfma_f32_16x16x32_bf16 v[28:31], v[222:225], v[178:181], v[28:31]
	v_mfma_f32_16x16x32_bf16 v[20:23], v[230:233], v[178:181], v[20:23]
	v_mfma_f32_16x16x32_bf16 v[12:15], v[222:225], v[206:209], v[12:15]
	v_mfma_f32_16x16x32_bf16 v[8:11], v[230:233], v[206:209], v[8:11]
	v_mfma_f32_16x16x32_bf16 v[4:7], v[222:225], v[214:217], v[4:7]
	v_mfma_f32_16x16x32_bf16 v[0:3], v[230:233], v[214:217], v[0:3]
	s_setprio 0
	s_barrier
	ds_read_b128 v[146:149], v144
	ds_read_b128 v[154:157], v144 offset:1024
	ds_read_b128 v[158:161], v144 offset:2048
	ds_read_b128 v[162:165], v144 offset:3072
	s_add_u32 s0, s36, 0x160000
	s_addc_u32 s1, s37, 0
	s_mov_b32 m0, s42
	ds_read_b128 v[166:169], v142 offset:32768
	ds_read_b128 v[170:173], v142 offset:33792
	ds_read_b128 v[174:177], v142 offset:34816
	ds_read_b128 v[178:181], v142 offset:35840
	ds_read_b128 v[188:191], v142 offset:36864
	ds_read_b128 v[206:209], v142 offset:37888
	ds_read_b128 v[210:213], v142 offset:38912
	global_load_lds_dwordx4 v130, s[0:1]
	s_mov_b32 m0, s43
	ds_read_b128 v[214:217], v142 offset:39936
	global_load_lds_dwordx4 v128, s[0:1]
	s_waitcnt lgkmcnt(8)
	s_barrier
; #define PG8_STAGE(bufoff, gbase, voff) do { _Pragma("unroll") for (int _i = 0; _i < 2; ++_i) \
;         __builtin_amdgcn_global_load_lds((const unsigned*)((const char*)(gbase) + (voff)[_i]), (LAS unsigned*)(lds + (bufoff) + ldsw + _i * 8192), 16, 0, 0); } while (0)
; #define PG8_LDA(dst, b, h) do { _Pragma("unroll") for (int m = 0; m < 4; ++m) _Pragma("unroll") for (int k = 0; k < 2; ++k) dst[m][k] = *(const LAS bf16x8*)(lds + PG8_SA(b, h) + aoff + m * 2048 + k * 1024); } while (0)
; #define PG8_LDB(dst, b, h) do { _Pragma("unroll") for (int n = 0; n < 2; ++n) _Pragma("unroll") for (int k = 0; k < 2; ++k) dst[n][k] = *(const LAS bf16x8*)(lds + PG8_SB(b, h) + boff + n * 2048 + k * 1024); } while (0)
; #define PG8_MMA(ai, bj, At, Bt) do { __builtin_amdgcn_s_setprio(1); _Pragma("unroll") for (int m = 0; m < 4; ++m) _Pragma("unroll") for (int n = 0; n < 2; ++n) _Pragma("unroll") for (int k = 0; k < 2; ++k) \
;         acc[ai][bj][m][n] = __builtin_amdgcn_mfma_f32_16x16x32_bf16(Bt[n][k], At[m][k], acc[ai][bj][m][n], 0, 0, 0); __builtin_amdgcn_s_setprio(0); } while (0)
; #define PG8_WAIT_V(n) asm volatile("s_waitcnt vmcnt(" #n ")" ::: "memory")
; #define PG8_WAIT_L(n) asm volatile("s_waitcnt lgkmcnt(" #n ")" ::: "memory")
; #define PG8_BAR __builtin_amdgcn_s_barrier()
; #define PG8_SCHED __builtin_amdgcn_sched_barrier(0)
; template <class Epi, class Sched>
; DI void gemm_phase(LAS unsigned char* lds, const Gemm g, const Sched& S, const Epi& E) {
;     ...
;             PG8_WAIT_L(8); PG8_BAR; PG8_WAIT_L(0); PG8_MMA(0, 0, At, B0); PG8_BAR; PG8_SCHED;
;             PG8_LDB(B1, 1, 1); PG8_STAGE(PG8_SB(1, 0), b3, voffB);
;             PG8_BAR; PG8_WAIT_L(0); PG8_MMA(0, 1, At, B1); PG8_BAR;
;             PG8_LDA(At, 1, 1); PG8_STAGE(PG8_SA(1, 0), a3, voffA);
;             PG8_BAR; PG8_WAIT_L(0); PG8_MMA(1, 0, At, B0); PG8_BAR; PG8_SCHED;
;             PG8_STAGE(PG8_SB(1, 1), b3 + hstep, voffB);
;             PG8_WAIT_V(6); PG8_BAR; PG8_MMA(1, 1, At, B1); PG8_BAR;
	s_waitcnt lgkmcnt(0)
	s_setprio 1
	v_mfma_f32_16x16x32_bf16 v[124:127], v[146:149], v[166:169], v[124:127]
	v_mfma_f32_16x16x32_bf16 v[120:123], v[158:161], v[166:169], v[120:123]
	v_mfma_f32_16x16x32_bf16 v[116:119], v[146:149], v[174:177], v[116:119]
	v_mfma_f32_16x16x32_bf16 v[112:115], v[158:161], v[174:177], v[112:115]
	v_mfma_f32_16x16x32_bf16 v[104:107], v[146:149], v[188:191], v[104:107]
	v_mfma_f32_16x16x32_bf16 v[96:99], v[158:161], v[188:191], v[96:99]
	v_mfma_f32_16x16x32_bf16 v[88:91], v[146:149], v[210:213], v[88:91]
	v_mfma_f32_16x16x32_bf16 v[80:83], v[158:161], v[210:213], v[80:83]
	v_mfma_f32_16x16x32_bf16 v[124:127], v[154:157], v[170:173], v[124:127]
	v_mfma_f32_16x16x32_bf16 v[120:123], v[162:165], v[170:173], v[120:123]
	v_mfma_f32_16x16x32_bf16 v[116:119], v[154:157], v[178:181], v[116:119]
	v_mfma_f32_16x16x32_bf16 v[112:115], v[162:165], v[178:181], v[112:115]
	v_mfma_f32_16x16x32_bf16 v[104:107], v[154:157], v[206:209], v[104:107]
	v_mfma_f32_16x16x32_bf16 v[96:99], v[162:165], v[206:209], v[96:99]
	v_mfma_f32_16x16x32_bf16 v[88:91], v[154:157], v[214:217], v[88:91]
	v_mfma_f32_16x16x32_bf16 v[80:83], v[162:165], v[214:217], v[80:83]
	s_setprio 0
	s_barrier
	s_add_i32 s4, 0, 0x1c000
	s_add_i32 s0, s62, s35
	v_add_u32_e32 v145, s4, v140
	s_add_i32 m0, s0, 0xffffff80
	ds_read_b128 v[218:221], v145
	ds_read_b128 v[222:225], v145 offset:1024
	ds_read_b128 v[226:229], v145 offset:2048
	global_load_lds_dwordx4 v130, s[30:31] offset:128
	s_add_i32 m0, s0, 0x1f80
	ds_read_b128 v[230:233], v145 offset:3072
	global_load_lds_dwordx4 v128, s[30:31] offset:128
	s_barrier
	s_waitcnt lgkmcnt(0)
	s_setprio 1
	v_mfma_f32_16x16x32_bf16 v[108:111], v[218:221], v[166:169], v[108:111]
	v_mfma_f32_16x16x32_bf16 v[100:103], v[226:229], v[166:169], v[100:103]
	v_mfma_f32_16x16x32_bf16 v[92:95], v[218:221], v[174:177], v[92:95]
	v_mfma_f32_16x16x32_bf16 v[84:87], v[226:229], v[174:177], v[84:87]
	v_mfma_f32_16x16x32_bf16 v[76:79], v[218:221], v[188:191], v[76:79]
	v_mfma_f32_16x16x32_bf16 v[72:75], v[226:229], v[188:191], v[72:75]
	v_mfma_f32_16x16x32_bf16 v[68:71], v[218:221], v[210:213], v[68:71]
	v_mfma_f32_16x16x32_bf16 v[64:67], v[226:229], v[210:213], v[64:67]
	v_mfma_f32_16x16x32_bf16 v[108:111], v[222:225], v[170:173], v[108:111]
	v_mfma_f32_16x16x32_bf16 v[100:103], v[230:233], v[170:173], v[100:103]
	v_mfma_f32_16x16x32_bf16 v[92:95], v[222:225], v[178:181], v[92:95]
	v_mfma_f32_16x16x32_bf16 v[84:87], v[230:233], v[178:181], v[84:87]
	v_mfma_f32_16x16x32_bf16 v[76:79], v[222:225], v[206:209], v[76:79]
	v_mfma_f32_16x16x32_bf16 v[72:75], v[230:233], v[206:209], v[72:75]
	v_mfma_f32_16x16x32_bf16 v[68:71], v[222:225], v[214:217], v[68:71]
	v_mfma_f32_16x16x32_bf16 v[64:67], v[230:233], v[214:217], v[64:67]
	s_setprio 0
	s_add_i32 m0, s54, 0xffffff80
	s_barrier
	ds_read_b128 v[166:169], v142 offset:49152
	ds_read_b128 v[170:173], v142 offset:50176
	ds_read_b128 v[174:177], v142 offset:51200
	ds_read_b128 v[178:181], v142 offset:52224
	ds_read_b128 v[188:191], v142 offset:53248
	ds_read_b128 v[206:209], v142 offset:54272
	ds_read_b128 v[210:213], v142 offset:55296
	global_load_lds_dwordx4 v130, s[36:37] offset:128
	s_add_i32 m0, s55, 0xffffff80
	ds_read_b128 v[214:217], v142 offset:56320
	global_load_lds_dwordx4 v128, s[36:37] offset:128
	s_barrier
	s_waitcnt lgkmcnt(0)
	s_setprio 1
	v_mfma_f32_16x16x32_bf16 v[60:63], v[146:149], v[166:169], v[60:63]
	v_mfma_f32_16x16x32_bf16 v[56:59], v[158:161], v[166:169], v[56:59]
	v_mfma_f32_16x16x32_bf16 v[52:55], v[146:149], v[174:177], v[52:55]
	v_mfma_f32_16x16x32_bf16 v[48:51], v[158:161], v[174:177], v[48:51]
	v_mfma_f32_16x16x32_bf16 v[40:43], v[146:149], v[188:191], v[40:43]
	v_mfma_f32_16x16x32_bf16 v[32:35], v[158:161], v[188:191], v[32:35]
	v_mfma_f32_16x16x32_bf16 v[24:27], v[146:149], v[210:213], v[24:27]
	v_mfma_f32_16x16x32_bf16 v[16:19], v[158:161], v[210:213], v[16:19]
	v_mfma_f32_16x16x32_bf16 v[60:63], v[154:157], v[170:173], v[60:63]
	v_mfma_f32_16x16x32_bf16 v[56:59], v[162:165], v[170:173], v[56:59]
	v_mfma_f32_16x16x32_bf16 v[52:55], v[154:157], v[178:181], v[52:55]
	v_mfma_f32_16x16x32_bf16 v[48:51], v[162:165], v[178:181], v[48:51]
	v_mfma_f32_16x16x32_bf16 v[40:43], v[154:157], v[206:209], v[40:43]
	v_mfma_f32_16x16x32_bf16 v[32:35], v[162:165], v[206:209], v[32:35]
	v_mfma_f32_16x16x32_bf16 v[24:27], v[154:157], v[214:217], v[24:27]
	v_mfma_f32_16x16x32_bf16 v[16:19], v[162:165], v[214:217], v[16:19]
	s_setprio 0
	s_barrier
	s_add_i32 s4, s4, s35
	s_mov_b32 m0, s4
	s_add_u32 s0, s30, 0x160080
	s_addc_u32 s1, s31, 0
	global_load_lds_dwordx4 v130, s[0:1]
	s_add_i32 m0, s4, 0x2000
	s_nop 0
	global_load_lds_dwordx4 v128, s[0:1]
	s_waitcnt vmcnt(6)
	s_barrier
	s_setprio 1
	v_mfma_f32_16x16x32_bf16 v[44:47], v[218:221], v[166:169], v[44:47]
	v_mfma_f32_16x16x32_bf16 v[36:39], v[226:229], v[166:169], v[36:39]
	v_mfma_f32_16x16x32_bf16 v[28:31], v[218:221], v[174:177], v[28:31]
	v_mfma_f32_16x16x32_bf16 v[20:23], v[226:229], v[174:177], v[20:23]
	v_mfma_f32_16x16x32_bf16 v[12:15], v[218:221], v[188:191], v[12:15]
	v_mfma_f32_16x16x32_bf16 v[8:11], v[226:229], v[188:191], v[8:11]
	v_mfma_f32_16x16x32_bf16 v[4:7], v[218:221], v[210:213], v[4:7]
	v_mfma_f32_16x16x32_bf16 v[0:3], v[226:229], v[210:213], v[0:3]
	v_mfma_f32_16x16x32_bf16 v[44:47], v[222:225], v[170:173], v[44:47]
	v_mfma_f32_16x16x32_bf16 v[36:39], v[230:233], v[170:173], v[36:39]
	v_mfma_f32_16x16x32_bf16 v[28:31], v[222:225], v[178:181], v[28:31]
	v_mfma_f32_16x16x32_bf16 v[20:23], v[230:233], v[178:181], v[20:23]
	v_mfma_f32_16x16x32_bf16 v[12:15], v[222:225], v[206:209], v[12:15]
	v_mfma_f32_16x16x32_bf16 v[8:11], v[230:233], v[206:209], v[8:11]
	v_mfma_f32_16x16x32_bf16 v[4:7], v[222:225], v[214:217], v[4:7]
	v_mfma_f32_16x16x32_bf16 v[0:3], v[230:233], v[214:217], v[0:3]
	s_setprio 0
	s_add_i32 s66, s66, 2
	s_add_u32 s8, s8, 0x100
	s_addc_u32 s9, s9, 0
	s_add_u32 s64, s64, 0x100
	s_addc_u32 s65, s65, 0
	s_cmp_gt_u32 s66, 5
	s_barrier
	s_cbranch_scc0 .LBB0_1775

; #define PG8_STAGE(bufoff, gbase, voff) do { _Pragma("unroll") for (int _i = 0; _i < 2; ++_i) \
;         __builtin_amdgcn_global_load_lds((const unsigned*)((const char*)(gbase) + (voff)[_i]), (LAS unsigned*)(lds + (bufoff) + ldsw + _i * 8192), 16, 0, 0); } while (0)
; #define PG8_LDA(dst, b, h) do { _Pragma("unroll") for (int m = 0; m < 4; ++m) _Pragma("unroll") for (int k = 0; k < 2; ++k) dst[m][k] = *(const LAS bf16x8*)(lds + PG8_SA(b, h) + aoff + m * 2048 + k * 1024); } while (0)
; #define PG8_LDB(dst, b, h) do { _Pragma("unroll") for (int n = 0; n < 2; ++n) _Pragma("unroll") for (int k = 0; k < 2; ++k) dst[n][k] = *(const LAS bf16x8*)(lds + PG8_SB(b, h) + boff + n * 2048 + k * 1024); } while (0)
; #define PG8_MMA(ai, bj, At, Bt) do { __builtin_amdgcn_s_setprio(1); _Pragma("unroll") for (int m = 0; m < 4; ++m) _Pragma("unroll") for (int n = 0; n < 2; ++n) _Pragma("unroll") for (int k = 0; k < 2; ++k) \
;         acc[ai][bj][m][n] = __builtin_amdgcn_mfma_f32_16x16x32_bf16(Bt[n][k], At[m][k], acc[ai][bj][m][n], 0, 0, 0); __builtin_amdgcn_s_setprio(0); } while (0)
; #define PG8_WAIT_V(n) asm volatile("s_waitcnt vmcnt(" #n ")" ::: "memory")
; #define PG8_WAIT_L(n) asm volatile("s_waitcnt lgkmcnt(" #n ")" ::: "memory")
; #define PG8_BAR __builtin_amdgcn_s_barrier()
; #define PG8_SCHED __builtin_amdgcn_sched_barrier(0)
; template <class Epi, class Sched>
; DI void gemm_phase(LAS unsigned char* lds, const Gemm g, const Sched& S, const Epi& E) {
;     ...
;             PG8_LDB(B0, 0, 0); PG8_SCHED; PG8_LDA(At, 0, 0); PG8_STAGE(PG8_SA(1, 1), a1 + hstep, voffA);
;             PG8_WAIT_L(8); PG8_BAR; PG8_WAIT_L(0); PG8_MMA(0, 0, At, B0); PG8_BAR; PG8_SCHED;
;             PG8_LDB(B1, 0, 1); PG8_STAGE(PG8_SB(0, 0), b2, voffB);
;             PG8_BAR; PG8_WAIT_L(0); PG8_MMA(0, 1, At, B1); PG8_BAR;
;             PG8_LDA(At, 0, 1); PG8_STAGE(PG8_SA(0, 0), a2, voffA);
;             PG8_BAR; PG8_WAIT_L(0); PG8_MMA(1, 0, At, B0); PG8_BAR; PG8_SCHED;
;             PG8_STAGE(PG8_SB(0, 1), b2 + hstep, voffB);
;             PG8_WAIT_V(6); PG8_BAR; PG8_MMA(1, 1, At, B1); PG8_BAR;
.LBB0_1920:
	v_add_u32_e32 v161, s62, v157
	s_add_u32 s0, s38, s8
	ds_read_b128 v[148:151], v161
	ds_read_b128 v[162:165], v161 offset:1024
	ds_read_b128 v[166:169], v161 offset:2048
	ds_read_b128 v[170:173], v161 offset:3072
	s_addc_u32 s1, s39, s9
	s_add_u32 s0, s0, 0x100
	s_addc_u32 s1, s1, 0
	s_add_u32 s4, s68, s8
	s_addc_u32 s5, s69, s9
	s_cmpk_eq_i32 s8, 0x1100
	s_cselect_b32 s43, s37, s1
	s_cselect_b32 s42, s36, s0
	s_cselect_b32 s41, s11, s5
	s_cselect_b32 s40, s10, s4
	v_lshl_add_u64 v[182:183], v[144:145], 0, s[8:9]
	s_add_i32 m0, s53, 0xc000
	ds_read_b128 v[174:177], v158
	ds_read_b128 v[178:181], v158 offset:1024
	ds_read_b128 v[188:191], v158 offset:2048
	ds_read_b128 v[196:199], v158 offset:3072
	ds_read_b128 v[200:203], v158 offset:4096
	ds_read_b128 v[206:209], v158 offset:5120
	ds_read_b128 v[210:213], v158 offset:6144
	ds_read_b128 v[214:217], v158 offset:7168
	global_load_lds_dwordx4 v[182:183], off
	v_lshl_add_u64 v[182:183], v[146:147], 0, s[8:9]
	s_add_i32 m0, s53, 0xe000
	s_nop 0
	global_load_lds_dwordx4 v[182:183], off
	s_waitcnt lgkmcnt(8)
	s_barrier
	s_waitcnt lgkmcnt(0)
	s_setprio 1
	v_mfma_f32_16x16x32_bf16 v[124:127], v[148:151], v[174:177], v[124:127]
	v_mfma_f32_16x16x32_bf16 v[120:123], v[166:169], v[174:177], v[120:123]
	v_mfma_f32_16x16x32_bf16 v[108:111], v[148:151], v[188:191], v[108:111]
	v_mfma_f32_16x16x32_bf16 v[104:107], v[166:169], v[188:191], v[104:107]
	v_mfma_f32_16x16x32_bf16 v[92:95], v[148:151], v[200:203], v[92:95]
	v_mfma_f32_16x16x32_bf16 v[88:91], v[166:169], v[200:203], v[88:91]
	v_mfma_f32_16x16x32_bf16 v[76:79], v[148:151], v[210:213], v[76:79]
	v_mfma_f32_16x16x32_bf16 v[72:75], v[166:169], v[210:213], v[72:75]
	v_mfma_f32_16x16x32_bf16 v[124:127], v[162:165], v[178:181], v[124:127]
	v_mfma_f32_16x16x32_bf16 v[120:123], v[170:173], v[178:181], v[120:123]
	v_mfma_f32_16x16x32_bf16 v[108:111], v[162:165], v[196:199], v[108:111]
	v_mfma_f32_16x16x32_bf16 v[104:107], v[170:173], v[196:199], v[104:107]
	v_mfma_f32_16x16x32_bf16 v[92:95], v[162:165], v[206:209], v[92:95]
	v_mfma_f32_16x16x32_bf16 v[88:91], v[170:173], v[206:209], v[88:91]
	v_mfma_f32_16x16x32_bf16 v[76:79], v[162:165], v[214:217], v[76:79]
	v_mfma_f32_16x16x32_bf16 v[72:75], v[170:173], v[214:217], v[72:75]
	s_setprio 0
	s_barrier
	s_add_i32 s0, s62, s52
	v_add_u32_e32 v161, s63, v157
	s_mov_b32 m0, s0
	ds_read_b128 v[218:221], v161
	ds_read_b128 v[222:225], v161 offset:1024
	ds_read_b128 v[226:229], v161 offset:2048
	global_load_lds_dwordx4 v130, s[40:41]
	s_add_i32 m0, s0, 0x2000
	ds_read_b128 v[230:233], v161 offset:3072
	global_load_lds_dwordx4 v134, s[40:41]
	s_barrier
	s_waitcnt lgkmcnt(0)
	s_setprio 1
	v_mfma_f32_16x16x32_bf16 v[116:119], v[218:221], v[174:177], v[116:119]
	v_mfma_f32_16x16x32_bf16 v[112:115], v[226:229], v[174:177], v[112:115]
	v_mfma_f32_16x16x32_bf16 v[100:103], v[218:221], v[188:191], v[100:103]
	v_mfma_f32_16x16x32_bf16 v[96:99], v[226:229], v[188:191], v[96:99]
	v_mfma_f32_16x16x32_bf16 v[84:87], v[218:221], v[200:203], v[84:87]
	v_mfma_f32_16x16x32_bf16 v[80:83], v[226:229], v[200:203], v[80:83]
	v_mfma_f32_16x16x32_bf16 v[68:71], v[218:221], v[210:213], v[68:71]
	v_mfma_f32_16x16x32_bf16 v[64:67], v[226:229], v[210:213], v[64:67]
	v_mfma_f32_16x16x32_bf16 v[116:119], v[222:225], v[178:181], v[116:119]
	v_mfma_f32_16x16x32_bf16 v[112:115], v[230:233], v[178:181], v[112:115]
	v_mfma_f32_16x16x32_bf16 v[100:103], v[222:225], v[196:199], v[100:103]
	v_mfma_f32_16x16x32_bf16 v[96:99], v[230:233], v[196:199], v[96:99]
	v_mfma_f32_16x16x32_bf16 v[84:87], v[222:225], v[206:209], v[84:87]
	v_mfma_f32_16x16x32_bf16 v[80:83], v[230:233], v[206:209], v[80:83]
	v_mfma_f32_16x16x32_bf16 v[68:71], v[222:225], v[214:217], v[68:71]
	v_mfma_f32_16x16x32_bf16 v[64:67], v[230:233], v[214:217], v[64:67]
	s_setprio 0
	s_mov_b32 m0, s53
	s_barrier
	ds_read_b128 v[174:177], v158 offset:16384
	ds_read_b128 v[178:181], v158 offset:17408
	ds_read_b128 v[188:191], v158 offset:18432
	ds_read_b128 v[196:199], v158 offset:19456
	ds_read_b128 v[200:203], v158 offset:20480
	ds_read_b128 v[206:209], v158 offset:21504
	ds_read_b128 v[210:213], v158 offset:22528
	global_load_lds_dwordx4 v128, s[42:43]
	s_mov_b32 m0, s54
	ds_read_b128 v[214:217], v158 offset:23552
	global_load_lds_dwordx4 v132, s[42:43]
	s_barrier
	s_waitcnt lgkmcnt(0)
	s_setprio 1
	v_mfma_f32_16x16x32_bf16 v[60:63], v[148:151], v[174:177], v[60:63]
	v_mfma_f32_16x16x32_bf16 v[56:59], v[166:169], v[174:177], v[56:59]
	v_mfma_f32_16x16x32_bf16 v[44:47], v[148:151], v[188:191], v[44:47]
	v_mfma_f32_16x16x32_bf16 v[40:43], v[166:169], v[188:191], v[40:43]
	v_mfma_f32_16x16x32_bf16 v[28:31], v[148:151], v[200:203], v[28:31]
	v_mfma_f32_16x16x32_bf16 v[24:27], v[166:169], v[200:203], v[24:27]
	v_mfma_f32_16x16x32_bf16 v[12:15], v[148:151], v[210:213], v[12:15]
	v_mfma_f32_16x16x32_bf16 v[8:11], v[166:169], v[210:213], v[8:11]
	v_mfma_f32_16x16x32_bf16 v[60:63], v[162:165], v[178:181], v[60:63]
	v_mfma_f32_16x16x32_bf16 v[56:59], v[170:173], v[178:181], v[56:59]
	v_mfma_f32_16x16x32_bf16 v[44:47], v[162:165], v[196:199], v[44:47]
	v_mfma_f32_16x16x32_bf16 v[40:43], v[170:173], v[196:199], v[40:43]
	v_mfma_f32_16x16x32_bf16 v[28:31], v[162:165], v[206:209], v[28:31]
	v_mfma_f32_16x16x32_bf16 v[24:27], v[170:173], v[206:209], v[24:27]
	v_mfma_f32_16x16x32_bf16 v[12:15], v[162:165], v[214:217], v[12:15]
	v_mfma_f32_16x16x32_bf16 v[8:11], v[170:173], v[214:217], v[8:11]
	s_setprio 0
	s_barrier
	s_add_i32 s4, s63, s52
	s_mov_b32 m0, s4
	s_add_u32 s0, s40, 0x90000
	s_addc_u32 s1, s41, 0
	global_load_lds_dwordx4 v130, s[0:1]
	s_add_i32 m0, s4, 0x2000
	s_nop 0
	global_load_lds_dwordx4 v134, s[0:1]
	s_waitcnt vmcnt(6)
	s_barrier
; #define PG8_STAGE(bufoff, gbase, voff) do { _Pragma("unroll") for (int _i = 0; _i < 2; ++_i) \
;         __builtin_amdgcn_global_load_lds((const unsigned*)((const char*)(gbase) + (voff)[_i]), (LAS unsigned*)(lds + (bufoff) + ldsw + _i * 8192), 16, 0, 0); } while (0)
; #define PG8_LDA(dst, b, h) do { _Pragma("unroll") for (int m = 0; m < 4; ++m) _Pragma("unroll") for (int k = 0; k < 2; ++k) dst[m][k] = *(const LAS bf16x8*)(lds + PG8_SA(b, h) + aoff + m * 2048 + k * 1024); } while (0)
; #define PG8_LDB(dst, b, h) do { _Pragma("unroll") for (int n = 0; n < 2; ++n) _Pragma("unroll") for (int k = 0; k < 2; ++k) dst[n][k] = *(const LAS bf16x8*)(lds + PG8_SB(b, h) + boff + n * 2048 + k * 1024); } while (0)
; #define PG8_MMA(ai, bj, At, Bt) do { __builtin_amdgcn_s_setprio(1); _Pragma("unroll") for (int m = 0; m < 4; ++m) _Pragma("unroll") for (int n = 0; n < 2; ++n) _Pragma("unroll") for (int k = 0; k < 2; ++k) \
;         acc[ai][bj][m][n] = __builtin_amdgcn_mfma_f32_16x16x32_bf16(Bt[n][k], At[m][k], acc[ai][bj][m][n], 0, 0, 0); __builtin_amdgcn_s_setprio(0); } while (0)
; #define PG8_WAIT_V(n) asm volatile("s_waitcnt vmcnt(" #n ")" ::: "memory")
; #define PG8_WAIT_L(n) asm volatile("s_waitcnt lgkmcnt(" #n ")" ::: "memory")
; #define PG8_BAR __builtin_amdgcn_s_barrier()
; #define PG8_SCHED __builtin_amdgcn_sched_barrier(0)
; template <class Epi, class Sched>
; DI void gemm_phase(LAS unsigned char* lds, const Gemm g, const Sched& S, const Epi& E) {
;     ...
;             PG8_WAIT_V(6); PG8_BAR; PG8_MMA(1, 1, At, B1); PG8_BAR;
;             PG8_LDB(B0, 1, 0); PG8_SCHED; PG8_LDA(At, 1, 0); PG8_STAGE(PG8_SA(0, 1), a2 + hstep, voffA);
;             PG8_WAIT_L(8); PG8_BAR; PG8_WAIT_L(0); PG8_MMA(0, 0, At, B0); PG8_BAR; PG8_SCHED;
;             PG8_LDB(B1, 1, 1); PG8_STAGE(PG8_SB(1, 0), b3, voffB);
;             PG8_BAR; PG8_WAIT_L(0); PG8_MMA(0, 1, At, B1); PG8_BAR;
;             PG8_LDA(At, 1, 1); PG8_STAGE(PG8_SA(1, 0), a3, voffA);
	s_setprio 1
	v_mfma_f32_16x16x32_bf16 v[52:55], v[218:221], v[174:177], v[52:55]
	v_mfma_f32_16x16x32_bf16 v[48:51], v[226:229], v[174:177], v[48:51]
	v_mfma_f32_16x16x32_bf16 v[36:39], v[218:221], v[188:191], v[36:39]
	v_mfma_f32_16x16x32_bf16 v[32:35], v[226:229], v[188:191], v[32:35]
	v_mfma_f32_16x16x32_bf16 v[20:23], v[218:221], v[200:203], v[20:23]
	v_mfma_f32_16x16x32_bf16 v[16:19], v[226:229], v[200:203], v[16:19]
	v_mfma_f32_16x16x32_bf16 v[4:7], v[218:221], v[210:213], v[4:7]
	v_mfma_f32_16x16x32_bf16 v[0:3], v[226:229], v[210:213], v[0:3]
	v_mfma_f32_16x16x32_bf16 v[52:55], v[222:225], v[178:181], v[52:55]
	v_mfma_f32_16x16x32_bf16 v[48:51], v[230:233], v[178:181], v[48:51]
	v_mfma_f32_16x16x32_bf16 v[36:39], v[222:225], v[196:199], v[36:39]
	v_mfma_f32_16x16x32_bf16 v[32:35], v[230:233], v[196:199], v[32:35]
	v_mfma_f32_16x16x32_bf16 v[20:23], v[222:225], v[206:209], v[20:23]
	v_mfma_f32_16x16x32_bf16 v[16:19], v[230:233], v[206:209], v[16:19]
	v_mfma_f32_16x16x32_bf16 v[4:7], v[222:225], v[214:217], v[4:7]
	v_mfma_f32_16x16x32_bf16 v[0:3], v[230:233], v[214:217], v[0:3]
	s_setprio 0
	s_add_i32 s4, 0, 0x18000
	v_add_u32_e32 v161, s4, v157
	s_barrier
	ds_read_b128 v[148:151], v161
	ds_read_b128 v[162:165], v161 offset:1024
	ds_read_b128 v[166:169], v161 offset:2048
	ds_read_b128 v[170:173], v161 offset:3072
	s_add_u32 s0, s42, 0x90000
	s_addc_u32 s1, s43, 0
	s_mov_b32 m0, s55
	ds_read_b128 v[174:177], v158 offset:32768
	ds_read_b128 v[178:181], v158 offset:33792
	ds_read_b128 v[188:191], v158 offset:34816
	ds_read_b128 v[196:199], v158 offset:35840
	ds_read_b128 v[200:203], v158 offset:36864
	ds_read_b128 v[206:209], v158 offset:37888
	ds_read_b128 v[210:213], v158 offset:38912
	global_load_lds_dwordx4 v128, s[0:1]
	s_mov_b32 m0, s56
	ds_read_b128 v[214:217], v158 offset:39936
	global_load_lds_dwordx4 v132, s[0:1]
	s_waitcnt lgkmcnt(8)
	s_barrier
	s_waitcnt lgkmcnt(0)
	s_setprio 1
	v_mfma_f32_16x16x32_bf16 v[124:127], v[148:151], v[174:177], v[124:127]
	v_mfma_f32_16x16x32_bf16 v[120:123], v[166:169], v[174:177], v[120:123]
	v_mfma_f32_16x16x32_bf16 v[108:111], v[148:151], v[188:191], v[108:111]
	v_mfma_f32_16x16x32_bf16 v[104:107], v[166:169], v[188:191], v[104:107]
	v_mfma_f32_16x16x32_bf16 v[92:95], v[148:151], v[200:203], v[92:95]
	v_mfma_f32_16x16x32_bf16 v[88:91], v[166:169], v[200:203], v[88:91]
	v_mfma_f32_16x16x32_bf16 v[76:79], v[148:151], v[210:213], v[76:79]
	v_mfma_f32_16x16x32_bf16 v[72:75], v[166:169], v[210:213], v[72:75]
	v_mfma_f32_16x16x32_bf16 v[124:127], v[162:165], v[178:181], v[124:127]
	v_mfma_f32_16x16x32_bf16 v[120:123], v[170:173], v[178:181], v[120:123]
	v_mfma_f32_16x16x32_bf16 v[108:111], v[162:165], v[196:199], v[108:111]
	v_mfma_f32_16x16x32_bf16 v[104:107], v[170:173], v[196:199], v[104:107]
	v_mfma_f32_16x16x32_bf16 v[92:95], v[162:165], v[206:209], v[92:95]
	v_mfma_f32_16x16x32_bf16 v[88:91], v[170:173], v[206:209], v[88:91]
	v_mfma_f32_16x16x32_bf16 v[76:79], v[162:165], v[214:217], v[76:79]
	v_mfma_f32_16x16x32_bf16 v[72:75], v[170:173], v[214:217], v[72:75]
	s_setprio 0
	s_barrier
	s_add_i32 s5, 0, 0x1c000
	s_add_i32 s0, s4, s52
	v_add_u32_e32 v161, s5, v157
	s_add_i32 m0, s0, 0xffffff80
	ds_read_b128 v[218:221], v161
	ds_read_b128 v[222:225], v161 offset:1024
	ds_read_b128 v[226:229], v161 offset:2048
	global_load_lds_dwordx4 v130, s[40:41] offset:128
	s_add_i32 m0, s0, 0x1f80
	ds_read_b128 v[230:233], v161 offset:3072
	global_load_lds_dwordx4 v134, s[40:41] offset:128
	s_barrier
; #define PG8_STAGE(bufoff, gbase, voff) do { _Pragma("unroll") for (int _i = 0; _i < 2; ++_i) \
;         __builtin_amdgcn_global_load_lds((const unsigned*)((const char*)(gbase) + (voff)[_i]), (LAS unsigned*)(lds + (bufoff) + ldsw + _i * 8192), 16, 0, 0); } while (0)
; #define PG8_MMA(ai, bj, At, Bt) do { __builtin_amdgcn_s_setprio(1); _Pragma("unroll") for (int m = 0; m < 4; ++m) _Pragma("unroll") for (int n = 0; n < 2; ++n) _Pragma("unroll") for (int k = 0; k < 2; ++k) \
;         acc[ai][bj][m][n] = __builtin_amdgcn_mfma_f32_16x16x32_bf16(Bt[n][k], At[m][k], acc[ai][bj][m][n], 0, 0, 0); __builtin_amdgcn_s_setprio(0); } while (0)
; #define PG8_WAIT_V(n) asm volatile("s_waitcnt vmcnt(" #n ")" ::: "memory")
; #define PG8_WAIT_L(n) asm volatile("s_waitcnt lgkmcnt(" #n ")" ::: "memory")
; #define PG8_BAR __builtin_amdgcn_s_barrier()
; #define PG8_SCHED __builtin_amdgcn_sched_barrier(0)
; template <class Epi, class Sched>
; DI void gemm_phase(LAS unsigned char* lds, const Gemm g, const Sched& S, const Epi& E) {
;     ...
;             PG8_BAR; PG8_WAIT_L(0); PG8_MMA(1, 0, At, B0); PG8_BAR; PG8_SCHED;
;             PG8_STAGE(PG8_SB(1, 1), b3 + hstep, voffB);
;             PG8_WAIT_V(6); PG8_BAR; PG8_MMA(1, 1, At, B1); PG8_BAR;
	s_waitcnt lgkmcnt(0)
	s_setprio 1
	v_mfma_f32_16x16x32_bf16 v[116:119], v[218:221], v[174:177], v[116:119]
	v_mfma_f32_16x16x32_bf16 v[112:115], v[226:229], v[174:177], v[112:115]
	v_mfma_f32_16x16x32_bf16 v[100:103], v[218:221], v[188:191], v[100:103]
	v_mfma_f32_16x16x32_bf16 v[96:99], v[226:229], v[188:191], v[96:99]
	v_mfma_f32_16x16x32_bf16 v[84:87], v[218:221], v[200:203], v[84:87]
	v_mfma_f32_16x16x32_bf16 v[80:83], v[226:229], v[200:203], v[80:83]
	v_mfma_f32_16x16x32_bf16 v[68:71], v[218:221], v[210:213], v[68:71]
	v_mfma_f32_16x16x32_bf16 v[64:67], v[226:229], v[210:213], v[64:67]
	v_mfma_f32_16x16x32_bf16 v[116:119], v[222:225], v[178:181], v[116:119]
	v_mfma_f32_16x16x32_bf16 v[112:115], v[230:233], v[178:181], v[112:115]
	v_mfma_f32_16x16x32_bf16 v[100:103], v[222:225], v[196:199], v[100:103]
	v_mfma_f32_16x16x32_bf16 v[96:99], v[230:233], v[196:199], v[96:99]
	v_mfma_f32_16x16x32_bf16 v[84:87], v[222:225], v[206:209], v[84:87]
	v_mfma_f32_16x16x32_bf16 v[80:83], v[230:233], v[206:209], v[80:83]
	v_mfma_f32_16x16x32_bf16 v[68:71], v[222:225], v[214:217], v[68:71]
	v_mfma_f32_16x16x32_bf16 v[64:67], v[230:233], v[214:217], v[64:67]
	s_setprio 0
	s_add_i32 m0, s59, 0xffffff80
	s_barrier
	ds_read_b128 v[174:177], v158 offset:49152
	ds_read_b128 v[178:181], v158 offset:50176
	ds_read_b128 v[188:191], v158 offset:51200
	ds_read_b128 v[196:199], v158 offset:52224
	ds_read_b128 v[200:203], v158 offset:53248
	ds_read_b128 v[206:209], v158 offset:54272
	ds_read_b128 v[210:213], v158 offset:55296
	global_load_lds_dwordx4 v128, s[42:43] offset:128
	s_add_i32 m0, s60, 0xffffff80
	ds_read_b128 v[214:217], v158 offset:56320
	global_load_lds_dwordx4 v132, s[42:43] offset:128
	s_barrier
	s_waitcnt lgkmcnt(0)
	s_setprio 1
	v_mfma_f32_16x16x32_bf16 v[60:63], v[148:151], v[174:177], v[60:63]
	v_mfma_f32_16x16x32_bf16 v[56:59], v[166:169], v[174:177], v[56:59]
	v_mfma_f32_16x16x32_bf16 v[44:47], v[148:151], v[188:191], v[44:47]
	v_mfma_f32_16x16x32_bf16 v[40:43], v[166:169], v[188:191], v[40:43]
	v_mfma_f32_16x16x32_bf16 v[28:31], v[148:151], v[200:203], v[28:31]
	v_mfma_f32_16x16x32_bf16 v[24:27], v[166:169], v[200:203], v[24:27]
	v_mfma_f32_16x16x32_bf16 v[12:15], v[148:151], v[210:213], v[12:15]
	v_mfma_f32_16x16x32_bf16 v[8:11], v[166:169], v[210:213], v[8:11]
	v_mfma_f32_16x16x32_bf16 v[60:63], v[162:165], v[178:181], v[60:63]
	v_mfma_f32_16x16x32_bf16 v[56:59], v[170:173], v[178:181], v[56:59]
	v_mfma_f32_16x16x32_bf16 v[44:47], v[162:165], v[196:199], v[44:47]
	v_mfma_f32_16x16x32_bf16 v[40:43], v[170:173], v[196:199], v[40:43]
	v_mfma_f32_16x16x32_bf16 v[28:31], v[162:165], v[206:209], v[28:31]
	v_mfma_f32_16x16x32_bf16 v[24:27], v[170:173], v[206:209], v[24:27]
	v_mfma_f32_16x16x32_bf16 v[12:15], v[162:165], v[214:217], v[12:15]
	v_mfma_f32_16x16x32_bf16 v[8:11], v[170:173], v[214:217], v[8:11]
	s_setprio 0
	s_barrier
	s_add_i32 s4, s5, s52
	s_mov_b32 m0, s4
	s_add_u32 s0, s40, 0x90080
	s_addc_u32 s1, s41, 0
	global_load_lds_dwordx4 v130, s[0:1]
	s_add_i32 m0, s4, 0x2000
	s_nop 0
	global_load_lds_dwordx4 v134, s[0:1]
	s_waitcnt vmcnt(6)
	s_barrier
	s_setprio 1
	v_mfma_f32_16x16x32_bf16 v[52:55], v[218:221], v[174:177], v[52:55]
	v_mfma_f32_16x16x32_bf16 v[48:51], v[226:229], v[174:177], v[48:51]
	v_mfma_f32_16x16x32_bf16 v[36:39], v[218:221], v[188:191], v[36:39]
	v_mfma_f32_16x16x32_bf16 v[32:35], v[226:229], v[188:191], v[32:35]
	v_mfma_f32_16x16x32_bf16 v[20:23], v[218:221], v[200:203], v[20:23]
	v_mfma_f32_16x16x32_bf16 v[16:19], v[226:229], v[200:203], v[16:19]
	v_mfma_f32_16x16x32_bf16 v[4:7], v[218:221], v[210:213], v[4:7]
	v_mfma_f32_16x16x32_bf16 v[0:3], v[226:229], v[210:213], v[0:3]
	v_mfma_f32_16x16x32_bf16 v[52:55], v[222:225], v[178:181], v[52:55]
	v_mfma_f32_16x16x32_bf16 v[48:51], v[230:233], v[178:181], v[48:51]
	v_mfma_f32_16x16x32_bf16 v[36:39], v[222:225], v[196:199], v[36:39]
	v_mfma_f32_16x16x32_bf16 v[32:35], v[230:233], v[196:199], v[32:35]
	v_mfma_f32_16x16x32_bf16 v[20:23], v[222:225], v[206:209], v[20:23]
	v_mfma_f32_16x16x32_bf16 v[16:19], v[230:233], v[206:209], v[16:19]
	v_mfma_f32_16x16x32_bf16 v[4:7], v[222:225], v[214:217], v[4:7]
	v_mfma_f32_16x16x32_bf16 v[0:3], v[230:233], v[214:217], v[0:3]
	s_setprio 0
	s_add_i32 s70, s70, 2
	s_add_u32 s8, s8, 0x100
	s_addc_u32 s9, s9, 0
	s_cmp_gt_u32 s70, 33
	s_barrier
	s_cbranch_scc1 .LBB0_1908
